# k16 + GEMM K-loop load segments issue the LDS-DMA transfers before the ds_read fragment loads (90 segments reordered)
# speedup vs baseline: 1.0030x; 1.0022x over previous
; #define PG8_STAGE(bufoff, gbase, voff) do { _Pragma("unroll") for (int _i = 0; _i < 2; ++_i) \
;         __builtin_amdgcn_global_load_lds((const unsigned*)((const char*)(gbase) + (voff)[_i]), (LAS unsigned*)(lds + (bufoff) + ldsw + _i * 8192), 16, 0, 0); } while (0)
; #define PG8_LDA(dst, b, h) do { _Pragma("unroll") for (int m = 0; m < 4; ++m) _Pragma("unroll") for (int k = 0; k < 2; ++k) dst[m][k] = *(const LAS bf16x8*)(lds + PG8_SA(b, h) + aoff + m * 2048 + k * 1024); } while (0)
; #define PG8_LDB(dst, b, h) do { _Pragma("unroll") for (int n = 0; n < 2; ++n) _Pragma("unroll") for (int k = 0; k < 2; ++k) dst[n][k] = *(const LAS bf16x8*)(lds + PG8_SB(b, h) + boff + n * 2048 + k * 1024); } while (0)
; #define PG8_MMA(ai, bj, At, Bt) do { __builtin_amdgcn_s_setprio(1); _Pragma("unroll") for (int m = 0; m < 4; ++m) _Pragma("unroll") for (int n = 0; n < 2; ++n) _Pragma("unroll") for (int k = 0; k < 2; ++k) \
;         acc[ai][bj][m][n] = __builtin_amdgcn_mfma_f32_16x16x32_bf16(Bt[n][k], At[m][k], acc[ai][bj][m][n], 0, 0, 0); __builtin_amdgcn_s_setprio(0); } while (0)
; #define PG8_WAIT_V(n) asm volatile("s_waitcnt vmcnt(" #n ")" ::: "memory")
; #define PG8_WAIT_L(n) asm volatile("s_waitcnt lgkmcnt(" #n ")" ::: "memory")
; #define PG8_BAR __builtin_amdgcn_s_barrier()
; #define PG8_SCHED __builtin_amdgcn_sched_barrier(0)
; template <class Epi>
; __device__ __forceinline__ void gemm_phase(LAS unsigned char* lds, const Gemm g, const StaticOrder& S, const Epi& E, int wave_s) {
;     ...
;             PG8_LDB(B0, 0, 0); PG8_LDB(B1, 0, 1); PG8_SCHED; PG8_LDA(At, 0, 0); PG8_STAGE(PG8_SA(1, 1), a1 + hstepA, voffA);
;             PG8_WAIT_V(8); PG8_WAIT_L(0); PG8_BAR; PG8_MMA(0, 0, At, B0); PG8_MMA(0, 1, At, B1); PG8_BAR; PG8_SCHED;
;             PG8_LDA(At, 0, 1); PG8_STAGE(PG8_SB(0, 0), b2, voffB); PG8_STAGE(PG8_SB(0, 1), b2 + hstepB, voffB); PG8_STAGE(PG8_SA(0, 0), a2, voffA);
;             PG8_WAIT_V(8); PG8_WAIT_L(0); PG8_BAR; PG8_MMA(1, 0, At, B0); PG8_MMA(1, 1, At, B1); PG8_BAR; PG8_SCHED;
.LBB0_241:
	s_add_u32 s36, s34, 0xfffc0080
	s_addc_u32 s37, s35, -1
	s_cmp_eq_u32 s60, 12
	s_cselect_b32 s39, s9, s37
	s_cselect_b32 s38, s25, s36
	s_cselect_b32 s37, s23, s59
	s_cselect_b32 s36, s57, s58
	v_lshl_add_u64 v[216:217], s[34:35], 0, v[136:137]
	s_add_i32 m0, s46, 0xc000
	s_nop 0
	global_load_lds_dwordx4 v[216:217], off
	v_lshl_add_u64 v[216:217], s[34:35], 0, v[138:139]
	s_add_i32 m0, s46, 0xe000
	s_nop 0
	global_load_lds_dwordx4 v[216:217], off
	ds_read_b128 v[144:147], v155
	ds_read_b128 v[148:151], v155 offset:1024
	ds_read_b128 v[160:163], v155 offset:2048
	ds_read_b128 v[164:167], v155 offset:3072
	ds_read_b128 v[168:171], v156
	ds_read_b128 v[172:175], v156 offset:1024
	ds_read_b128 v[176:179], v156 offset:2048
	ds_read_b128 v[180:183], v156 offset:3072
	ds_read_b128 v[184:187], v157
	ds_read_b128 v[188:191], v157 offset:1024
	ds_read_b128 v[192:195], v157 offset:2048
	ds_read_b128 v[196:199], v157 offset:3072
	ds_read_b128 v[200:203], v157 offset:4096
	ds_read_b128 v[204:207], v157 offset:5120
	ds_read_b128 v[208:211], v157 offset:6144
	ds_read_b128 v[212:215], v157 offset:7168
	s_waitcnt vmcnt(8)
	s_waitcnt lgkmcnt(0)
	s_barrier
	s_setprio 1
	s_waitcnt lgkmcnt(0)
	v_mfma_f32_16x16x32_bf16 v[124:127], v[144:147], v[184:187], v[124:127]
	v_mfma_f32_16x16x32_bf16 v[120:123], v[160:163], v[184:187], v[120:123]
	v_mfma_f32_16x16x32_bf16 v[108:111], v[144:147], v[192:195], v[108:111]
	v_mfma_f32_16x16x32_bf16 v[104:107], v[160:163], v[192:195], v[104:107]
	v_mfma_f32_16x16x32_bf16 v[92:95], v[144:147], v[200:203], v[92:95]
	v_mfma_f32_16x16x32_bf16 v[88:91], v[160:163], v[200:203], v[88:91]
	v_mfma_f32_16x16x32_bf16 v[76:79], v[144:147], v[208:211], v[76:79]
	v_mfma_f32_16x16x32_bf16 v[72:75], v[160:163], v[208:211], v[72:75]
	v_mfma_f32_16x16x32_bf16 v[124:127], v[148:151], v[188:191], v[124:127]
	v_mfma_f32_16x16x32_bf16 v[120:123], v[164:167], v[188:191], v[120:123]
	v_mfma_f32_16x16x32_bf16 v[108:111], v[148:151], v[196:199], v[108:111]
	v_mfma_f32_16x16x32_bf16 v[104:107], v[164:167], v[196:199], v[104:107]
	v_mfma_f32_16x16x32_bf16 v[92:95], v[148:151], v[204:207], v[92:95]
	v_mfma_f32_16x16x32_bf16 v[88:91], v[164:167], v[204:207], v[88:91]
	v_mfma_f32_16x16x32_bf16 v[76:79], v[148:151], v[212:215], v[76:79]
	v_mfma_f32_16x16x32_bf16 v[72:75], v[164:167], v[212:215], v[72:75]
	s_setprio 0
	s_setprio 1
	v_mfma_f32_16x16x32_bf16 v[116:119], v[168:171], v[184:187], v[116:119]
	v_mfma_f32_16x16x32_bf16 v[112:115], v[176:179], v[184:187], v[112:115]
	v_mfma_f32_16x16x32_bf16 v[100:103], v[168:171], v[192:195], v[100:103]
	v_mfma_f32_16x16x32_bf16 v[96:99], v[176:179], v[192:195], v[96:99]
	v_mfma_f32_16x16x32_bf16 v[84:87], v[168:171], v[200:203], v[84:87]
	v_mfma_f32_16x16x32_bf16 v[80:83], v[176:179], v[200:203], v[80:83]
	v_mfma_f32_16x16x32_bf16 v[68:71], v[168:171], v[208:211], v[68:71]
	v_mfma_f32_16x16x32_bf16 v[64:67], v[176:179], v[208:211], v[64:67]
	v_mfma_f32_16x16x32_bf16 v[116:119], v[172:175], v[188:191], v[116:119]
	v_mfma_f32_16x16x32_bf16 v[112:115], v[180:183], v[188:191], v[112:115]
	v_mfma_f32_16x16x32_bf16 v[100:103], v[172:175], v[196:199], v[100:103]
	v_mfma_f32_16x16x32_bf16 v[96:99], v[180:183], v[196:199], v[96:99]
	v_mfma_f32_16x16x32_bf16 v[84:87], v[172:175], v[204:207], v[84:87]
	v_mfma_f32_16x16x32_bf16 v[80:83], v[180:183], v[204:207], v[80:83]
	v_mfma_f32_16x16x32_bf16 v[68:71], v[172:175], v[212:215], v[68:71]
	v_mfma_f32_16x16x32_bf16 v[64:67], v[180:183], v[212:215], v[64:67]
	s_setprio 0
	s_barrier
	s_add_i32 s61, s53, s42
	v_lshl_add_u64 v[216:217], s[36:37], 0, v[132:133]
	s_mov_b32 m0, s61
	s_nop 0
	global_load_lds_dwordx4 v[216:217], off
	s_add_i32 m0, s61, 0x2000
	s_add_u32 s62, s36, 0x40000
	v_lshl_add_u64 v[218:219], s[36:37], 0, v[128:129]
	s_addc_u32 s63, s37, 0
	s_add_i32 s61, s54, s42
	global_load_lds_dwordx4 v[218:219], off
	v_lshl_add_u64 v[220:221], s[62:63], 0, v[132:133]
	s_mov_b32 m0, s61
	v_lshl_add_u64 v[222:223], s[38:39], 0, v[130:131]
	global_load_lds_dwordx4 v[220:221], off
	v_lshl_add_u64 v[220:221], s[62:63], 0, v[128:129]
	s_add_i32 m0, s61, 0x2000
	s_nop 0
	global_load_lds_dwordx4 v[220:221], off
	v_lshl_add_u64 v[220:221], s[38:39], 0, v[134:135]
	s_mov_b32 m0, s46
	s_nop 0
	global_load_lds_dwordx4 v[220:221], off
	s_mov_b32 m0, s47
	s_nop 0
	global_load_lds_dwordx4 v[222:223], off
	ds_read_b128 v[184:187], v157 offset:16384
	ds_read_b128 v[188:191], v157 offset:17408
	ds_read_b128 v[192:195], v157 offset:18432
	ds_read_b128 v[196:199], v157 offset:19456
	ds_read_b128 v[200:203], v157 offset:20480
	ds_read_b128 v[204:207], v157 offset:21504
	ds_read_b128 v[208:211], v157 offset:22528
	ds_read_b128 v[212:215], v157 offset:23552
	s_waitcnt vmcnt(8)
	s_waitcnt lgkmcnt(0)
	s_barrier
; #define PG8_STAGE(bufoff, gbase, voff) do { _Pragma("unroll") for (int _i = 0; _i < 2; ++_i) \
;         __builtin_amdgcn_global_load_lds((const unsigned*)((const char*)(gbase) + (voff)[_i]), (LAS unsigned*)(lds + (bufoff) + ldsw + _i * 8192), 16, 0, 0); } while (0)
; #define PG8_LDA(dst, b, h) do { _Pragma("unroll") for (int m = 0; m < 4; ++m) _Pragma("unroll") for (int k = 0; k < 2; ++k) dst[m][k] = *(const LAS bf16x8*)(lds + PG8_SA(b, h) + aoff + m * 2048 + k * 1024); } while (0)
; #define PG8_LDB(dst, b, h) do { _Pragma("unroll") for (int n = 0; n < 2; ++n) _Pragma("unroll") for (int k = 0; k < 2; ++k) dst[n][k] = *(const LAS bf16x8*)(lds + PG8_SB(b, h) + boff + n * 2048 + k * 1024); } while (0)
; #define PG8_MMA(ai, bj, At, Bt) do { __builtin_amdgcn_s_setprio(1); _Pragma("unroll") for (int m = 0; m < 4; ++m) _Pragma("unroll") for (int n = 0; n < 2; ++n) _Pragma("unroll") for (int k = 0; k < 2; ++k) \
;         acc[ai][bj][m][n] = __builtin_amdgcn_mfma_f32_16x16x32_bf16(Bt[n][k], At[m][k], acc[ai][bj][m][n], 0, 0, 0); __builtin_amdgcn_s_setprio(0); } while (0)
; #define PG8_WAIT_V(n) asm volatile("s_waitcnt vmcnt(" #n ")" ::: "memory")
; #define PG8_WAIT_L(n) asm volatile("s_waitcnt lgkmcnt(" #n ")" ::: "memory")
; #define PG8_BAR __builtin_amdgcn_s_barrier()
; #define PG8_SCHED __builtin_amdgcn_sched_barrier(0)
; template <class Epi>
; __device__ __forceinline__ void gemm_phase(LAS unsigned char* lds, const Gemm g, const StaticOrder& S, const Epi& E, int wave_s) {
;     ...
;             PG8_WAIT_V(8); PG8_WAIT_L(0); PG8_BAR; PG8_MMA(1, 0, At, B0); PG8_MMA(1, 1, At, B1); PG8_BAR; PG8_SCHED;
;             PG8_LDB(B0, 1, 0); PG8_LDB(B1, 1, 1); PG8_SCHED; PG8_LDA(At, 1, 0); PG8_STAGE(PG8_SA(0, 1), a2 + hstepA, voffA);
;             PG8_WAIT_V(8); PG8_WAIT_L(0); PG8_BAR; PG8_MMA(0, 0, At, B0); PG8_MMA(0, 1, At, B1); PG8_BAR; PG8_SCHED;
	s_setprio 1
	s_waitcnt lgkmcnt(0)
	v_mfma_f32_16x16x32_bf16 v[60:63], v[144:147], v[184:187], v[60:63]
	v_mfma_f32_16x16x32_bf16 v[56:59], v[160:163], v[184:187], v[56:59]
	v_mfma_f32_16x16x32_bf16 v[44:47], v[144:147], v[192:195], v[44:47]
	v_mfma_f32_16x16x32_bf16 v[40:43], v[160:163], v[192:195], v[40:43]
	v_mfma_f32_16x16x32_bf16 v[28:31], v[144:147], v[200:203], v[28:31]
	v_mfma_f32_16x16x32_bf16 v[24:27], v[160:163], v[200:203], v[24:27]
	v_mfma_f32_16x16x32_bf16 v[12:15], v[144:147], v[208:211], v[12:15]
	v_mfma_f32_16x16x32_bf16 v[8:11], v[160:163], v[208:211], v[8:11]
	v_mfma_f32_16x16x32_bf16 v[60:63], v[148:151], v[188:191], v[60:63]
	v_mfma_f32_16x16x32_bf16 v[56:59], v[164:167], v[188:191], v[56:59]
	v_mfma_f32_16x16x32_bf16 v[44:47], v[148:151], v[196:199], v[44:47]
	v_mfma_f32_16x16x32_bf16 v[40:43], v[164:167], v[196:199], v[40:43]
	v_mfma_f32_16x16x32_bf16 v[28:31], v[148:151], v[204:207], v[28:31]
	v_mfma_f32_16x16x32_bf16 v[24:27], v[164:167], v[204:207], v[24:27]
	v_mfma_f32_16x16x32_bf16 v[12:15], v[148:151], v[212:215], v[12:15]
	v_mfma_f32_16x16x32_bf16 v[8:11], v[164:167], v[212:215], v[8:11]
	s_setprio 0
	s_setprio 1
	v_mfma_f32_16x16x32_bf16 v[52:55], v[168:171], v[184:187], v[52:55]
	v_mfma_f32_16x16x32_bf16 v[48:51], v[176:179], v[184:187], v[48:51]
	v_mfma_f32_16x16x32_bf16 v[36:39], v[168:171], v[192:195], v[36:39]
	v_mfma_f32_16x16x32_bf16 v[32:35], v[176:179], v[192:195], v[32:35]
	v_mfma_f32_16x16x32_bf16 v[20:23], v[168:171], v[200:203], v[20:23]
	v_mfma_f32_16x16x32_bf16 v[16:19], v[176:179], v[200:203], v[16:19]
	v_mfma_f32_16x16x32_bf16 v[4:7], v[168:171], v[208:211], v[4:7]
	v_mfma_f32_16x16x32_bf16 v[0:3], v[176:179], v[208:211], v[0:3]
	v_mfma_f32_16x16x32_bf16 v[52:55], v[172:175], v[188:191], v[52:55]
	v_mfma_f32_16x16x32_bf16 v[48:51], v[180:183], v[188:191], v[48:51]
	v_mfma_f32_16x16x32_bf16 v[36:39], v[172:175], v[196:199], v[36:39]
	v_mfma_f32_16x16x32_bf16 v[32:35], v[180:183], v[196:199], v[32:35]
	v_mfma_f32_16x16x32_bf16 v[20:23], v[172:175], v[204:207], v[20:23]
	v_mfma_f32_16x16x32_bf16 v[16:19], v[180:183], v[204:207], v[16:19]
	v_mfma_f32_16x16x32_bf16 v[4:7], v[172:175], v[212:215], v[4:7]
	v_mfma_f32_16x16x32_bf16 v[0:3], v[180:183], v[212:215], v[0:3]
	s_setprio 0
	s_barrier
	s_add_i32 s61, 0, 0x18000
	s_add_i32 s62, 0, 0x1c000
	s_add_u32 s38, s38, 0x40000
	s_addc_u32 s39, s39, 0
	s_mov_b32 m0, s48
	v_lshl_add_u64 v[224:225], s[38:39], 0, v[134:135]
	global_load_lds_dwordx4 v[224:225], off
	v_lshl_add_u64 v[224:225], s[38:39], 0, v[130:131]
	s_mov_b32 m0, s49
	s_nop 0
	global_load_lds_dwordx4 v[224:225], off
	v_add_u32_e32 v164, s61, v153
	v_add_u32_e32 v180, s62, v153
	ds_read_b128 v[144:147], v164
	ds_read_b128 v[148:151], v164 offset:1024
	ds_read_b128 v[160:163], v164 offset:2048
	ds_read_b128 v[164:167], v164 offset:3072
	ds_read_b128 v[168:171], v180
	ds_read_b128 v[172:175], v180 offset:1024
	ds_read_b128 v[176:179], v180 offset:2048
	ds_read_b128 v[180:183], v180 offset:3072
	ds_read_b128 v[184:187], v157 offset:32768
	ds_read_b128 v[188:191], v157 offset:33792
	ds_read_b128 v[192:195], v157 offset:34816
	ds_read_b128 v[196:199], v157 offset:35840
	ds_read_b128 v[200:203], v157 offset:36864
	ds_read_b128 v[204:207], v157 offset:37888
	ds_read_b128 v[208:211], v157 offset:38912
	ds_read_b128 v[212:215], v157 offset:39936
	s_waitcnt vmcnt(8)
	s_waitcnt lgkmcnt(0)
	s_barrier
	s_setprio 1
	s_waitcnt lgkmcnt(0)
	v_mfma_f32_16x16x32_bf16 v[124:127], v[144:147], v[184:187], v[124:127]
	v_mfma_f32_16x16x32_bf16 v[120:123], v[160:163], v[184:187], v[120:123]
	v_mfma_f32_16x16x32_bf16 v[108:111], v[144:147], v[192:195], v[108:111]
	v_mfma_f32_16x16x32_bf16 v[104:107], v[160:163], v[192:195], v[104:107]
	v_mfma_f32_16x16x32_bf16 v[92:95], v[144:147], v[200:203], v[92:95]
	v_mfma_f32_16x16x32_bf16 v[88:91], v[160:163], v[200:203], v[88:91]
	v_mfma_f32_16x16x32_bf16 v[76:79], v[144:147], v[208:211], v[76:79]
	v_mfma_f32_16x16x32_bf16 v[72:75], v[160:163], v[208:211], v[72:75]
	v_mfma_f32_16x16x32_bf16 v[124:127], v[148:151], v[188:191], v[124:127]
	v_mfma_f32_16x16x32_bf16 v[120:123], v[164:167], v[188:191], v[120:123]
	v_mfma_f32_16x16x32_bf16 v[108:111], v[148:151], v[196:199], v[108:111]
	v_mfma_f32_16x16x32_bf16 v[104:107], v[164:167], v[196:199], v[104:107]
	v_mfma_f32_16x16x32_bf16 v[92:95], v[148:151], v[204:207], v[92:95]
	v_mfma_f32_16x16x32_bf16 v[88:91], v[164:167], v[204:207], v[88:91]
	v_mfma_f32_16x16x32_bf16 v[76:79], v[148:151], v[212:215], v[76:79]
	v_mfma_f32_16x16x32_bf16 v[72:75], v[164:167], v[212:215], v[72:75]
	s_setprio 0
	s_setprio 1
	v_mfma_f32_16x16x32_bf16 v[116:119], v[168:171], v[184:187], v[116:119]
	v_mfma_f32_16x16x32_bf16 v[112:115], v[176:179], v[184:187], v[112:115]
	v_mfma_f32_16x16x32_bf16 v[100:103], v[168:171], v[192:195], v[100:103]
	v_mfma_f32_16x16x32_bf16 v[96:99], v[176:179], v[192:195], v[96:99]
	v_mfma_f32_16x16x32_bf16 v[84:87], v[168:171], v[200:203], v[84:87]
	v_mfma_f32_16x16x32_bf16 v[80:83], v[176:179], v[200:203], v[80:83]
	v_mfma_f32_16x16x32_bf16 v[68:71], v[168:171], v[208:211], v[68:71]
	v_mfma_f32_16x16x32_bf16 v[64:67], v[176:179], v[208:211], v[64:67]
	v_mfma_f32_16x16x32_bf16 v[116:119], v[172:175], v[188:191], v[116:119]
	v_mfma_f32_16x16x32_bf16 v[112:115], v[180:183], v[188:191], v[112:115]
	v_mfma_f32_16x16x32_bf16 v[100:103], v[172:175], v[196:199], v[100:103]
	v_mfma_f32_16x16x32_bf16 v[96:99], v[180:183], v[196:199], v[96:99]
	v_mfma_f32_16x16x32_bf16 v[84:87], v[172:175], v[204:207], v[84:87]
	v_mfma_f32_16x16x32_bf16 v[80:83], v[180:183], v[204:207], v[80:83]
	v_mfma_f32_16x16x32_bf16 v[68:71], v[172:175], v[212:215], v[68:71]
	v_mfma_f32_16x16x32_bf16 v[64:67], v[180:183], v[212:215], v[64:67]
	s_setprio 0
	s_barrier
; #define PG8_STAGE(bufoff, gbase, voff) do { _Pragma("unroll") for (int _i = 0; _i < 2; ++_i) \
;         __builtin_amdgcn_global_load_lds((const unsigned*)((const char*)(gbase) + (voff)[_i]), (LAS unsigned*)(lds + (bufoff) + ldsw + _i * 8192), 16, 0, 0); } while (0)
; #define PG8_LDA(dst, b, h) do { _Pragma("unroll") for (int m = 0; m < 4; ++m) _Pragma("unroll") for (int k = 0; k < 2; ++k) dst[m][k] = *(const LAS bf16x8*)(lds + PG8_SA(b, h) + aoff + m * 2048 + k * 1024); } while (0)
; #define PG8_MMA(ai, bj, At, Bt) do { __builtin_amdgcn_s_setprio(1); _Pragma("unroll") for (int m = 0; m < 4; ++m) _Pragma("unroll") for (int n = 0; n < 2; ++n) _Pragma("unroll") for (int k = 0; k < 2; ++k) \
;         acc[ai][bj][m][n] = __builtin_amdgcn_mfma_f32_16x16x32_bf16(Bt[n][k], At[m][k], acc[ai][bj][m][n], 0, 0, 0); __builtin_amdgcn_s_setprio(0); } while (0)
; #define PG8_WAIT_V(n) asm volatile("s_waitcnt vmcnt(" #n ")" ::: "memory")
; #define PG8_WAIT_L(n) asm volatile("s_waitcnt lgkmcnt(" #n ")" ::: "memory")
; #define PG8_BAR __builtin_amdgcn_s_barrier()
; #define PG8_SCHED __builtin_amdgcn_sched_barrier(0)
; template <class Epi>
; __device__ __forceinline__ void gemm_phase(LAS unsigned char* lds, const Gemm g, const StaticOrder& S, const Epi& E, int wave_s) {
;     ...
;             PG8_LDA(At, 1, 1); PG8_STAGE(PG8_SB(1, 0), b3, voffB); PG8_STAGE(PG8_SB(1, 1), b3 + hstepB, voffB); PG8_STAGE(PG8_SA(1, 0), a3, voffA);
;             PG8_WAIT_V(8); PG8_WAIT_L(0); PG8_BAR; PG8_MMA(1, 0, At, B0); PG8_MMA(1, 1, At, B1); PG8_BAR; PG8_SCHED;
;         }
	s_add_i32 s38, s61, s42
	v_lshl_add_u64 v[216:217], v[216:217], 0, s[18:19]
	s_mov_b32 m0, s38
	s_nop 0
	global_load_lds_dwordx4 v[216:217], off
	s_add_i32 m0, s38, 0x2000
	s_add_u32 s36, s36, 0x40080
	v_lshl_add_u64 v[216:217], v[218:219], 0, s[18:19]
	s_addc_u32 s37, s37, 0
	s_add_i32 s38, s62, s42
	global_load_lds_dwordx4 v[216:217], off
	v_lshl_add_u64 v[216:217], s[36:37], 0, v[132:133]
	s_mov_b32 m0, s38
	s_nop 0
	global_load_lds_dwordx4 v[216:217], off
	v_lshl_add_u64 v[216:217], s[36:37], 0, v[128:129]
	s_add_i32 m0, s38, 0x2000
	s_nop 0
	global_load_lds_dwordx4 v[216:217], off
	v_lshl_add_u64 v[216:217], v[220:221], 0, s[18:19]
	s_mov_b32 m0, s51
	s_nop 0
	global_load_lds_dwordx4 v[216:217], off
	v_lshl_add_u64 v[216:217], v[222:223], 0, s[18:19]
	s_mov_b32 m0, s52
	s_nop 0
	global_load_lds_dwordx4 v[216:217], off
	ds_read_b128 v[184:187], v157 offset:49152
	ds_read_b128 v[188:191], v157 offset:50176
	ds_read_b128 v[192:195], v157 offset:51200
	ds_read_b128 v[196:199], v157 offset:52224
	ds_read_b128 v[200:203], v157 offset:53248
	ds_read_b128 v[204:207], v157 offset:54272
	ds_read_b128 v[208:211], v157 offset:55296
	ds_read_b128 v[212:215], v157 offset:56320
	s_waitcnt vmcnt(8)
	s_waitcnt lgkmcnt(0)
	s_barrier
	s_setprio 1
	s_waitcnt lgkmcnt(0)
	v_mfma_f32_16x16x32_bf16 v[60:63], v[144:147], v[184:187], v[60:63]
	v_mfma_f32_16x16x32_bf16 v[56:59], v[160:163], v[184:187], v[56:59]
	v_mfma_f32_16x16x32_bf16 v[44:47], v[144:147], v[192:195], v[44:47]
	v_mfma_f32_16x16x32_bf16 v[40:43], v[160:163], v[192:195], v[40:43]
	v_mfma_f32_16x16x32_bf16 v[28:31], v[144:147], v[200:203], v[28:31]
	v_mfma_f32_16x16x32_bf16 v[24:27], v[160:163], v[200:203], v[24:27]
	v_mfma_f32_16x16x32_bf16 v[12:15], v[144:147], v[208:211], v[12:15]
	v_mfma_f32_16x16x32_bf16 v[8:11], v[160:163], v[208:211], v[8:11]
	v_mfma_f32_16x16x32_bf16 v[60:63], v[148:151], v[188:191], v[60:63]
	v_mfma_f32_16x16x32_bf16 v[56:59], v[164:167], v[188:191], v[56:59]
	v_mfma_f32_16x16x32_bf16 v[44:47], v[148:151], v[196:199], v[44:47]
	v_mfma_f32_16x16x32_bf16 v[40:43], v[164:167], v[196:199], v[40:43]
	v_mfma_f32_16x16x32_bf16 v[28:31], v[148:151], v[204:207], v[28:31]
	v_mfma_f32_16x16x32_bf16 v[24:27], v[164:167], v[204:207], v[24:27]
	v_mfma_f32_16x16x32_bf16 v[12:15], v[148:151], v[212:215], v[12:15]
	v_mfma_f32_16x16x32_bf16 v[8:11], v[164:167], v[212:215], v[8:11]
	s_setprio 0
	s_setprio 1
	v_mfma_f32_16x16x32_bf16 v[52:55], v[168:171], v[184:187], v[52:55]
	v_mfma_f32_16x16x32_bf16 v[48:51], v[176:179], v[184:187], v[48:51]
	v_mfma_f32_16x16x32_bf16 v[36:39], v[168:171], v[192:195], v[36:39]
	v_mfma_f32_16x16x32_bf16 v[32:35], v[176:179], v[192:195], v[32:35]
	v_mfma_f32_16x16x32_bf16 v[20:23], v[168:171], v[200:203], v[20:23]
	v_mfma_f32_16x16x32_bf16 v[16:19], v[176:179], v[200:203], v[16:19]
	v_mfma_f32_16x16x32_bf16 v[4:7], v[168:171], v[208:211], v[4:7]
	v_mfma_f32_16x16x32_bf16 v[0:3], v[176:179], v[208:211], v[0:3]
	v_mfma_f32_16x16x32_bf16 v[52:55], v[172:175], v[188:191], v[52:55]
	v_mfma_f32_16x16x32_bf16 v[48:51], v[180:183], v[188:191], v[48:51]
	v_mfma_f32_16x16x32_bf16 v[36:39], v[172:175], v[196:199], v[36:39]
	v_mfma_f32_16x16x32_bf16 v[32:35], v[180:183], v[196:199], v[32:35]
	v_mfma_f32_16x16x32_bf16 v[20:23], v[172:175], v[204:207], v[20:23]
	v_mfma_f32_16x16x32_bf16 v[16:19], v[180:183], v[204:207], v[16:19]
	v_mfma_f32_16x16x32_bf16 v[4:7], v[172:175], v[212:215], v[4:7]
	v_mfma_f32_16x16x32_bf16 v[0:3], v[180:183], v[212:215], v[0:3]
	s_setprio 0
	s_barrier
	s_add_i32 s60, s60, 2
	s_add_u32 s34, s34, 0x100
	s_addc_u32 s35, s35, 0
	s_add_u32 s58, s58, 0x100
	s_addc_u32 s59, s59, 0
	s_cmp_gt_u32 s60, 13
	s_cbranch_scc0 .LBB0_241
	s_and_b64 vcc, exec, s[20:21]
	s_cbranch_vccz .LBB0_244
	s_barrier

; #define PG8_STAGE(bufoff, gbase, voff) do { _Pragma("unroll") for (int _i = 0; _i < 2; ++_i) \
;         __builtin_amdgcn_global_load_lds((const unsigned*)((const char*)(gbase) + (voff)[_i]), (LAS unsigned*)(lds + (bufoff) + ldsw + _i * 8192), 16, 0, 0); } while (0)
; #define PG8_LDA(dst, b, h) do { _Pragma("unroll") for (int m = 0; m < 4; ++m) _Pragma("unroll") for (int k = 0; k < 2; ++k) dst[m][k] = *(const LAS bf16x8*)(lds + PG8_SA(b, h) + aoff + m * 2048 + k * 1024); } while (0)
; #define PG8_LDB(dst, b, h) do { _Pragma("unroll") for (int n = 0; n < 2; ++n) _Pragma("unroll") for (int k = 0; k < 2; ++k) dst[n][k] = *(const LAS bf16x8*)(lds + PG8_SB(b, h) + boff + n * 2048 + k * 1024); } while (0)
; #define PG8_MMA(ai, bj, At, Bt) do { __builtin_amdgcn_s_setprio(1); _Pragma("unroll") for (int m = 0; m < 4; ++m) _Pragma("unroll") for (int n = 0; n < 2; ++n) _Pragma("unroll") for (int k = 0; k < 2; ++k) \
;         acc[ai][bj][m][n] = __builtin_amdgcn_mfma_f32_16x16x32_bf16(Bt[n][k], At[m][k], acc[ai][bj][m][n], 0, 0, 0); __builtin_amdgcn_s_setprio(0); } while (0)
; #define PG8_WAIT_V(n) asm volatile("s_waitcnt vmcnt(" #n ")" ::: "memory")
; #define PG8_WAIT_L(n) asm volatile("s_waitcnt lgkmcnt(" #n ")" ::: "memory")
; #define PG8_BAR __builtin_amdgcn_s_barrier()
; #define PG8_SCHED __builtin_amdgcn_sched_barrier(0)
; template <class Epi>
; __device__ __forceinline__ void gemm_phase(LAS unsigned char* lds, const Gemm g, const StaticOrder& S, const Epi& E, int wave_s) {
;     ...
;             PG8_LDB(B0, 0, 0); PG8_LDB(B1, 0, 1); PG8_SCHED; PG8_LDA(At, 0, 0); PG8_STAGE(PG8_SA(1, 1), a1 + hstepA, voffA);
;             PG8_WAIT_V(8); PG8_WAIT_L(0); PG8_BAR; PG8_MMA(0, 0, At, B0); PG8_MMA(0, 1, At, B1); PG8_BAR; PG8_SCHED;
;             PG8_LDA(At, 0, 1); PG8_STAGE(PG8_SB(0, 0), b2, voffB); PG8_STAGE(PG8_SB(0, 1), b2 + hstepB, voffB); PG8_STAGE(PG8_SA(0, 0), a2, voffA);
;             PG8_WAIT_V(8); PG8_WAIT_L(0); PG8_BAR; PG8_MMA(1, 0, At, B0); PG8_MMA(1, 1, At, B1); PG8_BAR; PG8_SCHED;
.LBB0_264:
	s_add_u32 s58, s8, 0xfffc0080
	s_addc_u32 s59, s9, -1
	s_add_i32 s89, 0, 0x10000
	s_cmp_eq_u32 s88, 12
	s_cselect_b32 s61, s53, s59
	s_cselect_b32 s60, s84, s58
	v_add_u32_e32 v156, s89, v145
	s_cselect_b32 s59, s51, s87
	s_cselect_b32 s58, s85, s86
	s_add_i32 s92, 0, 0x14000
	ds_read_b128 v[140:143], v156
	ds_read_b128 v[148:151], v156 offset:1024
	ds_read_b128 v[152:155], v156 offset:2048
	ds_read_b128 v[162:165], v156 offset:3072
	v_add_u32_e32 v156, s92, v145
	ds_read_b128 v[166:169], v156
	ds_read_b128 v[170:173], v156 offset:1024
	ds_read_b128 v[174:177], v156 offset:2048
	ds_read_b128 v[178:181], v156 offset:3072
	v_lshl_add_u64 v[156:157], s[8:9], 0, v[136:137]
	s_add_i32 m0, s73, 0xc000
	ds_read_b128 v[182:185], v147
	ds_read_b128 v[186:189], v147 offset:1024
	ds_read_b128 v[190:193], v147 offset:2048
	ds_read_b128 v[194:197], v147 offset:3072
	ds_read_b128 v[198:201], v147 offset:4096
	ds_read_b128 v[202:205], v147 offset:5120
	ds_read_b128 v[206:209], v147 offset:6144
	ds_read_b128 v[210:213], v147 offset:7168
	global_load_lds_dwordx4 v[156:157], off
	v_lshl_add_u64 v[156:157], s[8:9], 0, v[138:139]
	s_add_i32 m0, s73, 0xe000
	s_nop 0
	global_load_lds_dwordx4 v[156:157], off
	s_waitcnt vmcnt(8)
	s_waitcnt lgkmcnt(0)
	s_barrier
	s_setprio 1
	s_waitcnt lgkmcnt(0)
	v_mfma_f32_16x16x32_bf16 v[124:127], v[140:143], v[182:185], v[124:127]
	v_mfma_f32_16x16x32_bf16 v[120:123], v[152:155], v[182:185], v[120:123]
	v_mfma_f32_16x16x32_bf16 v[108:111], v[140:143], v[190:193], v[108:111]
	v_mfma_f32_16x16x32_bf16 v[104:107], v[152:155], v[190:193], v[104:107]
	v_mfma_f32_16x16x32_bf16 v[92:95], v[140:143], v[198:201], v[92:95]
	v_mfma_f32_16x16x32_bf16 v[88:91], v[152:155], v[198:201], v[88:91]
	v_mfma_f32_16x16x32_bf16 v[76:79], v[140:143], v[206:209], v[76:79]
	v_mfma_f32_16x16x32_bf16 v[72:75], v[152:155], v[206:209], v[72:75]
	v_mfma_f32_16x16x32_bf16 v[124:127], v[148:151], v[186:189], v[124:127]
	v_mfma_f32_16x16x32_bf16 v[120:123], v[162:165], v[186:189], v[120:123]
	v_mfma_f32_16x16x32_bf16 v[108:111], v[148:151], v[194:197], v[108:111]
	v_mfma_f32_16x16x32_bf16 v[104:107], v[162:165], v[194:197], v[104:107]
	v_mfma_f32_16x16x32_bf16 v[92:95], v[148:151], v[202:205], v[92:95]
	v_mfma_f32_16x16x32_bf16 v[88:91], v[162:165], v[202:205], v[88:91]
	v_mfma_f32_16x16x32_bf16 v[76:79], v[148:151], v[210:213], v[76:79]
	v_mfma_f32_16x16x32_bf16 v[72:75], v[162:165], v[210:213], v[72:75]
	s_setprio 0
	s_setprio 1
	v_mfma_f32_16x16x32_bf16 v[116:119], v[166:169], v[182:185], v[116:119]
	v_mfma_f32_16x16x32_bf16 v[112:115], v[174:177], v[182:185], v[112:115]
	v_mfma_f32_16x16x32_bf16 v[100:103], v[166:169], v[190:193], v[100:103]
	v_mfma_f32_16x16x32_bf16 v[96:99], v[174:177], v[190:193], v[96:99]
	v_mfma_f32_16x16x32_bf16 v[84:87], v[166:169], v[198:201], v[84:87]
	v_mfma_f32_16x16x32_bf16 v[80:83], v[174:177], v[198:201], v[80:83]
	v_mfma_f32_16x16x32_bf16 v[68:71], v[166:169], v[206:209], v[68:71]
	v_mfma_f32_16x16x32_bf16 v[64:67], v[174:177], v[206:209], v[64:67]
	v_mfma_f32_16x16x32_bf16 v[116:119], v[170:173], v[186:189], v[116:119]
	v_mfma_f32_16x16x32_bf16 v[112:115], v[178:181], v[186:189], v[112:115]
	v_mfma_f32_16x16x32_bf16 v[100:103], v[170:173], v[194:197], v[100:103]
	v_mfma_f32_16x16x32_bf16 v[96:99], v[178:181], v[194:197], v[96:99]
	v_mfma_f32_16x16x32_bf16 v[84:87], v[170:173], v[202:205], v[84:87]
	v_mfma_f32_16x16x32_bf16 v[80:83], v[178:181], v[202:205], v[80:83]
	v_mfma_f32_16x16x32_bf16 v[68:71], v[170:173], v[210:213], v[68:71]
	v_mfma_f32_16x16x32_bf16 v[64:67], v[178:181], v[210:213], v[64:67]
	s_setprio 0
	s_barrier
	s_add_i32 s89, s89, s72
	v_lshl_add_u64 v[156:157], s[58:59], 0, v[128:129]
	s_mov_b32 m0, s89
	s_nop 0
	global_load_lds_dwordx4 v[156:157], off
	s_add_i32 m0, s89, 0x2000
	s_add_u32 s90, s58, 0x40000
	v_lshl_add_u64 v[214:215], s[58:59], 0, v[130:131]
	s_addc_u32 s91, s59, 0
	s_add_i32 s89, s92, s72
	global_load_lds_dwordx4 v[214:215], off
	v_lshl_add_u64 v[216:217], s[90:91], 0, v[128:129]
	s_mov_b32 m0, s89
	v_lshl_add_u64 v[218:219], s[60:61], 0, v[132:133]
	global_load_lds_dwordx4 v[216:217], off
	v_lshl_add_u64 v[216:217], s[90:91], 0, v[130:131]
	s_add_i32 m0, s89, 0x2000
	s_nop 0
	global_load_lds_dwordx4 v[216:217], off
	v_lshl_add_u64 v[216:217], s[60:61], 0, v[134:135]
	s_mov_b32 m0, s73
	s_nop 0
	global_load_lds_dwordx4 v[216:217], off
	s_mov_b32 m0, s74
	s_nop 0
	global_load_lds_dwordx4 v[218:219], off
	ds_read_b128 v[182:185], v147 offset:16384
	ds_read_b128 v[186:189], v147 offset:17408
	ds_read_b128 v[190:193], v147 offset:18432
	ds_read_b128 v[194:197], v147 offset:19456
	ds_read_b128 v[198:201], v147 offset:20480
	ds_read_b128 v[202:205], v147 offset:21504
	ds_read_b128 v[206:209], v147 offset:22528
	ds_read_b128 v[210:213], v147 offset:23552
	s_waitcnt vmcnt(8)
	s_waitcnt lgkmcnt(0)
	s_barrier
; #define PG8_STAGE(bufoff, gbase, voff) do { _Pragma("unroll") for (int _i = 0; _i < 2; ++_i) \
;         __builtin_amdgcn_global_load_lds((const unsigned*)((const char*)(gbase) + (voff)[_i]), (LAS unsigned*)(lds + (bufoff) + ldsw + _i * 8192), 16, 0, 0); } while (0)
; #define PG8_LDA(dst, b, h) do { _Pragma("unroll") for (int m = 0; m < 4; ++m) _Pragma("unroll") for (int k = 0; k < 2; ++k) dst[m][k] = *(const LAS bf16x8*)(lds + PG8_SA(b, h) + aoff + m * 2048 + k * 1024); } while (0)
; #define PG8_LDB(dst, b, h) do { _Pragma("unroll") for (int n = 0; n < 2; ++n) _Pragma("unroll") for (int k = 0; k < 2; ++k) dst[n][k] = *(const LAS bf16x8*)(lds + PG8_SB(b, h) + boff + n * 2048 + k * 1024); } while (0)
; #define PG8_MMA(ai, bj, At, Bt) do { __builtin_amdgcn_s_setprio(1); _Pragma("unroll") for (int m = 0; m < 4; ++m) _Pragma("unroll") for (int n = 0; n < 2; ++n) _Pragma("unroll") for (int k = 0; k < 2; ++k) \
;         acc[ai][bj][m][n] = __builtin_amdgcn_mfma_f32_16x16x32_bf16(Bt[n][k], At[m][k], acc[ai][bj][m][n], 0, 0, 0); __builtin_amdgcn_s_setprio(0); } while (0)
; #define PG8_WAIT_V(n) asm volatile("s_waitcnt vmcnt(" #n ")" ::: "memory")
; #define PG8_WAIT_L(n) asm volatile("s_waitcnt lgkmcnt(" #n ")" ::: "memory")
; #define PG8_BAR __builtin_amdgcn_s_barrier()
; #define PG8_SCHED __builtin_amdgcn_sched_barrier(0)
; template <class Epi>
; __device__ __forceinline__ void gemm_phase(LAS unsigned char* lds, const Gemm g, const StaticOrder& S, const Epi& E, int wave_s) {
;     ...
;             PG8_WAIT_V(8); PG8_WAIT_L(0); PG8_BAR; PG8_MMA(1, 0, At, B0); PG8_MMA(1, 1, At, B1); PG8_BAR; PG8_SCHED;
;             PG8_LDB(B0, 1, 0); PG8_LDB(B1, 1, 1); PG8_SCHED; PG8_LDA(At, 1, 0); PG8_STAGE(PG8_SA(0, 1), a2 + hstepA, voffA);
;             PG8_WAIT_V(8); PG8_WAIT_L(0); PG8_BAR; PG8_MMA(0, 0, At, B0); PG8_MMA(0, 1, At, B1); PG8_BAR; PG8_SCHED;
	s_setprio 1
	s_waitcnt lgkmcnt(0)
	v_mfma_f32_16x16x32_bf16 v[60:63], v[140:143], v[182:185], v[60:63]
	v_mfma_f32_16x16x32_bf16 v[56:59], v[152:155], v[182:185], v[56:59]
	v_mfma_f32_16x16x32_bf16 v[44:47], v[140:143], v[190:193], v[44:47]
	v_mfma_f32_16x16x32_bf16 v[40:43], v[152:155], v[190:193], v[40:43]
	v_mfma_f32_16x16x32_bf16 v[28:31], v[140:143], v[198:201], v[28:31]
	v_mfma_f32_16x16x32_bf16 v[24:27], v[152:155], v[198:201], v[24:27]
	v_mfma_f32_16x16x32_bf16 v[12:15], v[140:143], v[206:209], v[12:15]
	v_mfma_f32_16x16x32_bf16 v[8:11], v[152:155], v[206:209], v[8:11]
	v_mfma_f32_16x16x32_bf16 v[60:63], v[148:151], v[186:189], v[60:63]
	v_mfma_f32_16x16x32_bf16 v[56:59], v[162:165], v[186:189], v[56:59]
	v_mfma_f32_16x16x32_bf16 v[44:47], v[148:151], v[194:197], v[44:47]
	v_mfma_f32_16x16x32_bf16 v[40:43], v[162:165], v[194:197], v[40:43]
	v_mfma_f32_16x16x32_bf16 v[28:31], v[148:151], v[202:205], v[28:31]
	v_mfma_f32_16x16x32_bf16 v[24:27], v[162:165], v[202:205], v[24:27]
	v_mfma_f32_16x16x32_bf16 v[12:15], v[148:151], v[210:213], v[12:15]
	v_mfma_f32_16x16x32_bf16 v[8:11], v[162:165], v[210:213], v[8:11]
	s_setprio 0
	s_setprio 1
	v_mfma_f32_16x16x32_bf16 v[52:55], v[166:169], v[182:185], v[52:55]
	v_mfma_f32_16x16x32_bf16 v[48:51], v[174:177], v[182:185], v[48:51]
	v_mfma_f32_16x16x32_bf16 v[36:39], v[166:169], v[190:193], v[36:39]
	v_mfma_f32_16x16x32_bf16 v[32:35], v[174:177], v[190:193], v[32:35]
	v_mfma_f32_16x16x32_bf16 v[20:23], v[166:169], v[198:201], v[20:23]
	v_mfma_f32_16x16x32_bf16 v[16:19], v[174:177], v[198:201], v[16:19]
	v_mfma_f32_16x16x32_bf16 v[4:7], v[166:169], v[206:209], v[4:7]
	v_mfma_f32_16x16x32_bf16 v[0:3], v[174:177], v[206:209], v[0:3]
	v_mfma_f32_16x16x32_bf16 v[52:55], v[170:173], v[186:189], v[52:55]
	v_mfma_f32_16x16x32_bf16 v[48:51], v[178:181], v[186:189], v[48:51]
	v_mfma_f32_16x16x32_bf16 v[36:39], v[170:173], v[194:197], v[36:39]
	v_mfma_f32_16x16x32_bf16 v[32:35], v[178:181], v[194:197], v[32:35]
	v_mfma_f32_16x16x32_bf16 v[20:23], v[170:173], v[202:205], v[20:23]
	v_mfma_f32_16x16x32_bf16 v[16:19], v[178:181], v[202:205], v[16:19]
	v_mfma_f32_16x16x32_bf16 v[4:7], v[170:173], v[210:213], v[4:7]
	v_mfma_f32_16x16x32_bf16 v[0:3], v[178:181], v[210:213], v[0:3]
	s_setprio 0
	s_barrier
	s_add_i32 s89, 0, 0x18000
	s_add_i32 s90, 0, 0x1c000
	s_add_u32 s60, s60, 0x40000
	s_addc_u32 s61, s61, 0
	s_mov_b32 m0, s75
	v_lshl_add_u64 v[220:221], s[60:61], 0, v[134:135]
	global_load_lds_dwordx4 v[220:221], off
	v_lshl_add_u64 v[220:221], s[60:61], 0, v[132:133]
	s_mov_b32 m0, s76
	s_nop 0
	global_load_lds_dwordx4 v[220:221], off
	v_add_u32_e32 v162, s89, v145
	v_add_u32_e32 v178, s90, v145
	ds_read_b128 v[140:143], v162
	ds_read_b128 v[148:151], v162 offset:1024
	ds_read_b128 v[152:155], v162 offset:2048
	ds_read_b128 v[162:165], v162 offset:3072
	ds_read_b128 v[166:169], v178
	ds_read_b128 v[170:173], v178 offset:1024
	ds_read_b128 v[174:177], v178 offset:2048
	ds_read_b128 v[178:181], v178 offset:3072
	ds_read_b128 v[182:185], v147 offset:32768
	ds_read_b128 v[186:189], v147 offset:33792
	ds_read_b128 v[190:193], v147 offset:34816
	ds_read_b128 v[194:197], v147 offset:35840
	ds_read_b128 v[198:201], v147 offset:36864
	ds_read_b128 v[202:205], v147 offset:37888
	ds_read_b128 v[206:209], v147 offset:38912
	ds_read_b128 v[210:213], v147 offset:39936
	s_waitcnt vmcnt(8)
	s_waitcnt lgkmcnt(0)
	s_barrier
	s_setprio 1
	s_waitcnt lgkmcnt(0)
	v_mfma_f32_16x16x32_bf16 v[124:127], v[140:143], v[182:185], v[124:127]
	v_mfma_f32_16x16x32_bf16 v[120:123], v[152:155], v[182:185], v[120:123]
	v_mfma_f32_16x16x32_bf16 v[108:111], v[140:143], v[190:193], v[108:111]
	v_mfma_f32_16x16x32_bf16 v[104:107], v[152:155], v[190:193], v[104:107]
	v_mfma_f32_16x16x32_bf16 v[92:95], v[140:143], v[198:201], v[92:95]
	v_mfma_f32_16x16x32_bf16 v[88:91], v[152:155], v[198:201], v[88:91]
	v_mfma_f32_16x16x32_bf16 v[76:79], v[140:143], v[206:209], v[76:79]
	v_mfma_f32_16x16x32_bf16 v[72:75], v[152:155], v[206:209], v[72:75]
	v_mfma_f32_16x16x32_bf16 v[124:127], v[148:151], v[186:189], v[124:127]
	v_mfma_f32_16x16x32_bf16 v[120:123], v[162:165], v[186:189], v[120:123]
	v_mfma_f32_16x16x32_bf16 v[108:111], v[148:151], v[194:197], v[108:111]
	v_mfma_f32_16x16x32_bf16 v[104:107], v[162:165], v[194:197], v[104:107]
	v_mfma_f32_16x16x32_bf16 v[92:95], v[148:151], v[202:205], v[92:95]
	v_mfma_f32_16x16x32_bf16 v[88:91], v[162:165], v[202:205], v[88:91]
	v_mfma_f32_16x16x32_bf16 v[76:79], v[148:151], v[210:213], v[76:79]
	v_mfma_f32_16x16x32_bf16 v[72:75], v[162:165], v[210:213], v[72:75]
	s_setprio 0
	s_setprio 1
	v_mfma_f32_16x16x32_bf16 v[116:119], v[166:169], v[182:185], v[116:119]
	v_mfma_f32_16x16x32_bf16 v[112:115], v[174:177], v[182:185], v[112:115]
	v_mfma_f32_16x16x32_bf16 v[100:103], v[166:169], v[190:193], v[100:103]
	v_mfma_f32_16x16x32_bf16 v[96:99], v[174:177], v[190:193], v[96:99]
	v_mfma_f32_16x16x32_bf16 v[84:87], v[166:169], v[198:201], v[84:87]
	v_mfma_f32_16x16x32_bf16 v[80:83], v[174:177], v[198:201], v[80:83]
	v_mfma_f32_16x16x32_bf16 v[68:71], v[166:169], v[206:209], v[68:71]
	v_mfma_f32_16x16x32_bf16 v[64:67], v[174:177], v[206:209], v[64:67]
	v_mfma_f32_16x16x32_bf16 v[116:119], v[170:173], v[186:189], v[116:119]
	v_mfma_f32_16x16x32_bf16 v[112:115], v[178:181], v[186:189], v[112:115]
	v_mfma_f32_16x16x32_bf16 v[100:103], v[170:173], v[194:197], v[100:103]
	v_mfma_f32_16x16x32_bf16 v[96:99], v[178:181], v[194:197], v[96:99]
	v_mfma_f32_16x16x32_bf16 v[84:87], v[170:173], v[202:205], v[84:87]
	v_mfma_f32_16x16x32_bf16 v[80:83], v[178:181], v[202:205], v[80:83]
	v_mfma_f32_16x16x32_bf16 v[68:71], v[170:173], v[210:213], v[68:71]
	v_mfma_f32_16x16x32_bf16 v[64:67], v[178:181], v[210:213], v[64:67]
	s_setprio 0
	s_barrier
; #define PG8_STAGE(bufoff, gbase, voff) do { _Pragma("unroll") for (int _i = 0; _i < 2; ++_i) \
;         __builtin_amdgcn_global_load_lds((const unsigned*)((const char*)(gbase) + (voff)[_i]), (LAS unsigned*)(lds + (bufoff) + ldsw + _i * 8192), 16, 0, 0); } while (0)
; #define PG8_LDA(dst, b, h) do { _Pragma("unroll") for (int m = 0; m < 4; ++m) _Pragma("unroll") for (int k = 0; k < 2; ++k) dst[m][k] = *(const LAS bf16x8*)(lds + PG8_SA(b, h) + aoff + m * 2048 + k * 1024); } while (0)
; #define PG8_MMA(ai, bj, At, Bt) do { __builtin_amdgcn_s_setprio(1); _Pragma("unroll") for (int m = 0; m < 4; ++m) _Pragma("unroll") for (int n = 0; n < 2; ++n) _Pragma("unroll") for (int k = 0; k < 2; ++k) \
;         acc[ai][bj][m][n] = __builtin_amdgcn_mfma_f32_16x16x32_bf16(Bt[n][k], At[m][k], acc[ai][bj][m][n], 0, 0, 0); __builtin_amdgcn_s_setprio(0); } while (0)
; #define PG8_WAIT_V(n) asm volatile("s_waitcnt vmcnt(" #n ")" ::: "memory")
; #define PG8_WAIT_L(n) asm volatile("s_waitcnt lgkmcnt(" #n ")" ::: "memory")
; #define PG8_BAR __builtin_amdgcn_s_barrier()
; #define PG8_SCHED __builtin_amdgcn_sched_barrier(0)
; template <class Epi>
; __device__ __forceinline__ void gemm_phase(LAS unsigned char* lds, const Gemm g, const StaticOrder& S, const Epi& E, int wave_s) {
;     ...
;             PG8_LDA(At, 1, 1); PG8_STAGE(PG8_SB(1, 0), b3, voffB); PG8_STAGE(PG8_SB(1, 1), b3 + hstepB, voffB); PG8_STAGE(PG8_SA(1, 0), a3, voffA);
;             PG8_WAIT_V(8); PG8_WAIT_L(0); PG8_BAR; PG8_MMA(1, 0, At, B0); PG8_MMA(1, 1, At, B1); PG8_BAR; PG8_SCHED;
;         }
	s_add_i32 s60, s89, s72
	v_lshl_add_u64 v[156:157], v[156:157], 0, s[38:39]
	s_mov_b32 m0, s60
	s_nop 0
	global_load_lds_dwordx4 v[156:157], off
	s_add_i32 m0, s60, 0x2000
	s_add_u32 s58, s58, 0x40080
	v_lshl_add_u64 v[156:157], v[214:215], 0, s[38:39]
	s_addc_u32 s59, s59, 0
	s_add_i32 s60, s90, s72
	global_load_lds_dwordx4 v[156:157], off
	v_lshl_add_u64 v[156:157], s[58:59], 0, v[128:129]
	s_mov_b32 m0, s60
	s_nop 0
	global_load_lds_dwordx4 v[156:157], off
	v_lshl_add_u64 v[156:157], s[58:59], 0, v[130:131]
	s_add_i32 m0, s60, 0x2000
	s_nop 0
	global_load_lds_dwordx4 v[156:157], off
	v_lshl_add_u64 v[156:157], v[216:217], 0, s[38:39]
	s_mov_b32 m0, s77
	s_nop 0
	global_load_lds_dwordx4 v[156:157], off
	v_lshl_add_u64 v[156:157], v[218:219], 0, s[38:39]
	s_mov_b32 m0, s78
	s_nop 0
	global_load_lds_dwordx4 v[156:157], off
	ds_read_b128 v[182:185], v147 offset:49152
	ds_read_b128 v[186:189], v147 offset:50176
	ds_read_b128 v[190:193], v147 offset:51200
	ds_read_b128 v[194:197], v147 offset:52224
	ds_read_b128 v[198:201], v147 offset:53248
	ds_read_b128 v[202:205], v147 offset:54272
	ds_read_b128 v[206:209], v147 offset:55296
	ds_read_b128 v[210:213], v147 offset:56320
	s_waitcnt vmcnt(8)
	s_waitcnt lgkmcnt(0)
	s_barrier
	s_setprio 1
	s_waitcnt lgkmcnt(0)
	v_mfma_f32_16x16x32_bf16 v[60:63], v[140:143], v[182:185], v[60:63]
	v_mfma_f32_16x16x32_bf16 v[56:59], v[152:155], v[182:185], v[56:59]
	v_mfma_f32_16x16x32_bf16 v[44:47], v[140:143], v[190:193], v[44:47]
	v_mfma_f32_16x16x32_bf16 v[40:43], v[152:155], v[190:193], v[40:43]
	v_mfma_f32_16x16x32_bf16 v[28:31], v[140:143], v[198:201], v[28:31]
	v_mfma_f32_16x16x32_bf16 v[24:27], v[152:155], v[198:201], v[24:27]
	v_mfma_f32_16x16x32_bf16 v[12:15], v[140:143], v[206:209], v[12:15]
	v_mfma_f32_16x16x32_bf16 v[8:11], v[152:155], v[206:209], v[8:11]
	v_mfma_f32_16x16x32_bf16 v[60:63], v[148:151], v[186:189], v[60:63]
	v_mfma_f32_16x16x32_bf16 v[56:59], v[162:165], v[186:189], v[56:59]
	v_mfma_f32_16x16x32_bf16 v[44:47], v[148:151], v[194:197], v[44:47]
	v_mfma_f32_16x16x32_bf16 v[40:43], v[162:165], v[194:197], v[40:43]
	v_mfma_f32_16x16x32_bf16 v[28:31], v[148:151], v[202:205], v[28:31]
	v_mfma_f32_16x16x32_bf16 v[24:27], v[162:165], v[202:205], v[24:27]
	v_mfma_f32_16x16x32_bf16 v[12:15], v[148:151], v[210:213], v[12:15]
	v_mfma_f32_16x16x32_bf16 v[8:11], v[162:165], v[210:213], v[8:11]
	s_setprio 0
	s_setprio 1
	v_mfma_f32_16x16x32_bf16 v[52:55], v[166:169], v[182:185], v[52:55]
	v_mfma_f32_16x16x32_bf16 v[48:51], v[174:177], v[182:185], v[48:51]
	v_mfma_f32_16x16x32_bf16 v[36:39], v[166:169], v[190:193], v[36:39]
	v_mfma_f32_16x16x32_bf16 v[32:35], v[174:177], v[190:193], v[32:35]
	v_mfma_f32_16x16x32_bf16 v[20:23], v[166:169], v[198:201], v[20:23]
	v_mfma_f32_16x16x32_bf16 v[16:19], v[174:177], v[198:201], v[16:19]
	v_mfma_f32_16x16x32_bf16 v[4:7], v[166:169], v[206:209], v[4:7]
	v_mfma_f32_16x16x32_bf16 v[0:3], v[174:177], v[206:209], v[0:3]
	v_mfma_f32_16x16x32_bf16 v[52:55], v[170:173], v[186:189], v[52:55]
	v_mfma_f32_16x16x32_bf16 v[48:51], v[178:181], v[186:189], v[48:51]
	v_mfma_f32_16x16x32_bf16 v[36:39], v[170:173], v[194:197], v[36:39]
	v_mfma_f32_16x16x32_bf16 v[32:35], v[178:181], v[194:197], v[32:35]
	v_mfma_f32_16x16x32_bf16 v[20:23], v[170:173], v[202:205], v[20:23]
	v_mfma_f32_16x16x32_bf16 v[16:19], v[178:181], v[202:205], v[16:19]
	v_mfma_f32_16x16x32_bf16 v[4:7], v[170:173], v[210:213], v[4:7]
	v_mfma_f32_16x16x32_bf16 v[0:3], v[178:181], v[210:213], v[0:3]
	s_setprio 0
	s_barrier
	s_add_i32 s88, s88, 2
	s_add_u32 s8, s8, 0x100
	s_addc_u32 s9, s9, 0
	s_add_u32 s86, s86, 0x100
	s_addc_u32 s87, s87, 0
	s_cmp_gt_u32 s88, 13
	s_cbranch_scc0 .LBB0_264
	s_and_b64 vcc, exec, s[46:47]
	s_cbranch_vccz .LBB0_267
	s_barrier

; #define PG8_STAGE(bufoff, gbase, voff) do { _Pragma("unroll") for (int _i = 0; _i < 2; ++_i) \
;         __builtin_amdgcn_global_load_lds((const unsigned*)((const char*)(gbase) + (voff)[_i]), (LAS unsigned*)(lds + (bufoff) + ldsw + _i * 8192), 16, 0, 0); } while (0)
; #define PG8_LDA(dst, b, h) do { _Pragma("unroll") for (int m = 0; m < 4; ++m) _Pragma("unroll") for (int k = 0; k < 2; ++k) dst[m][k] = *(const LAS bf16x8*)(lds + PG8_SA(b, h) + aoff + m * 2048 + k * 1024); } while (0)
; #define PG8_LDB(dst, b, h) do { _Pragma("unroll") for (int n = 0; n < 2; ++n) _Pragma("unroll") for (int k = 0; k < 2; ++k) dst[n][k] = *(const LAS bf16x8*)(lds + PG8_SB(b, h) + boff + n * 2048 + k * 1024); } while (0)
; #define PG8_MMA(ai, bj, At, Bt) do { __builtin_amdgcn_s_setprio(1); _Pragma("unroll") for (int m = 0; m < 4; ++m) _Pragma("unroll") for (int n = 0; n < 2; ++n) _Pragma("unroll") for (int k = 0; k < 2; ++k) \
;         acc[ai][bj][m][n] = __builtin_amdgcn_mfma_f32_16x16x32_bf16(Bt[n][k], At[m][k], acc[ai][bj][m][n], 0, 0, 0); __builtin_amdgcn_s_setprio(0); } while (0)
; #define PG8_WAIT_V(n) asm volatile("s_waitcnt vmcnt(" #n ")" ::: "memory")
; #define PG8_WAIT_L(n) asm volatile("s_waitcnt lgkmcnt(" #n ")" ::: "memory")
; #define PG8_BAR __builtin_amdgcn_s_barrier()
; #define PG8_SCHED __builtin_amdgcn_sched_barrier(0)
; template <class Epi>
; __device__ __forceinline__ void gemm_phase(LAS unsigned char* lds, const Gemm g, const StaticOrder& S, const Epi& E, int wave_s) {
;     ...
;             PG8_LDB(B0, 0, 0); PG8_LDB(B1, 0, 1); PG8_SCHED; PG8_LDA(At, 0, 0); PG8_STAGE(PG8_SA(1, 1), a1 + hstepA, voffA);
;             PG8_WAIT_V(8); PG8_WAIT_L(0); PG8_BAR; PG8_MMA(0, 0, At, B0); PG8_MMA(0, 1, At, B1); PG8_BAR; PG8_SCHED;
;             PG8_LDA(At, 0, 1); PG8_STAGE(PG8_SB(0, 0), b2, voffB); PG8_STAGE(PG8_SB(0, 1), b2 + hstepB, voffB); PG8_STAGE(PG8_SA(0, 0), a2, voffA);
;             PG8_WAIT_V(8); PG8_WAIT_L(0); PG8_BAR; PG8_MMA(1, 0, At, B0); PG8_MMA(1, 1, At, B1); PG8_BAR; PG8_SCHED;
.LBB0_284:
	s_add_u32 s8, s6, 0xfffc0080
	s_addc_u32 s9, s7, -1
	s_add_i32 s84, 0, 0x10000
	s_cmp_eq_u32 s83, 12
	s_cselect_b32 s59, s53, s9
	s_cselect_b32 s58, s77, s8
	s_cselect_b32 s9, s51, s82
	s_cselect_b32 s8, s78, s79
	s_add_i32 s86, 0, 0x14000
	v_add_u32_e32 v152, s84, v163
	v_add_u32_e32 v156, s86, v163
	ds_read_b128 v[140:143], v152
	ds_read_b128 v[144:147], v152 offset:1024
	ds_read_b128 v[148:151], v152 offset:2048
	ds_read_b128 v[152:155], v152 offset:3072
	ds_read_b128 v[166:169], v156
	ds_read_b128 v[170:173], v156 offset:1024
	ds_read_b128 v[174:177], v156 offset:2048
	ds_read_b128 v[178:181], v156 offset:3072
	v_lshl_add_u64 v[156:157], s[6:7], 0, v[136:137]
	s_add_i32 m0, s69, 0xc000
	ds_read_b128 v[182:185], v165
	ds_read_b128 v[186:189], v165 offset:1024
	ds_read_b128 v[190:193], v165 offset:2048
	ds_read_b128 v[194:197], v165 offset:3072
	ds_read_b128 v[198:201], v165 offset:4096
	ds_read_b128 v[202:205], v165 offset:5120
	ds_read_b128 v[206:209], v165 offset:6144
	ds_read_b128 v[210:213], v165 offset:7168
	global_load_lds_dwordx4 v[156:157], off
	v_lshl_add_u64 v[156:157], s[6:7], 0, v[138:139]
	s_add_i32 m0, s69, 0xe000
	s_nop 0
	global_load_lds_dwordx4 v[156:157], off
	s_waitcnt vmcnt(8)
	s_waitcnt lgkmcnt(0)
	s_barrier
	s_setprio 1
	s_waitcnt lgkmcnt(0)
	v_mfma_f32_16x16x32_bf16 v[124:127], v[140:143], v[182:185], v[124:127]
	v_mfma_f32_16x16x32_bf16 v[120:123], v[148:151], v[182:185], v[120:123]
	v_mfma_f32_16x16x32_bf16 v[112:115], v[140:143], v[190:193], v[112:115]
	v_mfma_f32_16x16x32_bf16 v[108:111], v[148:151], v[190:193], v[108:111]
	v_mfma_f32_16x16x32_bf16 v[100:103], v[140:143], v[198:201], v[100:103]
	v_mfma_f32_16x16x32_bf16 v[92:95], v[148:151], v[198:201], v[92:95]
	v_mfma_f32_16x16x32_bf16 v[84:87], v[140:143], v[206:209], v[84:87]
	v_mfma_f32_16x16x32_bf16 v[76:79], v[148:151], v[206:209], v[76:79]
	v_mfma_f32_16x16x32_bf16 v[124:127], v[144:147], v[186:189], v[124:127]
	v_mfma_f32_16x16x32_bf16 v[120:123], v[152:155], v[186:189], v[120:123]
	v_mfma_f32_16x16x32_bf16 v[112:115], v[144:147], v[194:197], v[112:115]
	v_mfma_f32_16x16x32_bf16 v[108:111], v[152:155], v[194:197], v[108:111]
	v_mfma_f32_16x16x32_bf16 v[100:103], v[144:147], v[202:205], v[100:103]
	v_mfma_f32_16x16x32_bf16 v[92:95], v[152:155], v[202:205], v[92:95]
	v_mfma_f32_16x16x32_bf16 v[84:87], v[144:147], v[210:213], v[84:87]
	v_mfma_f32_16x16x32_bf16 v[76:79], v[152:155], v[210:213], v[76:79]
	s_setprio 0
	s_setprio 1
	v_mfma_f32_16x16x32_bf16 v[116:119], v[166:169], v[182:185], v[116:119]
	v_mfma_f32_16x16x32_bf16 v[104:107], v[174:177], v[182:185], v[104:107]
	v_mfma_f32_16x16x32_bf16 v[96:99], v[166:169], v[190:193], v[96:99]
	v_mfma_f32_16x16x32_bf16 v[88:91], v[174:177], v[190:193], v[88:91]
	v_mfma_f32_16x16x32_bf16 v[80:83], v[166:169], v[198:201], v[80:83]
	v_mfma_f32_16x16x32_bf16 v[72:75], v[174:177], v[198:201], v[72:75]
	v_mfma_f32_16x16x32_bf16 v[68:71], v[166:169], v[206:209], v[68:71]
	v_mfma_f32_16x16x32_bf16 v[64:67], v[174:177], v[206:209], v[64:67]
	v_mfma_f32_16x16x32_bf16 v[116:119], v[170:173], v[186:189], v[116:119]
	v_mfma_f32_16x16x32_bf16 v[104:107], v[178:181], v[186:189], v[104:107]
	v_mfma_f32_16x16x32_bf16 v[96:99], v[170:173], v[194:197], v[96:99]
	v_mfma_f32_16x16x32_bf16 v[88:91], v[178:181], v[194:197], v[88:91]
	v_mfma_f32_16x16x32_bf16 v[80:83], v[170:173], v[202:205], v[80:83]
	v_mfma_f32_16x16x32_bf16 v[72:75], v[178:181], v[202:205], v[72:75]
	v_mfma_f32_16x16x32_bf16 v[68:71], v[170:173], v[210:213], v[68:71]
	v_mfma_f32_16x16x32_bf16 v[64:67], v[178:181], v[210:213], v[64:67]
	s_setprio 0
	s_barrier
	s_add_i32 s84, s84, s68
	v_lshl_add_u64 v[156:157], s[8:9], 0, v[134:135]
	s_mov_b32 m0, s84
	s_nop 0
	global_load_lds_dwordx4 v[156:157], off
	s_add_i32 m0, s84, 0x2000
	s_add_u32 s84, s8, 0x40000
	v_lshl_add_u64 v[214:215], s[8:9], 0, v[130:131]
	s_addc_u32 s85, s9, 0
	s_add_i32 s86, s86, s68
	global_load_lds_dwordx4 v[214:215], off
	v_lshl_add_u64 v[216:217], s[84:85], 0, v[134:135]
	s_mov_b32 m0, s86
	v_lshl_add_u64 v[218:219], s[58:59], 0, v[132:133]
	global_load_lds_dwordx4 v[216:217], off
	v_lshl_add_u64 v[216:217], s[84:85], 0, v[130:131]
	s_add_i32 m0, s86, 0x2000
	s_nop 0
	global_load_lds_dwordx4 v[216:217], off
	v_lshl_add_u64 v[216:217], s[58:59], 0, v[128:129]
	s_mov_b32 m0, s69
	s_nop 0
	global_load_lds_dwordx4 v[216:217], off
	s_mov_b32 m0, s70
	s_nop 0
	global_load_lds_dwordx4 v[218:219], off
	ds_read_b128 v[182:185], v165 offset:16384
	ds_read_b128 v[186:189], v165 offset:17408
	ds_read_b128 v[190:193], v165 offset:18432
	ds_read_b128 v[194:197], v165 offset:19456
	ds_read_b128 v[198:201], v165 offset:20480
	ds_read_b128 v[202:205], v165 offset:21504
	ds_read_b128 v[206:209], v165 offset:22528
	ds_read_b128 v[210:213], v165 offset:23552
	s_waitcnt vmcnt(8)
	s_waitcnt lgkmcnt(0)
	s_barrier
; #define PG8_STAGE(bufoff, gbase, voff) do { _Pragma("unroll") for (int _i = 0; _i < 2; ++_i) \
;         __builtin_amdgcn_global_load_lds((const unsigned*)((const char*)(gbase) + (voff)[_i]), (LAS unsigned*)(lds + (bufoff) + ldsw + _i * 8192), 16, 0, 0); } while (0)
; #define PG8_LDA(dst, b, h) do { _Pragma("unroll") for (int m = 0; m < 4; ++m) _Pragma("unroll") for (int k = 0; k < 2; ++k) dst[m][k] = *(const LAS bf16x8*)(lds + PG8_SA(b, h) + aoff + m * 2048 + k * 1024); } while (0)
; #define PG8_LDB(dst, b, h) do { _Pragma("unroll") for (int n = 0; n < 2; ++n) _Pragma("unroll") for (int k = 0; k < 2; ++k) dst[n][k] = *(const LAS bf16x8*)(lds + PG8_SB(b, h) + boff + n * 2048 + k * 1024); } while (0)
; #define PG8_MMA(ai, bj, At, Bt) do { __builtin_amdgcn_s_setprio(1); _Pragma("unroll") for (int m = 0; m < 4; ++m) _Pragma("unroll") for (int n = 0; n < 2; ++n) _Pragma("unroll") for (int k = 0; k < 2; ++k) \
;         acc[ai][bj][m][n] = __builtin_amdgcn_mfma_f32_16x16x32_bf16(Bt[n][k], At[m][k], acc[ai][bj][m][n], 0, 0, 0); __builtin_amdgcn_s_setprio(0); } while (0)
; #define PG8_WAIT_V(n) asm volatile("s_waitcnt vmcnt(" #n ")" ::: "memory")
; #define PG8_WAIT_L(n) asm volatile("s_waitcnt lgkmcnt(" #n ")" ::: "memory")
; #define PG8_BAR __builtin_amdgcn_s_barrier()
; #define PG8_SCHED __builtin_amdgcn_sched_barrier(0)
; template <class Epi>
; __device__ __forceinline__ void gemm_phase(LAS unsigned char* lds, const Gemm g, const StaticOrder& S, const Epi& E, int wave_s) {
;     ...
;             PG8_WAIT_V(8); PG8_WAIT_L(0); PG8_BAR; PG8_MMA(1, 0, At, B0); PG8_MMA(1, 1, At, B1); PG8_BAR; PG8_SCHED;
;             PG8_LDB(B0, 1, 0); PG8_LDB(B1, 1, 1); PG8_SCHED; PG8_LDA(At, 1, 0); PG8_STAGE(PG8_SA(0, 1), a2 + hstepA, voffA);
;             PG8_WAIT_V(8); PG8_WAIT_L(0); PG8_BAR; PG8_MMA(0, 0, At, B0); PG8_MMA(0, 1, At, B1); PG8_BAR; PG8_SCHED;
	s_setprio 1
	s_waitcnt lgkmcnt(0)
	v_mfma_f32_16x16x32_bf16 v[60:63], v[140:143], v[182:185], v[60:63]
	v_mfma_f32_16x16x32_bf16 v[56:59], v[148:151], v[182:185], v[56:59]
	v_mfma_f32_16x16x32_bf16 v[52:55], v[140:143], v[190:193], v[52:55]
	v_mfma_f32_16x16x32_bf16 v[44:47], v[148:151], v[190:193], v[44:47]
	v_mfma_f32_16x16x32_bf16 v[36:39], v[140:143], v[198:201], v[36:39]
	v_mfma_f32_16x16x32_bf16 v[28:31], v[148:151], v[198:201], v[28:31]
	v_mfma_f32_16x16x32_bf16 v[20:23], v[140:143], v[206:209], v[20:23]
	v_mfma_f32_16x16x32_bf16 v[12:15], v[148:151], v[206:209], v[12:15]
	v_mfma_f32_16x16x32_bf16 v[60:63], v[144:147], v[186:189], v[60:63]
	v_mfma_f32_16x16x32_bf16 v[56:59], v[152:155], v[186:189], v[56:59]
	v_mfma_f32_16x16x32_bf16 v[52:55], v[144:147], v[194:197], v[52:55]
	v_mfma_f32_16x16x32_bf16 v[44:47], v[152:155], v[194:197], v[44:47]
	v_mfma_f32_16x16x32_bf16 v[36:39], v[144:147], v[202:205], v[36:39]
	v_mfma_f32_16x16x32_bf16 v[28:31], v[152:155], v[202:205], v[28:31]
	v_mfma_f32_16x16x32_bf16 v[20:23], v[144:147], v[210:213], v[20:23]
	v_mfma_f32_16x16x32_bf16 v[12:15], v[152:155], v[210:213], v[12:15]
	s_setprio 0
	s_setprio 1
	v_mfma_f32_16x16x32_bf16 v[48:51], v[166:169], v[182:185], v[48:51]
	v_mfma_f32_16x16x32_bf16 v[40:43], v[174:177], v[182:185], v[40:43]
	v_mfma_f32_16x16x32_bf16 v[32:35], v[166:169], v[190:193], v[32:35]
	v_mfma_f32_16x16x32_bf16 v[24:27], v[174:177], v[190:193], v[24:27]
	v_mfma_f32_16x16x32_bf16 v[16:19], v[166:169], v[198:201], v[16:19]
	v_mfma_f32_16x16x32_bf16 v[8:11], v[174:177], v[198:201], v[8:11]
	v_mfma_f32_16x16x32_bf16 v[4:7], v[166:169], v[206:209], v[4:7]
	v_mfma_f32_16x16x32_bf16 v[0:3], v[174:177], v[206:209], v[0:3]
	v_mfma_f32_16x16x32_bf16 v[48:51], v[170:173], v[186:189], v[48:51]
	v_mfma_f32_16x16x32_bf16 v[40:43], v[178:181], v[186:189], v[40:43]
	v_mfma_f32_16x16x32_bf16 v[32:35], v[170:173], v[194:197], v[32:35]
	v_mfma_f32_16x16x32_bf16 v[24:27], v[178:181], v[194:197], v[24:27]
	v_mfma_f32_16x16x32_bf16 v[16:19], v[170:173], v[202:205], v[16:19]
	v_mfma_f32_16x16x32_bf16 v[8:11], v[178:181], v[202:205], v[8:11]
	v_mfma_f32_16x16x32_bf16 v[4:7], v[170:173], v[210:213], v[4:7]
	v_mfma_f32_16x16x32_bf16 v[0:3], v[178:181], v[210:213], v[0:3]
	s_setprio 0
	s_barrier
	s_add_i32 s84, 0, 0x18000
	s_add_i32 s85, 0, 0x1c000
	s_add_u32 s58, s58, 0x40000
	s_addc_u32 s59, s59, 0
	s_mov_b32 m0, s71
	v_lshl_add_u64 v[220:221], s[58:59], 0, v[128:129]
	global_load_lds_dwordx4 v[220:221], off
	v_lshl_add_u64 v[220:221], s[58:59], 0, v[132:133]
	s_mov_b32 m0, s72
	s_nop 0
	global_load_lds_dwordx4 v[220:221], off
	v_add_u32_e32 v152, s84, v163
	v_add_u32_e32 v178, s85, v163
	ds_read_b128 v[140:143], v152
	ds_read_b128 v[144:147], v152 offset:1024
	ds_read_b128 v[148:151], v152 offset:2048
	ds_read_b128 v[152:155], v152 offset:3072
	ds_read_b128 v[166:169], v178
	ds_read_b128 v[170:173], v178 offset:1024
	ds_read_b128 v[174:177], v178 offset:2048
	ds_read_b128 v[178:181], v178 offset:3072
	ds_read_b128 v[182:185], v165 offset:32768
	ds_read_b128 v[186:189], v165 offset:33792
	ds_read_b128 v[190:193], v165 offset:34816
	ds_read_b128 v[194:197], v165 offset:35840
	ds_read_b128 v[198:201], v165 offset:36864
	ds_read_b128 v[202:205], v165 offset:37888
	ds_read_b128 v[206:209], v165 offset:38912
	ds_read_b128 v[210:213], v165 offset:39936
	s_waitcnt vmcnt(8)
	s_waitcnt lgkmcnt(0)
	s_barrier
	s_setprio 1
	s_waitcnt lgkmcnt(0)
	v_mfma_f32_16x16x32_bf16 v[124:127], v[140:143], v[182:185], v[124:127]
	v_mfma_f32_16x16x32_bf16 v[120:123], v[148:151], v[182:185], v[120:123]
	v_mfma_f32_16x16x32_bf16 v[112:115], v[140:143], v[190:193], v[112:115]
	v_mfma_f32_16x16x32_bf16 v[108:111], v[148:151], v[190:193], v[108:111]
	v_mfma_f32_16x16x32_bf16 v[100:103], v[140:143], v[198:201], v[100:103]
	v_mfma_f32_16x16x32_bf16 v[92:95], v[148:151], v[198:201], v[92:95]
	v_mfma_f32_16x16x32_bf16 v[84:87], v[140:143], v[206:209], v[84:87]
	v_mfma_f32_16x16x32_bf16 v[76:79], v[148:151], v[206:209], v[76:79]
	v_mfma_f32_16x16x32_bf16 v[124:127], v[144:147], v[186:189], v[124:127]
	v_mfma_f32_16x16x32_bf16 v[120:123], v[152:155], v[186:189], v[120:123]
	v_mfma_f32_16x16x32_bf16 v[112:115], v[144:147], v[194:197], v[112:115]
	v_mfma_f32_16x16x32_bf16 v[108:111], v[152:155], v[194:197], v[108:111]
	v_mfma_f32_16x16x32_bf16 v[100:103], v[144:147], v[202:205], v[100:103]
	v_mfma_f32_16x16x32_bf16 v[92:95], v[152:155], v[202:205], v[92:95]
	v_mfma_f32_16x16x32_bf16 v[84:87], v[144:147], v[210:213], v[84:87]
	v_mfma_f32_16x16x32_bf16 v[76:79], v[152:155], v[210:213], v[76:79]
	s_setprio 0
	s_setprio 1
	v_mfma_f32_16x16x32_bf16 v[116:119], v[166:169], v[182:185], v[116:119]
	v_mfma_f32_16x16x32_bf16 v[104:107], v[174:177], v[182:185], v[104:107]
	v_mfma_f32_16x16x32_bf16 v[96:99], v[166:169], v[190:193], v[96:99]
	v_mfma_f32_16x16x32_bf16 v[88:91], v[174:177], v[190:193], v[88:91]
	v_mfma_f32_16x16x32_bf16 v[80:83], v[166:169], v[198:201], v[80:83]
	v_mfma_f32_16x16x32_bf16 v[72:75], v[174:177], v[198:201], v[72:75]
	v_mfma_f32_16x16x32_bf16 v[68:71], v[166:169], v[206:209], v[68:71]
	v_mfma_f32_16x16x32_bf16 v[64:67], v[174:177], v[206:209], v[64:67]
	v_mfma_f32_16x16x32_bf16 v[116:119], v[170:173], v[186:189], v[116:119]
	v_mfma_f32_16x16x32_bf16 v[104:107], v[178:181], v[186:189], v[104:107]
	v_mfma_f32_16x16x32_bf16 v[96:99], v[170:173], v[194:197], v[96:99]
	v_mfma_f32_16x16x32_bf16 v[88:91], v[178:181], v[194:197], v[88:91]
	v_mfma_f32_16x16x32_bf16 v[80:83], v[170:173], v[202:205], v[80:83]
	v_mfma_f32_16x16x32_bf16 v[72:75], v[178:181], v[202:205], v[72:75]
	v_mfma_f32_16x16x32_bf16 v[68:71], v[170:173], v[210:213], v[68:71]
	v_mfma_f32_16x16x32_bf16 v[64:67], v[178:181], v[210:213], v[64:67]
	s_setprio 0
	s_barrier
; #define PG8_STAGE(bufoff, gbase, voff) do { _Pragma("unroll") for (int _i = 0; _i < 2; ++_i) \
;         __builtin_amdgcn_global_load_lds((const unsigned*)((const char*)(gbase) + (voff)[_i]), (LAS unsigned*)(lds + (bufoff) + ldsw + _i * 8192), 16, 0, 0); } while (0)
; #define PG8_LDA(dst, b, h) do { _Pragma("unroll") for (int m = 0; m < 4; ++m) _Pragma("unroll") for (int k = 0; k < 2; ++k) dst[m][k] = *(const LAS bf16x8*)(lds + PG8_SA(b, h) + aoff + m * 2048 + k * 1024); } while (0)
; #define PG8_MMA(ai, bj, At, Bt) do { __builtin_amdgcn_s_setprio(1); _Pragma("unroll") for (int m = 0; m < 4; ++m) _Pragma("unroll") for (int n = 0; n < 2; ++n) _Pragma("unroll") for (int k = 0; k < 2; ++k) \
;         acc[ai][bj][m][n] = __builtin_amdgcn_mfma_f32_16x16x32_bf16(Bt[n][k], At[m][k], acc[ai][bj][m][n], 0, 0, 0); __builtin_amdgcn_s_setprio(0); } while (0)
; #define PG8_WAIT_V(n) asm volatile("s_waitcnt vmcnt(" #n ")" ::: "memory")
; #define PG8_WAIT_L(n) asm volatile("s_waitcnt lgkmcnt(" #n ")" ::: "memory")
; #define PG8_BAR __builtin_amdgcn_s_barrier()
; #define PG8_SCHED __builtin_amdgcn_sched_barrier(0)
; template <class Epi>
; __device__ __forceinline__ void gemm_phase(LAS unsigned char* lds, const Gemm g, const StaticOrder& S, const Epi& E, int wave_s) {
;     ...
;             PG8_LDA(At, 1, 1); PG8_STAGE(PG8_SB(1, 0), b3, voffB); PG8_STAGE(PG8_SB(1, 1), b3 + hstepB, voffB); PG8_STAGE(PG8_SA(1, 0), a3, voffA);
;             PG8_WAIT_V(8); PG8_WAIT_L(0); PG8_BAR; PG8_MMA(1, 0, At, B0); PG8_MMA(1, 1, At, B1); PG8_BAR; PG8_SCHED;
;         }
	s_add_i32 s58, s84, s68
	v_lshl_add_u64 v[156:157], v[156:157], 0, s[38:39]
	s_mov_b32 m0, s58
	s_nop 0
	global_load_lds_dwordx4 v[156:157], off
	s_add_i32 m0, s58, 0x2000
	s_add_u32 s8, s8, 0x40080
	v_lshl_add_u64 v[156:157], v[214:215], 0, s[38:39]
	s_addc_u32 s9, s9, 0
	s_add_i32 s58, s85, s68
	global_load_lds_dwordx4 v[156:157], off
	v_lshl_add_u64 v[156:157], s[8:9], 0, v[134:135]
	s_mov_b32 m0, s58
	s_nop 0
	global_load_lds_dwordx4 v[156:157], off
	v_lshl_add_u64 v[156:157], s[8:9], 0, v[130:131]
	s_add_i32 m0, s58, 0x2000
	s_nop 0
	global_load_lds_dwordx4 v[156:157], off
	v_lshl_add_u64 v[156:157], v[216:217], 0, s[38:39]
	s_mov_b32 m0, s73
	s_nop 0
	global_load_lds_dwordx4 v[156:157], off
	v_lshl_add_u64 v[156:157], v[218:219], 0, s[38:39]
	s_mov_b32 m0, s74
	s_nop 0
	global_load_lds_dwordx4 v[156:157], off
	ds_read_b128 v[182:185], v165 offset:49152
	ds_read_b128 v[186:189], v165 offset:50176
	ds_read_b128 v[190:193], v165 offset:51200
	ds_read_b128 v[194:197], v165 offset:52224
	ds_read_b128 v[198:201], v165 offset:53248
	ds_read_b128 v[202:205], v165 offset:54272
	ds_read_b128 v[206:209], v165 offset:55296
	ds_read_b128 v[210:213], v165 offset:56320
	s_waitcnt vmcnt(8)
	s_waitcnt lgkmcnt(0)
	s_barrier
	s_setprio 1
	s_waitcnt lgkmcnt(0)
	v_mfma_f32_16x16x32_bf16 v[60:63], v[140:143], v[182:185], v[60:63]
	v_mfma_f32_16x16x32_bf16 v[56:59], v[148:151], v[182:185], v[56:59]
	v_mfma_f32_16x16x32_bf16 v[52:55], v[140:143], v[190:193], v[52:55]
	v_mfma_f32_16x16x32_bf16 v[44:47], v[148:151], v[190:193], v[44:47]
	v_mfma_f32_16x16x32_bf16 v[36:39], v[140:143], v[198:201], v[36:39]
	v_mfma_f32_16x16x32_bf16 v[28:31], v[148:151], v[198:201], v[28:31]
	v_mfma_f32_16x16x32_bf16 v[20:23], v[140:143], v[206:209], v[20:23]
	v_mfma_f32_16x16x32_bf16 v[12:15], v[148:151], v[206:209], v[12:15]
	v_mfma_f32_16x16x32_bf16 v[60:63], v[144:147], v[186:189], v[60:63]
	v_mfma_f32_16x16x32_bf16 v[56:59], v[152:155], v[186:189], v[56:59]
	v_mfma_f32_16x16x32_bf16 v[52:55], v[144:147], v[194:197], v[52:55]
	v_mfma_f32_16x16x32_bf16 v[44:47], v[152:155], v[194:197], v[44:47]
	v_mfma_f32_16x16x32_bf16 v[36:39], v[144:147], v[202:205], v[36:39]
	v_mfma_f32_16x16x32_bf16 v[28:31], v[152:155], v[202:205], v[28:31]
	v_mfma_f32_16x16x32_bf16 v[20:23], v[144:147], v[210:213], v[20:23]
	v_mfma_f32_16x16x32_bf16 v[12:15], v[152:155], v[210:213], v[12:15]
	s_setprio 0
	s_setprio 1
	v_mfma_f32_16x16x32_bf16 v[48:51], v[166:169], v[182:185], v[48:51]
	v_mfma_f32_16x16x32_bf16 v[40:43], v[174:177], v[182:185], v[40:43]
	v_mfma_f32_16x16x32_bf16 v[32:35], v[166:169], v[190:193], v[32:35]
	v_mfma_f32_16x16x32_bf16 v[24:27], v[174:177], v[190:193], v[24:27]
	v_mfma_f32_16x16x32_bf16 v[16:19], v[166:169], v[198:201], v[16:19]
	v_mfma_f32_16x16x32_bf16 v[8:11], v[174:177], v[198:201], v[8:11]
	v_mfma_f32_16x16x32_bf16 v[4:7], v[166:169], v[206:209], v[4:7]
	v_mfma_f32_16x16x32_bf16 v[0:3], v[174:177], v[206:209], v[0:3]
	v_mfma_f32_16x16x32_bf16 v[48:51], v[170:173], v[186:189], v[48:51]
	v_mfma_f32_16x16x32_bf16 v[40:43], v[178:181], v[186:189], v[40:43]
	v_mfma_f32_16x16x32_bf16 v[32:35], v[170:173], v[194:197], v[32:35]
	v_mfma_f32_16x16x32_bf16 v[24:27], v[178:181], v[194:197], v[24:27]
	v_mfma_f32_16x16x32_bf16 v[16:19], v[170:173], v[202:205], v[16:19]
	v_mfma_f32_16x16x32_bf16 v[8:11], v[178:181], v[202:205], v[8:11]
	v_mfma_f32_16x16x32_bf16 v[4:7], v[170:173], v[210:213], v[4:7]
	v_mfma_f32_16x16x32_bf16 v[0:3], v[178:181], v[210:213], v[0:3]
	s_setprio 0
	s_barrier
	s_add_i32 s83, s83, 2
	s_add_u32 s6, s6, 0x100
	s_addc_u32 s7, s7, 0
	s_add_u32 s79, s79, 0x100
	s_addc_u32 s82, s82, 0
	s_cmp_gt_u32 s83, 13
	s_cbranch_scc0 .LBB0_284
	s_and_b64 vcc, exec, s[46:47]
	s_cbranch_vccz .LBB0_287
	s_barrier

; #define PG8_STAGE(bufoff, gbase, voff) do { _Pragma("unroll") for (int _i = 0; _i < 2; ++_i) \
;         __builtin_amdgcn_global_load_lds((const unsigned*)((const char*)(gbase) + (voff)[_i]), (LAS unsigned*)(lds + (bufoff) + ldsw + _i * 8192), 16, 0, 0); } while (0)
; #define PG8_LDA(dst, b, h) do { _Pragma("unroll") for (int m = 0; m < 4; ++m) _Pragma("unroll") for (int k = 0; k < 2; ++k) dst[m][k] = *(const LAS bf16x8*)(lds + PG8_SA(b, h) + aoff + m * 2048 + k * 1024); } while (0)
; #define PG8_LDB(dst, b, h) do { _Pragma("unroll") for (int n = 0; n < 2; ++n) _Pragma("unroll") for (int k = 0; k < 2; ++k) dst[n][k] = *(const LAS bf16x8*)(lds + PG8_SB(b, h) + boff + n * 2048 + k * 1024); } while (0)
; #define PG8_MMA(ai, bj, At, Bt) do { __builtin_amdgcn_s_setprio(1); _Pragma("unroll") for (int m = 0; m < 4; ++m) _Pragma("unroll") for (int n = 0; n < 2; ++n) _Pragma("unroll") for (int k = 0; k < 2; ++k) \
;         acc[ai][bj][m][n] = __builtin_amdgcn_mfma_f32_16x16x32_bf16(Bt[n][k], At[m][k], acc[ai][bj][m][n], 0, 0, 0); __builtin_amdgcn_s_setprio(0); } while (0)
; #define PG8_WAIT_V(n) asm volatile("s_waitcnt vmcnt(" #n ")" ::: "memory")
; #define PG8_WAIT_L(n) asm volatile("s_waitcnt lgkmcnt(" #n ")" ::: "memory")
; #define PG8_BAR __builtin_amdgcn_s_barrier()
; #define PG8_SCHED __builtin_amdgcn_sched_barrier(0)
; template <class Epi>
; __device__ __forceinline__ void gemm_phase(LAS unsigned char* lds, const Gemm g, const StaticOrder& S, const Epi& E, int wave_s) {
;     ...
;             PG8_LDB(B0, 0, 0); PG8_LDB(B1, 0, 1); PG8_SCHED; PG8_LDA(At, 0, 0); PG8_STAGE(PG8_SA(1, 1), a1 + hstepA, voffA);
;             PG8_WAIT_V(8); PG8_WAIT_L(0); PG8_BAR; PG8_MMA(0, 0, At, B0); PG8_MMA(0, 1, At, B1); PG8_BAR; PG8_SCHED;
;             PG8_LDA(At, 0, 1); PG8_STAGE(PG8_SB(0, 0), b2, voffB); PG8_STAGE(PG8_SB(0, 1), b2 + hstepB, voffB); PG8_STAGE(PG8_SA(0, 0), a2, voffA);
;             PG8_WAIT_V(8); PG8_WAIT_L(0); PG8_BAR; PG8_MMA(1, 0, At, B0); PG8_MMA(1, 1, At, B1); PG8_BAR; PG8_SCHED;
.LBB0_370:
	s_add_u32 s40, s38, 0x100
	s_addc_u32 s41, s39, 0
	s_cmp_eq_u32 s61, 40
	s_cselect_b32 s45, s11, s41
	s_cselect_b32 s44, s10, s40
	s_cselect_b32 s43, s37, s60
	s_cselect_b32 s42, s36, s59
	v_lshl_add_u64 v[216:217], s[38:39], 0, v[136:137]
	s_add_i32 m0, s5, 0xc000
	s_nop 0
	global_load_lds_dwordx4 v[216:217], off
	v_lshl_add_u64 v[216:217], s[38:39], 0, v[138:139]
	s_add_i32 m0, s5, 0xe000
	s_nop 0
	global_load_lds_dwordx4 v[216:217], off
	ds_read_b128 v[144:147], v152
	ds_read_b128 v[156:159], v152 offset:1024
	ds_read_b128 v[160:163], v152 offset:2048
	ds_read_b128 v[164:167], v152 offset:3072
	ds_read_b128 v[168:171], v153
	ds_read_b128 v[172:175], v153 offset:1024
	ds_read_b128 v[176:179], v153 offset:2048
	ds_read_b128 v[180:183], v153 offset:3072
	ds_read_b128 v[184:187], v154
	ds_read_b128 v[188:191], v154 offset:1024
	ds_read_b128 v[192:195], v154 offset:2048
	ds_read_b128 v[196:199], v154 offset:3072
	ds_read_b128 v[200:203], v154 offset:4096
	ds_read_b128 v[204:207], v154 offset:5120
	ds_read_b128 v[208:211], v154 offset:6144
	ds_read_b128 v[212:215], v154 offset:7168
	s_waitcnt vmcnt(8)
	s_waitcnt lgkmcnt(0)
	s_barrier
	s_setprio 1
	s_waitcnt lgkmcnt(0)
	v_mfma_f32_16x16x32_bf16 v[124:127], v[144:147], v[184:187], v[124:127]
	v_mfma_f32_16x16x32_bf16 v[120:123], v[160:163], v[184:187], v[120:123]
	v_mfma_f32_16x16x32_bf16 v[108:111], v[144:147], v[192:195], v[108:111]
	v_mfma_f32_16x16x32_bf16 v[104:107], v[160:163], v[192:195], v[104:107]
	v_mfma_f32_16x16x32_bf16 v[92:95], v[144:147], v[200:203], v[92:95]
	v_mfma_f32_16x16x32_bf16 v[88:91], v[160:163], v[200:203], v[88:91]
	v_mfma_f32_16x16x32_bf16 v[76:79], v[144:147], v[208:211], v[76:79]
	v_mfma_f32_16x16x32_bf16 v[72:75], v[160:163], v[208:211], v[72:75]
	v_mfma_f32_16x16x32_bf16 v[124:127], v[156:159], v[188:191], v[124:127]
	v_mfma_f32_16x16x32_bf16 v[120:123], v[164:167], v[188:191], v[120:123]
	v_mfma_f32_16x16x32_bf16 v[108:111], v[156:159], v[196:199], v[108:111]
	v_mfma_f32_16x16x32_bf16 v[104:107], v[164:167], v[196:199], v[104:107]
	v_mfma_f32_16x16x32_bf16 v[92:95], v[156:159], v[204:207], v[92:95]
	v_mfma_f32_16x16x32_bf16 v[88:91], v[164:167], v[204:207], v[88:91]
	v_mfma_f32_16x16x32_bf16 v[76:79], v[156:159], v[212:215], v[76:79]
	v_mfma_f32_16x16x32_bf16 v[72:75], v[164:167], v[212:215], v[72:75]
	s_setprio 0
	s_setprio 1
	v_mfma_f32_16x16x32_bf16 v[116:119], v[168:171], v[184:187], v[116:119]
	v_mfma_f32_16x16x32_bf16 v[112:115], v[176:179], v[184:187], v[112:115]
	v_mfma_f32_16x16x32_bf16 v[100:103], v[168:171], v[192:195], v[100:103]
	v_mfma_f32_16x16x32_bf16 v[96:99], v[176:179], v[192:195], v[96:99]
	v_mfma_f32_16x16x32_bf16 v[84:87], v[168:171], v[200:203], v[84:87]
	v_mfma_f32_16x16x32_bf16 v[80:83], v[176:179], v[200:203], v[80:83]
	v_mfma_f32_16x16x32_bf16 v[68:71], v[168:171], v[208:211], v[68:71]
	v_mfma_f32_16x16x32_bf16 v[64:67], v[176:179], v[208:211], v[64:67]
	v_mfma_f32_16x16x32_bf16 v[116:119], v[172:175], v[188:191], v[116:119]
	v_mfma_f32_16x16x32_bf16 v[112:115], v[180:183], v[188:191], v[112:115]
	v_mfma_f32_16x16x32_bf16 v[100:103], v[172:175], v[196:199], v[100:103]
	v_mfma_f32_16x16x32_bf16 v[96:99], v[180:183], v[196:199], v[96:99]
	v_mfma_f32_16x16x32_bf16 v[84:87], v[172:175], v[204:207], v[84:87]
	v_mfma_f32_16x16x32_bf16 v[80:83], v[180:183], v[204:207], v[80:83]
	v_mfma_f32_16x16x32_bf16 v[68:71], v[172:175], v[212:215], v[68:71]
	v_mfma_f32_16x16x32_bf16 v[64:67], v[180:183], v[212:215], v[64:67]
	s_setprio 0
	s_barrier
	s_add_i32 s38, s53, s4
	v_lshl_add_u64 v[216:217], s[42:43], 0, v[130:131]
	s_mov_b32 m0, s38
	s_nop 0
	global_load_lds_dwordx4 v[216:217], off
	s_add_i32 m0, s38, 0x2000
	s_add_u32 s38, s42, 0xb0000
	v_lshl_add_u64 v[218:219], s[42:43], 0, v[134:135]
	s_addc_u32 s39, s43, 0
	s_add_i32 s62, s54, s4
	global_load_lds_dwordx4 v[218:219], off
	v_lshl_add_u64 v[220:221], s[38:39], 0, v[130:131]
	s_mov_b32 m0, s62
	v_lshl_add_u64 v[222:223], s[44:45], 0, v[132:133]
	global_load_lds_dwordx4 v[220:221], off
	v_lshl_add_u64 v[220:221], s[38:39], 0, v[134:135]
	s_add_i32 m0, s62, 0x2000
	s_nop 0
	global_load_lds_dwordx4 v[220:221], off
	v_lshl_add_u64 v[220:221], s[44:45], 0, v[128:129]
	s_mov_b32 m0, s5
	s_nop 0
	global_load_lds_dwordx4 v[220:221], off
	s_mov_b32 m0, s29
	s_nop 0
	global_load_lds_dwordx4 v[222:223], off
	ds_read_b128 v[184:187], v154 offset:16384
	ds_read_b128 v[188:191], v154 offset:17408
	ds_read_b128 v[192:195], v154 offset:18432
	ds_read_b128 v[196:199], v154 offset:19456
	ds_read_b128 v[200:203], v154 offset:20480
	ds_read_b128 v[204:207], v154 offset:21504
	ds_read_b128 v[208:211], v154 offset:22528
	ds_read_b128 v[212:215], v154 offset:23552
	s_waitcnt vmcnt(8)
	s_waitcnt lgkmcnt(0)
	s_barrier
; #define PG8_STAGE(bufoff, gbase, voff) do { _Pragma("unroll") for (int _i = 0; _i < 2; ++_i) \
;         __builtin_amdgcn_global_load_lds((const unsigned*)((const char*)(gbase) + (voff)[_i]), (LAS unsigned*)(lds + (bufoff) + ldsw + _i * 8192), 16, 0, 0); } while (0)
; #define PG8_LDA(dst, b, h) do { _Pragma("unroll") for (int m = 0; m < 4; ++m) _Pragma("unroll") for (int k = 0; k < 2; ++k) dst[m][k] = *(const LAS bf16x8*)(lds + PG8_SA(b, h) + aoff + m * 2048 + k * 1024); } while (0)
; #define PG8_LDB(dst, b, h) do { _Pragma("unroll") for (int n = 0; n < 2; ++n) _Pragma("unroll") for (int k = 0; k < 2; ++k) dst[n][k] = *(const LAS bf16x8*)(lds + PG8_SB(b, h) + boff + n * 2048 + k * 1024); } while (0)
; #define PG8_MMA(ai, bj, At, Bt) do { __builtin_amdgcn_s_setprio(1); _Pragma("unroll") for (int m = 0; m < 4; ++m) _Pragma("unroll") for (int n = 0; n < 2; ++n) _Pragma("unroll") for (int k = 0; k < 2; ++k) \
;         acc[ai][bj][m][n] = __builtin_amdgcn_mfma_f32_16x16x32_bf16(Bt[n][k], At[m][k], acc[ai][bj][m][n], 0, 0, 0); __builtin_amdgcn_s_setprio(0); } while (0)
; #define PG8_WAIT_V(n) asm volatile("s_waitcnt vmcnt(" #n ")" ::: "memory")
; #define PG8_WAIT_L(n) asm volatile("s_waitcnt lgkmcnt(" #n ")" ::: "memory")
; #define PG8_BAR __builtin_amdgcn_s_barrier()
; #define PG8_SCHED __builtin_amdgcn_sched_barrier(0)
; template <class Epi>
; __device__ __forceinline__ void gemm_phase(LAS unsigned char* lds, const Gemm g, const StaticOrder& S, const Epi& E, int wave_s) {
;     ...
;             PG8_WAIT_V(8); PG8_WAIT_L(0); PG8_BAR; PG8_MMA(1, 0, At, B0); PG8_MMA(1, 1, At, B1); PG8_BAR; PG8_SCHED;
;             PG8_LDB(B0, 1, 0); PG8_LDB(B1, 1, 1); PG8_SCHED; PG8_LDA(At, 1, 0); PG8_STAGE(PG8_SA(0, 1), a2 + hstepA, voffA);
;             PG8_WAIT_V(8); PG8_WAIT_L(0); PG8_BAR; PG8_MMA(0, 0, At, B0); PG8_MMA(0, 1, At, B1); PG8_BAR; PG8_SCHED;
	s_setprio 1
	s_waitcnt lgkmcnt(0)
	v_mfma_f32_16x16x32_bf16 v[60:63], v[144:147], v[184:187], v[60:63]
	v_mfma_f32_16x16x32_bf16 v[56:59], v[160:163], v[184:187], v[56:59]
	v_mfma_f32_16x16x32_bf16 v[44:47], v[144:147], v[192:195], v[44:47]
	v_mfma_f32_16x16x32_bf16 v[40:43], v[160:163], v[192:195], v[40:43]
	v_mfma_f32_16x16x32_bf16 v[28:31], v[144:147], v[200:203], v[28:31]
	v_mfma_f32_16x16x32_bf16 v[24:27], v[160:163], v[200:203], v[24:27]
	v_mfma_f32_16x16x32_bf16 v[12:15], v[144:147], v[208:211], v[12:15]
	v_mfma_f32_16x16x32_bf16 v[8:11], v[160:163], v[208:211], v[8:11]
	v_mfma_f32_16x16x32_bf16 v[60:63], v[156:159], v[188:191], v[60:63]
	v_mfma_f32_16x16x32_bf16 v[56:59], v[164:167], v[188:191], v[56:59]
	v_mfma_f32_16x16x32_bf16 v[44:47], v[156:159], v[196:199], v[44:47]
	v_mfma_f32_16x16x32_bf16 v[40:43], v[164:167], v[196:199], v[40:43]
	v_mfma_f32_16x16x32_bf16 v[28:31], v[156:159], v[204:207], v[28:31]
	v_mfma_f32_16x16x32_bf16 v[24:27], v[164:167], v[204:207], v[24:27]
	v_mfma_f32_16x16x32_bf16 v[12:15], v[156:159], v[212:215], v[12:15]
	v_mfma_f32_16x16x32_bf16 v[8:11], v[164:167], v[212:215], v[8:11]
	s_setprio 0
	s_setprio 1
	v_mfma_f32_16x16x32_bf16 v[52:55], v[168:171], v[184:187], v[52:55]
	v_mfma_f32_16x16x32_bf16 v[48:51], v[176:179], v[184:187], v[48:51]
	v_mfma_f32_16x16x32_bf16 v[36:39], v[168:171], v[192:195], v[36:39]
	v_mfma_f32_16x16x32_bf16 v[32:35], v[176:179], v[192:195], v[32:35]
	v_mfma_f32_16x16x32_bf16 v[20:23], v[168:171], v[200:203], v[20:23]
	v_mfma_f32_16x16x32_bf16 v[16:19], v[176:179], v[200:203], v[16:19]
	v_mfma_f32_16x16x32_bf16 v[4:7], v[168:171], v[208:211], v[4:7]
	v_mfma_f32_16x16x32_bf16 v[0:3], v[176:179], v[208:211], v[0:3]
	v_mfma_f32_16x16x32_bf16 v[52:55], v[172:175], v[188:191], v[52:55]
	v_mfma_f32_16x16x32_bf16 v[48:51], v[180:183], v[188:191], v[48:51]
	v_mfma_f32_16x16x32_bf16 v[36:39], v[172:175], v[196:199], v[36:39]
	v_mfma_f32_16x16x32_bf16 v[32:35], v[180:183], v[196:199], v[32:35]
	v_mfma_f32_16x16x32_bf16 v[20:23], v[172:175], v[204:207], v[20:23]
	v_mfma_f32_16x16x32_bf16 v[16:19], v[180:183], v[204:207], v[16:19]
	v_mfma_f32_16x16x32_bf16 v[4:7], v[172:175], v[212:215], v[4:7]
	v_mfma_f32_16x16x32_bf16 v[0:3], v[180:183], v[212:215], v[0:3]
	s_setprio 0
	s_barrier
	s_add_i32 s62, 0, 0x18000
	s_add_i32 s63, 0, 0x1c000
	s_add_u32 s38, s44, 0xb0000
	s_addc_u32 s39, s45, 0
	s_mov_b32 m0, s33
	v_lshl_add_u64 v[224:225], s[38:39], 0, v[128:129]
	global_load_lds_dwordx4 v[224:225], off
	v_lshl_add_u64 v[224:225], s[38:39], 0, v[132:133]
	s_mov_b32 m0, s46
	s_nop 0
	global_load_lds_dwordx4 v[224:225], off
	v_add_u32_e32 v164, s62, v150
	v_add_u32_e32 v180, s63, v150
	ds_read_b128 v[144:147], v164
	ds_read_b128 v[156:159], v164 offset:1024
	ds_read_b128 v[160:163], v164 offset:2048
	ds_read_b128 v[164:167], v164 offset:3072
	ds_read_b128 v[168:171], v180
	ds_read_b128 v[172:175], v180 offset:1024
	ds_read_b128 v[176:179], v180 offset:2048
	ds_read_b128 v[180:183], v180 offset:3072
	ds_read_b128 v[184:187], v154 offset:32768
	ds_read_b128 v[188:191], v154 offset:33792
	ds_read_b128 v[192:195], v154 offset:34816
	ds_read_b128 v[196:199], v154 offset:35840
	ds_read_b128 v[200:203], v154 offset:36864
	ds_read_b128 v[204:207], v154 offset:37888
	ds_read_b128 v[208:211], v154 offset:38912
	ds_read_b128 v[212:215], v154 offset:39936
	s_waitcnt vmcnt(8)
	s_waitcnt lgkmcnt(0)
	s_barrier
	s_setprio 1
	s_waitcnt lgkmcnt(0)
	v_mfma_f32_16x16x32_bf16 v[124:127], v[144:147], v[184:187], v[124:127]
	v_mfma_f32_16x16x32_bf16 v[120:123], v[160:163], v[184:187], v[120:123]
	v_mfma_f32_16x16x32_bf16 v[108:111], v[144:147], v[192:195], v[108:111]
	v_mfma_f32_16x16x32_bf16 v[104:107], v[160:163], v[192:195], v[104:107]
	v_mfma_f32_16x16x32_bf16 v[92:95], v[144:147], v[200:203], v[92:95]
	v_mfma_f32_16x16x32_bf16 v[88:91], v[160:163], v[200:203], v[88:91]
	v_mfma_f32_16x16x32_bf16 v[76:79], v[144:147], v[208:211], v[76:79]
	v_mfma_f32_16x16x32_bf16 v[72:75], v[160:163], v[208:211], v[72:75]
	v_mfma_f32_16x16x32_bf16 v[124:127], v[156:159], v[188:191], v[124:127]
	v_mfma_f32_16x16x32_bf16 v[120:123], v[164:167], v[188:191], v[120:123]
	v_mfma_f32_16x16x32_bf16 v[108:111], v[156:159], v[196:199], v[108:111]
	v_mfma_f32_16x16x32_bf16 v[104:107], v[164:167], v[196:199], v[104:107]
	v_mfma_f32_16x16x32_bf16 v[92:95], v[156:159], v[204:207], v[92:95]
	v_mfma_f32_16x16x32_bf16 v[88:91], v[164:167], v[204:207], v[88:91]
	v_mfma_f32_16x16x32_bf16 v[76:79], v[156:159], v[212:215], v[76:79]
	v_mfma_f32_16x16x32_bf16 v[72:75], v[164:167], v[212:215], v[72:75]
	s_setprio 0
	s_setprio 1
	v_mfma_f32_16x16x32_bf16 v[116:119], v[168:171], v[184:187], v[116:119]
	v_mfma_f32_16x16x32_bf16 v[112:115], v[176:179], v[184:187], v[112:115]
	v_mfma_f32_16x16x32_bf16 v[100:103], v[168:171], v[192:195], v[100:103]
	v_mfma_f32_16x16x32_bf16 v[96:99], v[176:179], v[192:195], v[96:99]
	v_mfma_f32_16x16x32_bf16 v[84:87], v[168:171], v[200:203], v[84:87]
	v_mfma_f32_16x16x32_bf16 v[80:83], v[176:179], v[200:203], v[80:83]
	v_mfma_f32_16x16x32_bf16 v[68:71], v[168:171], v[208:211], v[68:71]
	v_mfma_f32_16x16x32_bf16 v[64:67], v[176:179], v[208:211], v[64:67]
	v_mfma_f32_16x16x32_bf16 v[116:119], v[172:175], v[188:191], v[116:119]
	v_mfma_f32_16x16x32_bf16 v[112:115], v[180:183], v[188:191], v[112:115]
	v_mfma_f32_16x16x32_bf16 v[100:103], v[172:175], v[196:199], v[100:103]
	v_mfma_f32_16x16x32_bf16 v[96:99], v[180:183], v[196:199], v[96:99]
	v_mfma_f32_16x16x32_bf16 v[84:87], v[172:175], v[204:207], v[84:87]
	v_mfma_f32_16x16x32_bf16 v[80:83], v[180:183], v[204:207], v[80:83]
	v_mfma_f32_16x16x32_bf16 v[68:71], v[172:175], v[212:215], v[68:71]
	v_mfma_f32_16x16x32_bf16 v[64:67], v[180:183], v[212:215], v[64:67]
	s_setprio 0
	s_barrier
; #define PG8_STAGE(bufoff, gbase, voff) do { _Pragma("unroll") for (int _i = 0; _i < 2; ++_i) \
;         __builtin_amdgcn_global_load_lds((const unsigned*)((const char*)(gbase) + (voff)[_i]), (LAS unsigned*)(lds + (bufoff) + ldsw + _i * 8192), 16, 0, 0); } while (0)
; #define PG8_LDA(dst, b, h) do { _Pragma("unroll") for (int m = 0; m < 4; ++m) _Pragma("unroll") for (int k = 0; k < 2; ++k) dst[m][k] = *(const LAS bf16x8*)(lds + PG8_SA(b, h) + aoff + m * 2048 + k * 1024); } while (0)
; #define PG8_MMA(ai, bj, At, Bt) do { __builtin_amdgcn_s_setprio(1); _Pragma("unroll") for (int m = 0; m < 4; ++m) _Pragma("unroll") for (int n = 0; n < 2; ++n) _Pragma("unroll") for (int k = 0; k < 2; ++k) \
;         acc[ai][bj][m][n] = __builtin_amdgcn_mfma_f32_16x16x32_bf16(Bt[n][k], At[m][k], acc[ai][bj][m][n], 0, 0, 0); __builtin_amdgcn_s_setprio(0); } while (0)
; #define PG8_WAIT_V(n) asm volatile("s_waitcnt vmcnt(" #n ")" ::: "memory")
; #define PG8_WAIT_L(n) asm volatile("s_waitcnt lgkmcnt(" #n ")" ::: "memory")
; #define PG8_BAR __builtin_amdgcn_s_barrier()
; #define PG8_SCHED __builtin_amdgcn_sched_barrier(0)
; template <class Epi>
; __device__ __forceinline__ void gemm_phase(LAS unsigned char* lds, const Gemm g, const StaticOrder& S, const Epi& E, int wave_s) {
;     ...
;             PG8_LDA(At, 1, 1); PG8_STAGE(PG8_SB(1, 0), b3, voffB); PG8_STAGE(PG8_SB(1, 1), b3 + hstepB, voffB); PG8_STAGE(PG8_SA(1, 0), a3, voffA);
;             PG8_WAIT_V(8); PG8_WAIT_L(0); PG8_BAR; PG8_MMA(1, 0, At, B0); PG8_MMA(1, 1, At, B1); PG8_BAR; PG8_SCHED;
;         }
	s_add_i32 s38, s62, s4
	v_lshl_add_u64 v[216:217], v[216:217], 0, s[30:31]
	s_mov_b32 m0, s38
	s_nop 0
	global_load_lds_dwordx4 v[216:217], off
	s_add_i32 m0, s38, 0x2000
	s_add_u32 s38, s42, 0xb0080
	v_lshl_add_u64 v[216:217], v[218:219], 0, s[30:31]
	s_addc_u32 s39, s43, 0
	s_add_i32 s42, s63, s4
	global_load_lds_dwordx4 v[216:217], off
	v_lshl_add_u64 v[216:217], s[38:39], 0, v[130:131]
	s_mov_b32 m0, s42
	s_nop 0
	global_load_lds_dwordx4 v[216:217], off
	v_lshl_add_u64 v[216:217], s[38:39], 0, v[134:135]
	s_add_i32 m0, s42, 0x2000
	s_nop 0
	global_load_lds_dwordx4 v[216:217], off
	v_lshl_add_u64 v[216:217], v[220:221], 0, s[30:31]
	s_mov_b32 m0, s48
	s_nop 0
	global_load_lds_dwordx4 v[216:217], off
	v_lshl_add_u64 v[216:217], v[222:223], 0, s[30:31]
	s_mov_b32 m0, s49
	s_nop 0
	global_load_lds_dwordx4 v[216:217], off
	ds_read_b128 v[184:187], v154 offset:49152
	ds_read_b128 v[188:191], v154 offset:50176
	ds_read_b128 v[192:195], v154 offset:51200
	ds_read_b128 v[196:199], v154 offset:52224
	ds_read_b128 v[200:203], v154 offset:53248
	ds_read_b128 v[204:207], v154 offset:54272
	ds_read_b128 v[208:211], v154 offset:55296
	ds_read_b128 v[212:215], v154 offset:56320
	s_waitcnt vmcnt(8)
	s_waitcnt lgkmcnt(0)
	s_barrier
	s_setprio 1
	s_waitcnt lgkmcnt(0)
	v_mfma_f32_16x16x32_bf16 v[60:63], v[144:147], v[184:187], v[60:63]
	v_mfma_f32_16x16x32_bf16 v[56:59], v[160:163], v[184:187], v[56:59]
	v_mfma_f32_16x16x32_bf16 v[44:47], v[144:147], v[192:195], v[44:47]
	v_mfma_f32_16x16x32_bf16 v[40:43], v[160:163], v[192:195], v[40:43]
	v_mfma_f32_16x16x32_bf16 v[28:31], v[144:147], v[200:203], v[28:31]
	v_mfma_f32_16x16x32_bf16 v[24:27], v[160:163], v[200:203], v[24:27]
	v_mfma_f32_16x16x32_bf16 v[12:15], v[144:147], v[208:211], v[12:15]
	v_mfma_f32_16x16x32_bf16 v[8:11], v[160:163], v[208:211], v[8:11]
	v_mfma_f32_16x16x32_bf16 v[60:63], v[156:159], v[188:191], v[60:63]
	v_mfma_f32_16x16x32_bf16 v[56:59], v[164:167], v[188:191], v[56:59]
	v_mfma_f32_16x16x32_bf16 v[44:47], v[156:159], v[196:199], v[44:47]
	v_mfma_f32_16x16x32_bf16 v[40:43], v[164:167], v[196:199], v[40:43]
	v_mfma_f32_16x16x32_bf16 v[28:31], v[156:159], v[204:207], v[28:31]
	v_mfma_f32_16x16x32_bf16 v[24:27], v[164:167], v[204:207], v[24:27]
	v_mfma_f32_16x16x32_bf16 v[12:15], v[156:159], v[212:215], v[12:15]
	v_mfma_f32_16x16x32_bf16 v[8:11], v[164:167], v[212:215], v[8:11]
	s_setprio 0
	s_setprio 1
	v_mfma_f32_16x16x32_bf16 v[52:55], v[168:171], v[184:187], v[52:55]
	v_mfma_f32_16x16x32_bf16 v[48:51], v[176:179], v[184:187], v[48:51]
	v_mfma_f32_16x16x32_bf16 v[36:39], v[168:171], v[192:195], v[36:39]
	v_mfma_f32_16x16x32_bf16 v[32:35], v[176:179], v[192:195], v[32:35]
	v_mfma_f32_16x16x32_bf16 v[20:23], v[168:171], v[200:203], v[20:23]
	v_mfma_f32_16x16x32_bf16 v[16:19], v[176:179], v[200:203], v[16:19]
	v_mfma_f32_16x16x32_bf16 v[4:7], v[168:171], v[208:211], v[4:7]
	v_mfma_f32_16x16x32_bf16 v[0:3], v[176:179], v[208:211], v[0:3]
	v_mfma_f32_16x16x32_bf16 v[52:55], v[172:175], v[188:191], v[52:55]
	v_mfma_f32_16x16x32_bf16 v[48:51], v[180:183], v[188:191], v[48:51]
	v_mfma_f32_16x16x32_bf16 v[36:39], v[172:175], v[196:199], v[36:39]
	v_mfma_f32_16x16x32_bf16 v[32:35], v[180:183], v[196:199], v[32:35]
	v_mfma_f32_16x16x32_bf16 v[20:23], v[172:175], v[204:207], v[20:23]
	v_mfma_f32_16x16x32_bf16 v[16:19], v[180:183], v[204:207], v[16:19]
	v_mfma_f32_16x16x32_bf16 v[4:7], v[172:175], v[212:215], v[4:7]
	v_mfma_f32_16x16x32_bf16 v[0:3], v[180:183], v[212:215], v[0:3]
	s_setprio 0
	s_barrier
	s_add_i32 s61, s61, 2
	s_add_u32 s59, s59, 0x100
	s_addc_u32 s60, s60, 0
	s_cmp_gt_u32 s61, 41
	s_mov_b64 s[38:39], s[40:41]
	s_cbranch_scc0 .LBB0_370
	s_and_b64 vcc, exec, s[34:35]
	s_cbranch_vccz .LBB0_373
	s_barrier

; #define PG8_STAGE(bufoff, gbase, voff) do { _Pragma("unroll") for (int _i = 0; _i < 2; ++_i) \
;         __builtin_amdgcn_global_load_lds((const unsigned*)((const char*)(gbase) + (voff)[_i]), (LAS unsigned*)(lds + (bufoff) + ldsw + _i * 8192), 16, 0, 0); } while (0)
; #define PG8_LDA(dst, b, h) do { _Pragma("unroll") for (int m = 0; m < 4; ++m) _Pragma("unroll") for (int k = 0; k < 2; ++k) dst[m][k] = *(const LAS bf16x8*)(lds + PG8_SA(b, h) + aoff + m * 2048 + k * 1024); } while (0)
; #define PG8_LDB(dst, b, h) do { _Pragma("unroll") for (int n = 0; n < 2; ++n) _Pragma("unroll") for (int k = 0; k < 2; ++k) dst[n][k] = *(const LAS bf16x8*)(lds + PG8_SB(b, h) + boff + n * 2048 + k * 1024); } while (0)
; #define PG8_MMA(ai, bj, At, Bt) do { __builtin_amdgcn_s_setprio(1); _Pragma("unroll") for (int m = 0; m < 4; ++m) _Pragma("unroll") for (int n = 0; n < 2; ++n) _Pragma("unroll") for (int k = 0; k < 2; ++k) \
;         acc[ai][bj][m][n] = __builtin_amdgcn_mfma_f32_16x16x32_bf16(Bt[n][k], At[m][k], acc[ai][bj][m][n], 0, 0, 0); __builtin_amdgcn_s_setprio(0); } while (0)
; #define PG8_WAIT_V(n) asm volatile("s_waitcnt vmcnt(" #n ")" ::: "memory")
; #define PG8_WAIT_L(n) asm volatile("s_waitcnt lgkmcnt(" #n ")" ::: "memory")
; #define PG8_BAR __builtin_amdgcn_s_barrier()
; #define PG8_SCHED __builtin_amdgcn_sched_barrier(0)
; template <class Epi>
; __device__ __forceinline__ void gemm_phase(LAS unsigned char* lds, const Gemm g, const StaticOrder& S, const Epi& E, int wave_s) {
;     ...
;             PG8_LDB(B0, 0, 0); PG8_LDB(B1, 0, 1); PG8_SCHED; PG8_LDA(At, 0, 0); PG8_STAGE(PG8_SA(1, 1), a1 + hstepA, voffA);
;             PG8_WAIT_V(8); PG8_WAIT_L(0); PG8_BAR; PG8_MMA(0, 0, At, B0); PG8_MMA(0, 1, At, B1); PG8_BAR; PG8_SCHED;
;             PG8_LDA(At, 0, 1); PG8_STAGE(PG8_SB(0, 0), b2, voffB); PG8_STAGE(PG8_SB(0, 1), b2 + hstepB, voffB); PG8_STAGE(PG8_SA(0, 0), a2, voffA);
;             PG8_WAIT_V(8); PG8_WAIT_L(0); PG8_BAR; PG8_MMA(1, 0, At, B0); PG8_MMA(1, 1, At, B1); PG8_BAR; PG8_SCHED;
.LBB0_472:
	s_add_u32 s38, s10, 0xfffc0080
	s_addc_u32 s39, s11, -1
	s_cmp_eq_u32 s33, 12
	s_cselect_b32 s41, s0, s39
	s_cselect_b32 s40, s1, s38
	s_cselect_b32 s39, s2, s31
	s_cselect_b32 s38, s9, s29
	v_lshl_add_u64 v[196:197], s[10:11], 0, v[160:161]
	s_add_i32 m0, s48, 0xc000
	s_nop 0
	global_load_lds_dwordx4 v[196:197], off
	v_lshl_add_u64 v[196:197], s[10:11], 0, v[162:163]
	s_add_i32 m0, s48, 0xe000
	s_nop 0
	global_load_lds_dwordx4 v[196:197], off
	ds_read_b128 v[128:131], v199
	ds_read_b128 v[132:135], v199 offset:1024
	ds_read_b128 v[136:139], v199 offset:2048
	ds_read_b128 v[140:143], v199 offset:3072
	ds_read_b128 v[144:147], v200
	ds_read_b128 v[148:151], v200 offset:1024
	ds_read_b128 v[168:171], v200 offset:2048
	ds_read_b128 v[172:175], v200 offset:3072
	ds_read_b128 v[176:179], v201
	ds_read_b128 v[180:183], v201 offset:1024
	ds_read_b128 v[184:187], v201 offset:2048
	ds_read_b128 v[188:191], v201 offset:3072
	ds_read_b128 v[192:195], v201 offset:4096
	ds_read_b128 v[206:209], v201 offset:5120
	ds_read_b128 v[210:213], v201 offset:6144
	ds_read_b128 v[214:217], v201 offset:7168
	s_waitcnt vmcnt(8)
	s_waitcnt lgkmcnt(0)
	s_barrier
	s_setprio 1
	s_waitcnt lgkmcnt(0)
	v_mfma_f32_16x16x32_bf16 v[124:127], v[128:131], v[176:179], v[124:127]
	v_mfma_f32_16x16x32_bf16 v[120:123], v[136:139], v[176:179], v[120:123]
	v_mfma_f32_16x16x32_bf16 v[108:111], v[128:131], v[184:187], v[108:111]
	v_mfma_f32_16x16x32_bf16 v[104:107], v[136:139], v[184:187], v[104:107]
	v_mfma_f32_16x16x32_bf16 v[92:95], v[128:131], v[192:195], v[92:95]
	v_mfma_f32_16x16x32_bf16 v[88:91], v[136:139], v[192:195], v[88:91]
	v_mfma_f32_16x16x32_bf16 v[76:79], v[128:131], v[210:213], v[76:79]
	v_mfma_f32_16x16x32_bf16 v[72:75], v[136:139], v[210:213], v[72:75]
	v_mfma_f32_16x16x32_bf16 v[124:127], v[132:135], v[180:183], v[124:127]
	v_mfma_f32_16x16x32_bf16 v[120:123], v[140:143], v[180:183], v[120:123]
	v_mfma_f32_16x16x32_bf16 v[108:111], v[132:135], v[188:191], v[108:111]
	v_mfma_f32_16x16x32_bf16 v[104:107], v[140:143], v[188:191], v[104:107]
	v_mfma_f32_16x16x32_bf16 v[92:95], v[132:135], v[206:209], v[92:95]
	v_mfma_f32_16x16x32_bf16 v[88:91], v[140:143], v[206:209], v[88:91]
	v_mfma_f32_16x16x32_bf16 v[76:79], v[132:135], v[214:217], v[76:79]
	v_mfma_f32_16x16x32_bf16 v[72:75], v[140:143], v[214:217], v[72:75]
	s_setprio 0
	s_setprio 1
	v_mfma_f32_16x16x32_bf16 v[116:119], v[144:147], v[176:179], v[116:119]
	v_mfma_f32_16x16x32_bf16 v[112:115], v[168:171], v[176:179], v[112:115]
	v_mfma_f32_16x16x32_bf16 v[100:103], v[144:147], v[184:187], v[100:103]
	v_mfma_f32_16x16x32_bf16 v[96:99], v[168:171], v[184:187], v[96:99]
	v_mfma_f32_16x16x32_bf16 v[84:87], v[144:147], v[192:195], v[84:87]
	v_mfma_f32_16x16x32_bf16 v[80:83], v[168:171], v[192:195], v[80:83]
	v_mfma_f32_16x16x32_bf16 v[68:71], v[144:147], v[210:213], v[68:71]
	v_mfma_f32_16x16x32_bf16 v[64:67], v[168:171], v[210:213], v[64:67]
	v_mfma_f32_16x16x32_bf16 v[116:119], v[148:151], v[180:183], v[116:119]
	v_mfma_f32_16x16x32_bf16 v[112:115], v[172:175], v[180:183], v[112:115]
	v_mfma_f32_16x16x32_bf16 v[100:103], v[148:151], v[188:191], v[100:103]
	v_mfma_f32_16x16x32_bf16 v[96:99], v[172:175], v[188:191], v[96:99]
	v_mfma_f32_16x16x32_bf16 v[84:87], v[148:151], v[206:209], v[84:87]
	v_mfma_f32_16x16x32_bf16 v[80:83], v[172:175], v[206:209], v[80:83]
	v_mfma_f32_16x16x32_bf16 v[68:71], v[148:151], v[214:217], v[68:71]
	v_mfma_f32_16x16x32_bf16 v[64:67], v[172:175], v[214:217], v[64:67]
	s_setprio 0
	s_barrier
	s_add_i32 s67, s60, s47
	v_lshl_add_u64 v[196:197], s[38:39], 0, v[154:155]
	s_mov_b32 m0, s67
	s_nop 0
	global_load_lds_dwordx4 v[196:197], off
	s_add_i32 m0, s67, 0x2000
	s_add_u32 s68, s38, 0x40000
	v_lshl_add_u64 v[218:219], s[38:39], 0, v[158:159]
	s_addc_u32 s69, s39, 0
	s_add_i32 s67, s61, s47
	global_load_lds_dwordx4 v[218:219], off
	v_lshl_add_u64 v[220:221], s[68:69], 0, v[154:155]
	s_mov_b32 m0, s67
	v_lshl_add_u64 v[222:223], s[40:41], 0, v[156:157]
	global_load_lds_dwordx4 v[220:221], off
	v_lshl_add_u64 v[220:221], s[68:69], 0, v[158:159]
	s_add_i32 m0, s67, 0x2000
	s_nop 0
	global_load_lds_dwordx4 v[220:221], off
	v_lshl_add_u64 v[220:221], s[40:41], 0, v[152:153]
	s_mov_b32 m0, s48
	s_nop 0
	global_load_lds_dwordx4 v[220:221], off
	s_mov_b32 m0, s49
	s_nop 0
	global_load_lds_dwordx4 v[222:223], off
	ds_read_b128 v[176:179], v201 offset:16384
	ds_read_b128 v[180:183], v201 offset:17408
	ds_read_b128 v[184:187], v201 offset:18432
	ds_read_b128 v[188:191], v201 offset:19456
	ds_read_b128 v[192:195], v201 offset:20480
	ds_read_b128 v[206:209], v201 offset:21504
	ds_read_b128 v[210:213], v201 offset:22528
	ds_read_b128 v[214:217], v201 offset:23552
	s_waitcnt vmcnt(8)
	s_waitcnt lgkmcnt(0)
	s_barrier
; #define PG8_STAGE(bufoff, gbase, voff) do { _Pragma("unroll") for (int _i = 0; _i < 2; ++_i) \
;         __builtin_amdgcn_global_load_lds((const unsigned*)((const char*)(gbase) + (voff)[_i]), (LAS unsigned*)(lds + (bufoff) + ldsw + _i * 8192), 16, 0, 0); } while (0)
; #define PG8_LDA(dst, b, h) do { _Pragma("unroll") for (int m = 0; m < 4; ++m) _Pragma("unroll") for (int k = 0; k < 2; ++k) dst[m][k] = *(const LAS bf16x8*)(lds + PG8_SA(b, h) + aoff + m * 2048 + k * 1024); } while (0)
; #define PG8_LDB(dst, b, h) do { _Pragma("unroll") for (int n = 0; n < 2; ++n) _Pragma("unroll") for (int k = 0; k < 2; ++k) dst[n][k] = *(const LAS bf16x8*)(lds + PG8_SB(b, h) + boff + n * 2048 + k * 1024); } while (0)
; #define PG8_MMA(ai, bj, At, Bt) do { __builtin_amdgcn_s_setprio(1); _Pragma("unroll") for (int m = 0; m < 4; ++m) _Pragma("unroll") for (int n = 0; n < 2; ++n) _Pragma("unroll") for (int k = 0; k < 2; ++k) \
;         acc[ai][bj][m][n] = __builtin_amdgcn_mfma_f32_16x16x32_bf16(Bt[n][k], At[m][k], acc[ai][bj][m][n], 0, 0, 0); __builtin_amdgcn_s_setprio(0); } while (0)
; #define PG8_WAIT_V(n) asm volatile("s_waitcnt vmcnt(" #n ")" ::: "memory")
; #define PG8_WAIT_L(n) asm volatile("s_waitcnt lgkmcnt(" #n ")" ::: "memory")
; #define PG8_BAR __builtin_amdgcn_s_barrier()
; #define PG8_SCHED __builtin_amdgcn_sched_barrier(0)
; template <class Epi>
; __device__ __forceinline__ void gemm_phase(LAS unsigned char* lds, const Gemm g, const StaticOrder& S, const Epi& E, int wave_s) {
;     ...
;             PG8_WAIT_V(8); PG8_WAIT_L(0); PG8_BAR; PG8_MMA(1, 0, At, B0); PG8_MMA(1, 1, At, B1); PG8_BAR; PG8_SCHED;
;             PG8_LDB(B0, 1, 0); PG8_LDB(B1, 1, 1); PG8_SCHED; PG8_LDA(At, 1, 0); PG8_STAGE(PG8_SA(0, 1), a2 + hstepA, voffA);
;             PG8_WAIT_V(8); PG8_WAIT_L(0); PG8_BAR; PG8_MMA(0, 0, At, B0); PG8_MMA(0, 1, At, B1); PG8_BAR; PG8_SCHED;
	s_setprio 1
	s_waitcnt lgkmcnt(0)
	v_mfma_f32_16x16x32_bf16 v[60:63], v[128:131], v[176:179], v[60:63]
	v_mfma_f32_16x16x32_bf16 v[56:59], v[136:139], v[176:179], v[56:59]
	v_mfma_f32_16x16x32_bf16 v[44:47], v[128:131], v[184:187], v[44:47]
	v_mfma_f32_16x16x32_bf16 v[40:43], v[136:139], v[184:187], v[40:43]
	v_mfma_f32_16x16x32_bf16 v[28:31], v[128:131], v[192:195], v[28:31]
	v_mfma_f32_16x16x32_bf16 v[24:27], v[136:139], v[192:195], v[24:27]
	v_mfma_f32_16x16x32_bf16 v[12:15], v[128:131], v[210:213], v[12:15]
	v_mfma_f32_16x16x32_bf16 v[8:11], v[136:139], v[210:213], v[8:11]
	v_mfma_f32_16x16x32_bf16 v[60:63], v[132:135], v[180:183], v[60:63]
	v_mfma_f32_16x16x32_bf16 v[56:59], v[140:143], v[180:183], v[56:59]
	v_mfma_f32_16x16x32_bf16 v[44:47], v[132:135], v[188:191], v[44:47]
	v_mfma_f32_16x16x32_bf16 v[40:43], v[140:143], v[188:191], v[40:43]
	v_mfma_f32_16x16x32_bf16 v[28:31], v[132:135], v[206:209], v[28:31]
	v_mfma_f32_16x16x32_bf16 v[24:27], v[140:143], v[206:209], v[24:27]
	v_mfma_f32_16x16x32_bf16 v[12:15], v[132:135], v[214:217], v[12:15]
	v_mfma_f32_16x16x32_bf16 v[8:11], v[140:143], v[214:217], v[8:11]
	s_setprio 0
	s_setprio 1
	v_mfma_f32_16x16x32_bf16 v[52:55], v[144:147], v[176:179], v[52:55]
	v_mfma_f32_16x16x32_bf16 v[48:51], v[168:171], v[176:179], v[48:51]
	v_mfma_f32_16x16x32_bf16 v[36:39], v[144:147], v[184:187], v[36:39]
	v_mfma_f32_16x16x32_bf16 v[32:35], v[168:171], v[184:187], v[32:35]
	v_mfma_f32_16x16x32_bf16 v[20:23], v[144:147], v[192:195], v[20:23]
	v_mfma_f32_16x16x32_bf16 v[16:19], v[168:171], v[192:195], v[16:19]
	v_mfma_f32_16x16x32_bf16 v[4:7], v[144:147], v[210:213], v[4:7]
	v_mfma_f32_16x16x32_bf16 v[0:3], v[168:171], v[210:213], v[0:3]
	v_mfma_f32_16x16x32_bf16 v[52:55], v[148:151], v[180:183], v[52:55]
	v_mfma_f32_16x16x32_bf16 v[48:51], v[172:175], v[180:183], v[48:51]
	v_mfma_f32_16x16x32_bf16 v[36:39], v[148:151], v[188:191], v[36:39]
	v_mfma_f32_16x16x32_bf16 v[32:35], v[172:175], v[188:191], v[32:35]
	v_mfma_f32_16x16x32_bf16 v[20:23], v[148:151], v[206:209], v[20:23]
	v_mfma_f32_16x16x32_bf16 v[16:19], v[172:175], v[206:209], v[16:19]
	v_mfma_f32_16x16x32_bf16 v[4:7], v[148:151], v[214:217], v[4:7]
	v_mfma_f32_16x16x32_bf16 v[0:3], v[172:175], v[214:217], v[0:3]
	s_setprio 0
	s_barrier
	s_add_i32 s67, 0, 0x18000
	s_add_i32 s68, 0, 0x1c000
	s_add_u32 s40, s40, 0x40000
	s_addc_u32 s41, s41, 0
	s_mov_b32 m0, s50
	v_lshl_add_u64 v[224:225], s[40:41], 0, v[152:153]
	global_load_lds_dwordx4 v[224:225], off
	v_lshl_add_u64 v[224:225], s[40:41], 0, v[156:157]
	s_mov_b32 m0, s51
	s_nop 0
	global_load_lds_dwordx4 v[224:225], off
	v_add_u32_e32 v140, s67, v198
	v_add_u32_e32 v172, s68, v198
	ds_read_b128 v[128:131], v140
	ds_read_b128 v[132:135], v140 offset:1024
	ds_read_b128 v[136:139], v140 offset:2048
	ds_read_b128 v[140:143], v140 offset:3072
	ds_read_b128 v[144:147], v172
	ds_read_b128 v[148:151], v172 offset:1024
	ds_read_b128 v[168:171], v172 offset:2048
	ds_read_b128 v[172:175], v172 offset:3072
	ds_read_b128 v[176:179], v201 offset:32768
	ds_read_b128 v[180:183], v201 offset:33792
	ds_read_b128 v[184:187], v201 offset:34816
	ds_read_b128 v[188:191], v201 offset:35840
	ds_read_b128 v[192:195], v201 offset:36864
	ds_read_b128 v[206:209], v201 offset:37888
	ds_read_b128 v[210:213], v201 offset:38912
	ds_read_b128 v[214:217], v201 offset:39936
	s_waitcnt vmcnt(8)
	s_waitcnt lgkmcnt(0)
	s_barrier
	s_setprio 1
	s_waitcnt lgkmcnt(0)
	v_mfma_f32_16x16x32_bf16 v[124:127], v[128:131], v[176:179], v[124:127]
	v_mfma_f32_16x16x32_bf16 v[120:123], v[136:139], v[176:179], v[120:123]
	v_mfma_f32_16x16x32_bf16 v[108:111], v[128:131], v[184:187], v[108:111]
	v_mfma_f32_16x16x32_bf16 v[104:107], v[136:139], v[184:187], v[104:107]
	v_mfma_f32_16x16x32_bf16 v[92:95], v[128:131], v[192:195], v[92:95]
	v_mfma_f32_16x16x32_bf16 v[88:91], v[136:139], v[192:195], v[88:91]
	v_mfma_f32_16x16x32_bf16 v[76:79], v[128:131], v[210:213], v[76:79]
	v_mfma_f32_16x16x32_bf16 v[72:75], v[136:139], v[210:213], v[72:75]
	v_mfma_f32_16x16x32_bf16 v[124:127], v[132:135], v[180:183], v[124:127]
	v_mfma_f32_16x16x32_bf16 v[120:123], v[140:143], v[180:183], v[120:123]
	v_mfma_f32_16x16x32_bf16 v[108:111], v[132:135], v[188:191], v[108:111]
	v_mfma_f32_16x16x32_bf16 v[104:107], v[140:143], v[188:191], v[104:107]
	v_mfma_f32_16x16x32_bf16 v[92:95], v[132:135], v[206:209], v[92:95]
	v_mfma_f32_16x16x32_bf16 v[88:91], v[140:143], v[206:209], v[88:91]
	v_mfma_f32_16x16x32_bf16 v[76:79], v[132:135], v[214:217], v[76:79]
	v_mfma_f32_16x16x32_bf16 v[72:75], v[140:143], v[214:217], v[72:75]
	s_setprio 0
	s_setprio 1
	v_mfma_f32_16x16x32_bf16 v[116:119], v[144:147], v[176:179], v[116:119]
	v_mfma_f32_16x16x32_bf16 v[112:115], v[168:171], v[176:179], v[112:115]
	v_mfma_f32_16x16x32_bf16 v[100:103], v[144:147], v[184:187], v[100:103]
	v_mfma_f32_16x16x32_bf16 v[96:99], v[168:171], v[184:187], v[96:99]
	v_mfma_f32_16x16x32_bf16 v[84:87], v[144:147], v[192:195], v[84:87]
	v_mfma_f32_16x16x32_bf16 v[80:83], v[168:171], v[192:195], v[80:83]
	v_mfma_f32_16x16x32_bf16 v[68:71], v[144:147], v[210:213], v[68:71]
	v_mfma_f32_16x16x32_bf16 v[64:67], v[168:171], v[210:213], v[64:67]
	v_mfma_f32_16x16x32_bf16 v[116:119], v[148:151], v[180:183], v[116:119]
	v_mfma_f32_16x16x32_bf16 v[112:115], v[172:175], v[180:183], v[112:115]
	v_mfma_f32_16x16x32_bf16 v[100:103], v[148:151], v[188:191], v[100:103]
	v_mfma_f32_16x16x32_bf16 v[96:99], v[172:175], v[188:191], v[96:99]
	v_mfma_f32_16x16x32_bf16 v[84:87], v[148:151], v[206:209], v[84:87]
	v_mfma_f32_16x16x32_bf16 v[80:83], v[172:175], v[206:209], v[80:83]
	v_mfma_f32_16x16x32_bf16 v[68:71], v[148:151], v[214:217], v[68:71]
	v_mfma_f32_16x16x32_bf16 v[64:67], v[172:175], v[214:217], v[64:67]
	s_setprio 0
	s_barrier
; #define PG8_STAGE(bufoff, gbase, voff) do { _Pragma("unroll") for (int _i = 0; _i < 2; ++_i) \
;         __builtin_amdgcn_global_load_lds((const unsigned*)((const char*)(gbase) + (voff)[_i]), (LAS unsigned*)(lds + (bufoff) + ldsw + _i * 8192), 16, 0, 0); } while (0)
; #define PG8_LDA(dst, b, h) do { _Pragma("unroll") for (int m = 0; m < 4; ++m) _Pragma("unroll") for (int k = 0; k < 2; ++k) dst[m][k] = *(const LAS bf16x8*)(lds + PG8_SA(b, h) + aoff + m * 2048 + k * 1024); } while (0)
; #define PG8_MMA(ai, bj, At, Bt) do { __builtin_amdgcn_s_setprio(1); _Pragma("unroll") for (int m = 0; m < 4; ++m) _Pragma("unroll") for (int n = 0; n < 2; ++n) _Pragma("unroll") for (int k = 0; k < 2; ++k) \
;         acc[ai][bj][m][n] = __builtin_amdgcn_mfma_f32_16x16x32_bf16(Bt[n][k], At[m][k], acc[ai][bj][m][n], 0, 0, 0); __builtin_amdgcn_s_setprio(0); } while (0)
; #define PG8_WAIT_V(n) asm volatile("s_waitcnt vmcnt(" #n ")" ::: "memory")
; #define PG8_WAIT_L(n) asm volatile("s_waitcnt lgkmcnt(" #n ")" ::: "memory")
; #define PG8_BAR __builtin_amdgcn_s_barrier()
; #define PG8_SCHED __builtin_amdgcn_sched_barrier(0)
; template <class Epi>
; __device__ __forceinline__ void gemm_phase(LAS unsigned char* lds, const Gemm g, const StaticOrder& S, const Epi& E, int wave_s) {
;     ...
;             PG8_LDA(At, 1, 1); PG8_STAGE(PG8_SB(1, 0), b3, voffB); PG8_STAGE(PG8_SB(1, 1), b3 + hstepB, voffB); PG8_STAGE(PG8_SA(1, 0), a3, voffA);
;             PG8_WAIT_V(8); PG8_WAIT_L(0); PG8_BAR; PG8_MMA(1, 0, At, B0); PG8_MMA(1, 1, At, B1); PG8_BAR; PG8_SCHED;
;         }
	s_add_i32 s40, s67, s47
	v_lshl_add_u64 v[196:197], v[196:197], 0, s[24:25]
	s_mov_b32 m0, s40
	s_nop 0
	global_load_lds_dwordx4 v[196:197], off
	s_add_i32 m0, s40, 0x2000
	s_add_u32 s38, s38, 0x40080
	v_lshl_add_u64 v[196:197], v[218:219], 0, s[24:25]
	s_addc_u32 s39, s39, 0
	s_add_i32 s40, s68, s47
	global_load_lds_dwordx4 v[196:197], off
	v_lshl_add_u64 v[196:197], s[38:39], 0, v[154:155]
	s_mov_b32 m0, s40
	s_nop 0
	global_load_lds_dwordx4 v[196:197], off
	v_lshl_add_u64 v[196:197], s[38:39], 0, v[158:159]
	s_add_i32 m0, s40, 0x2000
	s_nop 0
	global_load_lds_dwordx4 v[196:197], off
	v_lshl_add_u64 v[196:197], v[220:221], 0, s[24:25]
	s_mov_b32 m0, s56
	s_nop 0
	global_load_lds_dwordx4 v[196:197], off
	v_lshl_add_u64 v[196:197], v[222:223], 0, s[24:25]
	s_mov_b32 m0, s57
	s_nop 0
	global_load_lds_dwordx4 v[196:197], off
	ds_read_b128 v[176:179], v201 offset:49152
	ds_read_b128 v[180:183], v201 offset:50176
	ds_read_b128 v[184:187], v201 offset:51200
	ds_read_b128 v[188:191], v201 offset:52224
	ds_read_b128 v[192:195], v201 offset:53248
	ds_read_b128 v[206:209], v201 offset:54272
	ds_read_b128 v[210:213], v201 offset:55296
	ds_read_b128 v[214:217], v201 offset:56320
	s_waitcnt vmcnt(8)
	s_waitcnt lgkmcnt(0)
	s_barrier
	s_setprio 1
	s_waitcnt lgkmcnt(0)
	v_mfma_f32_16x16x32_bf16 v[60:63], v[128:131], v[176:179], v[60:63]
	v_mfma_f32_16x16x32_bf16 v[56:59], v[136:139], v[176:179], v[56:59]
	v_mfma_f32_16x16x32_bf16 v[44:47], v[128:131], v[184:187], v[44:47]
	v_mfma_f32_16x16x32_bf16 v[40:43], v[136:139], v[184:187], v[40:43]
	v_mfma_f32_16x16x32_bf16 v[28:31], v[128:131], v[192:195], v[28:31]
	v_mfma_f32_16x16x32_bf16 v[24:27], v[136:139], v[192:195], v[24:27]
	v_mfma_f32_16x16x32_bf16 v[12:15], v[128:131], v[210:213], v[12:15]
	v_mfma_f32_16x16x32_bf16 v[8:11], v[136:139], v[210:213], v[8:11]
	v_mfma_f32_16x16x32_bf16 v[60:63], v[132:135], v[180:183], v[60:63]
	v_mfma_f32_16x16x32_bf16 v[56:59], v[140:143], v[180:183], v[56:59]
	v_mfma_f32_16x16x32_bf16 v[44:47], v[132:135], v[188:191], v[44:47]
	v_mfma_f32_16x16x32_bf16 v[40:43], v[140:143], v[188:191], v[40:43]
	v_mfma_f32_16x16x32_bf16 v[28:31], v[132:135], v[206:209], v[28:31]
	v_mfma_f32_16x16x32_bf16 v[24:27], v[140:143], v[206:209], v[24:27]
	v_mfma_f32_16x16x32_bf16 v[12:15], v[132:135], v[214:217], v[12:15]
	v_mfma_f32_16x16x32_bf16 v[8:11], v[140:143], v[214:217], v[8:11]
	s_setprio 0
	s_setprio 1
	v_mfma_f32_16x16x32_bf16 v[52:55], v[144:147], v[176:179], v[52:55]
	v_mfma_f32_16x16x32_bf16 v[48:51], v[168:171], v[176:179], v[48:51]
	v_mfma_f32_16x16x32_bf16 v[36:39], v[144:147], v[184:187], v[36:39]
	v_mfma_f32_16x16x32_bf16 v[32:35], v[168:171], v[184:187], v[32:35]
	v_mfma_f32_16x16x32_bf16 v[20:23], v[144:147], v[192:195], v[20:23]
	v_mfma_f32_16x16x32_bf16 v[16:19], v[168:171], v[192:195], v[16:19]
	v_mfma_f32_16x16x32_bf16 v[4:7], v[144:147], v[210:213], v[4:7]
	v_mfma_f32_16x16x32_bf16 v[0:3], v[168:171], v[210:213], v[0:3]
	v_mfma_f32_16x16x32_bf16 v[52:55], v[148:151], v[180:183], v[52:55]
	v_mfma_f32_16x16x32_bf16 v[48:51], v[172:175], v[180:183], v[48:51]
	v_mfma_f32_16x16x32_bf16 v[36:39], v[148:151], v[188:191], v[36:39]
	v_mfma_f32_16x16x32_bf16 v[32:35], v[172:175], v[188:191], v[32:35]
	v_mfma_f32_16x16x32_bf16 v[20:23], v[148:151], v[206:209], v[20:23]
	v_mfma_f32_16x16x32_bf16 v[16:19], v[172:175], v[206:209], v[16:19]
	v_mfma_f32_16x16x32_bf16 v[4:7], v[148:151], v[214:217], v[4:7]
	v_mfma_f32_16x16x32_bf16 v[0:3], v[172:175], v[214:217], v[0:3]
	s_setprio 0
	s_barrier
	s_add_i32 s33, s33, 2
	s_add_u32 s10, s10, 0x100
	s_addc_u32 s11, s11, 0
	s_add_u32 s29, s29, 0x100
	s_addc_u32 s31, s31, 0
	s_cmp_gt_u32 s33, 13
	s_cbranch_scc0 .LBB0_472
	s_and_b64 vcc, exec, s[26:27]
	s_cbranch_vccz .LBB0_475
	s_barrier

; #define PG8_STAGE(bufoff, gbase, voff) do { _Pragma("unroll") for (int _i = 0; _i < 2; ++_i) \
;         __builtin_amdgcn_global_load_lds((const unsigned*)((const char*)(gbase) + (voff)[_i]), (LAS unsigned*)(lds + (bufoff) + ldsw + _i * 8192), 16, 0, 0); } while (0)
; #define PG8_LDA(dst, b, h) do { _Pragma("unroll") for (int m = 0; m < 4; ++m) _Pragma("unroll") for (int k = 0; k < 2; ++k) dst[m][k] = *(const LAS bf16x8*)(lds + PG8_SA(b, h) + aoff + m * 2048 + k * 1024); } while (0)
; #define PG8_LDB(dst, b, h) do { _Pragma("unroll") for (int n = 0; n < 2; ++n) _Pragma("unroll") for (int k = 0; k < 2; ++k) dst[n][k] = *(const LAS bf16x8*)(lds + PG8_SB(b, h) + boff + n * 2048 + k * 1024); } while (0)
; #define PG8_MMA(ai, bj, At, Bt) do { __builtin_amdgcn_s_setprio(1); _Pragma("unroll") for (int m = 0; m < 4; ++m) _Pragma("unroll") for (int n = 0; n < 2; ++n) _Pragma("unroll") for (int k = 0; k < 2; ++k) \
;         acc[ai][bj][m][n] = __builtin_amdgcn_mfma_f32_16x16x32_bf16(Bt[n][k], At[m][k], acc[ai][bj][m][n], 0, 0, 0); __builtin_amdgcn_s_setprio(0); } while (0)
; #define PG8_WAIT_V(n) asm volatile("s_waitcnt vmcnt(" #n ")" ::: "memory")
; #define PG8_WAIT_L(n) asm volatile("s_waitcnt lgkmcnt(" #n ")" ::: "memory")
; #define PG8_BAR __builtin_amdgcn_s_barrier()
; #define PG8_SCHED __builtin_amdgcn_sched_barrier(0)
; template <class Epi>
; __device__ __forceinline__ void gemm_phase(LAS unsigned char* lds, const Gemm g, const StaticOrder& S, const Epi& E, int wave_s) {
;     ...
;             PG8_LDB(B0, 0, 0); PG8_LDB(B1, 0, 1); PG8_SCHED; PG8_LDA(At, 0, 0); PG8_STAGE(PG8_SA(1, 1), a1 + hstepA, voffA);
;             PG8_WAIT_V(8); PG8_WAIT_L(0); PG8_BAR; PG8_MMA(0, 0, At, B0); PG8_MMA(0, 1, At, B1); PG8_BAR; PG8_SCHED;
;             PG8_LDA(At, 0, 1); PG8_STAGE(PG8_SB(0, 0), b2, voffB); PG8_STAGE(PG8_SB(0, 1), b2 + hstepB, voffB); PG8_STAGE(PG8_SA(0, 0), a2, voffA);
;             PG8_WAIT_V(8); PG8_WAIT_L(0); PG8_BAR; PG8_MMA(1, 0, At, B0); PG8_MMA(1, 1, At, B1); PG8_BAR; PG8_SCHED;
.LBB0_500:
	s_add_u32 s10, s8, 0xfffc0080
	s_addc_u32 s11, s9, -1
	s_cmp_eq_u32 s65, 12
	s_cselect_b32 s45, s37, s11
	s_cselect_b32 s44, s61, s10
	s_cselect_b32 s11, s35, s64
	s_cselect_b32 s10, s62, s63
	v_lshl_add_u64 v[160:161], s[8:9], 0, v[136:137]
	s_add_i32 m0, s43, 0xc000
	s_nop 0
	global_load_lds_dwordx4 v[160:161], off
	v_lshl_add_u64 v[160:161], s[8:9], 0, v[138:139]
	s_add_i32 m0, s43, 0xe000
	s_nop 0
	global_load_lds_dwordx4 v[160:161], off
	ds_read_b128 v[144:147], v165
	ds_read_b128 v[148:151], v165 offset:1024
	ds_read_b128 v[152:155], v165 offset:2048
	ds_read_b128 v[156:159], v165 offset:3072
	ds_read_b128 v[170:173], v166
	ds_read_b128 v[174:177], v166 offset:1024
	ds_read_b128 v[178:181], v166 offset:2048
	ds_read_b128 v[182:185], v166 offset:3072
	ds_read_b128 v[186:189], v167
	ds_read_b128 v[190:193], v167 offset:1024
	ds_read_b128 v[194:197], v167 offset:2048
	ds_read_b128 v[198:201], v167 offset:3072
	ds_read_b128 v[202:205], v167 offset:4096
	ds_read_b128 v[206:209], v167 offset:5120
	ds_read_b128 v[210:213], v167 offset:6144
	ds_read_b128 v[214:217], v167 offset:7168
	s_waitcnt vmcnt(8)
	s_waitcnt lgkmcnt(0)
	s_barrier
	s_setprio 1
	s_waitcnt lgkmcnt(0)
	v_mfma_f32_16x16x32_bf16 v[124:127], v[144:147], v[186:189], v[124:127]
	v_mfma_f32_16x16x32_bf16 v[120:123], v[152:155], v[186:189], v[120:123]
	v_mfma_f32_16x16x32_bf16 v[112:115], v[144:147], v[194:197], v[112:115]
	v_mfma_f32_16x16x32_bf16 v[108:111], v[152:155], v[194:197], v[108:111]
	v_mfma_f32_16x16x32_bf16 v[100:103], v[144:147], v[202:205], v[100:103]
	v_mfma_f32_16x16x32_bf16 v[92:95], v[152:155], v[202:205], v[92:95]
	v_mfma_f32_16x16x32_bf16 v[84:87], v[144:147], v[210:213], v[84:87]
	v_mfma_f32_16x16x32_bf16 v[76:79], v[152:155], v[210:213], v[76:79]
	v_mfma_f32_16x16x32_bf16 v[124:127], v[148:151], v[190:193], v[124:127]
	v_mfma_f32_16x16x32_bf16 v[120:123], v[156:159], v[190:193], v[120:123]
	v_mfma_f32_16x16x32_bf16 v[112:115], v[148:151], v[198:201], v[112:115]
	v_mfma_f32_16x16x32_bf16 v[108:111], v[156:159], v[198:201], v[108:111]
	v_mfma_f32_16x16x32_bf16 v[100:103], v[148:151], v[206:209], v[100:103]
	v_mfma_f32_16x16x32_bf16 v[92:95], v[156:159], v[206:209], v[92:95]
	v_mfma_f32_16x16x32_bf16 v[84:87], v[148:151], v[214:217], v[84:87]
	v_mfma_f32_16x16x32_bf16 v[76:79], v[156:159], v[214:217], v[76:79]
	s_setprio 0
	s_setprio 1
	v_mfma_f32_16x16x32_bf16 v[116:119], v[170:173], v[186:189], v[116:119]
	v_mfma_f32_16x16x32_bf16 v[104:107], v[178:181], v[186:189], v[104:107]
	v_mfma_f32_16x16x32_bf16 v[96:99], v[170:173], v[194:197], v[96:99]
	v_mfma_f32_16x16x32_bf16 v[88:91], v[178:181], v[194:197], v[88:91]
	v_mfma_f32_16x16x32_bf16 v[80:83], v[170:173], v[202:205], v[80:83]
	v_mfma_f32_16x16x32_bf16 v[72:75], v[178:181], v[202:205], v[72:75]
	v_mfma_f32_16x16x32_bf16 v[68:71], v[170:173], v[210:213], v[68:71]
	v_mfma_f32_16x16x32_bf16 v[64:67], v[178:181], v[210:213], v[64:67]
	v_mfma_f32_16x16x32_bf16 v[116:119], v[174:177], v[190:193], v[116:119]
	v_mfma_f32_16x16x32_bf16 v[104:107], v[182:185], v[190:193], v[104:107]
	v_mfma_f32_16x16x32_bf16 v[96:99], v[174:177], v[198:201], v[96:99]
	v_mfma_f32_16x16x32_bf16 v[88:91], v[182:185], v[198:201], v[88:91]
	v_mfma_f32_16x16x32_bf16 v[80:83], v[174:177], v[206:209], v[80:83]
	v_mfma_f32_16x16x32_bf16 v[72:75], v[182:185], v[206:209], v[72:75]
	v_mfma_f32_16x16x32_bf16 v[68:71], v[174:177], v[214:217], v[68:71]
	v_mfma_f32_16x16x32_bf16 v[64:67], v[182:185], v[214:217], v[64:67]
	s_setprio 0
	s_barrier
	s_add_i32 s66, s54, s46
	v_lshl_add_u64 v[160:161], s[10:11], 0, v[130:131]
	s_mov_b32 m0, s66
	s_nop 0
	global_load_lds_dwordx4 v[160:161], off
	s_add_i32 m0, s66, 0x2000
	s_add_u32 s66, s10, 0x40000
	v_lshl_add_u64 v[218:219], s[10:11], 0, v[134:135]
	s_addc_u32 s67, s11, 0
	s_add_i32 s68, s55, s46
	global_load_lds_dwordx4 v[218:219], off
	v_lshl_add_u64 v[220:221], s[66:67], 0, v[130:131]
	s_mov_b32 m0, s68
	v_lshl_add_u64 v[222:223], s[44:45], 0, v[132:133]
	global_load_lds_dwordx4 v[220:221], off
	v_lshl_add_u64 v[220:221], s[66:67], 0, v[134:135]
	s_add_i32 m0, s68, 0x2000
	s_nop 0
	global_load_lds_dwordx4 v[220:221], off
	v_lshl_add_u64 v[220:221], s[44:45], 0, v[128:129]
	s_mov_b32 m0, s43
	s_nop 0
	global_load_lds_dwordx4 v[220:221], off
	s_mov_b32 m0, s47
	s_nop 0
	global_load_lds_dwordx4 v[222:223], off
	ds_read_b128 v[186:189], v167 offset:16384
	ds_read_b128 v[190:193], v167 offset:17408
	ds_read_b128 v[194:197], v167 offset:18432
	ds_read_b128 v[198:201], v167 offset:19456
	ds_read_b128 v[202:205], v167 offset:20480
	ds_read_b128 v[206:209], v167 offset:21504
	ds_read_b128 v[210:213], v167 offset:22528
	ds_read_b128 v[214:217], v167 offset:23552
	s_waitcnt vmcnt(8)
	s_waitcnt lgkmcnt(0)
	s_barrier
; #define PG8_STAGE(bufoff, gbase, voff) do { _Pragma("unroll") for (int _i = 0; _i < 2; ++_i) \
;         __builtin_amdgcn_global_load_lds((const unsigned*)((const char*)(gbase) + (voff)[_i]), (LAS unsigned*)(lds + (bufoff) + ldsw + _i * 8192), 16, 0, 0); } while (0)
; #define PG8_LDA(dst, b, h) do { _Pragma("unroll") for (int m = 0; m < 4; ++m) _Pragma("unroll") for (int k = 0; k < 2; ++k) dst[m][k] = *(const LAS bf16x8*)(lds + PG8_SA(b, h) + aoff + m * 2048 + k * 1024); } while (0)
; #define PG8_LDB(dst, b, h) do { _Pragma("unroll") for (int n = 0; n < 2; ++n) _Pragma("unroll") for (int k = 0; k < 2; ++k) dst[n][k] = *(const LAS bf16x8*)(lds + PG8_SB(b, h) + boff + n * 2048 + k * 1024); } while (0)
; #define PG8_MMA(ai, bj, At, Bt) do { __builtin_amdgcn_s_setprio(1); _Pragma("unroll") for (int m = 0; m < 4; ++m) _Pragma("unroll") for (int n = 0; n < 2; ++n) _Pragma("unroll") for (int k = 0; k < 2; ++k) \
;         acc[ai][bj][m][n] = __builtin_amdgcn_mfma_f32_16x16x32_bf16(Bt[n][k], At[m][k], acc[ai][bj][m][n], 0, 0, 0); __builtin_amdgcn_s_setprio(0); } while (0)
; #define PG8_WAIT_V(n) asm volatile("s_waitcnt vmcnt(" #n ")" ::: "memory")
; #define PG8_WAIT_L(n) asm volatile("s_waitcnt lgkmcnt(" #n ")" ::: "memory")
; #define PG8_BAR __builtin_amdgcn_s_barrier()
; #define PG8_SCHED __builtin_amdgcn_sched_barrier(0)
; template <class Epi>
; __device__ __forceinline__ void gemm_phase(LAS unsigned char* lds, const Gemm g, const StaticOrder& S, const Epi& E, int wave_s) {
;     ...
;             PG8_WAIT_V(8); PG8_WAIT_L(0); PG8_BAR; PG8_MMA(1, 0, At, B0); PG8_MMA(1, 1, At, B1); PG8_BAR; PG8_SCHED;
;             PG8_LDB(B0, 1, 0); PG8_LDB(B1, 1, 1); PG8_SCHED; PG8_LDA(At, 1, 0); PG8_STAGE(PG8_SA(0, 1), a2 + hstepA, voffA);
;             PG8_WAIT_V(8); PG8_WAIT_L(0); PG8_BAR; PG8_MMA(0, 0, At, B0); PG8_MMA(0, 1, At, B1); PG8_BAR; PG8_SCHED;
	s_setprio 1
	s_waitcnt lgkmcnt(0)
	v_mfma_f32_16x16x32_bf16 v[60:63], v[144:147], v[186:189], v[60:63]
	v_mfma_f32_16x16x32_bf16 v[56:59], v[152:155], v[186:189], v[56:59]
	v_mfma_f32_16x16x32_bf16 v[52:55], v[144:147], v[194:197], v[52:55]
	v_mfma_f32_16x16x32_bf16 v[44:47], v[152:155], v[194:197], v[44:47]
	v_mfma_f32_16x16x32_bf16 v[36:39], v[144:147], v[202:205], v[36:39]
	v_mfma_f32_16x16x32_bf16 v[28:31], v[152:155], v[202:205], v[28:31]
	v_mfma_f32_16x16x32_bf16 v[20:23], v[144:147], v[210:213], v[20:23]
	v_mfma_f32_16x16x32_bf16 v[12:15], v[152:155], v[210:213], v[12:15]
	v_mfma_f32_16x16x32_bf16 v[60:63], v[148:151], v[190:193], v[60:63]
	v_mfma_f32_16x16x32_bf16 v[56:59], v[156:159], v[190:193], v[56:59]
	v_mfma_f32_16x16x32_bf16 v[52:55], v[148:151], v[198:201], v[52:55]
	v_mfma_f32_16x16x32_bf16 v[44:47], v[156:159], v[198:201], v[44:47]
	v_mfma_f32_16x16x32_bf16 v[36:39], v[148:151], v[206:209], v[36:39]
	v_mfma_f32_16x16x32_bf16 v[28:31], v[156:159], v[206:209], v[28:31]
	v_mfma_f32_16x16x32_bf16 v[20:23], v[148:151], v[214:217], v[20:23]
	v_mfma_f32_16x16x32_bf16 v[12:15], v[156:159], v[214:217], v[12:15]
	s_setprio 0
	s_setprio 1
	v_mfma_f32_16x16x32_bf16 v[48:51], v[170:173], v[186:189], v[48:51]
	v_mfma_f32_16x16x32_bf16 v[40:43], v[178:181], v[186:189], v[40:43]
	v_mfma_f32_16x16x32_bf16 v[32:35], v[170:173], v[194:197], v[32:35]
	v_mfma_f32_16x16x32_bf16 v[24:27], v[178:181], v[194:197], v[24:27]
	v_mfma_f32_16x16x32_bf16 v[16:19], v[170:173], v[202:205], v[16:19]
	v_mfma_f32_16x16x32_bf16 v[8:11], v[178:181], v[202:205], v[8:11]
	v_mfma_f32_16x16x32_bf16 v[4:7], v[170:173], v[210:213], v[4:7]
	v_mfma_f32_16x16x32_bf16 v[0:3], v[178:181], v[210:213], v[0:3]
	v_mfma_f32_16x16x32_bf16 v[48:51], v[174:177], v[190:193], v[48:51]
	v_mfma_f32_16x16x32_bf16 v[40:43], v[182:185], v[190:193], v[40:43]
	v_mfma_f32_16x16x32_bf16 v[32:35], v[174:177], v[198:201], v[32:35]
	v_mfma_f32_16x16x32_bf16 v[24:27], v[182:185], v[198:201], v[24:27]
	v_mfma_f32_16x16x32_bf16 v[16:19], v[174:177], v[206:209], v[16:19]
	v_mfma_f32_16x16x32_bf16 v[8:11], v[182:185], v[206:209], v[8:11]
	v_mfma_f32_16x16x32_bf16 v[4:7], v[174:177], v[214:217], v[4:7]
	v_mfma_f32_16x16x32_bf16 v[0:3], v[182:185], v[214:217], v[0:3]
	s_setprio 0
	s_barrier
	s_add_i32 s66, 0, 0x18000
	s_add_i32 s67, 0, 0x1c000
	s_add_u32 s44, s44, 0x40000
	s_addc_u32 s45, s45, 0
	s_mov_b32 m0, s48
	v_lshl_add_u64 v[224:225], s[44:45], 0, v[128:129]
	global_load_lds_dwordx4 v[224:225], off
	v_lshl_add_u64 v[224:225], s[44:45], 0, v[132:133]
	s_mov_b32 m0, s49
	s_nop 0
	global_load_lds_dwordx4 v[224:225], off
	v_add_u32_e32 v156, s66, v163
	v_add_u32_e32 v182, s67, v163
	ds_read_b128 v[144:147], v156
	ds_read_b128 v[148:151], v156 offset:1024
	ds_read_b128 v[152:155], v156 offset:2048
	ds_read_b128 v[156:159], v156 offset:3072
	ds_read_b128 v[170:173], v182
	ds_read_b128 v[174:177], v182 offset:1024
	ds_read_b128 v[178:181], v182 offset:2048
	ds_read_b128 v[182:185], v182 offset:3072
	ds_read_b128 v[186:189], v167 offset:32768
	ds_read_b128 v[190:193], v167 offset:33792
	ds_read_b128 v[194:197], v167 offset:34816
	ds_read_b128 v[198:201], v167 offset:35840
	ds_read_b128 v[202:205], v167 offset:36864
	ds_read_b128 v[206:209], v167 offset:37888
	ds_read_b128 v[210:213], v167 offset:38912
	ds_read_b128 v[214:217], v167 offset:39936
	s_waitcnt vmcnt(8)
	s_waitcnt lgkmcnt(0)
	s_barrier
	s_setprio 1
	s_waitcnt lgkmcnt(0)
	v_mfma_f32_16x16x32_bf16 v[124:127], v[144:147], v[186:189], v[124:127]
	v_mfma_f32_16x16x32_bf16 v[120:123], v[152:155], v[186:189], v[120:123]
	v_mfma_f32_16x16x32_bf16 v[112:115], v[144:147], v[194:197], v[112:115]
	v_mfma_f32_16x16x32_bf16 v[108:111], v[152:155], v[194:197], v[108:111]
	v_mfma_f32_16x16x32_bf16 v[100:103], v[144:147], v[202:205], v[100:103]
	v_mfma_f32_16x16x32_bf16 v[92:95], v[152:155], v[202:205], v[92:95]
	v_mfma_f32_16x16x32_bf16 v[84:87], v[144:147], v[210:213], v[84:87]
	v_mfma_f32_16x16x32_bf16 v[76:79], v[152:155], v[210:213], v[76:79]
	v_mfma_f32_16x16x32_bf16 v[124:127], v[148:151], v[190:193], v[124:127]
	v_mfma_f32_16x16x32_bf16 v[120:123], v[156:159], v[190:193], v[120:123]
	v_mfma_f32_16x16x32_bf16 v[112:115], v[148:151], v[198:201], v[112:115]
	v_mfma_f32_16x16x32_bf16 v[108:111], v[156:159], v[198:201], v[108:111]
	v_mfma_f32_16x16x32_bf16 v[100:103], v[148:151], v[206:209], v[100:103]
	v_mfma_f32_16x16x32_bf16 v[92:95], v[156:159], v[206:209], v[92:95]
	v_mfma_f32_16x16x32_bf16 v[84:87], v[148:151], v[214:217], v[84:87]
	v_mfma_f32_16x16x32_bf16 v[76:79], v[156:159], v[214:217], v[76:79]
	s_setprio 0
	s_setprio 1
	v_mfma_f32_16x16x32_bf16 v[116:119], v[170:173], v[186:189], v[116:119]
	v_mfma_f32_16x16x32_bf16 v[104:107], v[178:181], v[186:189], v[104:107]
	v_mfma_f32_16x16x32_bf16 v[96:99], v[170:173], v[194:197], v[96:99]
	v_mfma_f32_16x16x32_bf16 v[88:91], v[178:181], v[194:197], v[88:91]
	v_mfma_f32_16x16x32_bf16 v[80:83], v[170:173], v[202:205], v[80:83]
	v_mfma_f32_16x16x32_bf16 v[72:75], v[178:181], v[202:205], v[72:75]
	v_mfma_f32_16x16x32_bf16 v[68:71], v[170:173], v[210:213], v[68:71]
	v_mfma_f32_16x16x32_bf16 v[64:67], v[178:181], v[210:213], v[64:67]
	v_mfma_f32_16x16x32_bf16 v[116:119], v[174:177], v[190:193], v[116:119]
	v_mfma_f32_16x16x32_bf16 v[104:107], v[182:185], v[190:193], v[104:107]
	v_mfma_f32_16x16x32_bf16 v[96:99], v[174:177], v[198:201], v[96:99]
	v_mfma_f32_16x16x32_bf16 v[88:91], v[182:185], v[198:201], v[88:91]
	v_mfma_f32_16x16x32_bf16 v[80:83], v[174:177], v[206:209], v[80:83]
	v_mfma_f32_16x16x32_bf16 v[72:75], v[182:185], v[206:209], v[72:75]
	v_mfma_f32_16x16x32_bf16 v[68:71], v[174:177], v[214:217], v[68:71]
	v_mfma_f32_16x16x32_bf16 v[64:67], v[182:185], v[214:217], v[64:67]
	s_setprio 0
	s_barrier
; #define PG8_STAGE(bufoff, gbase, voff) do { _Pragma("unroll") for (int _i = 0; _i < 2; ++_i) \
;         __builtin_amdgcn_global_load_lds((const unsigned*)((const char*)(gbase) + (voff)[_i]), (LAS unsigned*)(lds + (bufoff) + ldsw + _i * 8192), 16, 0, 0); } while (0)
; #define PG8_LDA(dst, b, h) do { _Pragma("unroll") for (int m = 0; m < 4; ++m) _Pragma("unroll") for (int k = 0; k < 2; ++k) dst[m][k] = *(const LAS bf16x8*)(lds + PG8_SA(b, h) + aoff + m * 2048 + k * 1024); } while (0)
; #define PG8_MMA(ai, bj, At, Bt) do { __builtin_amdgcn_s_setprio(1); _Pragma("unroll") for (int m = 0; m < 4; ++m) _Pragma("unroll") for (int n = 0; n < 2; ++n) _Pragma("unroll") for (int k = 0; k < 2; ++k) \
;         acc[ai][bj][m][n] = __builtin_amdgcn_mfma_f32_16x16x32_bf16(Bt[n][k], At[m][k], acc[ai][bj][m][n], 0, 0, 0); __builtin_amdgcn_s_setprio(0); } while (0)
; #define PG8_WAIT_V(n) asm volatile("s_waitcnt vmcnt(" #n ")" ::: "memory")
; #define PG8_WAIT_L(n) asm volatile("s_waitcnt lgkmcnt(" #n ")" ::: "memory")
; #define PG8_BAR __builtin_amdgcn_s_barrier()
; #define PG8_SCHED __builtin_amdgcn_sched_barrier(0)
; template <class Epi>
; __device__ __forceinline__ void gemm_phase(LAS unsigned char* lds, const Gemm g, const StaticOrder& S, const Epi& E, int wave_s) {
;     ...
;             PG8_LDA(At, 1, 1); PG8_STAGE(PG8_SB(1, 0), b3, voffB); PG8_STAGE(PG8_SB(1, 1), b3 + hstepB, voffB); PG8_STAGE(PG8_SA(1, 0), a3, voffA);
;             PG8_WAIT_V(8); PG8_WAIT_L(0); PG8_BAR; PG8_MMA(1, 0, At, B0); PG8_MMA(1, 1, At, B1); PG8_BAR; PG8_SCHED;
;         }
	s_add_i32 s44, s66, s46
	v_lshl_add_u64 v[160:161], v[160:161], 0, s[20:21]
	s_mov_b32 m0, s44
	s_nop 0
	global_load_lds_dwordx4 v[160:161], off
	s_add_i32 m0, s44, 0x2000
	s_add_u32 s10, s10, 0x40080
	v_lshl_add_u64 v[160:161], v[218:219], 0, s[20:21]
	s_addc_u32 s11, s11, 0
	s_add_i32 s44, s67, s46
	global_load_lds_dwordx4 v[160:161], off
	v_lshl_add_u64 v[160:161], s[10:11], 0, v[130:131]
	s_mov_b32 m0, s44
	s_nop 0
	global_load_lds_dwordx4 v[160:161], off
	v_lshl_add_u64 v[160:161], s[10:11], 0, v[134:135]
	s_add_i32 m0, s44, 0x2000
	s_nop 0
	global_load_lds_dwordx4 v[160:161], off
	v_lshl_add_u64 v[160:161], v[220:221], 0, s[20:21]
	s_mov_b32 m0, s5
	s_nop 0
	global_load_lds_dwordx4 v[160:161], off
	v_lshl_add_u64 v[160:161], v[222:223], 0, s[20:21]
	s_mov_b32 m0, s51
	s_nop 0
	global_load_lds_dwordx4 v[160:161], off
	ds_read_b128 v[186:189], v167 offset:49152
	ds_read_b128 v[190:193], v167 offset:50176
	ds_read_b128 v[194:197], v167 offset:51200
	ds_read_b128 v[198:201], v167 offset:52224
	ds_read_b128 v[202:205], v167 offset:53248
	ds_read_b128 v[206:209], v167 offset:54272
	ds_read_b128 v[210:213], v167 offset:55296
	ds_read_b128 v[214:217], v167 offset:56320
	s_waitcnt vmcnt(8)
	s_waitcnt lgkmcnt(0)
	s_barrier
	s_setprio 1
	s_waitcnt lgkmcnt(0)
	v_mfma_f32_16x16x32_bf16 v[60:63], v[144:147], v[186:189], v[60:63]
	v_mfma_f32_16x16x32_bf16 v[56:59], v[152:155], v[186:189], v[56:59]
	v_mfma_f32_16x16x32_bf16 v[52:55], v[144:147], v[194:197], v[52:55]
	v_mfma_f32_16x16x32_bf16 v[44:47], v[152:155], v[194:197], v[44:47]
	v_mfma_f32_16x16x32_bf16 v[36:39], v[144:147], v[202:205], v[36:39]
	v_mfma_f32_16x16x32_bf16 v[28:31], v[152:155], v[202:205], v[28:31]
	v_mfma_f32_16x16x32_bf16 v[20:23], v[144:147], v[210:213], v[20:23]
	v_mfma_f32_16x16x32_bf16 v[12:15], v[152:155], v[210:213], v[12:15]
	v_mfma_f32_16x16x32_bf16 v[60:63], v[148:151], v[190:193], v[60:63]
	v_mfma_f32_16x16x32_bf16 v[56:59], v[156:159], v[190:193], v[56:59]
	v_mfma_f32_16x16x32_bf16 v[52:55], v[148:151], v[198:201], v[52:55]
	v_mfma_f32_16x16x32_bf16 v[44:47], v[156:159], v[198:201], v[44:47]
	v_mfma_f32_16x16x32_bf16 v[36:39], v[148:151], v[206:209], v[36:39]
	v_mfma_f32_16x16x32_bf16 v[28:31], v[156:159], v[206:209], v[28:31]
	v_mfma_f32_16x16x32_bf16 v[20:23], v[148:151], v[214:217], v[20:23]
	v_mfma_f32_16x16x32_bf16 v[12:15], v[156:159], v[214:217], v[12:15]
	s_setprio 0
	s_setprio 1
	v_mfma_f32_16x16x32_bf16 v[48:51], v[170:173], v[186:189], v[48:51]
	v_mfma_f32_16x16x32_bf16 v[40:43], v[178:181], v[186:189], v[40:43]
	v_mfma_f32_16x16x32_bf16 v[32:35], v[170:173], v[194:197], v[32:35]
	v_mfma_f32_16x16x32_bf16 v[24:27], v[178:181], v[194:197], v[24:27]
	v_mfma_f32_16x16x32_bf16 v[16:19], v[170:173], v[202:205], v[16:19]
	v_mfma_f32_16x16x32_bf16 v[8:11], v[178:181], v[202:205], v[8:11]
	v_mfma_f32_16x16x32_bf16 v[4:7], v[170:173], v[210:213], v[4:7]
	v_mfma_f32_16x16x32_bf16 v[0:3], v[178:181], v[210:213], v[0:3]
	v_mfma_f32_16x16x32_bf16 v[48:51], v[174:177], v[190:193], v[48:51]
	v_mfma_f32_16x16x32_bf16 v[40:43], v[182:185], v[190:193], v[40:43]
	v_mfma_f32_16x16x32_bf16 v[32:35], v[174:177], v[198:201], v[32:35]
	v_mfma_f32_16x16x32_bf16 v[24:27], v[182:185], v[198:201], v[24:27]
	v_mfma_f32_16x16x32_bf16 v[16:19], v[174:177], v[206:209], v[16:19]
	v_mfma_f32_16x16x32_bf16 v[8:11], v[182:185], v[206:209], v[8:11]
	v_mfma_f32_16x16x32_bf16 v[4:7], v[174:177], v[214:217], v[4:7]
	v_mfma_f32_16x16x32_bf16 v[0:3], v[182:185], v[214:217], v[0:3]
	s_setprio 0
	s_barrier
	s_add_i32 s65, s65, 2
	s_add_u32 s8, s8, 0x100
	s_addc_u32 s9, s9, 0
	s_add_u32 s63, s63, 0x100
	s_addc_u32 s64, s64, 0
	s_cmp_gt_u32 s65, 13
	s_cbranch_scc0 .LBB0_500
	s_and_b64 vcc, exec, s[22:23]
	s_cbranch_vccz .LBB0_503
	s_barrier

; #define PG8_STAGE(bufoff, gbase, voff) do { _Pragma("unroll") for (int _i = 0; _i < 2; ++_i) \
;         __builtin_amdgcn_global_load_lds((const unsigned*)((const char*)(gbase) + (voff)[_i]), (LAS unsigned*)(lds + (bufoff) + ldsw + _i * 8192), 16, 0, 0); } while (0)
; #define PG8_LDA(dst, b, h) do { _Pragma("unroll") for (int m = 0; m < 4; ++m) _Pragma("unroll") for (int k = 0; k < 2; ++k) dst[m][k] = *(const LAS bf16x8*)(lds + PG8_SA(b, h) + aoff + m * 2048 + k * 1024); } while (0)
; #define PG8_LDB(dst, b, h) do { _Pragma("unroll") for (int n = 0; n < 2; ++n) _Pragma("unroll") for (int k = 0; k < 2; ++k) dst[n][k] = *(const LAS bf16x8*)(lds + PG8_SB(b, h) + boff + n * 2048 + k * 1024); } while (0)
; #define PG8_MMA(ai, bj, At, Bt) do { __builtin_amdgcn_s_setprio(1); _Pragma("unroll") for (int m = 0; m < 4; ++m) _Pragma("unroll") for (int n = 0; n < 2; ++n) _Pragma("unroll") for (int k = 0; k < 2; ++k) \
;         acc[ai][bj][m][n] = __builtin_amdgcn_mfma_f32_16x16x32_bf16(Bt[n][k], At[m][k], acc[ai][bj][m][n], 0, 0, 0); __builtin_amdgcn_s_setprio(0); } while (0)
; #define PG8_WAIT_V(n) asm volatile("s_waitcnt vmcnt(" #n ")" ::: "memory")
; #define PG8_WAIT_L(n) asm volatile("s_waitcnt lgkmcnt(" #n ")" ::: "memory")
; #define PG8_BAR __builtin_amdgcn_s_barrier()
; #define PG8_SCHED __builtin_amdgcn_sched_barrier(0)
; template <class Epi>
; __device__ __forceinline__ void gemm_phase(LAS unsigned char* lds, const Gemm g, const StaticOrder& S, const Epi& E, int wave_s) {
;     ...
;             PG8_LDB(B0, 0, 0); PG8_LDB(B1, 0, 1); PG8_SCHED; PG8_LDA(At, 0, 0); PG8_STAGE(PG8_SA(1, 1), a1 + hstepA, voffA);
;             PG8_WAIT_V(8); PG8_WAIT_L(0); PG8_BAR; PG8_MMA(0, 0, At, B0); PG8_MMA(0, 1, At, B1); PG8_BAR; PG8_SCHED;
;             PG8_LDA(At, 0, 1); PG8_STAGE(PG8_SB(0, 0), b2, voffB); PG8_STAGE(PG8_SB(0, 1), b2 + hstepB, voffB); PG8_STAGE(PG8_SA(0, 0), a2, voffA);
;             PG8_WAIT_V(8); PG8_WAIT_L(0); PG8_BAR; PG8_MMA(1, 0, At, B0); PG8_MMA(1, 1, At, B1); PG8_BAR; PG8_SCHED;
.LBB0_714:
	s_add_u32 s38, s36, 0xfffc0080
	s_addc_u32 s39, s37, -1
	s_cmp_eq_u32 s56, 12
	s_cselect_b32 s41, s27, s39
	s_cselect_b32 s40, s35, s38
	s_cselect_b32 s39, s25, s55
	s_cselect_b32 s38, s53, s54
	v_lshl_add_u64 v[204:205], s[36:37], 0, v[200:201]
	s_add_i32 m0, s5, 0xc000
	s_nop 0
	global_load_lds_dwordx4 v[204:205], off
	v_lshl_add_u64 v[204:205], s[36:37], 0, v[202:203]
	s_add_i32 m0, s5, 0xe000
	s_nop 0
	global_load_lds_dwordx4 v[204:205], off
	ds_read_b128 v[120:123], v243
	ds_read_b128 v[124:127], v243 offset:1024
	ds_read_b128 v[128:131], v243 offset:2048
	ds_read_b128 v[132:135], v243 offset:3072
	ds_read_b128 v[136:139], v244
	ds_read_b128 v[140:143], v244 offset:1024
	ds_read_b128 v[152:155], v244 offset:2048
	ds_read_b128 v[156:159], v244 offset:3072
	ds_read_b128 v[160:163], v245
	ds_read_b128 v[164:167], v245 offset:1024
	ds_read_b128 v[168:171], v245 offset:2048
	ds_read_b128 v[172:175], v245 offset:3072
	ds_read_b128 v[176:179], v245 offset:4096
	ds_read_b128 v[180:183], v245 offset:5120
	ds_read_b128 v[184:187], v245 offset:6144
	ds_read_b128 v[188:191], v245 offset:7168
	s_waitcnt vmcnt(8)
	s_waitcnt lgkmcnt(0)
	s_barrier
	s_setprio 1
	s_waitcnt lgkmcnt(0)
	v_mfma_f32_16x16x32_bf16 v[148:151], v[120:123], v[160:163], v[148:151]
	v_mfma_f32_16x16x32_bf16 v[144:147], v[128:131], v[160:163], v[144:147]
	v_mfma_f32_16x16x32_bf16 v[108:111], v[120:123], v[168:171], v[108:111]
	v_mfma_f32_16x16x32_bf16 v[104:107], v[128:131], v[168:171], v[104:107]
	v_mfma_f32_16x16x32_bf16 v[92:95], v[120:123], v[176:179], v[92:95]
	v_mfma_f32_16x16x32_bf16 v[88:91], v[128:131], v[176:179], v[88:91]
	v_mfma_f32_16x16x32_bf16 v[76:79], v[120:123], v[184:187], v[76:79]
	v_mfma_f32_16x16x32_bf16 v[72:75], v[128:131], v[184:187], v[72:75]
	v_mfma_f32_16x16x32_bf16 v[148:151], v[124:127], v[164:167], v[148:151]
	v_mfma_f32_16x16x32_bf16 v[144:147], v[132:135], v[164:167], v[144:147]
	v_mfma_f32_16x16x32_bf16 v[108:111], v[124:127], v[172:175], v[108:111]
	v_mfma_f32_16x16x32_bf16 v[104:107], v[132:135], v[172:175], v[104:107]
	v_mfma_f32_16x16x32_bf16 v[92:95], v[124:127], v[180:183], v[92:95]
	v_mfma_f32_16x16x32_bf16 v[88:91], v[132:135], v[180:183], v[88:91]
	v_mfma_f32_16x16x32_bf16 v[76:79], v[124:127], v[188:191], v[76:79]
	v_mfma_f32_16x16x32_bf16 v[72:75], v[132:135], v[188:191], v[72:75]
	s_setprio 0
	s_setprio 1
	v_mfma_f32_16x16x32_bf16 v[116:119], v[136:139], v[160:163], v[116:119]
	v_mfma_f32_16x16x32_bf16 v[112:115], v[152:155], v[160:163], v[112:115]
	v_mfma_f32_16x16x32_bf16 v[100:103], v[136:139], v[168:171], v[100:103]
	v_mfma_f32_16x16x32_bf16 v[96:99], v[152:155], v[168:171], v[96:99]
	v_mfma_f32_16x16x32_bf16 v[84:87], v[136:139], v[176:179], v[84:87]
	v_mfma_f32_16x16x32_bf16 v[80:83], v[152:155], v[176:179], v[80:83]
	v_mfma_f32_16x16x32_bf16 v[68:71], v[136:139], v[184:187], v[68:71]
	v_mfma_f32_16x16x32_bf16 v[64:67], v[152:155], v[184:187], v[64:67]
	v_mfma_f32_16x16x32_bf16 v[116:119], v[140:143], v[164:167], v[116:119]
	v_mfma_f32_16x16x32_bf16 v[112:115], v[156:159], v[164:167], v[112:115]
	v_mfma_f32_16x16x32_bf16 v[100:103], v[140:143], v[172:175], v[100:103]
	v_mfma_f32_16x16x32_bf16 v[96:99], v[156:159], v[172:175], v[96:99]
	v_mfma_f32_16x16x32_bf16 v[84:87], v[140:143], v[180:183], v[84:87]
	v_mfma_f32_16x16x32_bf16 v[80:83], v[156:159], v[180:183], v[80:83]
	v_mfma_f32_16x16x32_bf16 v[68:71], v[140:143], v[188:191], v[68:71]
	v_mfma_f32_16x16x32_bf16 v[64:67], v[156:159], v[188:191], v[64:67]
	s_setprio 0
	s_barrier
	s_add_i32 s57, s50, s4
	v_lshl_add_u64 v[204:205], s[38:39], 0, v[194:195]
	s_mov_b32 m0, s57
	s_nop 0
	global_load_lds_dwordx4 v[204:205], off
	s_add_i32 m0, s57, 0x2000
	s_add_u32 s58, s38, 0x40000
	v_lshl_add_u64 v[206:207], s[38:39], 0, v[198:199]
	s_addc_u32 s59, s39, 0
	s_add_i32 s57, s51, s4
	global_load_lds_dwordx4 v[206:207], off
	v_lshl_add_u64 v[208:209], s[58:59], 0, v[194:195]
	s_mov_b32 m0, s57
	v_lshl_add_u64 v[210:211], s[40:41], 0, v[196:197]
	global_load_lds_dwordx4 v[208:209], off
	v_lshl_add_u64 v[208:209], s[58:59], 0, v[198:199]
	s_add_i32 m0, s57, 0x2000
	s_nop 0
	global_load_lds_dwordx4 v[208:209], off
	v_lshl_add_u64 v[208:209], s[40:41], 0, v[192:193]
	s_mov_b32 m0, s5
	s_nop 0
	global_load_lds_dwordx4 v[208:209], off
	s_mov_b32 m0, s33
	s_nop 0
	global_load_lds_dwordx4 v[210:211], off
	ds_read_b128 v[160:163], v245 offset:16384
	ds_read_b128 v[164:167], v245 offset:17408
	ds_read_b128 v[168:171], v245 offset:18432
	ds_read_b128 v[172:175], v245 offset:19456
	ds_read_b128 v[176:179], v245 offset:20480
	ds_read_b128 v[180:183], v245 offset:21504
	ds_read_b128 v[184:187], v245 offset:22528
	ds_read_b128 v[188:191], v245 offset:23552
	s_waitcnt vmcnt(8)
	s_waitcnt lgkmcnt(0)
	s_barrier
; #define PG8_STAGE(bufoff, gbase, voff) do { _Pragma("unroll") for (int _i = 0; _i < 2; ++_i) \
;         __builtin_amdgcn_global_load_lds((const unsigned*)((const char*)(gbase) + (voff)[_i]), (LAS unsigned*)(lds + (bufoff) + ldsw + _i * 8192), 16, 0, 0); } while (0)
; #define PG8_LDA(dst, b, h) do { _Pragma("unroll") for (int m = 0; m < 4; ++m) _Pragma("unroll") for (int k = 0; k < 2; ++k) dst[m][k] = *(const LAS bf16x8*)(lds + PG8_SA(b, h) + aoff + m * 2048 + k * 1024); } while (0)
; #define PG8_LDB(dst, b, h) do { _Pragma("unroll") for (int n = 0; n < 2; ++n) _Pragma("unroll") for (int k = 0; k < 2; ++k) dst[n][k] = *(const LAS bf16x8*)(lds + PG8_SB(b, h) + boff + n * 2048 + k * 1024); } while (0)
; #define PG8_MMA(ai, bj, At, Bt) do { __builtin_amdgcn_s_setprio(1); _Pragma("unroll") for (int m = 0; m < 4; ++m) _Pragma("unroll") for (int n = 0; n < 2; ++n) _Pragma("unroll") for (int k = 0; k < 2; ++k) \
;         acc[ai][bj][m][n] = __builtin_amdgcn_mfma_f32_16x16x32_bf16(Bt[n][k], At[m][k], acc[ai][bj][m][n], 0, 0, 0); __builtin_amdgcn_s_setprio(0); } while (0)
; #define PG8_WAIT_V(n) asm volatile("s_waitcnt vmcnt(" #n ")" ::: "memory")
; #define PG8_WAIT_L(n) asm volatile("s_waitcnt lgkmcnt(" #n ")" ::: "memory")
; #define PG8_BAR __builtin_amdgcn_s_barrier()
; #define PG8_SCHED __builtin_amdgcn_sched_barrier(0)
; template <class Epi>
; __device__ __forceinline__ void gemm_phase(LAS unsigned char* lds, const Gemm g, const StaticOrder& S, const Epi& E, int wave_s) {
;     ...
;             PG8_WAIT_V(8); PG8_WAIT_L(0); PG8_BAR; PG8_MMA(1, 0, At, B0); PG8_MMA(1, 1, At, B1); PG8_BAR; PG8_SCHED;
;             PG8_LDB(B0, 1, 0); PG8_LDB(B1, 1, 1); PG8_SCHED; PG8_LDA(At, 1, 0); PG8_STAGE(PG8_SA(0, 1), a2 + hstepA, voffA);
;             PG8_WAIT_V(8); PG8_WAIT_L(0); PG8_BAR; PG8_MMA(0, 0, At, B0); PG8_MMA(0, 1, At, B1); PG8_BAR; PG8_SCHED;
	s_setprio 1
	s_waitcnt lgkmcnt(0)
	v_mfma_f32_16x16x32_bf16 v[60:63], v[120:123], v[160:163], v[60:63]
	v_mfma_f32_16x16x32_bf16 v[56:59], v[128:131], v[160:163], v[56:59]
	v_mfma_f32_16x16x32_bf16 v[44:47], v[120:123], v[168:171], v[44:47]
	v_mfma_f32_16x16x32_bf16 v[40:43], v[128:131], v[168:171], v[40:43]
	v_mfma_f32_16x16x32_bf16 v[28:31], v[120:123], v[176:179], v[28:31]
	v_mfma_f32_16x16x32_bf16 v[24:27], v[128:131], v[176:179], v[24:27]
	v_mfma_f32_16x16x32_bf16 v[12:15], v[120:123], v[184:187], v[12:15]
	v_mfma_f32_16x16x32_bf16 v[8:11], v[128:131], v[184:187], v[8:11]
	v_mfma_f32_16x16x32_bf16 v[60:63], v[124:127], v[164:167], v[60:63]
	v_mfma_f32_16x16x32_bf16 v[56:59], v[132:135], v[164:167], v[56:59]
	v_mfma_f32_16x16x32_bf16 v[44:47], v[124:127], v[172:175], v[44:47]
	v_mfma_f32_16x16x32_bf16 v[40:43], v[132:135], v[172:175], v[40:43]
	v_mfma_f32_16x16x32_bf16 v[28:31], v[124:127], v[180:183], v[28:31]
	v_mfma_f32_16x16x32_bf16 v[24:27], v[132:135], v[180:183], v[24:27]
	v_mfma_f32_16x16x32_bf16 v[12:15], v[124:127], v[188:191], v[12:15]
	v_mfma_f32_16x16x32_bf16 v[8:11], v[132:135], v[188:191], v[8:11]
	s_setprio 0
	s_setprio 1
	v_mfma_f32_16x16x32_bf16 v[52:55], v[136:139], v[160:163], v[52:55]
	v_mfma_f32_16x16x32_bf16 v[48:51], v[152:155], v[160:163], v[48:51]
	v_mfma_f32_16x16x32_bf16 v[36:39], v[136:139], v[168:171], v[36:39]
	v_mfma_f32_16x16x32_bf16 v[32:35], v[152:155], v[168:171], v[32:35]
	v_mfma_f32_16x16x32_bf16 v[20:23], v[136:139], v[176:179], v[20:23]
	v_mfma_f32_16x16x32_bf16 v[16:19], v[152:155], v[176:179], v[16:19]
	v_mfma_f32_16x16x32_bf16 v[4:7], v[136:139], v[184:187], v[4:7]
	v_mfma_f32_16x16x32_bf16 v[0:3], v[152:155], v[184:187], v[0:3]
	v_mfma_f32_16x16x32_bf16 v[52:55], v[140:143], v[164:167], v[52:55]
	v_mfma_f32_16x16x32_bf16 v[48:51], v[156:159], v[164:167], v[48:51]
	v_mfma_f32_16x16x32_bf16 v[36:39], v[140:143], v[172:175], v[36:39]
	v_mfma_f32_16x16x32_bf16 v[32:35], v[156:159], v[172:175], v[32:35]
	v_mfma_f32_16x16x32_bf16 v[20:23], v[140:143], v[180:183], v[20:23]
	v_mfma_f32_16x16x32_bf16 v[16:19], v[156:159], v[180:183], v[16:19]
	v_mfma_f32_16x16x32_bf16 v[4:7], v[140:143], v[188:191], v[4:7]
	v_mfma_f32_16x16x32_bf16 v[0:3], v[156:159], v[188:191], v[0:3]
	s_setprio 0
	s_barrier
	s_add_i32 s57, 0, 0x18000
	s_add_i32 s58, 0, 0x1c000
	s_add_u32 s40, s40, 0x40000
	s_addc_u32 s41, s41, 0
	s_mov_b32 m0, s42
	v_lshl_add_u64 v[212:213], s[40:41], 0, v[192:193]
	global_load_lds_dwordx4 v[212:213], off
	v_lshl_add_u64 v[212:213], s[40:41], 0, v[196:197]
	s_mov_b32 m0, s43
	s_nop 0
	global_load_lds_dwordx4 v[212:213], off
	v_add_u32_e32 v132, s57, v241
	v_add_u32_e32 v156, s58, v241
	ds_read_b128 v[120:123], v132
	ds_read_b128 v[124:127], v132 offset:1024
	ds_read_b128 v[128:131], v132 offset:2048
	ds_read_b128 v[132:135], v132 offset:3072
	ds_read_b128 v[136:139], v156
	ds_read_b128 v[140:143], v156 offset:1024
	ds_read_b128 v[152:155], v156 offset:2048
	ds_read_b128 v[156:159], v156 offset:3072
	ds_read_b128 v[160:163], v245 offset:32768
	ds_read_b128 v[164:167], v245 offset:33792
	ds_read_b128 v[168:171], v245 offset:34816
	ds_read_b128 v[172:175], v245 offset:35840
	ds_read_b128 v[176:179], v245 offset:36864
	ds_read_b128 v[180:183], v245 offset:37888
	ds_read_b128 v[184:187], v245 offset:38912
	ds_read_b128 v[188:191], v245 offset:39936
	s_waitcnt vmcnt(8)
	s_waitcnt lgkmcnt(0)
	s_barrier
	s_setprio 1
	s_waitcnt lgkmcnt(0)
	v_mfma_f32_16x16x32_bf16 v[148:151], v[120:123], v[160:163], v[148:151]
	v_mfma_f32_16x16x32_bf16 v[144:147], v[128:131], v[160:163], v[144:147]
	v_mfma_f32_16x16x32_bf16 v[108:111], v[120:123], v[168:171], v[108:111]
	v_mfma_f32_16x16x32_bf16 v[104:107], v[128:131], v[168:171], v[104:107]
	v_mfma_f32_16x16x32_bf16 v[92:95], v[120:123], v[176:179], v[92:95]
	v_mfma_f32_16x16x32_bf16 v[88:91], v[128:131], v[176:179], v[88:91]
	v_mfma_f32_16x16x32_bf16 v[76:79], v[120:123], v[184:187], v[76:79]
	v_mfma_f32_16x16x32_bf16 v[72:75], v[128:131], v[184:187], v[72:75]
	v_mfma_f32_16x16x32_bf16 v[148:151], v[124:127], v[164:167], v[148:151]
	v_mfma_f32_16x16x32_bf16 v[144:147], v[132:135], v[164:167], v[144:147]
	v_mfma_f32_16x16x32_bf16 v[108:111], v[124:127], v[172:175], v[108:111]
	v_mfma_f32_16x16x32_bf16 v[104:107], v[132:135], v[172:175], v[104:107]
	v_mfma_f32_16x16x32_bf16 v[92:95], v[124:127], v[180:183], v[92:95]
	v_mfma_f32_16x16x32_bf16 v[88:91], v[132:135], v[180:183], v[88:91]
	v_mfma_f32_16x16x32_bf16 v[76:79], v[124:127], v[188:191], v[76:79]
	v_mfma_f32_16x16x32_bf16 v[72:75], v[132:135], v[188:191], v[72:75]
	s_setprio 0
	s_setprio 1
	v_mfma_f32_16x16x32_bf16 v[116:119], v[136:139], v[160:163], v[116:119]
	v_mfma_f32_16x16x32_bf16 v[112:115], v[152:155], v[160:163], v[112:115]
	v_mfma_f32_16x16x32_bf16 v[100:103], v[136:139], v[168:171], v[100:103]
	v_mfma_f32_16x16x32_bf16 v[96:99], v[152:155], v[168:171], v[96:99]
	v_mfma_f32_16x16x32_bf16 v[84:87], v[136:139], v[176:179], v[84:87]
	v_mfma_f32_16x16x32_bf16 v[80:83], v[152:155], v[176:179], v[80:83]
	v_mfma_f32_16x16x32_bf16 v[68:71], v[136:139], v[184:187], v[68:71]
	v_mfma_f32_16x16x32_bf16 v[64:67], v[152:155], v[184:187], v[64:67]
	v_mfma_f32_16x16x32_bf16 v[116:119], v[140:143], v[164:167], v[116:119]
	v_mfma_f32_16x16x32_bf16 v[112:115], v[156:159], v[164:167], v[112:115]
	v_mfma_f32_16x16x32_bf16 v[100:103], v[140:143], v[172:175], v[100:103]
	v_mfma_f32_16x16x32_bf16 v[96:99], v[156:159], v[172:175], v[96:99]
	v_mfma_f32_16x16x32_bf16 v[84:87], v[140:143], v[180:183], v[84:87]
	v_mfma_f32_16x16x32_bf16 v[80:83], v[156:159], v[180:183], v[80:83]
	v_mfma_f32_16x16x32_bf16 v[68:71], v[140:143], v[188:191], v[68:71]
	v_mfma_f32_16x16x32_bf16 v[64:67], v[156:159], v[188:191], v[64:67]
	s_setprio 0
	s_barrier
; #define PG8_STAGE(bufoff, gbase, voff) do { _Pragma("unroll") for (int _i = 0; _i < 2; ++_i) \
;         __builtin_amdgcn_global_load_lds((const unsigned*)((const char*)(gbase) + (voff)[_i]), (LAS unsigned*)(lds + (bufoff) + ldsw + _i * 8192), 16, 0, 0); } while (0)
; #define PG8_LDA(dst, b, h) do { _Pragma("unroll") for (int m = 0; m < 4; ++m) _Pragma("unroll") for (int k = 0; k < 2; ++k) dst[m][k] = *(const LAS bf16x8*)(lds + PG8_SA(b, h) + aoff + m * 2048 + k * 1024); } while (0)
; #define PG8_MMA(ai, bj, At, Bt) do { __builtin_amdgcn_s_setprio(1); _Pragma("unroll") for (int m = 0; m < 4; ++m) _Pragma("unroll") for (int n = 0; n < 2; ++n) _Pragma("unroll") for (int k = 0; k < 2; ++k) \
;         acc[ai][bj][m][n] = __builtin_amdgcn_mfma_f32_16x16x32_bf16(Bt[n][k], At[m][k], acc[ai][bj][m][n], 0, 0, 0); __builtin_amdgcn_s_setprio(0); } while (0)
; #define PG8_WAIT_V(n) asm volatile("s_waitcnt vmcnt(" #n ")" ::: "memory")
; #define PG8_WAIT_L(n) asm volatile("s_waitcnt lgkmcnt(" #n ")" ::: "memory")
; #define PG8_BAR __builtin_amdgcn_s_barrier()
; #define PG8_SCHED __builtin_amdgcn_sched_barrier(0)
; template <class Epi>
; __device__ __forceinline__ void gemm_phase(LAS unsigned char* lds, const Gemm g, const StaticOrder& S, const Epi& E, int wave_s) {
;     ...
;             PG8_LDA(At, 1, 1); PG8_STAGE(PG8_SB(1, 0), b3, voffB); PG8_STAGE(PG8_SB(1, 1), b3 + hstepB, voffB); PG8_STAGE(PG8_SA(1, 0), a3, voffA);
;             PG8_WAIT_V(8); PG8_WAIT_L(0); PG8_BAR; PG8_MMA(1, 0, At, B0); PG8_MMA(1, 1, At, B1); PG8_BAR; PG8_SCHED;
;         }
	s_add_i32 s40, s57, s4
	v_lshl_add_u64 v[204:205], v[204:205], 0, s[20:21]
	s_mov_b32 m0, s40
	s_nop 0
	global_load_lds_dwordx4 v[204:205], off
	s_add_i32 m0, s40, 0x2000
	s_add_u32 s38, s38, 0x40080
	v_lshl_add_u64 v[204:205], v[206:207], 0, s[20:21]
	s_addc_u32 s39, s39, 0
	s_add_i32 s40, s58, s4
	global_load_lds_dwordx4 v[204:205], off
	v_lshl_add_u64 v[204:205], s[38:39], 0, v[194:195]
	s_mov_b32 m0, s40
	s_nop 0
	global_load_lds_dwordx4 v[204:205], off
	v_lshl_add_u64 v[204:205], s[38:39], 0, v[198:199]
	s_add_i32 m0, s40, 0x2000
	s_nop 0
	global_load_lds_dwordx4 v[204:205], off
	v_lshl_add_u64 v[204:205], v[208:209], 0, s[20:21]
	s_mov_b32 m0, s45
	s_nop 0
	global_load_lds_dwordx4 v[204:205], off
	v_lshl_add_u64 v[204:205], v[210:211], 0, s[20:21]
	s_mov_b32 m0, s46
	s_nop 0
	global_load_lds_dwordx4 v[204:205], off
	ds_read_b128 v[160:163], v245 offset:49152
	ds_read_b128 v[164:167], v245 offset:50176
	ds_read_b128 v[168:171], v245 offset:51200
	ds_read_b128 v[172:175], v245 offset:52224
	ds_read_b128 v[176:179], v245 offset:53248
	ds_read_b128 v[180:183], v245 offset:54272
	ds_read_b128 v[184:187], v245 offset:55296
	ds_read_b128 v[188:191], v245 offset:56320
	s_waitcnt vmcnt(8)
	s_waitcnt lgkmcnt(0)
	s_barrier
	s_setprio 1
	s_waitcnt lgkmcnt(0)
	v_mfma_f32_16x16x32_bf16 v[60:63], v[120:123], v[160:163], v[60:63]
	v_mfma_f32_16x16x32_bf16 v[56:59], v[128:131], v[160:163], v[56:59]
	v_mfma_f32_16x16x32_bf16 v[44:47], v[120:123], v[168:171], v[44:47]
	v_mfma_f32_16x16x32_bf16 v[40:43], v[128:131], v[168:171], v[40:43]
	v_mfma_f32_16x16x32_bf16 v[28:31], v[120:123], v[176:179], v[28:31]
	v_mfma_f32_16x16x32_bf16 v[24:27], v[128:131], v[176:179], v[24:27]
	v_mfma_f32_16x16x32_bf16 v[12:15], v[120:123], v[184:187], v[12:15]
	v_mfma_f32_16x16x32_bf16 v[8:11], v[128:131], v[184:187], v[8:11]
	v_mfma_f32_16x16x32_bf16 v[60:63], v[124:127], v[164:167], v[60:63]
	v_mfma_f32_16x16x32_bf16 v[56:59], v[132:135], v[164:167], v[56:59]
	v_mfma_f32_16x16x32_bf16 v[44:47], v[124:127], v[172:175], v[44:47]
	v_mfma_f32_16x16x32_bf16 v[40:43], v[132:135], v[172:175], v[40:43]
	v_mfma_f32_16x16x32_bf16 v[28:31], v[124:127], v[180:183], v[28:31]
	v_mfma_f32_16x16x32_bf16 v[24:27], v[132:135], v[180:183], v[24:27]
	v_mfma_f32_16x16x32_bf16 v[12:15], v[124:127], v[188:191], v[12:15]
	v_mfma_f32_16x16x32_bf16 v[8:11], v[132:135], v[188:191], v[8:11]
	s_setprio 0
	s_setprio 1
	v_mfma_f32_16x16x32_bf16 v[52:55], v[136:139], v[160:163], v[52:55]
	v_mfma_f32_16x16x32_bf16 v[48:51], v[152:155], v[160:163], v[48:51]
	v_mfma_f32_16x16x32_bf16 v[36:39], v[136:139], v[168:171], v[36:39]
	v_mfma_f32_16x16x32_bf16 v[32:35], v[152:155], v[168:171], v[32:35]
	v_mfma_f32_16x16x32_bf16 v[20:23], v[136:139], v[176:179], v[20:23]
	v_mfma_f32_16x16x32_bf16 v[16:19], v[152:155], v[176:179], v[16:19]
	v_mfma_f32_16x16x32_bf16 v[4:7], v[136:139], v[184:187], v[4:7]
	v_mfma_f32_16x16x32_bf16 v[0:3], v[152:155], v[184:187], v[0:3]
	v_mfma_f32_16x16x32_bf16 v[52:55], v[140:143], v[164:167], v[52:55]
	v_mfma_f32_16x16x32_bf16 v[48:51], v[156:159], v[164:167], v[48:51]
	v_mfma_f32_16x16x32_bf16 v[36:39], v[140:143], v[172:175], v[36:39]
	v_mfma_f32_16x16x32_bf16 v[32:35], v[156:159], v[172:175], v[32:35]
	v_mfma_f32_16x16x32_bf16 v[20:23], v[140:143], v[180:183], v[20:23]
	v_mfma_f32_16x16x32_bf16 v[16:19], v[156:159], v[180:183], v[16:19]
	v_mfma_f32_16x16x32_bf16 v[4:7], v[140:143], v[188:191], v[4:7]
	v_mfma_f32_16x16x32_bf16 v[0:3], v[156:159], v[188:191], v[0:3]
	s_setprio 0
	s_barrier
	s_add_i32 s56, s56, 2
	s_add_u32 s36, s36, 0x100
	s_addc_u32 s37, s37, 0
	s_add_u32 s54, s54, 0x100
	s_addc_u32 s55, s55, 0
	s_cmp_gt_u32 s56, 13
	s_cbranch_scc0 .LBB0_714
	s_and_b64 vcc, exec, s[22:23]
	s_cbranch_vccz .LBB0_717
	s_barrier

; #define PG8_STAGE(bufoff, gbase, voff) do { _Pragma("unroll") for (int _i = 0; _i < 2; ++_i) \
;         __builtin_amdgcn_global_load_lds((const unsigned*)((const char*)(gbase) + (voff)[_i]), (LAS unsigned*)(lds + (bufoff) + ldsw + _i * 8192), 16, 0, 0); } while (0)
; #define PG8_LDA(dst, b, h) do { _Pragma("unroll") for (int m = 0; m < 4; ++m) _Pragma("unroll") for (int k = 0; k < 2; ++k) dst[m][k] = *(const LAS bf16x8*)(lds + PG8_SA(b, h) + aoff + m * 2048 + k * 1024); } while (0)
; #define PG8_LDB(dst, b, h) do { _Pragma("unroll") for (int n = 0; n < 2; ++n) _Pragma("unroll") for (int k = 0; k < 2; ++k) dst[n][k] = *(const LAS bf16x8*)(lds + PG8_SB(b, h) + boff + n * 2048 + k * 1024); } while (0)
; #define PG8_MMA(ai, bj, At, Bt) do { __builtin_amdgcn_s_setprio(1); _Pragma("unroll") for (int m = 0; m < 4; ++m) _Pragma("unroll") for (int n = 0; n < 2; ++n) _Pragma("unroll") for (int k = 0; k < 2; ++k) \
;         acc[ai][bj][m][n] = __builtin_amdgcn_mfma_f32_16x16x32_bf16(Bt[n][k], At[m][k], acc[ai][bj][m][n], 0, 0, 0); __builtin_amdgcn_s_setprio(0); } while (0)
; #define PG8_WAIT_V(n) asm volatile("s_waitcnt vmcnt(" #n ")" ::: "memory")
; #define PG8_WAIT_L(n) asm volatile("s_waitcnt lgkmcnt(" #n ")" ::: "memory")
; #define PG8_BAR __builtin_amdgcn_s_barrier()
; #define PG8_SCHED __builtin_amdgcn_sched_barrier(0)
; template <class Epi>
; __device__ __forceinline__ void gemm_phase(LAS unsigned char* lds, const Gemm g, const StaticOrder& S, const Epi& E, int wave_s) {
;     ...
;             PG8_LDB(B0, 0, 0); PG8_LDB(B1, 0, 1); PG8_SCHED; PG8_LDA(At, 0, 0); PG8_STAGE(PG8_SA(1, 1), a1 + hstepA, voffA);
;             PG8_WAIT_V(8); PG8_WAIT_L(0); PG8_BAR; PG8_MMA(0, 0, At, B0); PG8_MMA(0, 1, At, B1); PG8_BAR; PG8_SCHED;
;             PG8_LDA(At, 0, 1); PG8_STAGE(PG8_SB(0, 0), b2, voffB); PG8_STAGE(PG8_SB(0, 1), b2 + hstepB, voffB); PG8_STAGE(PG8_SA(0, 0), a2, voffA);
;             PG8_WAIT_V(8); PG8_WAIT_L(0); PG8_BAR; PG8_MMA(1, 0, At, B0); PG8_MMA(1, 1, At, B1); PG8_BAR; PG8_SCHED;
.LBB0_811:
	s_add_u32 s34, s30, 0xfffc0080
	s_addc_u32 s35, s31, -1
	s_cmp_eq_u32 s53, 12
	s_cselect_b32 s37, s25, s35
	s_cselect_b32 s36, s49, s34
	s_cselect_b32 s35, s23, s52
	s_cselect_b32 s34, s50, s51
	v_lshl_add_u64 v[216:217], s[30:31], 0, v[136:137]
	s_add_i32 m0, s33, 0xc000
	s_nop 0
	global_load_lds_dwordx4 v[216:217], off
	v_lshl_add_u64 v[216:217], s[30:31], 0, v[138:139]
	s_add_i32 m0, s33, 0xe000
	s_nop 0
	global_load_lds_dwordx4 v[216:217], off
	ds_read_b128 v[144:147], v151
	ds_read_b128 v[156:159], v151 offset:1024
	ds_read_b128 v[160:163], v151 offset:2048
	ds_read_b128 v[164:167], v151 offset:3072
	ds_read_b128 v[168:171], v152
	ds_read_b128 v[172:175], v152 offset:1024
	ds_read_b128 v[176:179], v152 offset:2048
	ds_read_b128 v[180:183], v152 offset:3072
	ds_read_b128 v[184:187], v153
	ds_read_b128 v[188:191], v153 offset:1024
	ds_read_b128 v[192:195], v153 offset:2048
	ds_read_b128 v[196:199], v153 offset:3072
	ds_read_b128 v[200:203], v153 offset:4096
	ds_read_b128 v[204:207], v153 offset:5120
	ds_read_b128 v[208:211], v153 offset:6144
	ds_read_b128 v[212:215], v153 offset:7168
	s_waitcnt vmcnt(8)
	s_waitcnt lgkmcnt(0)
	s_barrier
	s_setprio 1
	s_waitcnt lgkmcnt(0)
	v_mfma_f32_16x16x32_bf16 v[124:127], v[144:147], v[184:187], v[124:127]
	v_mfma_f32_16x16x32_bf16 v[120:123], v[160:163], v[184:187], v[120:123]
	v_mfma_f32_16x16x32_bf16 v[108:111], v[144:147], v[192:195], v[108:111]
	v_mfma_f32_16x16x32_bf16 v[104:107], v[160:163], v[192:195], v[104:107]
	v_mfma_f32_16x16x32_bf16 v[92:95], v[144:147], v[200:203], v[92:95]
	v_mfma_f32_16x16x32_bf16 v[88:91], v[160:163], v[200:203], v[88:91]
	v_mfma_f32_16x16x32_bf16 v[76:79], v[144:147], v[208:211], v[76:79]
	v_mfma_f32_16x16x32_bf16 v[72:75], v[160:163], v[208:211], v[72:75]
	v_mfma_f32_16x16x32_bf16 v[124:127], v[156:159], v[188:191], v[124:127]
	v_mfma_f32_16x16x32_bf16 v[120:123], v[164:167], v[188:191], v[120:123]
	v_mfma_f32_16x16x32_bf16 v[108:111], v[156:159], v[196:199], v[108:111]
	v_mfma_f32_16x16x32_bf16 v[104:107], v[164:167], v[196:199], v[104:107]
	v_mfma_f32_16x16x32_bf16 v[92:95], v[156:159], v[204:207], v[92:95]
	v_mfma_f32_16x16x32_bf16 v[88:91], v[164:167], v[204:207], v[88:91]
	v_mfma_f32_16x16x32_bf16 v[76:79], v[156:159], v[212:215], v[76:79]
	v_mfma_f32_16x16x32_bf16 v[72:75], v[164:167], v[212:215], v[72:75]
	s_setprio 0
	s_setprio 1
	v_mfma_f32_16x16x32_bf16 v[116:119], v[168:171], v[184:187], v[116:119]
	v_mfma_f32_16x16x32_bf16 v[112:115], v[176:179], v[184:187], v[112:115]
	v_mfma_f32_16x16x32_bf16 v[100:103], v[168:171], v[192:195], v[100:103]
	v_mfma_f32_16x16x32_bf16 v[96:99], v[176:179], v[192:195], v[96:99]
	v_mfma_f32_16x16x32_bf16 v[84:87], v[168:171], v[200:203], v[84:87]
	v_mfma_f32_16x16x32_bf16 v[80:83], v[176:179], v[200:203], v[80:83]
	v_mfma_f32_16x16x32_bf16 v[68:71], v[168:171], v[208:211], v[68:71]
	v_mfma_f32_16x16x32_bf16 v[64:67], v[176:179], v[208:211], v[64:67]
	v_mfma_f32_16x16x32_bf16 v[116:119], v[172:175], v[188:191], v[116:119]
	v_mfma_f32_16x16x32_bf16 v[112:115], v[180:183], v[188:191], v[112:115]
	v_mfma_f32_16x16x32_bf16 v[100:103], v[172:175], v[196:199], v[100:103]
	v_mfma_f32_16x16x32_bf16 v[96:99], v[180:183], v[196:199], v[96:99]
	v_mfma_f32_16x16x32_bf16 v[84:87], v[172:175], v[204:207], v[84:87]
	v_mfma_f32_16x16x32_bf16 v[80:83], v[180:183], v[204:207], v[80:83]
	v_mfma_f32_16x16x32_bf16 v[68:71], v[172:175], v[212:215], v[68:71]
	v_mfma_f32_16x16x32_bf16 v[64:67], v[180:183], v[212:215], v[64:67]
	s_setprio 0
	s_barrier
	s_add_i32 s54, s46, s5
	v_lshl_add_u64 v[216:217], s[34:35], 0, v[130:131]
	s_mov_b32 m0, s54
	s_nop 0
	global_load_lds_dwordx4 v[216:217], off
	s_add_i32 m0, s54, 0x2000
	s_add_u32 s54, s34, 0x40000
	v_lshl_add_u64 v[218:219], s[34:35], 0, v[134:135]
	s_addc_u32 s55, s35, 0
	s_add_i32 s56, s47, s5
	global_load_lds_dwordx4 v[218:219], off
	v_lshl_add_u64 v[220:221], s[54:55], 0, v[130:131]
	s_mov_b32 m0, s56
	v_lshl_add_u64 v[222:223], s[36:37], 0, v[132:133]
	global_load_lds_dwordx4 v[220:221], off
	v_lshl_add_u64 v[220:221], s[54:55], 0, v[134:135]
	s_add_i32 m0, s56, 0x2000
	s_nop 0
	global_load_lds_dwordx4 v[220:221], off
	v_lshl_add_u64 v[220:221], s[36:37], 0, v[128:129]
	s_mov_b32 m0, s33
	s_nop 0
	global_load_lds_dwordx4 v[220:221], off
	s_mov_b32 m0, s38
	s_nop 0
	global_load_lds_dwordx4 v[222:223], off
	ds_read_b128 v[184:187], v153 offset:16384
	ds_read_b128 v[188:191], v153 offset:17408
	ds_read_b128 v[192:195], v153 offset:18432
	ds_read_b128 v[196:199], v153 offset:19456
	ds_read_b128 v[200:203], v153 offset:20480
	ds_read_b128 v[204:207], v153 offset:21504
	ds_read_b128 v[208:211], v153 offset:22528
	ds_read_b128 v[212:215], v153 offset:23552
	s_waitcnt vmcnt(8)
	s_waitcnt lgkmcnt(0)
	s_barrier
; #define PG8_STAGE(bufoff, gbase, voff) do { _Pragma("unroll") for (int _i = 0; _i < 2; ++_i) \
;         __builtin_amdgcn_global_load_lds((const unsigned*)((const char*)(gbase) + (voff)[_i]), (LAS unsigned*)(lds + (bufoff) + ldsw + _i * 8192), 16, 0, 0); } while (0)
; #define PG8_LDA(dst, b, h) do { _Pragma("unroll") for (int m = 0; m < 4; ++m) _Pragma("unroll") for (int k = 0; k < 2; ++k) dst[m][k] = *(const LAS bf16x8*)(lds + PG8_SA(b, h) + aoff + m * 2048 + k * 1024); } while (0)
; #define PG8_LDB(dst, b, h) do { _Pragma("unroll") for (int n = 0; n < 2; ++n) _Pragma("unroll") for (int k = 0; k < 2; ++k) dst[n][k] = *(const LAS bf16x8*)(lds + PG8_SB(b, h) + boff + n * 2048 + k * 1024); } while (0)
; #define PG8_MMA(ai, bj, At, Bt) do { __builtin_amdgcn_s_setprio(1); _Pragma("unroll") for (int m = 0; m < 4; ++m) _Pragma("unroll") for (int n = 0; n < 2; ++n) _Pragma("unroll") for (int k = 0; k < 2; ++k) \
;         acc[ai][bj][m][n] = __builtin_amdgcn_mfma_f32_16x16x32_bf16(Bt[n][k], At[m][k], acc[ai][bj][m][n], 0, 0, 0); __builtin_amdgcn_s_setprio(0); } while (0)
; #define PG8_WAIT_V(n) asm volatile("s_waitcnt vmcnt(" #n ")" ::: "memory")
; #define PG8_WAIT_L(n) asm volatile("s_waitcnt lgkmcnt(" #n ")" ::: "memory")
; #define PG8_BAR __builtin_amdgcn_s_barrier()
; #define PG8_SCHED __builtin_amdgcn_sched_barrier(0)
; template <class Epi>
; __device__ __forceinline__ void gemm_phase(LAS unsigned char* lds, const Gemm g, const StaticOrder& S, const Epi& E, int wave_s) {
;     ...
;             PG8_WAIT_V(8); PG8_WAIT_L(0); PG8_BAR; PG8_MMA(1, 0, At, B0); PG8_MMA(1, 1, At, B1); PG8_BAR; PG8_SCHED;
;             PG8_LDB(B0, 1, 0); PG8_LDB(B1, 1, 1); PG8_SCHED; PG8_LDA(At, 1, 0); PG8_STAGE(PG8_SA(0, 1), a2 + hstepA, voffA);
;             PG8_WAIT_V(8); PG8_WAIT_L(0); PG8_BAR; PG8_MMA(0, 0, At, B0); PG8_MMA(0, 1, At, B1); PG8_BAR; PG8_SCHED;
	s_setprio 1
	s_waitcnt lgkmcnt(0)
	v_mfma_f32_16x16x32_bf16 v[60:63], v[144:147], v[184:187], v[60:63]
	v_mfma_f32_16x16x32_bf16 v[56:59], v[160:163], v[184:187], v[56:59]
	v_mfma_f32_16x16x32_bf16 v[44:47], v[144:147], v[192:195], v[44:47]
	v_mfma_f32_16x16x32_bf16 v[40:43], v[160:163], v[192:195], v[40:43]
	v_mfma_f32_16x16x32_bf16 v[28:31], v[144:147], v[200:203], v[28:31]
	v_mfma_f32_16x16x32_bf16 v[24:27], v[160:163], v[200:203], v[24:27]
	v_mfma_f32_16x16x32_bf16 v[12:15], v[144:147], v[208:211], v[12:15]
	v_mfma_f32_16x16x32_bf16 v[8:11], v[160:163], v[208:211], v[8:11]
	v_mfma_f32_16x16x32_bf16 v[60:63], v[156:159], v[188:191], v[60:63]
	v_mfma_f32_16x16x32_bf16 v[56:59], v[164:167], v[188:191], v[56:59]
	v_mfma_f32_16x16x32_bf16 v[44:47], v[156:159], v[196:199], v[44:47]
	v_mfma_f32_16x16x32_bf16 v[40:43], v[164:167], v[196:199], v[40:43]
	v_mfma_f32_16x16x32_bf16 v[28:31], v[156:159], v[204:207], v[28:31]
	v_mfma_f32_16x16x32_bf16 v[24:27], v[164:167], v[204:207], v[24:27]
	v_mfma_f32_16x16x32_bf16 v[12:15], v[156:159], v[212:215], v[12:15]
	v_mfma_f32_16x16x32_bf16 v[8:11], v[164:167], v[212:215], v[8:11]
	s_setprio 0
	s_setprio 1
	v_mfma_f32_16x16x32_bf16 v[52:55], v[168:171], v[184:187], v[52:55]
	v_mfma_f32_16x16x32_bf16 v[48:51], v[176:179], v[184:187], v[48:51]
	v_mfma_f32_16x16x32_bf16 v[36:39], v[168:171], v[192:195], v[36:39]
	v_mfma_f32_16x16x32_bf16 v[32:35], v[176:179], v[192:195], v[32:35]
	v_mfma_f32_16x16x32_bf16 v[20:23], v[168:171], v[200:203], v[20:23]
	v_mfma_f32_16x16x32_bf16 v[16:19], v[176:179], v[200:203], v[16:19]
	v_mfma_f32_16x16x32_bf16 v[4:7], v[168:171], v[208:211], v[4:7]
	v_mfma_f32_16x16x32_bf16 v[0:3], v[176:179], v[208:211], v[0:3]
	v_mfma_f32_16x16x32_bf16 v[52:55], v[172:175], v[188:191], v[52:55]
	v_mfma_f32_16x16x32_bf16 v[48:51], v[180:183], v[188:191], v[48:51]
	v_mfma_f32_16x16x32_bf16 v[36:39], v[172:175], v[196:199], v[36:39]
	v_mfma_f32_16x16x32_bf16 v[32:35], v[180:183], v[196:199], v[32:35]
	v_mfma_f32_16x16x32_bf16 v[20:23], v[172:175], v[204:207], v[20:23]
	v_mfma_f32_16x16x32_bf16 v[16:19], v[180:183], v[204:207], v[16:19]
	v_mfma_f32_16x16x32_bf16 v[4:7], v[172:175], v[212:215], v[4:7]
	v_mfma_f32_16x16x32_bf16 v[0:3], v[180:183], v[212:215], v[0:3]
	s_setprio 0
	s_barrier
	s_add_i32 s54, 0, 0x18000
	s_add_i32 s55, 0, 0x1c000
	s_add_u32 s36, s36, 0x40000
	s_addc_u32 s37, s37, 0
	s_mov_b32 m0, s39
	v_lshl_add_u64 v[224:225], s[36:37], 0, v[128:129]
	global_load_lds_dwordx4 v[224:225], off
	v_lshl_add_u64 v[224:225], s[36:37], 0, v[132:133]
	s_mov_b32 m0, s40
	s_nop 0
	global_load_lds_dwordx4 v[224:225], off
	v_add_u32_e32 v164, s54, v149
	v_add_u32_e32 v180, s55, v149
	ds_read_b128 v[144:147], v164
	ds_read_b128 v[156:159], v164 offset:1024
	ds_read_b128 v[160:163], v164 offset:2048
	ds_read_b128 v[164:167], v164 offset:3072
	ds_read_b128 v[168:171], v180
	ds_read_b128 v[172:175], v180 offset:1024
	ds_read_b128 v[176:179], v180 offset:2048
	ds_read_b128 v[180:183], v180 offset:3072
	ds_read_b128 v[184:187], v153 offset:32768
	ds_read_b128 v[188:191], v153 offset:33792
	ds_read_b128 v[192:195], v153 offset:34816
	ds_read_b128 v[196:199], v153 offset:35840
	ds_read_b128 v[200:203], v153 offset:36864
	ds_read_b128 v[204:207], v153 offset:37888
	ds_read_b128 v[208:211], v153 offset:38912
	ds_read_b128 v[212:215], v153 offset:39936
	s_waitcnt vmcnt(8)
	s_waitcnt lgkmcnt(0)
	s_barrier
	s_setprio 1
	s_waitcnt lgkmcnt(0)
	v_mfma_f32_16x16x32_bf16 v[124:127], v[144:147], v[184:187], v[124:127]
	v_mfma_f32_16x16x32_bf16 v[120:123], v[160:163], v[184:187], v[120:123]
	v_mfma_f32_16x16x32_bf16 v[108:111], v[144:147], v[192:195], v[108:111]
	v_mfma_f32_16x16x32_bf16 v[104:107], v[160:163], v[192:195], v[104:107]
	v_mfma_f32_16x16x32_bf16 v[92:95], v[144:147], v[200:203], v[92:95]
	v_mfma_f32_16x16x32_bf16 v[88:91], v[160:163], v[200:203], v[88:91]
	v_mfma_f32_16x16x32_bf16 v[76:79], v[144:147], v[208:211], v[76:79]
	v_mfma_f32_16x16x32_bf16 v[72:75], v[160:163], v[208:211], v[72:75]
	v_mfma_f32_16x16x32_bf16 v[124:127], v[156:159], v[188:191], v[124:127]
	v_mfma_f32_16x16x32_bf16 v[120:123], v[164:167], v[188:191], v[120:123]
	v_mfma_f32_16x16x32_bf16 v[108:111], v[156:159], v[196:199], v[108:111]
	v_mfma_f32_16x16x32_bf16 v[104:107], v[164:167], v[196:199], v[104:107]
	v_mfma_f32_16x16x32_bf16 v[92:95], v[156:159], v[204:207], v[92:95]
	v_mfma_f32_16x16x32_bf16 v[88:91], v[164:167], v[204:207], v[88:91]
	v_mfma_f32_16x16x32_bf16 v[76:79], v[156:159], v[212:215], v[76:79]
	v_mfma_f32_16x16x32_bf16 v[72:75], v[164:167], v[212:215], v[72:75]
	s_setprio 0
	s_setprio 1
	v_mfma_f32_16x16x32_bf16 v[116:119], v[168:171], v[184:187], v[116:119]
	v_mfma_f32_16x16x32_bf16 v[112:115], v[176:179], v[184:187], v[112:115]
	v_mfma_f32_16x16x32_bf16 v[100:103], v[168:171], v[192:195], v[100:103]
	v_mfma_f32_16x16x32_bf16 v[96:99], v[176:179], v[192:195], v[96:99]
	v_mfma_f32_16x16x32_bf16 v[84:87], v[168:171], v[200:203], v[84:87]
	v_mfma_f32_16x16x32_bf16 v[80:83], v[176:179], v[200:203], v[80:83]
	v_mfma_f32_16x16x32_bf16 v[68:71], v[168:171], v[208:211], v[68:71]
	v_mfma_f32_16x16x32_bf16 v[64:67], v[176:179], v[208:211], v[64:67]
	v_mfma_f32_16x16x32_bf16 v[116:119], v[172:175], v[188:191], v[116:119]
	v_mfma_f32_16x16x32_bf16 v[112:115], v[180:183], v[188:191], v[112:115]
	v_mfma_f32_16x16x32_bf16 v[100:103], v[172:175], v[196:199], v[100:103]
	v_mfma_f32_16x16x32_bf16 v[96:99], v[180:183], v[196:199], v[96:99]
	v_mfma_f32_16x16x32_bf16 v[84:87], v[172:175], v[204:207], v[84:87]
	v_mfma_f32_16x16x32_bf16 v[80:83], v[180:183], v[204:207], v[80:83]
	v_mfma_f32_16x16x32_bf16 v[68:71], v[172:175], v[212:215], v[68:71]
	v_mfma_f32_16x16x32_bf16 v[64:67], v[180:183], v[212:215], v[64:67]
	s_setprio 0
	s_barrier
; #define PG8_STAGE(bufoff, gbase, voff) do { _Pragma("unroll") for (int _i = 0; _i < 2; ++_i) \
;         __builtin_amdgcn_global_load_lds((const unsigned*)((const char*)(gbase) + (voff)[_i]), (LAS unsigned*)(lds + (bufoff) + ldsw + _i * 8192), 16, 0, 0); } while (0)
; #define PG8_LDA(dst, b, h) do { _Pragma("unroll") for (int m = 0; m < 4; ++m) _Pragma("unroll") for (int k = 0; k < 2; ++k) dst[m][k] = *(const LAS bf16x8*)(lds + PG8_SA(b, h) + aoff + m * 2048 + k * 1024); } while (0)
; #define PG8_MMA(ai, bj, At, Bt) do { __builtin_amdgcn_s_setprio(1); _Pragma("unroll") for (int m = 0; m < 4; ++m) _Pragma("unroll") for (int n = 0; n < 2; ++n) _Pragma("unroll") for (int k = 0; k < 2; ++k) \
;         acc[ai][bj][m][n] = __builtin_amdgcn_mfma_f32_16x16x32_bf16(Bt[n][k], At[m][k], acc[ai][bj][m][n], 0, 0, 0); __builtin_amdgcn_s_setprio(0); } while (0)
; #define PG8_WAIT_V(n) asm volatile("s_waitcnt vmcnt(" #n ")" ::: "memory")
; #define PG8_WAIT_L(n) asm volatile("s_waitcnt lgkmcnt(" #n ")" ::: "memory")
; #define PG8_BAR __builtin_amdgcn_s_barrier()
; #define PG8_SCHED __builtin_amdgcn_sched_barrier(0)
; template <class Epi>
; __device__ __forceinline__ void gemm_phase(LAS unsigned char* lds, const Gemm g, const StaticOrder& S, const Epi& E, int wave_s) {
;     ...
;             PG8_LDA(At, 1, 1); PG8_STAGE(PG8_SB(1, 0), b3, voffB); PG8_STAGE(PG8_SB(1, 1), b3 + hstepB, voffB); PG8_STAGE(PG8_SA(1, 0), a3, voffA);
;             PG8_WAIT_V(8); PG8_WAIT_L(0); PG8_BAR; PG8_MMA(1, 0, At, B0); PG8_MMA(1, 1, At, B1); PG8_BAR; PG8_SCHED;
;         }
	s_add_i32 s36, s54, s5
	v_lshl_add_u64 v[216:217], v[216:217], 0, s[18:19]
	s_mov_b32 m0, s36
	s_nop 0
	global_load_lds_dwordx4 v[216:217], off
	s_add_i32 m0, s36, 0x2000
	s_add_u32 s34, s34, 0x40080
	v_lshl_add_u64 v[216:217], v[218:219], 0, s[18:19]
	s_addc_u32 s35, s35, 0
	s_add_i32 s36, s55, s5
	global_load_lds_dwordx4 v[216:217], off
	v_lshl_add_u64 v[216:217], s[34:35], 0, v[130:131]
	s_mov_b32 m0, s36
	s_nop 0
	global_load_lds_dwordx4 v[216:217], off
	v_lshl_add_u64 v[216:217], s[34:35], 0, v[134:135]
	s_add_i32 m0, s36, 0x2000
	s_nop 0
	global_load_lds_dwordx4 v[216:217], off
	v_lshl_add_u64 v[216:217], v[220:221], 0, s[18:19]
	s_mov_b32 m0, s42
	s_nop 0
	global_load_lds_dwordx4 v[216:217], off
	v_lshl_add_u64 v[216:217], v[222:223], 0, s[18:19]
	s_mov_b32 m0, s43
	s_nop 0
	global_load_lds_dwordx4 v[216:217], off
	ds_read_b128 v[184:187], v153 offset:49152
	ds_read_b128 v[188:191], v153 offset:50176
	ds_read_b128 v[192:195], v153 offset:51200
	ds_read_b128 v[196:199], v153 offset:52224
	ds_read_b128 v[200:203], v153 offset:53248
	ds_read_b128 v[204:207], v153 offset:54272
	ds_read_b128 v[208:211], v153 offset:55296
	ds_read_b128 v[212:215], v153 offset:56320
	s_waitcnt vmcnt(8)
	s_waitcnt lgkmcnt(0)
	s_barrier
	s_setprio 1
	s_waitcnt lgkmcnt(0)
	v_mfma_f32_16x16x32_bf16 v[60:63], v[144:147], v[184:187], v[60:63]
	v_mfma_f32_16x16x32_bf16 v[56:59], v[160:163], v[184:187], v[56:59]
	v_mfma_f32_16x16x32_bf16 v[44:47], v[144:147], v[192:195], v[44:47]
	v_mfma_f32_16x16x32_bf16 v[40:43], v[160:163], v[192:195], v[40:43]
	v_mfma_f32_16x16x32_bf16 v[28:31], v[144:147], v[200:203], v[28:31]
	v_mfma_f32_16x16x32_bf16 v[24:27], v[160:163], v[200:203], v[24:27]
	v_mfma_f32_16x16x32_bf16 v[12:15], v[144:147], v[208:211], v[12:15]
	v_mfma_f32_16x16x32_bf16 v[8:11], v[160:163], v[208:211], v[8:11]
	v_mfma_f32_16x16x32_bf16 v[60:63], v[156:159], v[188:191], v[60:63]
	v_mfma_f32_16x16x32_bf16 v[56:59], v[164:167], v[188:191], v[56:59]
	v_mfma_f32_16x16x32_bf16 v[44:47], v[156:159], v[196:199], v[44:47]
	v_mfma_f32_16x16x32_bf16 v[40:43], v[164:167], v[196:199], v[40:43]
	v_mfma_f32_16x16x32_bf16 v[28:31], v[156:159], v[204:207], v[28:31]
	v_mfma_f32_16x16x32_bf16 v[24:27], v[164:167], v[204:207], v[24:27]
	v_mfma_f32_16x16x32_bf16 v[12:15], v[156:159], v[212:215], v[12:15]
	v_mfma_f32_16x16x32_bf16 v[8:11], v[164:167], v[212:215], v[8:11]
	s_setprio 0
	s_setprio 1
	v_mfma_f32_16x16x32_bf16 v[52:55], v[168:171], v[184:187], v[52:55]
	v_mfma_f32_16x16x32_bf16 v[48:51], v[176:179], v[184:187], v[48:51]
	v_mfma_f32_16x16x32_bf16 v[36:39], v[168:171], v[192:195], v[36:39]
	v_mfma_f32_16x16x32_bf16 v[32:35], v[176:179], v[192:195], v[32:35]
	v_mfma_f32_16x16x32_bf16 v[20:23], v[168:171], v[200:203], v[20:23]
	v_mfma_f32_16x16x32_bf16 v[16:19], v[176:179], v[200:203], v[16:19]
	v_mfma_f32_16x16x32_bf16 v[4:7], v[168:171], v[208:211], v[4:7]
	v_mfma_f32_16x16x32_bf16 v[0:3], v[176:179], v[208:211], v[0:3]
	v_mfma_f32_16x16x32_bf16 v[52:55], v[172:175], v[188:191], v[52:55]
	v_mfma_f32_16x16x32_bf16 v[48:51], v[180:183], v[188:191], v[48:51]
	v_mfma_f32_16x16x32_bf16 v[36:39], v[172:175], v[196:199], v[36:39]
	v_mfma_f32_16x16x32_bf16 v[32:35], v[180:183], v[196:199], v[32:35]
	v_mfma_f32_16x16x32_bf16 v[20:23], v[172:175], v[204:207], v[20:23]
	v_mfma_f32_16x16x32_bf16 v[16:19], v[180:183], v[204:207], v[16:19]
	v_mfma_f32_16x16x32_bf16 v[4:7], v[172:175], v[212:215], v[4:7]
	v_mfma_f32_16x16x32_bf16 v[0:3], v[180:183], v[212:215], v[0:3]
	s_setprio 0
	s_barrier
	s_add_i32 s53, s53, 2
	s_add_u32 s30, s30, 0x100
	s_addc_u32 s31, s31, 0
	s_add_u32 s51, s51, 0x100
	s_addc_u32 s52, s52, 0
	s_cmp_gt_u32 s53, 13
	s_cbranch_scc0 .LBB0_811
	s_and_b64 vcc, exec, s[20:21]
	s_cbranch_vccz .LBB0_814
	s_barrier

; #define PG8_STAGE(bufoff, gbase, voff) do { _Pragma("unroll") for (int _i = 0; _i < 2; ++_i) \
;         __builtin_amdgcn_global_load_lds((const unsigned*)((const char*)(gbase) + (voff)[_i]), (LAS unsigned*)(lds + (bufoff) + ldsw + _i * 8192), 16, 0, 0); } while (0)
; #define PG8_LDA(dst, b, h) do { _Pragma("unroll") for (int m = 0; m < 4; ++m) _Pragma("unroll") for (int k = 0; k < 2; ++k) dst[m][k] = *(const LAS bf16x8*)(lds + PG8_SA(b, h) + aoff + m * 2048 + k * 1024); } while (0)
; #define PG8_LDB(dst, b, h) do { _Pragma("unroll") for (int n = 0; n < 2; ++n) _Pragma("unroll") for (int k = 0; k < 2; ++k) dst[n][k] = *(const LAS bf16x8*)(lds + PG8_SB(b, h) + boff + n * 2048 + k * 1024); } while (0)
; #define PG8_MMA(ai, bj, At, Bt) do { __builtin_amdgcn_s_setprio(1); _Pragma("unroll") for (int m = 0; m < 4; ++m) _Pragma("unroll") for (int n = 0; n < 2; ++n) _Pragma("unroll") for (int k = 0; k < 2; ++k) \
;         acc[ai][bj][m][n] = __builtin_amdgcn_mfma_f32_16x16x32_bf16(Bt[n][k], At[m][k], acc[ai][bj][m][n], 0, 0, 0); __builtin_amdgcn_s_setprio(0); } while (0)
; #define PG8_WAIT_V(n) asm volatile("s_waitcnt vmcnt(" #n ")" ::: "memory")
; #define PG8_WAIT_L(n) asm volatile("s_waitcnt lgkmcnt(" #n ")" ::: "memory")
; #define PG8_BAR __builtin_amdgcn_s_barrier()
; #define PG8_SCHED __builtin_amdgcn_sched_barrier(0)
; template <class Epi>
; __device__ __forceinline__ void gemm_phase(LAS unsigned char* lds, const Gemm g, const StaticOrder& S, const Epi& E, int wave_s) {
;     ...
;             PG8_LDB(B0, 0, 0); PG8_LDB(B1, 0, 1); PG8_SCHED; PG8_LDA(At, 0, 0); PG8_STAGE(PG8_SA(1, 1), a1 + hstepA, voffA);
;             PG8_WAIT_V(8); PG8_WAIT_L(0); PG8_BAR; PG8_MMA(0, 0, At, B0); PG8_MMA(0, 1, At, B1); PG8_BAR; PG8_SCHED;
;             PG8_LDA(At, 0, 1); PG8_STAGE(PG8_SB(0, 0), b2, voffB); PG8_STAGE(PG8_SB(0, 1), b2 + hstepB, voffB); PG8_STAGE(PG8_SA(0, 0), a2, voffA);
;             PG8_WAIT_V(8); PG8_WAIT_L(0); PG8_BAR; PG8_MMA(1, 0, At, B0); PG8_MMA(1, 1, At, B1); PG8_BAR; PG8_SCHED;
.LBB0_962:
	s_add_u32 s38, s36, 0xfffe0080
	s_addc_u32 s39, s37, -1
	s_cmp_eq_u32 s56, 4
	s_cselect_b32 s41, s27, s39
	s_cselect_b32 s40, s35, s38
	s_cselect_b32 s39, s25, s55
	s_cselect_b32 s38, s53, s54
	v_lshl_add_u64 v[204:205], s[36:37], 0, v[200:201]
	s_add_i32 m0, s5, 0xc000
	s_nop 0
	global_load_lds_dwordx4 v[204:205], off
	v_lshl_add_u64 v[204:205], s[36:37], 0, v[202:203]
	s_add_i32 m0, s5, 0xe000
	s_nop 0
	global_load_lds_dwordx4 v[204:205], off
	ds_read_b128 v[120:123], v243
	ds_read_b128 v[124:127], v243 offset:1024
	ds_read_b128 v[128:131], v243 offset:2048
	ds_read_b128 v[132:135], v243 offset:3072
	ds_read_b128 v[136:139], v244
	ds_read_b128 v[140:143], v244 offset:1024
	ds_read_b128 v[152:155], v244 offset:2048
	ds_read_b128 v[156:159], v244 offset:3072
	ds_read_b128 v[160:163], v245
	ds_read_b128 v[164:167], v245 offset:1024
	ds_read_b128 v[168:171], v245 offset:2048
	ds_read_b128 v[172:175], v245 offset:3072
	ds_read_b128 v[176:179], v245 offset:4096
	ds_read_b128 v[180:183], v245 offset:5120
	ds_read_b128 v[184:187], v245 offset:6144
	ds_read_b128 v[188:191], v245 offset:7168
	s_waitcnt vmcnt(8)
	s_waitcnt lgkmcnt(0)
	s_barrier
	s_setprio 1
	s_waitcnt lgkmcnt(0)
	v_mfma_f32_16x16x32_bf16 v[148:151], v[120:123], v[160:163], v[148:151]
	v_mfma_f32_16x16x32_bf16 v[144:147], v[128:131], v[160:163], v[144:147]
	v_mfma_f32_16x16x32_bf16 v[108:111], v[120:123], v[168:171], v[108:111]
	v_mfma_f32_16x16x32_bf16 v[104:107], v[128:131], v[168:171], v[104:107]
	v_mfma_f32_16x16x32_bf16 v[92:95], v[120:123], v[176:179], v[92:95]
	v_mfma_f32_16x16x32_bf16 v[88:91], v[128:131], v[176:179], v[88:91]
	v_mfma_f32_16x16x32_bf16 v[76:79], v[120:123], v[184:187], v[76:79]
	v_mfma_f32_16x16x32_bf16 v[72:75], v[128:131], v[184:187], v[72:75]
	v_mfma_f32_16x16x32_bf16 v[148:151], v[124:127], v[164:167], v[148:151]
	v_mfma_f32_16x16x32_bf16 v[144:147], v[132:135], v[164:167], v[144:147]
	v_mfma_f32_16x16x32_bf16 v[108:111], v[124:127], v[172:175], v[108:111]
	v_mfma_f32_16x16x32_bf16 v[104:107], v[132:135], v[172:175], v[104:107]
	v_mfma_f32_16x16x32_bf16 v[92:95], v[124:127], v[180:183], v[92:95]
	v_mfma_f32_16x16x32_bf16 v[88:91], v[132:135], v[180:183], v[88:91]
	v_mfma_f32_16x16x32_bf16 v[76:79], v[124:127], v[188:191], v[76:79]
	v_mfma_f32_16x16x32_bf16 v[72:75], v[132:135], v[188:191], v[72:75]
	s_setprio 0
	s_setprio 1
	v_mfma_f32_16x16x32_bf16 v[116:119], v[136:139], v[160:163], v[116:119]
	v_mfma_f32_16x16x32_bf16 v[112:115], v[152:155], v[160:163], v[112:115]
	v_mfma_f32_16x16x32_bf16 v[100:103], v[136:139], v[168:171], v[100:103]
	v_mfma_f32_16x16x32_bf16 v[96:99], v[152:155], v[168:171], v[96:99]
	v_mfma_f32_16x16x32_bf16 v[84:87], v[136:139], v[176:179], v[84:87]
	v_mfma_f32_16x16x32_bf16 v[80:83], v[152:155], v[176:179], v[80:83]
	v_mfma_f32_16x16x32_bf16 v[68:71], v[136:139], v[184:187], v[68:71]
	v_mfma_f32_16x16x32_bf16 v[64:67], v[152:155], v[184:187], v[64:67]
	v_mfma_f32_16x16x32_bf16 v[116:119], v[140:143], v[164:167], v[116:119]
	v_mfma_f32_16x16x32_bf16 v[112:115], v[156:159], v[164:167], v[112:115]
	v_mfma_f32_16x16x32_bf16 v[100:103], v[140:143], v[172:175], v[100:103]
	v_mfma_f32_16x16x32_bf16 v[96:99], v[156:159], v[172:175], v[96:99]
	v_mfma_f32_16x16x32_bf16 v[84:87], v[140:143], v[180:183], v[84:87]
	v_mfma_f32_16x16x32_bf16 v[80:83], v[156:159], v[180:183], v[80:83]
	v_mfma_f32_16x16x32_bf16 v[68:71], v[140:143], v[188:191], v[68:71]
	v_mfma_f32_16x16x32_bf16 v[64:67], v[156:159], v[188:191], v[64:67]
	s_setprio 0
	s_barrier
	s_add_i32 s57, s50, s4
	v_lshl_add_u64 v[204:205], s[38:39], 0, v[194:195]
	s_mov_b32 m0, s57
	s_nop 0
	global_load_lds_dwordx4 v[204:205], off
	s_add_i32 m0, s57, 0x2000
	s_add_u32 s58, s38, 0x20000
	v_lshl_add_u64 v[206:207], s[38:39], 0, v[198:199]
	s_addc_u32 s59, s39, 0
	s_add_i32 s57, s51, s4
	global_load_lds_dwordx4 v[206:207], off
	v_lshl_add_u64 v[208:209], s[58:59], 0, v[194:195]
	s_mov_b32 m0, s57
	v_lshl_add_u64 v[210:211], s[40:41], 0, v[196:197]
	global_load_lds_dwordx4 v[208:209], off
	v_lshl_add_u64 v[208:209], s[58:59], 0, v[198:199]
	s_add_i32 m0, s57, 0x2000
	s_nop 0
	global_load_lds_dwordx4 v[208:209], off
	v_lshl_add_u64 v[208:209], s[40:41], 0, v[192:193]
	s_mov_b32 m0, s5
	s_nop 0
	global_load_lds_dwordx4 v[208:209], off
	s_mov_b32 m0, s33
	s_nop 0
	global_load_lds_dwordx4 v[210:211], off
	ds_read_b128 v[160:163], v245 offset:16384
	ds_read_b128 v[164:167], v245 offset:17408
	ds_read_b128 v[168:171], v245 offset:18432
	ds_read_b128 v[172:175], v245 offset:19456
	ds_read_b128 v[176:179], v245 offset:20480
	ds_read_b128 v[180:183], v245 offset:21504
	ds_read_b128 v[184:187], v245 offset:22528
	ds_read_b128 v[188:191], v245 offset:23552
	s_waitcnt vmcnt(8)
	s_waitcnt lgkmcnt(0)
	s_barrier
; #define PG8_STAGE(bufoff, gbase, voff) do { _Pragma("unroll") for (int _i = 0; _i < 2; ++_i) \
;         __builtin_amdgcn_global_load_lds((const unsigned*)((const char*)(gbase) + (voff)[_i]), (LAS unsigned*)(lds + (bufoff) + ldsw + _i * 8192), 16, 0, 0); } while (0)
; #define PG8_LDA(dst, b, h) do { _Pragma("unroll") for (int m = 0; m < 4; ++m) _Pragma("unroll") for (int k = 0; k < 2; ++k) dst[m][k] = *(const LAS bf16x8*)(lds + PG8_SA(b, h) + aoff + m * 2048 + k * 1024); } while (0)
; #define PG8_LDB(dst, b, h) do { _Pragma("unroll") for (int n = 0; n < 2; ++n) _Pragma("unroll") for (int k = 0; k < 2; ++k) dst[n][k] = *(const LAS bf16x8*)(lds + PG8_SB(b, h) + boff + n * 2048 + k * 1024); } while (0)
; #define PG8_MMA(ai, bj, At, Bt) do { __builtin_amdgcn_s_setprio(1); _Pragma("unroll") for (int m = 0; m < 4; ++m) _Pragma("unroll") for (int n = 0; n < 2; ++n) _Pragma("unroll") for (int k = 0; k < 2; ++k) \
;         acc[ai][bj][m][n] = __builtin_amdgcn_mfma_f32_16x16x32_bf16(Bt[n][k], At[m][k], acc[ai][bj][m][n], 0, 0, 0); __builtin_amdgcn_s_setprio(0); } while (0)
; #define PG8_WAIT_V(n) asm volatile("s_waitcnt vmcnt(" #n ")" ::: "memory")
; #define PG8_WAIT_L(n) asm volatile("s_waitcnt lgkmcnt(" #n ")" ::: "memory")
; #define PG8_BAR __builtin_amdgcn_s_barrier()
; #define PG8_SCHED __builtin_amdgcn_sched_barrier(0)
; template <class Epi>
; __device__ __forceinline__ void gemm_phase(LAS unsigned char* lds, const Gemm g, const StaticOrder& S, const Epi& E, int wave_s) {
;     ...
;             PG8_WAIT_V(8); PG8_WAIT_L(0); PG8_BAR; PG8_MMA(1, 0, At, B0); PG8_MMA(1, 1, At, B1); PG8_BAR; PG8_SCHED;
;             PG8_LDB(B0, 1, 0); PG8_LDB(B1, 1, 1); PG8_SCHED; PG8_LDA(At, 1, 0); PG8_STAGE(PG8_SA(0, 1), a2 + hstepA, voffA);
;             PG8_WAIT_V(8); PG8_WAIT_L(0); PG8_BAR; PG8_MMA(0, 0, At, B0); PG8_MMA(0, 1, At, B1); PG8_BAR; PG8_SCHED;
	s_setprio 1
	s_waitcnt lgkmcnt(0)
	v_mfma_f32_16x16x32_bf16 v[60:63], v[120:123], v[160:163], v[60:63]
	v_mfma_f32_16x16x32_bf16 v[56:59], v[128:131], v[160:163], v[56:59]
	v_mfma_f32_16x16x32_bf16 v[44:47], v[120:123], v[168:171], v[44:47]
	v_mfma_f32_16x16x32_bf16 v[40:43], v[128:131], v[168:171], v[40:43]
	v_mfma_f32_16x16x32_bf16 v[28:31], v[120:123], v[176:179], v[28:31]
	v_mfma_f32_16x16x32_bf16 v[24:27], v[128:131], v[176:179], v[24:27]
	v_mfma_f32_16x16x32_bf16 v[12:15], v[120:123], v[184:187], v[12:15]
	v_mfma_f32_16x16x32_bf16 v[8:11], v[128:131], v[184:187], v[8:11]
	v_mfma_f32_16x16x32_bf16 v[60:63], v[124:127], v[164:167], v[60:63]
	v_mfma_f32_16x16x32_bf16 v[56:59], v[132:135], v[164:167], v[56:59]
	v_mfma_f32_16x16x32_bf16 v[44:47], v[124:127], v[172:175], v[44:47]
	v_mfma_f32_16x16x32_bf16 v[40:43], v[132:135], v[172:175], v[40:43]
	v_mfma_f32_16x16x32_bf16 v[28:31], v[124:127], v[180:183], v[28:31]
	v_mfma_f32_16x16x32_bf16 v[24:27], v[132:135], v[180:183], v[24:27]
	v_mfma_f32_16x16x32_bf16 v[12:15], v[124:127], v[188:191], v[12:15]
	v_mfma_f32_16x16x32_bf16 v[8:11], v[132:135], v[188:191], v[8:11]
	s_setprio 0
	s_setprio 1
	v_mfma_f32_16x16x32_bf16 v[52:55], v[136:139], v[160:163], v[52:55]
	v_mfma_f32_16x16x32_bf16 v[48:51], v[152:155], v[160:163], v[48:51]
	v_mfma_f32_16x16x32_bf16 v[36:39], v[136:139], v[168:171], v[36:39]
	v_mfma_f32_16x16x32_bf16 v[32:35], v[152:155], v[168:171], v[32:35]
	v_mfma_f32_16x16x32_bf16 v[20:23], v[136:139], v[176:179], v[20:23]
	v_mfma_f32_16x16x32_bf16 v[16:19], v[152:155], v[176:179], v[16:19]
	v_mfma_f32_16x16x32_bf16 v[4:7], v[136:139], v[184:187], v[4:7]
	v_mfma_f32_16x16x32_bf16 v[0:3], v[152:155], v[184:187], v[0:3]
	v_mfma_f32_16x16x32_bf16 v[52:55], v[140:143], v[164:167], v[52:55]
	v_mfma_f32_16x16x32_bf16 v[48:51], v[156:159], v[164:167], v[48:51]
	v_mfma_f32_16x16x32_bf16 v[36:39], v[140:143], v[172:175], v[36:39]
	v_mfma_f32_16x16x32_bf16 v[32:35], v[156:159], v[172:175], v[32:35]
	v_mfma_f32_16x16x32_bf16 v[20:23], v[140:143], v[180:183], v[20:23]
	v_mfma_f32_16x16x32_bf16 v[16:19], v[156:159], v[180:183], v[16:19]
	v_mfma_f32_16x16x32_bf16 v[4:7], v[140:143], v[188:191], v[4:7]
	v_mfma_f32_16x16x32_bf16 v[0:3], v[156:159], v[188:191], v[0:3]
	s_setprio 0
	s_barrier
	s_add_i32 s57, 0, 0x18000
	s_add_i32 s58, 0, 0x1c000
	s_add_u32 s40, s40, 0x20000
	s_addc_u32 s41, s41, 0
	s_mov_b32 m0, s42
	v_lshl_add_u64 v[212:213], s[40:41], 0, v[192:193]
	global_load_lds_dwordx4 v[212:213], off
	v_lshl_add_u64 v[212:213], s[40:41], 0, v[196:197]
	s_mov_b32 m0, s43
	s_nop 0
	global_load_lds_dwordx4 v[212:213], off
	v_add_u32_e32 v132, s57, v241
	v_add_u32_e32 v156, s58, v241
	ds_read_b128 v[120:123], v132
	ds_read_b128 v[124:127], v132 offset:1024
	ds_read_b128 v[128:131], v132 offset:2048
	ds_read_b128 v[132:135], v132 offset:3072
	ds_read_b128 v[136:139], v156
	ds_read_b128 v[140:143], v156 offset:1024
	ds_read_b128 v[152:155], v156 offset:2048
	ds_read_b128 v[156:159], v156 offset:3072
	ds_read_b128 v[160:163], v245 offset:32768
	ds_read_b128 v[164:167], v245 offset:33792
	ds_read_b128 v[168:171], v245 offset:34816
	ds_read_b128 v[172:175], v245 offset:35840
	ds_read_b128 v[176:179], v245 offset:36864
	ds_read_b128 v[180:183], v245 offset:37888
	ds_read_b128 v[184:187], v245 offset:38912
	ds_read_b128 v[188:191], v245 offset:39936
	s_waitcnt vmcnt(8)
	s_waitcnt lgkmcnt(0)
	s_barrier
	s_setprio 1
	s_waitcnt lgkmcnt(0)
	v_mfma_f32_16x16x32_bf16 v[148:151], v[120:123], v[160:163], v[148:151]
	v_mfma_f32_16x16x32_bf16 v[144:147], v[128:131], v[160:163], v[144:147]
	v_mfma_f32_16x16x32_bf16 v[108:111], v[120:123], v[168:171], v[108:111]
	v_mfma_f32_16x16x32_bf16 v[104:107], v[128:131], v[168:171], v[104:107]
	v_mfma_f32_16x16x32_bf16 v[92:95], v[120:123], v[176:179], v[92:95]
	v_mfma_f32_16x16x32_bf16 v[88:91], v[128:131], v[176:179], v[88:91]
	v_mfma_f32_16x16x32_bf16 v[76:79], v[120:123], v[184:187], v[76:79]
	v_mfma_f32_16x16x32_bf16 v[72:75], v[128:131], v[184:187], v[72:75]
	v_mfma_f32_16x16x32_bf16 v[148:151], v[124:127], v[164:167], v[148:151]
	v_mfma_f32_16x16x32_bf16 v[144:147], v[132:135], v[164:167], v[144:147]
	v_mfma_f32_16x16x32_bf16 v[108:111], v[124:127], v[172:175], v[108:111]
	v_mfma_f32_16x16x32_bf16 v[104:107], v[132:135], v[172:175], v[104:107]
	v_mfma_f32_16x16x32_bf16 v[92:95], v[124:127], v[180:183], v[92:95]
	v_mfma_f32_16x16x32_bf16 v[88:91], v[132:135], v[180:183], v[88:91]
	v_mfma_f32_16x16x32_bf16 v[76:79], v[124:127], v[188:191], v[76:79]
	v_mfma_f32_16x16x32_bf16 v[72:75], v[132:135], v[188:191], v[72:75]
	s_setprio 0
	s_setprio 1
	v_mfma_f32_16x16x32_bf16 v[116:119], v[136:139], v[160:163], v[116:119]
	v_mfma_f32_16x16x32_bf16 v[112:115], v[152:155], v[160:163], v[112:115]
	v_mfma_f32_16x16x32_bf16 v[100:103], v[136:139], v[168:171], v[100:103]
	v_mfma_f32_16x16x32_bf16 v[96:99], v[152:155], v[168:171], v[96:99]
	v_mfma_f32_16x16x32_bf16 v[84:87], v[136:139], v[176:179], v[84:87]
	v_mfma_f32_16x16x32_bf16 v[80:83], v[152:155], v[176:179], v[80:83]
	v_mfma_f32_16x16x32_bf16 v[68:71], v[136:139], v[184:187], v[68:71]
	v_mfma_f32_16x16x32_bf16 v[64:67], v[152:155], v[184:187], v[64:67]
	v_mfma_f32_16x16x32_bf16 v[116:119], v[140:143], v[164:167], v[116:119]
	v_mfma_f32_16x16x32_bf16 v[112:115], v[156:159], v[164:167], v[112:115]
	v_mfma_f32_16x16x32_bf16 v[100:103], v[140:143], v[172:175], v[100:103]
	v_mfma_f32_16x16x32_bf16 v[96:99], v[156:159], v[172:175], v[96:99]
	v_mfma_f32_16x16x32_bf16 v[84:87], v[140:143], v[180:183], v[84:87]
	v_mfma_f32_16x16x32_bf16 v[80:83], v[156:159], v[180:183], v[80:83]
	v_mfma_f32_16x16x32_bf16 v[68:71], v[140:143], v[188:191], v[68:71]
	v_mfma_f32_16x16x32_bf16 v[64:67], v[156:159], v[188:191], v[64:67]
	s_setprio 0
	s_barrier
; #define PG8_STAGE(bufoff, gbase, voff) do { _Pragma("unroll") for (int _i = 0; _i < 2; ++_i) \
;         __builtin_amdgcn_global_load_lds((const unsigned*)((const char*)(gbase) + (voff)[_i]), (LAS unsigned*)(lds + (bufoff) + ldsw + _i * 8192), 16, 0, 0); } while (0)
; #define PG8_LDA(dst, b, h) do { _Pragma("unroll") for (int m = 0; m < 4; ++m) _Pragma("unroll") for (int k = 0; k < 2; ++k) dst[m][k] = *(const LAS bf16x8*)(lds + PG8_SA(b, h) + aoff + m * 2048 + k * 1024); } while (0)
; #define PG8_MMA(ai, bj, At, Bt) do { __builtin_amdgcn_s_setprio(1); _Pragma("unroll") for (int m = 0; m < 4; ++m) _Pragma("unroll") for (int n = 0; n < 2; ++n) _Pragma("unroll") for (int k = 0; k < 2; ++k) \
;         acc[ai][bj][m][n] = __builtin_amdgcn_mfma_f32_16x16x32_bf16(Bt[n][k], At[m][k], acc[ai][bj][m][n], 0, 0, 0); __builtin_amdgcn_s_setprio(0); } while (0)
; #define PG8_WAIT_V(n) asm volatile("s_waitcnt vmcnt(" #n ")" ::: "memory")
; #define PG8_WAIT_L(n) asm volatile("s_waitcnt lgkmcnt(" #n ")" ::: "memory")
; #define PG8_BAR __builtin_amdgcn_s_barrier()
; #define PG8_SCHED __builtin_amdgcn_sched_barrier(0)
; template <class Epi>
; __device__ __forceinline__ void gemm_phase(LAS unsigned char* lds, const Gemm g, const StaticOrder& S, const Epi& E, int wave_s) {
;     ...
;             PG8_LDA(At, 1, 1); PG8_STAGE(PG8_SB(1, 0), b3, voffB); PG8_STAGE(PG8_SB(1, 1), b3 + hstepB, voffB); PG8_STAGE(PG8_SA(1, 0), a3, voffA);
;             PG8_WAIT_V(8); PG8_WAIT_L(0); PG8_BAR; PG8_MMA(1, 0, At, B0); PG8_MMA(1, 1, At, B1); PG8_BAR; PG8_SCHED;
;         }
	s_add_i32 s40, s57, s4
	v_lshl_add_u64 v[204:205], v[204:205], 0, s[20:21]
	s_mov_b32 m0, s40
	s_nop 0
	global_load_lds_dwordx4 v[204:205], off
	s_add_i32 m0, s40, 0x2000
	s_add_u32 s38, s38, 0x20080
	v_lshl_add_u64 v[204:205], v[206:207], 0, s[20:21]
	s_addc_u32 s39, s39, 0
	s_add_i32 s40, s58, s4
	global_load_lds_dwordx4 v[204:205], off
	v_lshl_add_u64 v[204:205], s[38:39], 0, v[194:195]
	s_mov_b32 m0, s40
	s_nop 0
	global_load_lds_dwordx4 v[204:205], off
	v_lshl_add_u64 v[204:205], s[38:39], 0, v[198:199]
	s_add_i32 m0, s40, 0x2000
	s_nop 0
	global_load_lds_dwordx4 v[204:205], off
	v_lshl_add_u64 v[204:205], v[208:209], 0, s[20:21]
	s_mov_b32 m0, s45
	s_nop 0
	global_load_lds_dwordx4 v[204:205], off
	v_lshl_add_u64 v[204:205], v[210:211], 0, s[20:21]
	s_mov_b32 m0, s46
	s_nop 0
	global_load_lds_dwordx4 v[204:205], off
	ds_read_b128 v[160:163], v245 offset:49152
	ds_read_b128 v[164:167], v245 offset:50176
	ds_read_b128 v[168:171], v245 offset:51200
	ds_read_b128 v[172:175], v245 offset:52224
	ds_read_b128 v[176:179], v245 offset:53248
	ds_read_b128 v[180:183], v245 offset:54272
	ds_read_b128 v[184:187], v245 offset:55296
	ds_read_b128 v[188:191], v245 offset:56320
	s_waitcnt vmcnt(8)
	s_waitcnt lgkmcnt(0)
	s_barrier
	s_setprio 1
	s_waitcnt lgkmcnt(0)
	v_mfma_f32_16x16x32_bf16 v[60:63], v[120:123], v[160:163], v[60:63]
	v_mfma_f32_16x16x32_bf16 v[56:59], v[128:131], v[160:163], v[56:59]
	v_mfma_f32_16x16x32_bf16 v[44:47], v[120:123], v[168:171], v[44:47]
	v_mfma_f32_16x16x32_bf16 v[40:43], v[128:131], v[168:171], v[40:43]
	v_mfma_f32_16x16x32_bf16 v[28:31], v[120:123], v[176:179], v[28:31]
	v_mfma_f32_16x16x32_bf16 v[24:27], v[128:131], v[176:179], v[24:27]
	v_mfma_f32_16x16x32_bf16 v[12:15], v[120:123], v[184:187], v[12:15]
	v_mfma_f32_16x16x32_bf16 v[8:11], v[128:131], v[184:187], v[8:11]
	v_mfma_f32_16x16x32_bf16 v[60:63], v[124:127], v[164:167], v[60:63]
	v_mfma_f32_16x16x32_bf16 v[56:59], v[132:135], v[164:167], v[56:59]
	v_mfma_f32_16x16x32_bf16 v[44:47], v[124:127], v[172:175], v[44:47]
	v_mfma_f32_16x16x32_bf16 v[40:43], v[132:135], v[172:175], v[40:43]
	v_mfma_f32_16x16x32_bf16 v[28:31], v[124:127], v[180:183], v[28:31]
	v_mfma_f32_16x16x32_bf16 v[24:27], v[132:135], v[180:183], v[24:27]
	v_mfma_f32_16x16x32_bf16 v[12:15], v[124:127], v[188:191], v[12:15]
	v_mfma_f32_16x16x32_bf16 v[8:11], v[132:135], v[188:191], v[8:11]
	s_setprio 0
	s_setprio 1
	v_mfma_f32_16x16x32_bf16 v[52:55], v[136:139], v[160:163], v[52:55]
	v_mfma_f32_16x16x32_bf16 v[48:51], v[152:155], v[160:163], v[48:51]
	v_mfma_f32_16x16x32_bf16 v[36:39], v[136:139], v[168:171], v[36:39]
	v_mfma_f32_16x16x32_bf16 v[32:35], v[152:155], v[168:171], v[32:35]
	v_mfma_f32_16x16x32_bf16 v[20:23], v[136:139], v[176:179], v[20:23]
	v_mfma_f32_16x16x32_bf16 v[16:19], v[152:155], v[176:179], v[16:19]
	v_mfma_f32_16x16x32_bf16 v[4:7], v[136:139], v[184:187], v[4:7]
	v_mfma_f32_16x16x32_bf16 v[0:3], v[152:155], v[184:187], v[0:3]
	v_mfma_f32_16x16x32_bf16 v[52:55], v[140:143], v[164:167], v[52:55]
	v_mfma_f32_16x16x32_bf16 v[48:51], v[156:159], v[164:167], v[48:51]
	v_mfma_f32_16x16x32_bf16 v[36:39], v[140:143], v[172:175], v[36:39]
	v_mfma_f32_16x16x32_bf16 v[32:35], v[156:159], v[172:175], v[32:35]
	v_mfma_f32_16x16x32_bf16 v[20:23], v[140:143], v[180:183], v[20:23]
	v_mfma_f32_16x16x32_bf16 v[16:19], v[156:159], v[180:183], v[16:19]
	v_mfma_f32_16x16x32_bf16 v[4:7], v[140:143], v[188:191], v[4:7]
	v_mfma_f32_16x16x32_bf16 v[0:3], v[156:159], v[188:191], v[0:3]
	s_setprio 0
	s_barrier
	s_add_i32 s56, s56, 2
	s_add_u32 s36, s36, 0x100
	s_addc_u32 s37, s37, 0
	s_add_u32 s54, s54, 0x100
	s_addc_u32 s55, s55, 0
	s_cmp_gt_u32 s56, 5
	s_cbranch_scc0 .LBB0_962
	s_and_b64 vcc, exec, s[22:23]
	s_cbranch_vccz .LBB0_965
	s_barrier

; #define PG8_STAGE(bufoff, gbase, voff) do { _Pragma("unroll") for (int _i = 0; _i < 2; ++_i) \
;         __builtin_amdgcn_global_load_lds((const unsigned*)((const char*)(gbase) + (voff)[_i]), (LAS unsigned*)(lds + (bufoff) + ldsw + _i * 8192), 16, 0, 0); } while (0)
; #define PG8_LDA(dst, b, h) do { _Pragma("unroll") for (int m = 0; m < 4; ++m) _Pragma("unroll") for (int k = 0; k < 2; ++k) dst[m][k] = *(const LAS bf16x8*)(lds + PG8_SA(b, h) + aoff + m * 2048 + k * 1024); } while (0)
; #define PG8_LDB(dst, b, h) do { _Pragma("unroll") for (int n = 0; n < 2; ++n) _Pragma("unroll") for (int k = 0; k < 2; ++k) dst[n][k] = *(const LAS bf16x8*)(lds + PG8_SB(b, h) + boff + n * 2048 + k * 1024); } while (0)
; #define PG8_MMA(ai, bj, At, Bt) do { __builtin_amdgcn_s_setprio(1); _Pragma("unroll") for (int m = 0; m < 4; ++m) _Pragma("unroll") for (int n = 0; n < 2; ++n) _Pragma("unroll") for (int k = 0; k < 2; ++k) \
;         acc[ai][bj][m][n] = __builtin_amdgcn_mfma_f32_16x16x32_bf16(Bt[n][k], At[m][k], acc[ai][bj][m][n], 0, 0, 0); __builtin_amdgcn_s_setprio(0); } while (0)
; #define PG8_WAIT_V(n) asm volatile("s_waitcnt vmcnt(" #n ")" ::: "memory")
; #define PG8_WAIT_L(n) asm volatile("s_waitcnt lgkmcnt(" #n ")" ::: "memory")
; #define PG8_BAR __builtin_amdgcn_s_barrier()
; #define PG8_SCHED __builtin_amdgcn_sched_barrier(0)
; template <class Epi>
; __device__ __forceinline__ void gemm_phase(LAS unsigned char* lds, const Gemm g, const StaticOrder& S, const Epi& E, int wave_s) {
;     ...
;             PG8_LDB(B0, 0, 0); PG8_LDB(B1, 0, 1); PG8_SCHED; PG8_LDA(At, 0, 0); PG8_STAGE(PG8_SA(1, 1), a1 + hstepA, voffA);
;             PG8_WAIT_V(8); PG8_WAIT_L(0); PG8_BAR; PG8_MMA(0, 0, At, B0); PG8_MMA(0, 1, At, B1); PG8_BAR; PG8_SCHED;
;             PG8_LDA(At, 0, 1); PG8_STAGE(PG8_SB(0, 0), b2, voffB); PG8_STAGE(PG8_SB(0, 1), b2 + hstepB, voffB); PG8_STAGE(PG8_SA(0, 0), a2, voffA);
;             PG8_WAIT_V(8); PG8_WAIT_L(0); PG8_BAR; PG8_MMA(1, 0, At, B0); PG8_MMA(1, 1, At, B1); PG8_BAR; PG8_SCHED;
.LBB0_1051:
	s_add_u32 s34, s30, 0xfffc0080
	s_addc_u32 s35, s31, -1
	s_cmp_eq_u32 s55, 12
	s_cselect_b32 s37, s9, s35
	s_cselect_b32 s36, s25, s34
	s_cselect_b32 s35, s23, s54
	s_cselect_b32 s34, s52, s53
	v_lshl_add_u64 v[216:217], s[30:31], 0, v[136:137]
	s_add_i32 m0, s39, 0xc000
	s_nop 0
	global_load_lds_dwordx4 v[216:217], off
	v_lshl_add_u64 v[216:217], s[30:31], 0, v[138:139]
	s_add_i32 m0, s39, 0xe000
	s_nop 0
	global_load_lds_dwordx4 v[216:217], off
	ds_read_b128 v[144:147], v155
	ds_read_b128 v[148:151], v155 offset:1024
	ds_read_b128 v[160:163], v155 offset:2048
	ds_read_b128 v[164:167], v155 offset:3072
	ds_read_b128 v[168:171], v156
	ds_read_b128 v[172:175], v156 offset:1024
	ds_read_b128 v[176:179], v156 offset:2048
	ds_read_b128 v[180:183], v156 offset:3072
	ds_read_b128 v[184:187], v157
	ds_read_b128 v[188:191], v157 offset:1024
	ds_read_b128 v[192:195], v157 offset:2048
	ds_read_b128 v[196:199], v157 offset:3072
	ds_read_b128 v[200:203], v157 offset:4096
	ds_read_b128 v[204:207], v157 offset:5120
	ds_read_b128 v[208:211], v157 offset:6144
	ds_read_b128 v[212:215], v157 offset:7168
	s_waitcnt vmcnt(8)
	s_waitcnt lgkmcnt(0)
	s_barrier
	s_setprio 1
	s_waitcnt lgkmcnt(0)
	v_mfma_f32_16x16x32_bf16 v[124:127], v[144:147], v[184:187], v[124:127]
	v_mfma_f32_16x16x32_bf16 v[120:123], v[160:163], v[184:187], v[120:123]
	v_mfma_f32_16x16x32_bf16 v[108:111], v[144:147], v[192:195], v[108:111]
	v_mfma_f32_16x16x32_bf16 v[104:107], v[160:163], v[192:195], v[104:107]
	v_mfma_f32_16x16x32_bf16 v[92:95], v[144:147], v[200:203], v[92:95]
	v_mfma_f32_16x16x32_bf16 v[88:91], v[160:163], v[200:203], v[88:91]
	v_mfma_f32_16x16x32_bf16 v[76:79], v[144:147], v[208:211], v[76:79]
	v_mfma_f32_16x16x32_bf16 v[72:75], v[160:163], v[208:211], v[72:75]
	v_mfma_f32_16x16x32_bf16 v[124:127], v[148:151], v[188:191], v[124:127]
	v_mfma_f32_16x16x32_bf16 v[120:123], v[164:167], v[188:191], v[120:123]
	v_mfma_f32_16x16x32_bf16 v[108:111], v[148:151], v[196:199], v[108:111]
	v_mfma_f32_16x16x32_bf16 v[104:107], v[164:167], v[196:199], v[104:107]
	v_mfma_f32_16x16x32_bf16 v[92:95], v[148:151], v[204:207], v[92:95]
	v_mfma_f32_16x16x32_bf16 v[88:91], v[164:167], v[204:207], v[88:91]
	v_mfma_f32_16x16x32_bf16 v[76:79], v[148:151], v[212:215], v[76:79]
	v_mfma_f32_16x16x32_bf16 v[72:75], v[164:167], v[212:215], v[72:75]
	s_setprio 0
	s_setprio 1
	v_mfma_f32_16x16x32_bf16 v[116:119], v[168:171], v[184:187], v[116:119]
	v_mfma_f32_16x16x32_bf16 v[112:115], v[176:179], v[184:187], v[112:115]
	v_mfma_f32_16x16x32_bf16 v[100:103], v[168:171], v[192:195], v[100:103]
	v_mfma_f32_16x16x32_bf16 v[96:99], v[176:179], v[192:195], v[96:99]
	v_mfma_f32_16x16x32_bf16 v[84:87], v[168:171], v[200:203], v[84:87]
	v_mfma_f32_16x16x32_bf16 v[80:83], v[176:179], v[200:203], v[80:83]
	v_mfma_f32_16x16x32_bf16 v[68:71], v[168:171], v[208:211], v[68:71]
	v_mfma_f32_16x16x32_bf16 v[64:67], v[176:179], v[208:211], v[64:67]
	v_mfma_f32_16x16x32_bf16 v[116:119], v[172:175], v[188:191], v[116:119]
	v_mfma_f32_16x16x32_bf16 v[112:115], v[180:183], v[188:191], v[112:115]
	v_mfma_f32_16x16x32_bf16 v[100:103], v[172:175], v[196:199], v[100:103]
	v_mfma_f32_16x16x32_bf16 v[96:99], v[180:183], v[196:199], v[96:99]
	v_mfma_f32_16x16x32_bf16 v[84:87], v[172:175], v[204:207], v[84:87]
	v_mfma_f32_16x16x32_bf16 v[80:83], v[180:183], v[204:207], v[80:83]
	v_mfma_f32_16x16x32_bf16 v[68:71], v[172:175], v[212:215], v[68:71]
	v_mfma_f32_16x16x32_bf16 v[64:67], v[180:183], v[212:215], v[64:67]
	s_setprio 0
	s_barrier
	s_add_i32 s56, s48, s5
	v_lshl_add_u64 v[216:217], s[34:35], 0, v[132:133]
	s_mov_b32 m0, s56
	s_nop 0
	global_load_lds_dwordx4 v[216:217], off
	s_add_i32 m0, s56, 0x2000
	s_add_u32 s56, s34, 0x40000
	v_lshl_add_u64 v[218:219], s[34:35], 0, v[128:129]
	s_addc_u32 s57, s35, 0
	s_add_i32 s58, s49, s5
	global_load_lds_dwordx4 v[218:219], off
	v_lshl_add_u64 v[220:221], s[56:57], 0, v[132:133]
	s_mov_b32 m0, s58
	v_lshl_add_u64 v[222:223], s[36:37], 0, v[130:131]
	global_load_lds_dwordx4 v[220:221], off
	v_lshl_add_u64 v[220:221], s[56:57], 0, v[128:129]
	s_add_i32 m0, s58, 0x2000
	s_nop 0
	global_load_lds_dwordx4 v[220:221], off
	v_lshl_add_u64 v[220:221], s[36:37], 0, v[134:135]
	s_mov_b32 m0, s39
	s_nop 0
	global_load_lds_dwordx4 v[220:221], off
	s_mov_b32 m0, s40
	s_nop 0
	global_load_lds_dwordx4 v[222:223], off
	ds_read_b128 v[184:187], v157 offset:16384
	ds_read_b128 v[188:191], v157 offset:17408
	ds_read_b128 v[192:195], v157 offset:18432
	ds_read_b128 v[196:199], v157 offset:19456
	ds_read_b128 v[200:203], v157 offset:20480
	ds_read_b128 v[204:207], v157 offset:21504
	ds_read_b128 v[208:211], v157 offset:22528
	ds_read_b128 v[212:215], v157 offset:23552
	s_waitcnt vmcnt(8)
	s_waitcnt lgkmcnt(0)
	s_barrier
; #define PG8_STAGE(bufoff, gbase, voff) do { _Pragma("unroll") for (int _i = 0; _i < 2; ++_i) \
;         __builtin_amdgcn_global_load_lds((const unsigned*)((const char*)(gbase) + (voff)[_i]), (LAS unsigned*)(lds + (bufoff) + ldsw + _i * 8192), 16, 0, 0); } while (0)
; #define PG8_LDA(dst, b, h) do { _Pragma("unroll") for (int m = 0; m < 4; ++m) _Pragma("unroll") for (int k = 0; k < 2; ++k) dst[m][k] = *(const LAS bf16x8*)(lds + PG8_SA(b, h) + aoff + m * 2048 + k * 1024); } while (0)
; #define PG8_LDB(dst, b, h) do { _Pragma("unroll") for (int n = 0; n < 2; ++n) _Pragma("unroll") for (int k = 0; k < 2; ++k) dst[n][k] = *(const LAS bf16x8*)(lds + PG8_SB(b, h) + boff + n * 2048 + k * 1024); } while (0)
; #define PG8_MMA(ai, bj, At, Bt) do { __builtin_amdgcn_s_setprio(1); _Pragma("unroll") for (int m = 0; m < 4; ++m) _Pragma("unroll") for (int n = 0; n < 2; ++n) _Pragma("unroll") for (int k = 0; k < 2; ++k) \
;         acc[ai][bj][m][n] = __builtin_amdgcn_mfma_f32_16x16x32_bf16(Bt[n][k], At[m][k], acc[ai][bj][m][n], 0, 0, 0); __builtin_amdgcn_s_setprio(0); } while (0)
; #define PG8_WAIT_V(n) asm volatile("s_waitcnt vmcnt(" #n ")" ::: "memory")
; #define PG8_WAIT_L(n) asm volatile("s_waitcnt lgkmcnt(" #n ")" ::: "memory")
; #define PG8_BAR __builtin_amdgcn_s_barrier()
; #define PG8_SCHED __builtin_amdgcn_sched_barrier(0)
; template <class Epi>
; __device__ __forceinline__ void gemm_phase(LAS unsigned char* lds, const Gemm g, const StaticOrder& S, const Epi& E, int wave_s) {
;     ...
;             PG8_WAIT_V(8); PG8_WAIT_L(0); PG8_BAR; PG8_MMA(1, 0, At, B0); PG8_MMA(1, 1, At, B1); PG8_BAR; PG8_SCHED;
;             PG8_LDB(B0, 1, 0); PG8_LDB(B1, 1, 1); PG8_SCHED; PG8_LDA(At, 1, 0); PG8_STAGE(PG8_SA(0, 1), a2 + hstepA, voffA);
;             PG8_WAIT_V(8); PG8_WAIT_L(0); PG8_BAR; PG8_MMA(0, 0, At, B0); PG8_MMA(0, 1, At, B1); PG8_BAR; PG8_SCHED;
	s_setprio 1
	s_waitcnt lgkmcnt(0)
	v_mfma_f32_16x16x32_bf16 v[60:63], v[144:147], v[184:187], v[60:63]
	v_mfma_f32_16x16x32_bf16 v[56:59], v[160:163], v[184:187], v[56:59]
	v_mfma_f32_16x16x32_bf16 v[44:47], v[144:147], v[192:195], v[44:47]
	v_mfma_f32_16x16x32_bf16 v[40:43], v[160:163], v[192:195], v[40:43]
	v_mfma_f32_16x16x32_bf16 v[28:31], v[144:147], v[200:203], v[28:31]
	v_mfma_f32_16x16x32_bf16 v[24:27], v[160:163], v[200:203], v[24:27]
	v_mfma_f32_16x16x32_bf16 v[12:15], v[144:147], v[208:211], v[12:15]
	v_mfma_f32_16x16x32_bf16 v[8:11], v[160:163], v[208:211], v[8:11]
	v_mfma_f32_16x16x32_bf16 v[60:63], v[148:151], v[188:191], v[60:63]
	v_mfma_f32_16x16x32_bf16 v[56:59], v[164:167], v[188:191], v[56:59]
	v_mfma_f32_16x16x32_bf16 v[44:47], v[148:151], v[196:199], v[44:47]
	v_mfma_f32_16x16x32_bf16 v[40:43], v[164:167], v[196:199], v[40:43]
	v_mfma_f32_16x16x32_bf16 v[28:31], v[148:151], v[204:207], v[28:31]
	v_mfma_f32_16x16x32_bf16 v[24:27], v[164:167], v[204:207], v[24:27]
	v_mfma_f32_16x16x32_bf16 v[12:15], v[148:151], v[212:215], v[12:15]
	v_mfma_f32_16x16x32_bf16 v[8:11], v[164:167], v[212:215], v[8:11]
	s_setprio 0
	s_setprio 1
	v_mfma_f32_16x16x32_bf16 v[52:55], v[168:171], v[184:187], v[52:55]
	v_mfma_f32_16x16x32_bf16 v[48:51], v[176:179], v[184:187], v[48:51]
	v_mfma_f32_16x16x32_bf16 v[36:39], v[168:171], v[192:195], v[36:39]
	v_mfma_f32_16x16x32_bf16 v[32:35], v[176:179], v[192:195], v[32:35]
	v_mfma_f32_16x16x32_bf16 v[20:23], v[168:171], v[200:203], v[20:23]
	v_mfma_f32_16x16x32_bf16 v[16:19], v[176:179], v[200:203], v[16:19]
	v_mfma_f32_16x16x32_bf16 v[4:7], v[168:171], v[208:211], v[4:7]
	v_mfma_f32_16x16x32_bf16 v[0:3], v[176:179], v[208:211], v[0:3]
	v_mfma_f32_16x16x32_bf16 v[52:55], v[172:175], v[188:191], v[52:55]
	v_mfma_f32_16x16x32_bf16 v[48:51], v[180:183], v[188:191], v[48:51]
	v_mfma_f32_16x16x32_bf16 v[36:39], v[172:175], v[196:199], v[36:39]
	v_mfma_f32_16x16x32_bf16 v[32:35], v[180:183], v[196:199], v[32:35]
	v_mfma_f32_16x16x32_bf16 v[20:23], v[172:175], v[204:207], v[20:23]
	v_mfma_f32_16x16x32_bf16 v[16:19], v[180:183], v[204:207], v[16:19]
	v_mfma_f32_16x16x32_bf16 v[4:7], v[172:175], v[212:215], v[4:7]
	v_mfma_f32_16x16x32_bf16 v[0:3], v[180:183], v[212:215], v[0:3]
	s_setprio 0
	s_barrier
	s_add_i32 s56, 0, 0x18000
	s_add_i32 s57, 0, 0x1c000
	s_add_u32 s36, s36, 0x40000
	s_addc_u32 s37, s37, 0
	s_mov_b32 m0, s41
	v_lshl_add_u64 v[224:225], s[36:37], 0, v[134:135]
	global_load_lds_dwordx4 v[224:225], off
	v_lshl_add_u64 v[224:225], s[36:37], 0, v[130:131]
	s_mov_b32 m0, s42
	s_nop 0
	global_load_lds_dwordx4 v[224:225], off
	v_add_u32_e32 v164, s56, v153
	v_add_u32_e32 v180, s57, v153
	ds_read_b128 v[144:147], v164
	ds_read_b128 v[148:151], v164 offset:1024
	ds_read_b128 v[160:163], v164 offset:2048
	ds_read_b128 v[164:167], v164 offset:3072
	ds_read_b128 v[168:171], v180
	ds_read_b128 v[172:175], v180 offset:1024
	ds_read_b128 v[176:179], v180 offset:2048
	ds_read_b128 v[180:183], v180 offset:3072
	ds_read_b128 v[184:187], v157 offset:32768
	ds_read_b128 v[188:191], v157 offset:33792
	ds_read_b128 v[192:195], v157 offset:34816
	ds_read_b128 v[196:199], v157 offset:35840
	ds_read_b128 v[200:203], v157 offset:36864
	ds_read_b128 v[204:207], v157 offset:37888
	ds_read_b128 v[208:211], v157 offset:38912
	ds_read_b128 v[212:215], v157 offset:39936
	s_waitcnt vmcnt(8)
	s_waitcnt lgkmcnt(0)
	s_barrier
	s_setprio 1
	s_waitcnt lgkmcnt(0)
	v_mfma_f32_16x16x32_bf16 v[124:127], v[144:147], v[184:187], v[124:127]
	v_mfma_f32_16x16x32_bf16 v[120:123], v[160:163], v[184:187], v[120:123]
	v_mfma_f32_16x16x32_bf16 v[108:111], v[144:147], v[192:195], v[108:111]
	v_mfma_f32_16x16x32_bf16 v[104:107], v[160:163], v[192:195], v[104:107]
	v_mfma_f32_16x16x32_bf16 v[92:95], v[144:147], v[200:203], v[92:95]
	v_mfma_f32_16x16x32_bf16 v[88:91], v[160:163], v[200:203], v[88:91]
	v_mfma_f32_16x16x32_bf16 v[76:79], v[144:147], v[208:211], v[76:79]
	v_mfma_f32_16x16x32_bf16 v[72:75], v[160:163], v[208:211], v[72:75]
	v_mfma_f32_16x16x32_bf16 v[124:127], v[148:151], v[188:191], v[124:127]
	v_mfma_f32_16x16x32_bf16 v[120:123], v[164:167], v[188:191], v[120:123]
	v_mfma_f32_16x16x32_bf16 v[108:111], v[148:151], v[196:199], v[108:111]
	v_mfma_f32_16x16x32_bf16 v[104:107], v[164:167], v[196:199], v[104:107]
	v_mfma_f32_16x16x32_bf16 v[92:95], v[148:151], v[204:207], v[92:95]
	v_mfma_f32_16x16x32_bf16 v[88:91], v[164:167], v[204:207], v[88:91]
	v_mfma_f32_16x16x32_bf16 v[76:79], v[148:151], v[212:215], v[76:79]
	v_mfma_f32_16x16x32_bf16 v[72:75], v[164:167], v[212:215], v[72:75]
	s_setprio 0
	s_setprio 1
	v_mfma_f32_16x16x32_bf16 v[116:119], v[168:171], v[184:187], v[116:119]
	v_mfma_f32_16x16x32_bf16 v[112:115], v[176:179], v[184:187], v[112:115]
	v_mfma_f32_16x16x32_bf16 v[100:103], v[168:171], v[192:195], v[100:103]
	v_mfma_f32_16x16x32_bf16 v[96:99], v[176:179], v[192:195], v[96:99]
	v_mfma_f32_16x16x32_bf16 v[84:87], v[168:171], v[200:203], v[84:87]
	v_mfma_f32_16x16x32_bf16 v[80:83], v[176:179], v[200:203], v[80:83]
	v_mfma_f32_16x16x32_bf16 v[68:71], v[168:171], v[208:211], v[68:71]
	v_mfma_f32_16x16x32_bf16 v[64:67], v[176:179], v[208:211], v[64:67]
	v_mfma_f32_16x16x32_bf16 v[116:119], v[172:175], v[188:191], v[116:119]
	v_mfma_f32_16x16x32_bf16 v[112:115], v[180:183], v[188:191], v[112:115]
	v_mfma_f32_16x16x32_bf16 v[100:103], v[172:175], v[196:199], v[100:103]
	v_mfma_f32_16x16x32_bf16 v[96:99], v[180:183], v[196:199], v[96:99]
	v_mfma_f32_16x16x32_bf16 v[84:87], v[172:175], v[204:207], v[84:87]
	v_mfma_f32_16x16x32_bf16 v[80:83], v[180:183], v[204:207], v[80:83]
	v_mfma_f32_16x16x32_bf16 v[68:71], v[172:175], v[212:215], v[68:71]
	v_mfma_f32_16x16x32_bf16 v[64:67], v[180:183], v[212:215], v[64:67]
	s_setprio 0
	s_barrier
; #define PG8_STAGE(bufoff, gbase, voff) do { _Pragma("unroll") for (int _i = 0; _i < 2; ++_i) \
;         __builtin_amdgcn_global_load_lds((const unsigned*)((const char*)(gbase) + (voff)[_i]), (LAS unsigned*)(lds + (bufoff) + ldsw + _i * 8192), 16, 0, 0); } while (0)
; #define PG8_LDA(dst, b, h) do { _Pragma("unroll") for (int m = 0; m < 4; ++m) _Pragma("unroll") for (int k = 0; k < 2; ++k) dst[m][k] = *(const LAS bf16x8*)(lds + PG8_SA(b, h) + aoff + m * 2048 + k * 1024); } while (0)
; #define PG8_MMA(ai, bj, At, Bt) do { __builtin_amdgcn_s_setprio(1); _Pragma("unroll") for (int m = 0; m < 4; ++m) _Pragma("unroll") for (int n = 0; n < 2; ++n) _Pragma("unroll") for (int k = 0; k < 2; ++k) \
;         acc[ai][bj][m][n] = __builtin_amdgcn_mfma_f32_16x16x32_bf16(Bt[n][k], At[m][k], acc[ai][bj][m][n], 0, 0, 0); __builtin_amdgcn_s_setprio(0); } while (0)
; #define PG8_WAIT_V(n) asm volatile("s_waitcnt vmcnt(" #n ")" ::: "memory")
; #define PG8_WAIT_L(n) asm volatile("s_waitcnt lgkmcnt(" #n ")" ::: "memory")
; #define PG8_BAR __builtin_amdgcn_s_barrier()
; #define PG8_SCHED __builtin_amdgcn_sched_barrier(0)
; template <class Epi>
; __device__ __forceinline__ void gemm_phase(LAS unsigned char* lds, const Gemm g, const StaticOrder& S, const Epi& E, int wave_s) {
;     ...
;             PG8_LDA(At, 1, 1); PG8_STAGE(PG8_SB(1, 0), b3, voffB); PG8_STAGE(PG8_SB(1, 1), b3 + hstepB, voffB); PG8_STAGE(PG8_SA(1, 0), a3, voffA);
;             PG8_WAIT_V(8); PG8_WAIT_L(0); PG8_BAR; PG8_MMA(1, 0, At, B0); PG8_MMA(1, 1, At, B1); PG8_BAR; PG8_SCHED;
;         }
	s_add_i32 s36, s56, s5
	v_lshl_add_u64 v[216:217], v[216:217], 0, s[18:19]
	s_mov_b32 m0, s36
	s_nop 0
	global_load_lds_dwordx4 v[216:217], off
	s_add_i32 m0, s36, 0x2000
	s_add_u32 s34, s34, 0x40080
	v_lshl_add_u64 v[216:217], v[218:219], 0, s[18:19]
	s_addc_u32 s35, s35, 0
	s_add_i32 s36, s57, s5
	global_load_lds_dwordx4 v[216:217], off
	v_lshl_add_u64 v[216:217], s[34:35], 0, v[132:133]
	s_mov_b32 m0, s36
	s_nop 0
	global_load_lds_dwordx4 v[216:217], off
	v_lshl_add_u64 v[216:217], s[34:35], 0, v[128:129]
	s_add_i32 m0, s36, 0x2000
	s_nop 0
	global_load_lds_dwordx4 v[216:217], off
	v_lshl_add_u64 v[216:217], v[220:221], 0, s[18:19]
	s_mov_b32 m0, s45
	s_nop 0
	global_load_lds_dwordx4 v[216:217], off
	v_lshl_add_u64 v[216:217], v[222:223], 0, s[18:19]
	s_mov_b32 m0, s46
	s_nop 0
	global_load_lds_dwordx4 v[216:217], off
	ds_read_b128 v[184:187], v157 offset:49152
	ds_read_b128 v[188:191], v157 offset:50176
	ds_read_b128 v[192:195], v157 offset:51200
	ds_read_b128 v[196:199], v157 offset:52224
	ds_read_b128 v[200:203], v157 offset:53248
	ds_read_b128 v[204:207], v157 offset:54272
	ds_read_b128 v[208:211], v157 offset:55296
	ds_read_b128 v[212:215], v157 offset:56320
	s_waitcnt vmcnt(8)
	s_waitcnt lgkmcnt(0)
	s_barrier
	s_setprio 1
	s_waitcnt lgkmcnt(0)
	v_mfma_f32_16x16x32_bf16 v[60:63], v[144:147], v[184:187], v[60:63]
	v_mfma_f32_16x16x32_bf16 v[56:59], v[160:163], v[184:187], v[56:59]
	v_mfma_f32_16x16x32_bf16 v[44:47], v[144:147], v[192:195], v[44:47]
	v_mfma_f32_16x16x32_bf16 v[40:43], v[160:163], v[192:195], v[40:43]
	v_mfma_f32_16x16x32_bf16 v[28:31], v[144:147], v[200:203], v[28:31]
	v_mfma_f32_16x16x32_bf16 v[24:27], v[160:163], v[200:203], v[24:27]
	v_mfma_f32_16x16x32_bf16 v[12:15], v[144:147], v[208:211], v[12:15]
	v_mfma_f32_16x16x32_bf16 v[8:11], v[160:163], v[208:211], v[8:11]
	v_mfma_f32_16x16x32_bf16 v[60:63], v[148:151], v[188:191], v[60:63]
	v_mfma_f32_16x16x32_bf16 v[56:59], v[164:167], v[188:191], v[56:59]
	v_mfma_f32_16x16x32_bf16 v[44:47], v[148:151], v[196:199], v[44:47]
	v_mfma_f32_16x16x32_bf16 v[40:43], v[164:167], v[196:199], v[40:43]
	v_mfma_f32_16x16x32_bf16 v[28:31], v[148:151], v[204:207], v[28:31]
	v_mfma_f32_16x16x32_bf16 v[24:27], v[164:167], v[204:207], v[24:27]
	v_mfma_f32_16x16x32_bf16 v[12:15], v[148:151], v[212:215], v[12:15]
	v_mfma_f32_16x16x32_bf16 v[8:11], v[164:167], v[212:215], v[8:11]
	s_setprio 0
	s_setprio 1
	v_mfma_f32_16x16x32_bf16 v[52:55], v[168:171], v[184:187], v[52:55]
	v_mfma_f32_16x16x32_bf16 v[48:51], v[176:179], v[184:187], v[48:51]
	v_mfma_f32_16x16x32_bf16 v[36:39], v[168:171], v[192:195], v[36:39]
	v_mfma_f32_16x16x32_bf16 v[32:35], v[176:179], v[192:195], v[32:35]
	v_mfma_f32_16x16x32_bf16 v[20:23], v[168:171], v[200:203], v[20:23]
	v_mfma_f32_16x16x32_bf16 v[16:19], v[176:179], v[200:203], v[16:19]
	v_mfma_f32_16x16x32_bf16 v[4:7], v[168:171], v[208:211], v[4:7]
	v_mfma_f32_16x16x32_bf16 v[0:3], v[176:179], v[208:211], v[0:3]
	v_mfma_f32_16x16x32_bf16 v[52:55], v[172:175], v[188:191], v[52:55]
	v_mfma_f32_16x16x32_bf16 v[48:51], v[180:183], v[188:191], v[48:51]
	v_mfma_f32_16x16x32_bf16 v[36:39], v[172:175], v[196:199], v[36:39]
	v_mfma_f32_16x16x32_bf16 v[32:35], v[180:183], v[196:199], v[32:35]
	v_mfma_f32_16x16x32_bf16 v[20:23], v[172:175], v[204:207], v[20:23]
	v_mfma_f32_16x16x32_bf16 v[16:19], v[180:183], v[204:207], v[16:19]
	v_mfma_f32_16x16x32_bf16 v[4:7], v[172:175], v[212:215], v[4:7]
	v_mfma_f32_16x16x32_bf16 v[0:3], v[180:183], v[212:215], v[0:3]
	s_setprio 0
	s_barrier
	s_add_i32 s55, s55, 2
	s_add_u32 s30, s30, 0x100
	s_addc_u32 s31, s31, 0
	s_add_u32 s53, s53, 0x100
	s_addc_u32 s54, s54, 0
	s_cmp_gt_u32 s55, 13
	s_cbranch_scc0 .LBB0_1051
	s_and_b64 vcc, exec, s[20:21]
	s_cbranch_vccz .LBB0_1054
	s_barrier

; #define PG8_STAGE(bufoff, gbase, voff) do { _Pragma("unroll") for (int _i = 0; _i < 2; ++_i) \
;         __builtin_amdgcn_global_load_lds((const unsigned*)((const char*)(gbase) + (voff)[_i]), (LAS unsigned*)(lds + (bufoff) + ldsw + _i * 8192), 16, 0, 0); } while (0)
; #define PG8_LDA(dst, b, h) do { _Pragma("unroll") for (int m = 0; m < 4; ++m) _Pragma("unroll") for (int k = 0; k < 2; ++k) dst[m][k] = *(const LAS bf16x8*)(lds + PG8_SA(b, h) + aoff + m * 2048 + k * 1024); } while (0)
; #define PG8_LDB(dst, b, h) do { _Pragma("unroll") for (int n = 0; n < 2; ++n) _Pragma("unroll") for (int k = 0; k < 2; ++k) dst[n][k] = *(const LAS bf16x8*)(lds + PG8_SB(b, h) + boff + n * 2048 + k * 1024); } while (0)
; #define PG8_MMA(ai, bj, At, Bt) do { __builtin_amdgcn_s_setprio(1); _Pragma("unroll") for (int m = 0; m < 4; ++m) _Pragma("unroll") for (int n = 0; n < 2; ++n) _Pragma("unroll") for (int k = 0; k < 2; ++k) \
;         acc[ai][bj][m][n] = __builtin_amdgcn_mfma_f32_16x16x32_bf16(Bt[n][k], At[m][k], acc[ai][bj][m][n], 0, 0, 0); __builtin_amdgcn_s_setprio(0); } while (0)
; #define PG8_WAIT_V(n) asm volatile("s_waitcnt vmcnt(" #n ")" ::: "memory")
; #define PG8_WAIT_L(n) asm volatile("s_waitcnt lgkmcnt(" #n ")" ::: "memory")
; #define PG8_BAR __builtin_amdgcn_s_barrier()
; #define PG8_SCHED __builtin_amdgcn_sched_barrier(0)
; template <class Epi>
; __device__ __forceinline__ void gemm_phase(LAS unsigned char* lds, const Gemm g, const StaticOrder& S, const Epi& E, int wave_s) {
;     ...
;             PG8_LDB(B0, 0, 0); PG8_LDB(B1, 0, 1); PG8_SCHED; PG8_LDA(At, 0, 0); PG8_STAGE(PG8_SA(1, 1), a1 + hstepA, voffA);
;             PG8_WAIT_V(8); PG8_WAIT_L(0); PG8_BAR; PG8_MMA(0, 0, At, B0); PG8_MMA(0, 1, At, B1); PG8_BAR; PG8_SCHED;
;             PG8_LDA(At, 0, 1); PG8_STAGE(PG8_SB(0, 0), b2, voffB); PG8_STAGE(PG8_SB(0, 1), b2 + hstepB, voffB); PG8_STAGE(PG8_SA(0, 0), a2, voffA);
;             PG8_WAIT_V(8); PG8_WAIT_L(0); PG8_BAR; PG8_MMA(1, 0, At, B0); PG8_MMA(1, 1, At, B1); PG8_BAR; PG8_SCHED;
.LBB0_1138:
	s_add_u32 s30, s28, 0x100
	s_addc_u32 s31, s29, 0
	s_cmp_eq_u32 s54, 40
	s_cselect_b32 s37, s11, s31
	s_cselect_b32 s36, s10, s30
	s_cselect_b32 s35, s27, s53
	s_cselect_b32 s34, s26, s52
	v_lshl_add_u64 v[204:205], s[28:29], 0, v[200:201]
	s_add_i32 m0, s5, 0xc000
	s_nop 0
	global_load_lds_dwordx4 v[204:205], off
	v_lshl_add_u64 v[204:205], s[28:29], 0, v[202:203]
	s_add_i32 m0, s5, 0xe000
	s_nop 0
	global_load_lds_dwordx4 v[204:205], off
	ds_read_b128 v[120:123], v243
	ds_read_b128 v[124:127], v243 offset:1024
	ds_read_b128 v[128:131], v243 offset:2048
	ds_read_b128 v[132:135], v243 offset:3072
	ds_read_b128 v[136:139], v244
	ds_read_b128 v[140:143], v244 offset:1024
	ds_read_b128 v[152:155], v244 offset:2048
	ds_read_b128 v[156:159], v244 offset:3072
	ds_read_b128 v[160:163], v245
	ds_read_b128 v[164:167], v245 offset:1024
	ds_read_b128 v[168:171], v245 offset:2048
	ds_read_b128 v[172:175], v245 offset:3072
	ds_read_b128 v[176:179], v245 offset:4096
	ds_read_b128 v[180:183], v245 offset:5120
	ds_read_b128 v[184:187], v245 offset:6144
	ds_read_b128 v[188:191], v245 offset:7168
	s_waitcnt vmcnt(8)
	s_waitcnt lgkmcnt(0)
	s_barrier
	s_setprio 1
	s_waitcnt lgkmcnt(0)
	v_mfma_f32_16x16x32_bf16 v[148:151], v[120:123], v[160:163], v[148:151]
	v_mfma_f32_16x16x32_bf16 v[144:147], v[128:131], v[160:163], v[144:147]
	v_mfma_f32_16x16x32_bf16 v[108:111], v[120:123], v[168:171], v[108:111]
	v_mfma_f32_16x16x32_bf16 v[104:107], v[128:131], v[168:171], v[104:107]
	v_mfma_f32_16x16x32_bf16 v[92:95], v[120:123], v[176:179], v[92:95]
	v_mfma_f32_16x16x32_bf16 v[88:91], v[128:131], v[176:179], v[88:91]
	v_mfma_f32_16x16x32_bf16 v[76:79], v[120:123], v[184:187], v[76:79]
	v_mfma_f32_16x16x32_bf16 v[72:75], v[128:131], v[184:187], v[72:75]
	v_mfma_f32_16x16x32_bf16 v[148:151], v[124:127], v[164:167], v[148:151]
	v_mfma_f32_16x16x32_bf16 v[144:147], v[132:135], v[164:167], v[144:147]
	v_mfma_f32_16x16x32_bf16 v[108:111], v[124:127], v[172:175], v[108:111]
	v_mfma_f32_16x16x32_bf16 v[104:107], v[132:135], v[172:175], v[104:107]
	v_mfma_f32_16x16x32_bf16 v[92:95], v[124:127], v[180:183], v[92:95]
	v_mfma_f32_16x16x32_bf16 v[88:91], v[132:135], v[180:183], v[88:91]
	v_mfma_f32_16x16x32_bf16 v[76:79], v[124:127], v[188:191], v[76:79]
	v_mfma_f32_16x16x32_bf16 v[72:75], v[132:135], v[188:191], v[72:75]
	s_setprio 0
	s_setprio 1
	v_mfma_f32_16x16x32_bf16 v[116:119], v[136:139], v[160:163], v[116:119]
	v_mfma_f32_16x16x32_bf16 v[112:115], v[152:155], v[160:163], v[112:115]
	v_mfma_f32_16x16x32_bf16 v[100:103], v[136:139], v[168:171], v[100:103]
	v_mfma_f32_16x16x32_bf16 v[96:99], v[152:155], v[168:171], v[96:99]
	v_mfma_f32_16x16x32_bf16 v[84:87], v[136:139], v[176:179], v[84:87]
	v_mfma_f32_16x16x32_bf16 v[80:83], v[152:155], v[176:179], v[80:83]
	v_mfma_f32_16x16x32_bf16 v[68:71], v[136:139], v[184:187], v[68:71]
	v_mfma_f32_16x16x32_bf16 v[64:67], v[152:155], v[184:187], v[64:67]
	v_mfma_f32_16x16x32_bf16 v[116:119], v[140:143], v[164:167], v[116:119]
	v_mfma_f32_16x16x32_bf16 v[112:115], v[156:159], v[164:167], v[112:115]
	v_mfma_f32_16x16x32_bf16 v[100:103], v[140:143], v[172:175], v[100:103]
	v_mfma_f32_16x16x32_bf16 v[96:99], v[156:159], v[172:175], v[96:99]
	v_mfma_f32_16x16x32_bf16 v[84:87], v[140:143], v[180:183], v[84:87]
	v_mfma_f32_16x16x32_bf16 v[80:83], v[156:159], v[180:183], v[80:83]
	v_mfma_f32_16x16x32_bf16 v[68:71], v[140:143], v[188:191], v[68:71]
	v_mfma_f32_16x16x32_bf16 v[64:67], v[156:159], v[188:191], v[64:67]
	s_setprio 0
	s_barrier
	s_add_i32 s28, s46, s4
	v_lshl_add_u64 v[204:205], s[34:35], 0, v[194:195]
	s_mov_b32 m0, s28
	s_nop 0
	global_load_lds_dwordx4 v[204:205], off
	s_add_i32 m0, s28, 0x2000
	s_add_u32 s28, s34, 0xb0000
	v_lshl_add_u64 v[206:207], s[34:35], 0, v[198:199]
	s_addc_u32 s29, s35, 0
	s_add_i32 s55, s47, s4
	global_load_lds_dwordx4 v[206:207], off
	v_lshl_add_u64 v[208:209], s[28:29], 0, v[194:195]
	s_mov_b32 m0, s55
	v_lshl_add_u64 v[210:211], s[36:37], 0, v[196:197]
	global_load_lds_dwordx4 v[208:209], off
	v_lshl_add_u64 v[208:209], s[28:29], 0, v[198:199]
	s_add_i32 m0, s55, 0x2000
	s_nop 0
	global_load_lds_dwordx4 v[208:209], off
	v_lshl_add_u64 v[208:209], s[36:37], 0, v[192:193]
	s_mov_b32 m0, s5
	s_nop 0
	global_load_lds_dwordx4 v[208:209], off
	s_mov_b32 m0, s33
	s_nop 0
	global_load_lds_dwordx4 v[210:211], off
	ds_read_b128 v[160:163], v245 offset:16384
	ds_read_b128 v[164:167], v245 offset:17408
	ds_read_b128 v[168:171], v245 offset:18432
	ds_read_b128 v[172:175], v245 offset:19456
	ds_read_b128 v[176:179], v245 offset:20480
	ds_read_b128 v[180:183], v245 offset:21504
	ds_read_b128 v[184:187], v245 offset:22528
	ds_read_b128 v[188:191], v245 offset:23552
	s_waitcnt vmcnt(8)
	s_waitcnt lgkmcnt(0)
	s_barrier
; #define PG8_STAGE(bufoff, gbase, voff) do { _Pragma("unroll") for (int _i = 0; _i < 2; ++_i) \
;         __builtin_amdgcn_global_load_lds((const unsigned*)((const char*)(gbase) + (voff)[_i]), (LAS unsigned*)(lds + (bufoff) + ldsw + _i * 8192), 16, 0, 0); } while (0)
; #define PG8_LDA(dst, b, h) do { _Pragma("unroll") for (int m = 0; m < 4; ++m) _Pragma("unroll") for (int k = 0; k < 2; ++k) dst[m][k] = *(const LAS bf16x8*)(lds + PG8_SA(b, h) + aoff + m * 2048 + k * 1024); } while (0)
; #define PG8_LDB(dst, b, h) do { _Pragma("unroll") for (int n = 0; n < 2; ++n) _Pragma("unroll") for (int k = 0; k < 2; ++k) dst[n][k] = *(const LAS bf16x8*)(lds + PG8_SB(b, h) + boff + n * 2048 + k * 1024); } while (0)
; #define PG8_MMA(ai, bj, At, Bt) do { __builtin_amdgcn_s_setprio(1); _Pragma("unroll") for (int m = 0; m < 4; ++m) _Pragma("unroll") for (int n = 0; n < 2; ++n) _Pragma("unroll") for (int k = 0; k < 2; ++k) \
;         acc[ai][bj][m][n] = __builtin_amdgcn_mfma_f32_16x16x32_bf16(Bt[n][k], At[m][k], acc[ai][bj][m][n], 0, 0, 0); __builtin_amdgcn_s_setprio(0); } while (0)
; #define PG8_WAIT_V(n) asm volatile("s_waitcnt vmcnt(" #n ")" ::: "memory")
; #define PG8_WAIT_L(n) asm volatile("s_waitcnt lgkmcnt(" #n ")" ::: "memory")
; #define PG8_BAR __builtin_amdgcn_s_barrier()
; #define PG8_SCHED __builtin_amdgcn_sched_barrier(0)
; template <class Epi>
; __device__ __forceinline__ void gemm_phase(LAS unsigned char* lds, const Gemm g, const StaticOrder& S, const Epi& E, int wave_s) {
;     ...
;             PG8_WAIT_V(8); PG8_WAIT_L(0); PG8_BAR; PG8_MMA(1, 0, At, B0); PG8_MMA(1, 1, At, B1); PG8_BAR; PG8_SCHED;
;             PG8_LDB(B0, 1, 0); PG8_LDB(B1, 1, 1); PG8_SCHED; PG8_LDA(At, 1, 0); PG8_STAGE(PG8_SA(0, 1), a2 + hstepA, voffA);
;             PG8_WAIT_V(8); PG8_WAIT_L(0); PG8_BAR; PG8_MMA(0, 0, At, B0); PG8_MMA(0, 1, At, B1); PG8_BAR; PG8_SCHED;
	s_setprio 1
	s_waitcnt lgkmcnt(0)
	v_mfma_f32_16x16x32_bf16 v[60:63], v[120:123], v[160:163], v[60:63]
	v_mfma_f32_16x16x32_bf16 v[56:59], v[128:131], v[160:163], v[56:59]
	v_mfma_f32_16x16x32_bf16 v[44:47], v[120:123], v[168:171], v[44:47]
	v_mfma_f32_16x16x32_bf16 v[40:43], v[128:131], v[168:171], v[40:43]
	v_mfma_f32_16x16x32_bf16 v[28:31], v[120:123], v[176:179], v[28:31]
	v_mfma_f32_16x16x32_bf16 v[24:27], v[128:131], v[176:179], v[24:27]
	v_mfma_f32_16x16x32_bf16 v[12:15], v[120:123], v[184:187], v[12:15]
	v_mfma_f32_16x16x32_bf16 v[8:11], v[128:131], v[184:187], v[8:11]
	v_mfma_f32_16x16x32_bf16 v[60:63], v[124:127], v[164:167], v[60:63]
	v_mfma_f32_16x16x32_bf16 v[56:59], v[132:135], v[164:167], v[56:59]
	v_mfma_f32_16x16x32_bf16 v[44:47], v[124:127], v[172:175], v[44:47]
	v_mfma_f32_16x16x32_bf16 v[40:43], v[132:135], v[172:175], v[40:43]
	v_mfma_f32_16x16x32_bf16 v[28:31], v[124:127], v[180:183], v[28:31]
	v_mfma_f32_16x16x32_bf16 v[24:27], v[132:135], v[180:183], v[24:27]
	v_mfma_f32_16x16x32_bf16 v[12:15], v[124:127], v[188:191], v[12:15]
	v_mfma_f32_16x16x32_bf16 v[8:11], v[132:135], v[188:191], v[8:11]
	s_setprio 0
	s_setprio 1
	v_mfma_f32_16x16x32_bf16 v[52:55], v[136:139], v[160:163], v[52:55]
	v_mfma_f32_16x16x32_bf16 v[48:51], v[152:155], v[160:163], v[48:51]
	v_mfma_f32_16x16x32_bf16 v[36:39], v[136:139], v[168:171], v[36:39]
	v_mfma_f32_16x16x32_bf16 v[32:35], v[152:155], v[168:171], v[32:35]
	v_mfma_f32_16x16x32_bf16 v[20:23], v[136:139], v[176:179], v[20:23]
	v_mfma_f32_16x16x32_bf16 v[16:19], v[152:155], v[176:179], v[16:19]
	v_mfma_f32_16x16x32_bf16 v[4:7], v[136:139], v[184:187], v[4:7]
	v_mfma_f32_16x16x32_bf16 v[0:3], v[152:155], v[184:187], v[0:3]
	v_mfma_f32_16x16x32_bf16 v[52:55], v[140:143], v[164:167], v[52:55]
	v_mfma_f32_16x16x32_bf16 v[48:51], v[156:159], v[164:167], v[48:51]
	v_mfma_f32_16x16x32_bf16 v[36:39], v[140:143], v[172:175], v[36:39]
	v_mfma_f32_16x16x32_bf16 v[32:35], v[156:159], v[172:175], v[32:35]
	v_mfma_f32_16x16x32_bf16 v[20:23], v[140:143], v[180:183], v[20:23]
	v_mfma_f32_16x16x32_bf16 v[16:19], v[156:159], v[180:183], v[16:19]
	v_mfma_f32_16x16x32_bf16 v[4:7], v[140:143], v[188:191], v[4:7]
	v_mfma_f32_16x16x32_bf16 v[0:3], v[156:159], v[188:191], v[0:3]
	s_setprio 0
	s_barrier
	s_add_i32 s55, 0, 0x18000
	s_add_i32 s56, 0, 0x1c000
	s_add_u32 s28, s36, 0xb0000
	s_addc_u32 s29, s37, 0
	s_mov_b32 m0, s38
	v_lshl_add_u64 v[212:213], s[28:29], 0, v[192:193]
	global_load_lds_dwordx4 v[212:213], off
	v_lshl_add_u64 v[212:213], s[28:29], 0, v[196:197]
	s_mov_b32 m0, s39
	s_nop 0
	global_load_lds_dwordx4 v[212:213], off
	v_add_u32_e32 v132, s55, v241
	v_add_u32_e32 v156, s56, v241
	ds_read_b128 v[120:123], v132
	ds_read_b128 v[124:127], v132 offset:1024
	ds_read_b128 v[128:131], v132 offset:2048
	ds_read_b128 v[132:135], v132 offset:3072
	ds_read_b128 v[136:139], v156
	ds_read_b128 v[140:143], v156 offset:1024
	ds_read_b128 v[152:155], v156 offset:2048
	ds_read_b128 v[156:159], v156 offset:3072
	ds_read_b128 v[160:163], v245 offset:32768
	ds_read_b128 v[164:167], v245 offset:33792
	ds_read_b128 v[168:171], v245 offset:34816
	ds_read_b128 v[172:175], v245 offset:35840
	ds_read_b128 v[176:179], v245 offset:36864
	ds_read_b128 v[180:183], v245 offset:37888
	ds_read_b128 v[184:187], v245 offset:38912
	ds_read_b128 v[188:191], v245 offset:39936
	s_waitcnt vmcnt(8)
	s_waitcnt lgkmcnt(0)
	s_barrier
	s_setprio 1
	s_waitcnt lgkmcnt(0)
	v_mfma_f32_16x16x32_bf16 v[148:151], v[120:123], v[160:163], v[148:151]
	v_mfma_f32_16x16x32_bf16 v[144:147], v[128:131], v[160:163], v[144:147]
	v_mfma_f32_16x16x32_bf16 v[108:111], v[120:123], v[168:171], v[108:111]
	v_mfma_f32_16x16x32_bf16 v[104:107], v[128:131], v[168:171], v[104:107]
	v_mfma_f32_16x16x32_bf16 v[92:95], v[120:123], v[176:179], v[92:95]
	v_mfma_f32_16x16x32_bf16 v[88:91], v[128:131], v[176:179], v[88:91]
	v_mfma_f32_16x16x32_bf16 v[76:79], v[120:123], v[184:187], v[76:79]
	v_mfma_f32_16x16x32_bf16 v[72:75], v[128:131], v[184:187], v[72:75]
	v_mfma_f32_16x16x32_bf16 v[148:151], v[124:127], v[164:167], v[148:151]
	v_mfma_f32_16x16x32_bf16 v[144:147], v[132:135], v[164:167], v[144:147]
	v_mfma_f32_16x16x32_bf16 v[108:111], v[124:127], v[172:175], v[108:111]
	v_mfma_f32_16x16x32_bf16 v[104:107], v[132:135], v[172:175], v[104:107]
	v_mfma_f32_16x16x32_bf16 v[92:95], v[124:127], v[180:183], v[92:95]
	v_mfma_f32_16x16x32_bf16 v[88:91], v[132:135], v[180:183], v[88:91]
	v_mfma_f32_16x16x32_bf16 v[76:79], v[124:127], v[188:191], v[76:79]
	v_mfma_f32_16x16x32_bf16 v[72:75], v[132:135], v[188:191], v[72:75]
	s_setprio 0
	s_setprio 1
	v_mfma_f32_16x16x32_bf16 v[116:119], v[136:139], v[160:163], v[116:119]
	v_mfma_f32_16x16x32_bf16 v[112:115], v[152:155], v[160:163], v[112:115]
	v_mfma_f32_16x16x32_bf16 v[100:103], v[136:139], v[168:171], v[100:103]
	v_mfma_f32_16x16x32_bf16 v[96:99], v[152:155], v[168:171], v[96:99]
	v_mfma_f32_16x16x32_bf16 v[84:87], v[136:139], v[176:179], v[84:87]
	v_mfma_f32_16x16x32_bf16 v[80:83], v[152:155], v[176:179], v[80:83]
	v_mfma_f32_16x16x32_bf16 v[68:71], v[136:139], v[184:187], v[68:71]
	v_mfma_f32_16x16x32_bf16 v[64:67], v[152:155], v[184:187], v[64:67]
	v_mfma_f32_16x16x32_bf16 v[116:119], v[140:143], v[164:167], v[116:119]
	v_mfma_f32_16x16x32_bf16 v[112:115], v[156:159], v[164:167], v[112:115]
	v_mfma_f32_16x16x32_bf16 v[100:103], v[140:143], v[172:175], v[100:103]
	v_mfma_f32_16x16x32_bf16 v[96:99], v[156:159], v[172:175], v[96:99]
	v_mfma_f32_16x16x32_bf16 v[84:87], v[140:143], v[180:183], v[84:87]
	v_mfma_f32_16x16x32_bf16 v[80:83], v[156:159], v[180:183], v[80:83]
	v_mfma_f32_16x16x32_bf16 v[68:71], v[140:143], v[188:191], v[68:71]
	v_mfma_f32_16x16x32_bf16 v[64:67], v[156:159], v[188:191], v[64:67]
	s_setprio 0
	s_barrier
; #define PG8_STAGE(bufoff, gbase, voff) do { _Pragma("unroll") for (int _i = 0; _i < 2; ++_i) \
;         __builtin_amdgcn_global_load_lds((const unsigned*)((const char*)(gbase) + (voff)[_i]), (LAS unsigned*)(lds + (bufoff) + ldsw + _i * 8192), 16, 0, 0); } while (0)
; #define PG8_LDA(dst, b, h) do { _Pragma("unroll") for (int m = 0; m < 4; ++m) _Pragma("unroll") for (int k = 0; k < 2; ++k) dst[m][k] = *(const LAS bf16x8*)(lds + PG8_SA(b, h) + aoff + m * 2048 + k * 1024); } while (0)
; #define PG8_MMA(ai, bj, At, Bt) do { __builtin_amdgcn_s_setprio(1); _Pragma("unroll") for (int m = 0; m < 4; ++m) _Pragma("unroll") for (int n = 0; n < 2; ++n) _Pragma("unroll") for (int k = 0; k < 2; ++k) \
;         acc[ai][bj][m][n] = __builtin_amdgcn_mfma_f32_16x16x32_bf16(Bt[n][k], At[m][k], acc[ai][bj][m][n], 0, 0, 0); __builtin_amdgcn_s_setprio(0); } while (0)
; #define PG8_WAIT_V(n) asm volatile("s_waitcnt vmcnt(" #n ")" ::: "memory")
; #define PG8_WAIT_L(n) asm volatile("s_waitcnt lgkmcnt(" #n ")" ::: "memory")
; #define PG8_BAR __builtin_amdgcn_s_barrier()
; #define PG8_SCHED __builtin_amdgcn_sched_barrier(0)
; template <class Epi>
; __device__ __forceinline__ void gemm_phase(LAS unsigned char* lds, const Gemm g, const StaticOrder& S, const Epi& E, int wave_s) {
;     ...
;             PG8_LDA(At, 1, 1); PG8_STAGE(PG8_SB(1, 0), b3, voffB); PG8_STAGE(PG8_SB(1, 1), b3 + hstepB, voffB); PG8_STAGE(PG8_SA(1, 0), a3, voffA);
;             PG8_WAIT_V(8); PG8_WAIT_L(0); PG8_BAR; PG8_MMA(1, 0, At, B0); PG8_MMA(1, 1, At, B1); PG8_BAR; PG8_SCHED;
;         }
	s_add_i32 s28, s55, s4
	v_lshl_add_u64 v[204:205], v[204:205], 0, s[22:23]
	s_mov_b32 m0, s28
	s_nop 0
	global_load_lds_dwordx4 v[204:205], off
	s_add_i32 m0, s28, 0x2000
	s_add_u32 s28, s34, 0xb0080
	v_lshl_add_u64 v[204:205], v[206:207], 0, s[22:23]
	s_addc_u32 s29, s35, 0
	s_add_i32 s34, s56, s4
	global_load_lds_dwordx4 v[204:205], off
	v_lshl_add_u64 v[204:205], s[28:29], 0, v[194:195]
	s_mov_b32 m0, s34
	s_nop 0
	global_load_lds_dwordx4 v[204:205], off
	v_lshl_add_u64 v[204:205], s[28:29], 0, v[198:199]
	s_add_i32 m0, s34, 0x2000
	s_nop 0
	global_load_lds_dwordx4 v[204:205], off
	v_lshl_add_u64 v[204:205], v[208:209], 0, s[22:23]
	s_mov_b32 m0, s41
	s_nop 0
	global_load_lds_dwordx4 v[204:205], off
	v_lshl_add_u64 v[204:205], v[210:211], 0, s[22:23]
	s_mov_b32 m0, s42
	s_nop 0
	global_load_lds_dwordx4 v[204:205], off
	ds_read_b128 v[160:163], v245 offset:49152
	ds_read_b128 v[164:167], v245 offset:50176
	ds_read_b128 v[168:171], v245 offset:51200
	ds_read_b128 v[172:175], v245 offset:52224
	ds_read_b128 v[176:179], v245 offset:53248
	ds_read_b128 v[180:183], v245 offset:54272
	ds_read_b128 v[184:187], v245 offset:55296
	ds_read_b128 v[188:191], v245 offset:56320
	s_waitcnt vmcnt(8)
	s_waitcnt lgkmcnt(0)
	s_barrier
	s_setprio 1
	s_waitcnt lgkmcnt(0)
	v_mfma_f32_16x16x32_bf16 v[60:63], v[120:123], v[160:163], v[60:63]
	v_mfma_f32_16x16x32_bf16 v[56:59], v[128:131], v[160:163], v[56:59]
	v_mfma_f32_16x16x32_bf16 v[44:47], v[120:123], v[168:171], v[44:47]
	v_mfma_f32_16x16x32_bf16 v[40:43], v[128:131], v[168:171], v[40:43]
	v_mfma_f32_16x16x32_bf16 v[28:31], v[120:123], v[176:179], v[28:31]
	v_mfma_f32_16x16x32_bf16 v[24:27], v[128:131], v[176:179], v[24:27]
	v_mfma_f32_16x16x32_bf16 v[12:15], v[120:123], v[184:187], v[12:15]
	v_mfma_f32_16x16x32_bf16 v[8:11], v[128:131], v[184:187], v[8:11]
	v_mfma_f32_16x16x32_bf16 v[60:63], v[124:127], v[164:167], v[60:63]
	v_mfma_f32_16x16x32_bf16 v[56:59], v[132:135], v[164:167], v[56:59]
	v_mfma_f32_16x16x32_bf16 v[44:47], v[124:127], v[172:175], v[44:47]
	v_mfma_f32_16x16x32_bf16 v[40:43], v[132:135], v[172:175], v[40:43]
	v_mfma_f32_16x16x32_bf16 v[28:31], v[124:127], v[180:183], v[28:31]
	v_mfma_f32_16x16x32_bf16 v[24:27], v[132:135], v[180:183], v[24:27]
	v_mfma_f32_16x16x32_bf16 v[12:15], v[124:127], v[188:191], v[12:15]
	v_mfma_f32_16x16x32_bf16 v[8:11], v[132:135], v[188:191], v[8:11]
	s_setprio 0
	s_setprio 1
	v_mfma_f32_16x16x32_bf16 v[52:55], v[136:139], v[160:163], v[52:55]
	v_mfma_f32_16x16x32_bf16 v[48:51], v[152:155], v[160:163], v[48:51]
	v_mfma_f32_16x16x32_bf16 v[36:39], v[136:139], v[168:171], v[36:39]
	v_mfma_f32_16x16x32_bf16 v[32:35], v[152:155], v[168:171], v[32:35]
	v_mfma_f32_16x16x32_bf16 v[20:23], v[136:139], v[176:179], v[20:23]
	v_mfma_f32_16x16x32_bf16 v[16:19], v[152:155], v[176:179], v[16:19]
	v_mfma_f32_16x16x32_bf16 v[4:7], v[136:139], v[184:187], v[4:7]
	v_mfma_f32_16x16x32_bf16 v[0:3], v[152:155], v[184:187], v[0:3]
	v_mfma_f32_16x16x32_bf16 v[52:55], v[140:143], v[164:167], v[52:55]
	v_mfma_f32_16x16x32_bf16 v[48:51], v[156:159], v[164:167], v[48:51]
	v_mfma_f32_16x16x32_bf16 v[36:39], v[140:143], v[172:175], v[36:39]
	v_mfma_f32_16x16x32_bf16 v[32:35], v[156:159], v[172:175], v[32:35]
	v_mfma_f32_16x16x32_bf16 v[20:23], v[140:143], v[180:183], v[20:23]
	v_mfma_f32_16x16x32_bf16 v[16:19], v[156:159], v[180:183], v[16:19]
	v_mfma_f32_16x16x32_bf16 v[4:7], v[140:143], v[188:191], v[4:7]
	v_mfma_f32_16x16x32_bf16 v[0:3], v[156:159], v[188:191], v[0:3]
	s_setprio 0
	s_barrier
	s_add_i32 s54, s54, 2
	s_add_u32 s52, s52, 0x100
	s_addc_u32 s53, s53, 0
	s_cmp_gt_u32 s54, 41
	s_mov_b64 s[28:29], s[30:31]
	s_cbranch_scc0 .LBB0_1138
	s_and_b64 vcc, exec, s[24:25]
	s_cbranch_vccz .LBB0_1141
	s_barrier

; #define PG8_STAGE(bufoff, gbase, voff) do { _Pragma("unroll") for (int _i = 0; _i < 2; ++_i) \
;         __builtin_amdgcn_global_load_lds((const unsigned*)((const char*)(gbase) + (voff)[_i]), (LAS unsigned*)(lds + (bufoff) + ldsw + _i * 8192), 16, 0, 0); } while (0)
; #define PG8_LDA(dst, b, h) do { _Pragma("unroll") for (int m = 0; m < 4; ++m) _Pragma("unroll") for (int k = 0; k < 2; ++k) dst[m][k] = *(const LAS bf16x8*)(lds + PG8_SA(b, h) + aoff + m * 2048 + k * 1024); } while (0)
; #define PG8_LDB(dst, b, h) do { _Pragma("unroll") for (int n = 0; n < 2; ++n) _Pragma("unroll") for (int k = 0; k < 2; ++k) dst[n][k] = *(const LAS bf16x8*)(lds + PG8_SB(b, h) + boff + n * 2048 + k * 1024); } while (0)
; #define PG8_MMA(ai, bj, At, Bt) do { __builtin_amdgcn_s_setprio(1); _Pragma("unroll") for (int m = 0; m < 4; ++m) _Pragma("unroll") for (int n = 0; n < 2; ++n) _Pragma("unroll") for (int k = 0; k < 2; ++k) \
;         acc[ai][bj][m][n] = __builtin_amdgcn_mfma_f32_16x16x32_bf16(Bt[n][k], At[m][k], acc[ai][bj][m][n], 0, 0, 0); __builtin_amdgcn_s_setprio(0); } while (0)
; #define PG8_WAIT_V(n) asm volatile("s_waitcnt vmcnt(" #n ")" ::: "memory")
; #define PG8_WAIT_L(n) asm volatile("s_waitcnt lgkmcnt(" #n ")" ::: "memory")
; #define PG8_BAR __builtin_amdgcn_s_barrier()
; #define PG8_SCHED __builtin_amdgcn_sched_barrier(0)
; template <class Epi>
; __device__ __forceinline__ void gemm_phase(LAS unsigned char* lds, const Gemm g, const StaticOrder& S, const Epi& E, int wave_s) {
;     ...
;             PG8_LDB(B0, 0, 0); PG8_LDB(B1, 0, 1); PG8_SCHED; PG8_LDA(At, 0, 0); PG8_STAGE(PG8_SA(1, 1), a1 + hstepA, voffA);
;             PG8_WAIT_V(8); PG8_WAIT_L(0); PG8_BAR; PG8_MMA(0, 0, At, B0); PG8_MMA(0, 1, At, B1); PG8_BAR; PG8_SCHED;
;             PG8_LDA(At, 0, 1); PG8_STAGE(PG8_SB(0, 0), b2, voffB); PG8_STAGE(PG8_SB(0, 1), b2 + hstepB, voffB); PG8_STAGE(PG8_SA(0, 0), a2, voffA);
;             PG8_WAIT_V(8); PG8_WAIT_L(0); PG8_BAR; PG8_MMA(1, 0, At, B0); PG8_MMA(1, 1, At, B1); PG8_BAR; PG8_SCHED;
.LBB0_1413:
	s_add_u32 s42, s40, 0xfffc0080
	s_addc_u32 s43, s41, -1
	s_cmp_eq_u32 s60, 12
	s_cselect_b32 s45, s11, s43
	s_cselect_b32 s44, s13, s42
	s_cselect_b32 s43, s31, s59
	s_cselect_b32 s42, s35, s58
	v_lshl_add_u64 v[148:149], s[40:41], 0, v[136:137]
	s_add_i32 m0, s33, 0xc000
	s_nop 0
	global_load_lds_dwordx4 v[148:149], off
	v_lshl_add_u64 v[148:149], s[40:41], 0, v[138:139]
	s_add_i32 m0, s33, 0xe000
	s_nop 0
	global_load_lds_dwordx4 v[148:149], off
	ds_read_b128 v[144:147], v153
	ds_read_b128 v[160:163], v153 offset:1024
	ds_read_b128 v[164:167], v153 offset:2048
	ds_read_b128 v[168:171], v153 offset:3072
	ds_read_b128 v[172:175], v154
	ds_read_b128 v[176:179], v154 offset:1024
	ds_read_b128 v[180:183], v154 offset:2048
	ds_read_b128 v[184:187], v154 offset:3072
	ds_read_b128 v[188:191], v155
	ds_read_b128 v[192:195], v155 offset:1024
	ds_read_b128 v[196:199], v155 offset:2048
	ds_read_b128 v[200:203], v155 offset:3072
	ds_read_b128 v[204:207], v155 offset:4096
	ds_read_b128 v[208:211], v155 offset:5120
	ds_read_b128 v[212:215], v155 offset:6144
	ds_read_b128 v[216:219], v155 offset:7168
	s_waitcnt vmcnt(8)
	s_waitcnt lgkmcnt(0)
	s_barrier
	s_setprio 1
	s_waitcnt lgkmcnt(0)
	v_mfma_f32_16x16x32_bf16 v[124:127], v[144:147], v[188:191], v[124:127]
	v_mfma_f32_16x16x32_bf16 v[120:123], v[164:167], v[188:191], v[120:123]
	v_mfma_f32_16x16x32_bf16 v[108:111], v[144:147], v[196:199], v[108:111]
	v_mfma_f32_16x16x32_bf16 v[104:107], v[164:167], v[196:199], v[104:107]
	v_mfma_f32_16x16x32_bf16 v[92:95], v[144:147], v[204:207], v[92:95]
	v_mfma_f32_16x16x32_bf16 v[88:91], v[164:167], v[204:207], v[88:91]
	v_mfma_f32_16x16x32_bf16 v[76:79], v[144:147], v[212:215], v[76:79]
	v_mfma_f32_16x16x32_bf16 v[72:75], v[164:167], v[212:215], v[72:75]
	v_mfma_f32_16x16x32_bf16 v[124:127], v[160:163], v[192:195], v[124:127]
	v_mfma_f32_16x16x32_bf16 v[120:123], v[168:171], v[192:195], v[120:123]
	v_mfma_f32_16x16x32_bf16 v[108:111], v[160:163], v[200:203], v[108:111]
	v_mfma_f32_16x16x32_bf16 v[104:107], v[168:171], v[200:203], v[104:107]
	v_mfma_f32_16x16x32_bf16 v[92:95], v[160:163], v[208:211], v[92:95]
	v_mfma_f32_16x16x32_bf16 v[88:91], v[168:171], v[208:211], v[88:91]
	v_mfma_f32_16x16x32_bf16 v[76:79], v[160:163], v[216:219], v[76:79]
	v_mfma_f32_16x16x32_bf16 v[72:75], v[168:171], v[216:219], v[72:75]
	s_setprio 0
	s_setprio 1
	v_mfma_f32_16x16x32_bf16 v[116:119], v[172:175], v[188:191], v[116:119]
	v_mfma_f32_16x16x32_bf16 v[112:115], v[180:183], v[188:191], v[112:115]
	v_mfma_f32_16x16x32_bf16 v[100:103], v[172:175], v[196:199], v[100:103]
	v_mfma_f32_16x16x32_bf16 v[96:99], v[180:183], v[196:199], v[96:99]
	v_mfma_f32_16x16x32_bf16 v[84:87], v[172:175], v[204:207], v[84:87]
	v_mfma_f32_16x16x32_bf16 v[80:83], v[180:183], v[204:207], v[80:83]
	v_mfma_f32_16x16x32_bf16 v[68:71], v[172:175], v[212:215], v[68:71]
	v_mfma_f32_16x16x32_bf16 v[64:67], v[180:183], v[212:215], v[64:67]
	v_mfma_f32_16x16x32_bf16 v[116:119], v[176:179], v[192:195], v[116:119]
	v_mfma_f32_16x16x32_bf16 v[112:115], v[184:187], v[192:195], v[112:115]
	v_mfma_f32_16x16x32_bf16 v[100:103], v[176:179], v[200:203], v[100:103]
	v_mfma_f32_16x16x32_bf16 v[96:99], v[184:187], v[200:203], v[96:99]
	v_mfma_f32_16x16x32_bf16 v[84:87], v[176:179], v[208:211], v[84:87]
	v_mfma_f32_16x16x32_bf16 v[80:83], v[184:187], v[208:211], v[80:83]
	v_mfma_f32_16x16x32_bf16 v[68:71], v[176:179], v[216:219], v[68:71]
	v_mfma_f32_16x16x32_bf16 v[64:67], v[184:187], v[216:219], v[64:67]
	s_setprio 0
	s_barrier
	s_add_i32 s61, s54, s5
	v_lshl_add_u64 v[148:149], s[42:43], 0, v[130:131]
	s_mov_b32 m0, s61
	s_nop 0
	global_load_lds_dwordx4 v[148:149], off
	s_add_i32 m0, s61, 0x2000
	s_add_u32 s62, s42, 0x40000
	v_lshl_add_u64 v[220:221], s[42:43], 0, v[134:135]
	s_addc_u32 s63, s43, 0
	s_add_i32 s61, s55, s5
	global_load_lds_dwordx4 v[220:221], off
	v_lshl_add_u64 v[222:223], s[62:63], 0, v[130:131]
	s_mov_b32 m0, s61
	v_lshl_add_u64 v[224:225], s[44:45], 0, v[132:133]
	global_load_lds_dwordx4 v[222:223], off
	v_lshl_add_u64 v[222:223], s[62:63], 0, v[134:135]
	s_add_i32 m0, s61, 0x2000
	s_nop 0
	global_load_lds_dwordx4 v[222:223], off
	v_lshl_add_u64 v[222:223], s[44:45], 0, v[128:129]
	s_mov_b32 m0, s33
	s_nop 0
	global_load_lds_dwordx4 v[222:223], off
	s_mov_b32 m0, s46
	s_nop 0
	global_load_lds_dwordx4 v[224:225], off
	ds_read_b128 v[188:191], v155 offset:16384
	ds_read_b128 v[192:195], v155 offset:17408
	ds_read_b128 v[196:199], v155 offset:18432
	ds_read_b128 v[200:203], v155 offset:19456
	ds_read_b128 v[204:207], v155 offset:20480
	ds_read_b128 v[208:211], v155 offset:21504
	ds_read_b128 v[212:215], v155 offset:22528
	ds_read_b128 v[216:219], v155 offset:23552
	s_waitcnt vmcnt(8)
	s_waitcnt lgkmcnt(0)
	s_barrier
; #define PG8_STAGE(bufoff, gbase, voff) do { _Pragma("unroll") for (int _i = 0; _i < 2; ++_i) \
;         __builtin_amdgcn_global_load_lds((const unsigned*)((const char*)(gbase) + (voff)[_i]), (LAS unsigned*)(lds + (bufoff) + ldsw + _i * 8192), 16, 0, 0); } while (0)
; #define PG8_LDA(dst, b, h) do { _Pragma("unroll") for (int m = 0; m < 4; ++m) _Pragma("unroll") for (int k = 0; k < 2; ++k) dst[m][k] = *(const LAS bf16x8*)(lds + PG8_SA(b, h) + aoff + m * 2048 + k * 1024); } while (0)
; #define PG8_LDB(dst, b, h) do { _Pragma("unroll") for (int n = 0; n < 2; ++n) _Pragma("unroll") for (int k = 0; k < 2; ++k) dst[n][k] = *(const LAS bf16x8*)(lds + PG8_SB(b, h) + boff + n * 2048 + k * 1024); } while (0)
; #define PG8_MMA(ai, bj, At, Bt) do { __builtin_amdgcn_s_setprio(1); _Pragma("unroll") for (int m = 0; m < 4; ++m) _Pragma("unroll") for (int n = 0; n < 2; ++n) _Pragma("unroll") for (int k = 0; k < 2; ++k) \
;         acc[ai][bj][m][n] = __builtin_amdgcn_mfma_f32_16x16x32_bf16(Bt[n][k], At[m][k], acc[ai][bj][m][n], 0, 0, 0); __builtin_amdgcn_s_setprio(0); } while (0)
; #define PG8_WAIT_V(n) asm volatile("s_waitcnt vmcnt(" #n ")" ::: "memory")
; #define PG8_WAIT_L(n) asm volatile("s_waitcnt lgkmcnt(" #n ")" ::: "memory")
; #define PG8_BAR __builtin_amdgcn_s_barrier()
; #define PG8_SCHED __builtin_amdgcn_sched_barrier(0)
; template <class Epi>
; __device__ __forceinline__ void gemm_phase(LAS unsigned char* lds, const Gemm g, const StaticOrder& S, const Epi& E, int wave_s) {
;     ...
;             PG8_WAIT_V(8); PG8_WAIT_L(0); PG8_BAR; PG8_MMA(1, 0, At, B0); PG8_MMA(1, 1, At, B1); PG8_BAR; PG8_SCHED;
;             PG8_LDB(B0, 1, 0); PG8_LDB(B1, 1, 1); PG8_SCHED; PG8_LDA(At, 1, 0); PG8_STAGE(PG8_SA(0, 1), a2 + hstepA, voffA);
;             PG8_WAIT_V(8); PG8_WAIT_L(0); PG8_BAR; PG8_MMA(0, 0, At, B0); PG8_MMA(0, 1, At, B1); PG8_BAR; PG8_SCHED;
	s_setprio 1
	s_waitcnt lgkmcnt(0)
	v_mfma_f32_16x16x32_bf16 v[60:63], v[144:147], v[188:191], v[60:63]
	v_mfma_f32_16x16x32_bf16 v[56:59], v[164:167], v[188:191], v[56:59]
	v_mfma_f32_16x16x32_bf16 v[44:47], v[144:147], v[196:199], v[44:47]
	v_mfma_f32_16x16x32_bf16 v[40:43], v[164:167], v[196:199], v[40:43]
	v_mfma_f32_16x16x32_bf16 v[28:31], v[144:147], v[204:207], v[28:31]
	v_mfma_f32_16x16x32_bf16 v[24:27], v[164:167], v[204:207], v[24:27]
	v_mfma_f32_16x16x32_bf16 v[12:15], v[144:147], v[212:215], v[12:15]
	v_mfma_f32_16x16x32_bf16 v[8:11], v[164:167], v[212:215], v[8:11]
	v_mfma_f32_16x16x32_bf16 v[60:63], v[160:163], v[192:195], v[60:63]
	v_mfma_f32_16x16x32_bf16 v[56:59], v[168:171], v[192:195], v[56:59]
	v_mfma_f32_16x16x32_bf16 v[44:47], v[160:163], v[200:203], v[44:47]
	v_mfma_f32_16x16x32_bf16 v[40:43], v[168:171], v[200:203], v[40:43]
	v_mfma_f32_16x16x32_bf16 v[28:31], v[160:163], v[208:211], v[28:31]
	v_mfma_f32_16x16x32_bf16 v[24:27], v[168:171], v[208:211], v[24:27]
	v_mfma_f32_16x16x32_bf16 v[12:15], v[160:163], v[216:219], v[12:15]
	v_mfma_f32_16x16x32_bf16 v[8:11], v[168:171], v[216:219], v[8:11]
	s_setprio 0
	s_setprio 1
	v_mfma_f32_16x16x32_bf16 v[52:55], v[172:175], v[188:191], v[52:55]
	v_mfma_f32_16x16x32_bf16 v[48:51], v[180:183], v[188:191], v[48:51]
	v_mfma_f32_16x16x32_bf16 v[36:39], v[172:175], v[196:199], v[36:39]
	v_mfma_f32_16x16x32_bf16 v[32:35], v[180:183], v[196:199], v[32:35]
	v_mfma_f32_16x16x32_bf16 v[20:23], v[172:175], v[204:207], v[20:23]
	v_mfma_f32_16x16x32_bf16 v[16:19], v[180:183], v[204:207], v[16:19]
	v_mfma_f32_16x16x32_bf16 v[4:7], v[172:175], v[212:215], v[4:7]
	v_mfma_f32_16x16x32_bf16 v[0:3], v[180:183], v[212:215], v[0:3]
	v_mfma_f32_16x16x32_bf16 v[52:55], v[176:179], v[192:195], v[52:55]
	v_mfma_f32_16x16x32_bf16 v[48:51], v[184:187], v[192:195], v[48:51]
	v_mfma_f32_16x16x32_bf16 v[36:39], v[176:179], v[200:203], v[36:39]
	v_mfma_f32_16x16x32_bf16 v[32:35], v[184:187], v[200:203], v[32:35]
	v_mfma_f32_16x16x32_bf16 v[20:23], v[176:179], v[208:211], v[20:23]
	v_mfma_f32_16x16x32_bf16 v[16:19], v[184:187], v[208:211], v[16:19]
	v_mfma_f32_16x16x32_bf16 v[4:7], v[176:179], v[216:219], v[4:7]
	v_mfma_f32_16x16x32_bf16 v[0:3], v[184:187], v[216:219], v[0:3]
	s_setprio 0
	s_barrier
	s_add_i32 s61, 0, 0x18000
	s_add_i32 s62, 0, 0x1c000
	s_add_u32 s44, s44, 0x40000
	s_addc_u32 s45, s45, 0
	s_mov_b32 m0, s47
	v_lshl_add_u64 v[226:227], s[44:45], 0, v[128:129]
	global_load_lds_dwordx4 v[226:227], off
	v_lshl_add_u64 v[226:227], s[44:45], 0, v[132:133]
	s_mov_b32 m0, s48
	s_nop 0
	global_load_lds_dwordx4 v[226:227], off
	v_add_u32_e32 v159, s61, v151
	ds_read_b128 v[144:147], v159
	ds_read_b128 v[160:163], v159 offset:1024
	ds_read_b128 v[164:167], v159 offset:2048
	ds_read_b128 v[168:171], v159 offset:3072
	v_add_u32_e32 v159, s62, v151
	ds_read_b128 v[172:175], v159
	ds_read_b128 v[176:179], v159 offset:1024
	ds_read_b128 v[180:183], v159 offset:2048
	ds_read_b128 v[184:187], v159 offset:3072
	ds_read_b128 v[188:191], v155 offset:32768
	ds_read_b128 v[192:195], v155 offset:33792
	ds_read_b128 v[196:199], v155 offset:34816
	ds_read_b128 v[200:203], v155 offset:35840
	ds_read_b128 v[204:207], v155 offset:36864
	ds_read_b128 v[208:211], v155 offset:37888
	ds_read_b128 v[212:215], v155 offset:38912
	ds_read_b128 v[216:219], v155 offset:39936
	s_waitcnt vmcnt(8)
	s_waitcnt lgkmcnt(0)
	s_barrier
	s_setprio 1
	s_waitcnt lgkmcnt(0)
	v_mfma_f32_16x16x32_bf16 v[124:127], v[144:147], v[188:191], v[124:127]
	v_mfma_f32_16x16x32_bf16 v[120:123], v[164:167], v[188:191], v[120:123]
	v_mfma_f32_16x16x32_bf16 v[108:111], v[144:147], v[196:199], v[108:111]
	v_mfma_f32_16x16x32_bf16 v[104:107], v[164:167], v[196:199], v[104:107]
	v_mfma_f32_16x16x32_bf16 v[92:95], v[144:147], v[204:207], v[92:95]
	v_mfma_f32_16x16x32_bf16 v[88:91], v[164:167], v[204:207], v[88:91]
	v_mfma_f32_16x16x32_bf16 v[76:79], v[144:147], v[212:215], v[76:79]
	v_mfma_f32_16x16x32_bf16 v[72:75], v[164:167], v[212:215], v[72:75]
	v_mfma_f32_16x16x32_bf16 v[124:127], v[160:163], v[192:195], v[124:127]
	v_mfma_f32_16x16x32_bf16 v[120:123], v[168:171], v[192:195], v[120:123]
	v_mfma_f32_16x16x32_bf16 v[108:111], v[160:163], v[200:203], v[108:111]
	v_mfma_f32_16x16x32_bf16 v[104:107], v[168:171], v[200:203], v[104:107]
	v_mfma_f32_16x16x32_bf16 v[92:95], v[160:163], v[208:211], v[92:95]
	v_mfma_f32_16x16x32_bf16 v[88:91], v[168:171], v[208:211], v[88:91]
	v_mfma_f32_16x16x32_bf16 v[76:79], v[160:163], v[216:219], v[76:79]
	v_mfma_f32_16x16x32_bf16 v[72:75], v[168:171], v[216:219], v[72:75]
	s_setprio 0
	s_setprio 1
	v_mfma_f32_16x16x32_bf16 v[116:119], v[172:175], v[188:191], v[116:119]
	v_mfma_f32_16x16x32_bf16 v[112:115], v[180:183], v[188:191], v[112:115]
	v_mfma_f32_16x16x32_bf16 v[100:103], v[172:175], v[196:199], v[100:103]
	v_mfma_f32_16x16x32_bf16 v[96:99], v[180:183], v[196:199], v[96:99]
	v_mfma_f32_16x16x32_bf16 v[84:87], v[172:175], v[204:207], v[84:87]
	v_mfma_f32_16x16x32_bf16 v[80:83], v[180:183], v[204:207], v[80:83]
	v_mfma_f32_16x16x32_bf16 v[68:71], v[172:175], v[212:215], v[68:71]
	v_mfma_f32_16x16x32_bf16 v[64:67], v[180:183], v[212:215], v[64:67]
	v_mfma_f32_16x16x32_bf16 v[116:119], v[176:179], v[192:195], v[116:119]
	v_mfma_f32_16x16x32_bf16 v[112:115], v[184:187], v[192:195], v[112:115]
	v_mfma_f32_16x16x32_bf16 v[100:103], v[176:179], v[200:203], v[100:103]
	v_mfma_f32_16x16x32_bf16 v[96:99], v[184:187], v[200:203], v[96:99]
	v_mfma_f32_16x16x32_bf16 v[84:87], v[176:179], v[208:211], v[84:87]
	v_mfma_f32_16x16x32_bf16 v[80:83], v[184:187], v[208:211], v[80:83]
	v_mfma_f32_16x16x32_bf16 v[68:71], v[176:179], v[216:219], v[68:71]
	v_mfma_f32_16x16x32_bf16 v[64:67], v[184:187], v[216:219], v[64:67]
	s_setprio 0
	s_barrier
; #define PG8_STAGE(bufoff, gbase, voff) do { _Pragma("unroll") for (int _i = 0; _i < 2; ++_i) \
;         __builtin_amdgcn_global_load_lds((const unsigned*)((const char*)(gbase) + (voff)[_i]), (LAS unsigned*)(lds + (bufoff) + ldsw + _i * 8192), 16, 0, 0); } while (0)
; #define PG8_LDA(dst, b, h) do { _Pragma("unroll") for (int m = 0; m < 4; ++m) _Pragma("unroll") for (int k = 0; k < 2; ++k) dst[m][k] = *(const LAS bf16x8*)(lds + PG8_SA(b, h) + aoff + m * 2048 + k * 1024); } while (0)
; #define PG8_MMA(ai, bj, At, Bt) do { __builtin_amdgcn_s_setprio(1); _Pragma("unroll") for (int m = 0; m < 4; ++m) _Pragma("unroll") for (int n = 0; n < 2; ++n) _Pragma("unroll") for (int k = 0; k < 2; ++k) \
;         acc[ai][bj][m][n] = __builtin_amdgcn_mfma_f32_16x16x32_bf16(Bt[n][k], At[m][k], acc[ai][bj][m][n], 0, 0, 0); __builtin_amdgcn_s_setprio(0); } while (0)
; #define PG8_WAIT_V(n) asm volatile("s_waitcnt vmcnt(" #n ")" ::: "memory")
; #define PG8_WAIT_L(n) asm volatile("s_waitcnt lgkmcnt(" #n ")" ::: "memory")
; #define PG8_BAR __builtin_amdgcn_s_barrier()
; #define PG8_SCHED __builtin_amdgcn_sched_barrier(0)
; template <class Epi>
; __device__ __forceinline__ void gemm_phase(LAS unsigned char* lds, const Gemm g, const StaticOrder& S, const Epi& E, int wave_s) {
;     ...
;             PG8_LDA(At, 1, 1); PG8_STAGE(PG8_SB(1, 0), b3, voffB); PG8_STAGE(PG8_SB(1, 1), b3 + hstepB, voffB); PG8_STAGE(PG8_SA(1, 0), a3, voffA);
;             PG8_WAIT_V(8); PG8_WAIT_L(0); PG8_BAR; PG8_MMA(1, 0, At, B0); PG8_MMA(1, 1, At, B1); PG8_BAR; PG8_SCHED;
;         }
	s_add_i32 s44, s61, s5
	v_lshl_add_u64 v[148:149], v[148:149], 0, s[26:27]
	s_mov_b32 m0, s44
	s_nop 0
	global_load_lds_dwordx4 v[148:149], off
	s_add_i32 m0, s44, 0x2000
	s_add_u32 s42, s42, 0x40080
	v_lshl_add_u64 v[148:149], v[220:221], 0, s[26:27]
	s_addc_u32 s43, s43, 0
	s_add_i32 s44, s62, s5
	global_load_lds_dwordx4 v[148:149], off
	v_lshl_add_u64 v[148:149], s[42:43], 0, v[130:131]
	s_mov_b32 m0, s44
	s_nop 0
	global_load_lds_dwordx4 v[148:149], off
	v_lshl_add_u64 v[148:149], s[42:43], 0, v[134:135]
	s_add_i32 m0, s44, 0x2000
	s_nop 0
	global_load_lds_dwordx4 v[148:149], off
	v_lshl_add_u64 v[148:149], v[222:223], 0, s[26:27]
	s_mov_b32 m0, s2
	s_nop 0
	global_load_lds_dwordx4 v[148:149], off
	v_lshl_add_u64 v[148:149], v[224:225], 0, s[26:27]
	s_mov_b32 m0, s50
	s_nop 0
	global_load_lds_dwordx4 v[148:149], off
	ds_read_b128 v[188:191], v155 offset:49152
	ds_read_b128 v[192:195], v155 offset:50176
	ds_read_b128 v[196:199], v155 offset:51200
	ds_read_b128 v[200:203], v155 offset:52224
	ds_read_b128 v[204:207], v155 offset:53248
	ds_read_b128 v[208:211], v155 offset:54272
	ds_read_b128 v[212:215], v155 offset:55296
	ds_read_b128 v[216:219], v155 offset:56320
	s_waitcnt vmcnt(8)
	s_waitcnt lgkmcnt(0)
	s_barrier
	s_setprio 1
	s_waitcnt lgkmcnt(0)
	v_mfma_f32_16x16x32_bf16 v[60:63], v[144:147], v[188:191], v[60:63]
	v_mfma_f32_16x16x32_bf16 v[56:59], v[164:167], v[188:191], v[56:59]
	v_mfma_f32_16x16x32_bf16 v[44:47], v[144:147], v[196:199], v[44:47]
	v_mfma_f32_16x16x32_bf16 v[40:43], v[164:167], v[196:199], v[40:43]
	v_mfma_f32_16x16x32_bf16 v[28:31], v[144:147], v[204:207], v[28:31]
	v_mfma_f32_16x16x32_bf16 v[24:27], v[164:167], v[204:207], v[24:27]
	v_mfma_f32_16x16x32_bf16 v[12:15], v[144:147], v[212:215], v[12:15]
	v_mfma_f32_16x16x32_bf16 v[8:11], v[164:167], v[212:215], v[8:11]
	v_mfma_f32_16x16x32_bf16 v[60:63], v[160:163], v[192:195], v[60:63]
	v_mfma_f32_16x16x32_bf16 v[56:59], v[168:171], v[192:195], v[56:59]
	v_mfma_f32_16x16x32_bf16 v[44:47], v[160:163], v[200:203], v[44:47]
	v_mfma_f32_16x16x32_bf16 v[40:43], v[168:171], v[200:203], v[40:43]
	v_mfma_f32_16x16x32_bf16 v[28:31], v[160:163], v[208:211], v[28:31]
	v_mfma_f32_16x16x32_bf16 v[24:27], v[168:171], v[208:211], v[24:27]
	v_mfma_f32_16x16x32_bf16 v[12:15], v[160:163], v[216:219], v[12:15]
	v_mfma_f32_16x16x32_bf16 v[8:11], v[168:171], v[216:219], v[8:11]
	s_setprio 0
	s_setprio 1
	v_mfma_f32_16x16x32_bf16 v[52:55], v[172:175], v[188:191], v[52:55]
	v_mfma_f32_16x16x32_bf16 v[48:51], v[180:183], v[188:191], v[48:51]
	v_mfma_f32_16x16x32_bf16 v[36:39], v[172:175], v[196:199], v[36:39]
	v_mfma_f32_16x16x32_bf16 v[32:35], v[180:183], v[196:199], v[32:35]
	v_mfma_f32_16x16x32_bf16 v[20:23], v[172:175], v[204:207], v[20:23]
	v_mfma_f32_16x16x32_bf16 v[16:19], v[180:183], v[204:207], v[16:19]
	v_mfma_f32_16x16x32_bf16 v[4:7], v[172:175], v[212:215], v[4:7]
	v_mfma_f32_16x16x32_bf16 v[0:3], v[180:183], v[212:215], v[0:3]
	v_mfma_f32_16x16x32_bf16 v[52:55], v[176:179], v[192:195], v[52:55]
	v_mfma_f32_16x16x32_bf16 v[48:51], v[184:187], v[192:195], v[48:51]
	v_mfma_f32_16x16x32_bf16 v[36:39], v[176:179], v[200:203], v[36:39]
	v_mfma_f32_16x16x32_bf16 v[32:35], v[184:187], v[200:203], v[32:35]
	v_mfma_f32_16x16x32_bf16 v[20:23], v[176:179], v[208:211], v[20:23]
	v_mfma_f32_16x16x32_bf16 v[16:19], v[184:187], v[208:211], v[16:19]
	v_mfma_f32_16x16x32_bf16 v[4:7], v[176:179], v[216:219], v[4:7]
	v_mfma_f32_16x16x32_bf16 v[0:3], v[184:187], v[216:219], v[0:3]
	s_setprio 0
	s_barrier
	s_add_i32 s60, s60, 2
	s_add_u32 s40, s40, 0x100
	s_addc_u32 s41, s41, 0
	s_add_u32 s58, s58, 0x100
	s_addc_u32 s59, s59, 0
	s_cmp_gt_u32 s60, 13
	s_cbranch_scc0 .LBB0_1413
	s_and_b64 vcc, exec, s[28:29]
	s_cbranch_vccz .LBB0_1416
	s_barrier

; #define PG8_STAGE(bufoff, gbase, voff) do { _Pragma("unroll") for (int _i = 0; _i < 2; ++_i) \
;         __builtin_amdgcn_global_load_lds((const unsigned*)((const char*)(gbase) + (voff)[_i]), (LAS unsigned*)(lds + (bufoff) + ldsw + _i * 8192), 16, 0, 0); } while (0)
; #define PG8_LDA(dst, b, h) do { _Pragma("unroll") for (int m = 0; m < 4; ++m) _Pragma("unroll") for (int k = 0; k < 2; ++k) dst[m][k] = *(const LAS bf16x8*)(lds + PG8_SA(b, h) + aoff + m * 2048 + k * 1024); } while (0)
; #define PG8_LDB(dst, b, h) do { _Pragma("unroll") for (int n = 0; n < 2; ++n) _Pragma("unroll") for (int k = 0; k < 2; ++k) dst[n][k] = *(const LAS bf16x8*)(lds + PG8_SB(b, h) + boff + n * 2048 + k * 1024); } while (0)
; #define PG8_MMA(ai, bj, At, Bt) do { __builtin_amdgcn_s_setprio(1); _Pragma("unroll") for (int m = 0; m < 4; ++m) _Pragma("unroll") for (int n = 0; n < 2; ++n) _Pragma("unroll") for (int k = 0; k < 2; ++k) \
;         acc[ai][bj][m][n] = __builtin_amdgcn_mfma_f32_16x16x32_bf16(Bt[n][k], At[m][k], acc[ai][bj][m][n], 0, 0, 0); __builtin_amdgcn_s_setprio(0); } while (0)
; #define PG8_WAIT_V(n) asm volatile("s_waitcnt vmcnt(" #n ")" ::: "memory")
; #define PG8_WAIT_L(n) asm volatile("s_waitcnt lgkmcnt(" #n ")" ::: "memory")
; #define PG8_BAR __builtin_amdgcn_s_barrier()
; #define PG8_SCHED __builtin_amdgcn_sched_barrier(0)
; template <class Epi>
; __device__ __forceinline__ void gemm_phase(LAS unsigned char* lds, const Gemm g, const StaticOrder& S, const Epi& E, int wave_s) {
;     ...
;             PG8_LDB(B0, 0, 0); PG8_LDB(B1, 0, 1); PG8_SCHED; PG8_LDA(At, 0, 0); PG8_STAGE(PG8_SA(1, 1), a1 + hstepA, voffA);
;             PG8_WAIT_V(8); PG8_WAIT_L(0); PG8_BAR; PG8_MMA(0, 0, At, B0); PG8_MMA(0, 1, At, B1); PG8_BAR; PG8_SCHED;
;             PG8_LDA(At, 0, 1); PG8_STAGE(PG8_SB(0, 0), b2, voffB); PG8_STAGE(PG8_SB(0, 1), b2 + hstepB, voffB); PG8_STAGE(PG8_SA(0, 0), a2, voffA);
;             PG8_WAIT_V(8); PG8_WAIT_L(0); PG8_BAR; PG8_MMA(1, 0, At, B0); PG8_MMA(1, 1, At, B1); PG8_BAR; PG8_SCHED;
.LBB0_1524:
	s_add_u32 s38, s36, 0xfffc0080
	s_addc_u32 s39, s37, -1
	s_cmp_eq_u32 s60, 4
	s_cselect_b32 s41, s29, s39
	s_cselect_b32 s40, s56, s38
	s_cselect_b32 s39, s27, s59
	s_cselect_b32 s38, s57, s58
	v_lshl_add_u64 v[148:149], s[36:37], 0, v[136:137]
	s_add_i32 m0, s33, 0xc000
	s_nop 0
	global_load_lds_dwordx4 v[148:149], off
	v_lshl_add_u64 v[148:149], s[36:37], 0, v[138:139]
	s_add_i32 m0, s33, 0xe000
	s_nop 0
	global_load_lds_dwordx4 v[148:149], off
	ds_read_b128 v[144:147], v153
	ds_read_b128 v[158:161], v153 offset:1024
	ds_read_b128 v[162:165], v153 offset:2048
	ds_read_b128 v[166:169], v153 offset:3072
	ds_read_b128 v[170:173], v154
	ds_read_b128 v[174:177], v154 offset:1024
	ds_read_b128 v[178:181], v154 offset:2048
	ds_read_b128 v[182:185], v154 offset:3072
	ds_read_b128 v[186:189], v155
	ds_read_b128 v[190:193], v155 offset:1024
	ds_read_b128 v[194:197], v155 offset:2048
	ds_read_b128 v[198:201], v155 offset:3072
	ds_read_b128 v[202:205], v155 offset:4096
	ds_read_b128 v[206:209], v155 offset:5120
	ds_read_b128 v[210:213], v155 offset:6144
	ds_read_b128 v[214:217], v155 offset:7168
	s_waitcnt vmcnt(8)
	s_waitcnt lgkmcnt(0)
	s_barrier
	s_setprio 1
	s_waitcnt lgkmcnt(0)
	v_mfma_f32_16x16x32_bf16 v[124:127], v[144:147], v[186:189], v[124:127]
	v_mfma_f32_16x16x32_bf16 v[120:123], v[162:165], v[186:189], v[120:123]
	v_mfma_f32_16x16x32_bf16 v[108:111], v[144:147], v[194:197], v[108:111]
	v_mfma_f32_16x16x32_bf16 v[104:107], v[162:165], v[194:197], v[104:107]
	v_mfma_f32_16x16x32_bf16 v[92:95], v[144:147], v[202:205], v[92:95]
	v_mfma_f32_16x16x32_bf16 v[88:91], v[162:165], v[202:205], v[88:91]
	v_mfma_f32_16x16x32_bf16 v[76:79], v[144:147], v[210:213], v[76:79]
	v_mfma_f32_16x16x32_bf16 v[72:75], v[162:165], v[210:213], v[72:75]
	v_mfma_f32_16x16x32_bf16 v[124:127], v[158:161], v[190:193], v[124:127]
	v_mfma_f32_16x16x32_bf16 v[120:123], v[166:169], v[190:193], v[120:123]
	v_mfma_f32_16x16x32_bf16 v[108:111], v[158:161], v[198:201], v[108:111]
	v_mfma_f32_16x16x32_bf16 v[104:107], v[166:169], v[198:201], v[104:107]
	v_mfma_f32_16x16x32_bf16 v[92:95], v[158:161], v[206:209], v[92:95]
	v_mfma_f32_16x16x32_bf16 v[88:91], v[166:169], v[206:209], v[88:91]
	v_mfma_f32_16x16x32_bf16 v[76:79], v[158:161], v[214:217], v[76:79]
	v_mfma_f32_16x16x32_bf16 v[72:75], v[166:169], v[214:217], v[72:75]
	s_setprio 0
	s_setprio 1
	v_mfma_f32_16x16x32_bf16 v[116:119], v[170:173], v[186:189], v[116:119]
	v_mfma_f32_16x16x32_bf16 v[112:115], v[178:181], v[186:189], v[112:115]
	v_mfma_f32_16x16x32_bf16 v[100:103], v[170:173], v[194:197], v[100:103]
	v_mfma_f32_16x16x32_bf16 v[96:99], v[178:181], v[194:197], v[96:99]
	v_mfma_f32_16x16x32_bf16 v[84:87], v[170:173], v[202:205], v[84:87]
	v_mfma_f32_16x16x32_bf16 v[80:83], v[178:181], v[202:205], v[80:83]
	v_mfma_f32_16x16x32_bf16 v[68:71], v[170:173], v[210:213], v[68:71]
	v_mfma_f32_16x16x32_bf16 v[64:67], v[178:181], v[210:213], v[64:67]
	v_mfma_f32_16x16x32_bf16 v[116:119], v[174:177], v[190:193], v[116:119]
	v_mfma_f32_16x16x32_bf16 v[112:115], v[182:185], v[190:193], v[112:115]
	v_mfma_f32_16x16x32_bf16 v[100:103], v[174:177], v[198:201], v[100:103]
	v_mfma_f32_16x16x32_bf16 v[96:99], v[182:185], v[198:201], v[96:99]
	v_mfma_f32_16x16x32_bf16 v[84:87], v[174:177], v[206:209], v[84:87]
	v_mfma_f32_16x16x32_bf16 v[80:83], v[182:185], v[206:209], v[80:83]
	v_mfma_f32_16x16x32_bf16 v[68:71], v[174:177], v[214:217], v[68:71]
	v_mfma_f32_16x16x32_bf16 v[64:67], v[182:185], v[214:217], v[64:67]
	s_setprio 0
	s_barrier
	s_add_i32 s61, s50, s2
	v_lshl_add_u64 v[148:149], s[38:39], 0, v[132:133]
	s_mov_b32 m0, s61
	s_nop 0
	global_load_lds_dwordx4 v[148:149], off
	s_add_i32 m0, s61, 0x2000
	s_add_u32 s62, s38, 0x20000
	v_lshl_add_u64 v[218:219], s[38:39], 0, v[128:129]
	s_addc_u32 s63, s39, 0
	s_add_i32 s61, s51, s2
	global_load_lds_dwordx4 v[218:219], off
	v_lshl_add_u64 v[220:221], s[62:63], 0, v[132:133]
	s_mov_b32 m0, s61
	v_lshl_add_u64 v[222:223], s[40:41], 0, v[130:131]
	global_load_lds_dwordx4 v[220:221], off
	v_lshl_add_u64 v[220:221], s[62:63], 0, v[128:129]
	s_add_i32 m0, s61, 0x2000
	s_nop 0
	global_load_lds_dwordx4 v[220:221], off
	v_lshl_add_u64 v[220:221], s[40:41], 0, v[134:135]
	s_mov_b32 m0, s33
	s_nop 0
	global_load_lds_dwordx4 v[220:221], off
	s_mov_b32 m0, s42
	s_nop 0
	global_load_lds_dwordx4 v[222:223], off
	ds_read_b128 v[186:189], v155 offset:16384
	ds_read_b128 v[190:193], v155 offset:17408
	ds_read_b128 v[194:197], v155 offset:18432
	ds_read_b128 v[198:201], v155 offset:19456
	ds_read_b128 v[202:205], v155 offset:20480
	ds_read_b128 v[206:209], v155 offset:21504
	ds_read_b128 v[210:213], v155 offset:22528
	ds_read_b128 v[214:217], v155 offset:23552
	s_waitcnt vmcnt(8)
	s_waitcnt lgkmcnt(0)
	s_barrier
; #define PG8_STAGE(bufoff, gbase, voff) do { _Pragma("unroll") for (int _i = 0; _i < 2; ++_i) \
;         __builtin_amdgcn_global_load_lds((const unsigned*)((const char*)(gbase) + (voff)[_i]), (LAS unsigned*)(lds + (bufoff) + ldsw + _i * 8192), 16, 0, 0); } while (0)
; #define PG8_LDA(dst, b, h) do { _Pragma("unroll") for (int m = 0; m < 4; ++m) _Pragma("unroll") for (int k = 0; k < 2; ++k) dst[m][k] = *(const LAS bf16x8*)(lds + PG8_SA(b, h) + aoff + m * 2048 + k * 1024); } while (0)
; #define PG8_LDB(dst, b, h) do { _Pragma("unroll") for (int n = 0; n < 2; ++n) _Pragma("unroll") for (int k = 0; k < 2; ++k) dst[n][k] = *(const LAS bf16x8*)(lds + PG8_SB(b, h) + boff + n * 2048 + k * 1024); } while (0)
; #define PG8_MMA(ai, bj, At, Bt) do { __builtin_amdgcn_s_setprio(1); _Pragma("unroll") for (int m = 0; m < 4; ++m) _Pragma("unroll") for (int n = 0; n < 2; ++n) _Pragma("unroll") for (int k = 0; k < 2; ++k) \
;         acc[ai][bj][m][n] = __builtin_amdgcn_mfma_f32_16x16x32_bf16(Bt[n][k], At[m][k], acc[ai][bj][m][n], 0, 0, 0); __builtin_amdgcn_s_setprio(0); } while (0)
; #define PG8_WAIT_V(n) asm volatile("s_waitcnt vmcnt(" #n ")" ::: "memory")
; #define PG8_WAIT_L(n) asm volatile("s_waitcnt lgkmcnt(" #n ")" ::: "memory")
; #define PG8_BAR __builtin_amdgcn_s_barrier()
; #define PG8_SCHED __builtin_amdgcn_sched_barrier(0)
; template <class Epi>
; __device__ __forceinline__ void gemm_phase(LAS unsigned char* lds, const Gemm g, const StaticOrder& S, const Epi& E, int wave_s) {
;     ...
;             PG8_WAIT_V(8); PG8_WAIT_L(0); PG8_BAR; PG8_MMA(1, 0, At, B0); PG8_MMA(1, 1, At, B1); PG8_BAR; PG8_SCHED;
;             PG8_LDB(B0, 1, 0); PG8_LDB(B1, 1, 1); PG8_SCHED; PG8_LDA(At, 1, 0); PG8_STAGE(PG8_SA(0, 1), a2 + hstepA, voffA);
;             PG8_WAIT_V(8); PG8_WAIT_L(0); PG8_BAR; PG8_MMA(0, 0, At, B0); PG8_MMA(0, 1, At, B1); PG8_BAR; PG8_SCHED;
	s_setprio 1
	s_waitcnt lgkmcnt(0)
	v_mfma_f32_16x16x32_bf16 v[60:63], v[144:147], v[186:189], v[60:63]
	v_mfma_f32_16x16x32_bf16 v[56:59], v[162:165], v[186:189], v[56:59]
	v_mfma_f32_16x16x32_bf16 v[44:47], v[144:147], v[194:197], v[44:47]
	v_mfma_f32_16x16x32_bf16 v[40:43], v[162:165], v[194:197], v[40:43]
	v_mfma_f32_16x16x32_bf16 v[28:31], v[144:147], v[202:205], v[28:31]
	v_mfma_f32_16x16x32_bf16 v[24:27], v[162:165], v[202:205], v[24:27]
	v_mfma_f32_16x16x32_bf16 v[12:15], v[144:147], v[210:213], v[12:15]
	v_mfma_f32_16x16x32_bf16 v[8:11], v[162:165], v[210:213], v[8:11]
	v_mfma_f32_16x16x32_bf16 v[60:63], v[158:161], v[190:193], v[60:63]
	v_mfma_f32_16x16x32_bf16 v[56:59], v[166:169], v[190:193], v[56:59]
	v_mfma_f32_16x16x32_bf16 v[44:47], v[158:161], v[198:201], v[44:47]
	v_mfma_f32_16x16x32_bf16 v[40:43], v[166:169], v[198:201], v[40:43]
	v_mfma_f32_16x16x32_bf16 v[28:31], v[158:161], v[206:209], v[28:31]
	v_mfma_f32_16x16x32_bf16 v[24:27], v[166:169], v[206:209], v[24:27]
	v_mfma_f32_16x16x32_bf16 v[12:15], v[158:161], v[214:217], v[12:15]
	v_mfma_f32_16x16x32_bf16 v[8:11], v[166:169], v[214:217], v[8:11]
	s_setprio 0
	s_setprio 1
	v_mfma_f32_16x16x32_bf16 v[52:55], v[170:173], v[186:189], v[52:55]
	v_mfma_f32_16x16x32_bf16 v[48:51], v[178:181], v[186:189], v[48:51]
	v_mfma_f32_16x16x32_bf16 v[36:39], v[170:173], v[194:197], v[36:39]
	v_mfma_f32_16x16x32_bf16 v[32:35], v[178:181], v[194:197], v[32:35]
	v_mfma_f32_16x16x32_bf16 v[20:23], v[170:173], v[202:205], v[20:23]
	v_mfma_f32_16x16x32_bf16 v[16:19], v[178:181], v[202:205], v[16:19]
	v_mfma_f32_16x16x32_bf16 v[4:7], v[170:173], v[210:213], v[4:7]
	v_mfma_f32_16x16x32_bf16 v[0:3], v[178:181], v[210:213], v[0:3]
	v_mfma_f32_16x16x32_bf16 v[52:55], v[174:177], v[190:193], v[52:55]
	v_mfma_f32_16x16x32_bf16 v[48:51], v[182:185], v[190:193], v[48:51]
	v_mfma_f32_16x16x32_bf16 v[36:39], v[174:177], v[198:201], v[36:39]
	v_mfma_f32_16x16x32_bf16 v[32:35], v[182:185], v[198:201], v[32:35]
	v_mfma_f32_16x16x32_bf16 v[20:23], v[174:177], v[206:209], v[20:23]
	v_mfma_f32_16x16x32_bf16 v[16:19], v[182:185], v[206:209], v[16:19]
	v_mfma_f32_16x16x32_bf16 v[4:7], v[174:177], v[214:217], v[4:7]
	v_mfma_f32_16x16x32_bf16 v[0:3], v[182:185], v[214:217], v[0:3]
	s_setprio 0
	s_barrier
	s_add_i32 s61, 0, 0x18000
	s_add_i32 s62, 0, 0x1c000
	s_add_u32 s40, s40, 0x40000
	s_addc_u32 s41, s41, 0
	s_mov_b32 m0, s43
	v_lshl_add_u64 v[224:225], s[40:41], 0, v[134:135]
	global_load_lds_dwordx4 v[224:225], off
	v_lshl_add_u64 v[224:225], s[40:41], 0, v[130:131]
	s_mov_b32 m0, s44
	s_nop 0
	global_load_lds_dwordx4 v[224:225], off
	v_add_u32_e32 v166, s61, v151
	v_add_u32_e32 v182, s62, v151
	ds_read_b128 v[144:147], v166
	ds_read_b128 v[158:161], v166 offset:1024
	ds_read_b128 v[162:165], v166 offset:2048
	ds_read_b128 v[166:169], v166 offset:3072
	ds_read_b128 v[170:173], v182
	ds_read_b128 v[174:177], v182 offset:1024
	ds_read_b128 v[178:181], v182 offset:2048
	ds_read_b128 v[182:185], v182 offset:3072
	ds_read_b128 v[186:189], v155 offset:32768
	ds_read_b128 v[190:193], v155 offset:33792
	ds_read_b128 v[194:197], v155 offset:34816
	ds_read_b128 v[198:201], v155 offset:35840
	ds_read_b128 v[202:205], v155 offset:36864
	ds_read_b128 v[206:209], v155 offset:37888
	ds_read_b128 v[210:213], v155 offset:38912
	ds_read_b128 v[214:217], v155 offset:39936
	s_waitcnt vmcnt(8)
	s_waitcnt lgkmcnt(0)
	s_barrier
	s_setprio 1
	s_waitcnt lgkmcnt(0)
	v_mfma_f32_16x16x32_bf16 v[124:127], v[144:147], v[186:189], v[124:127]
	v_mfma_f32_16x16x32_bf16 v[120:123], v[162:165], v[186:189], v[120:123]
	v_mfma_f32_16x16x32_bf16 v[108:111], v[144:147], v[194:197], v[108:111]
	v_mfma_f32_16x16x32_bf16 v[104:107], v[162:165], v[194:197], v[104:107]
	v_mfma_f32_16x16x32_bf16 v[92:95], v[144:147], v[202:205], v[92:95]
	v_mfma_f32_16x16x32_bf16 v[88:91], v[162:165], v[202:205], v[88:91]
	v_mfma_f32_16x16x32_bf16 v[76:79], v[144:147], v[210:213], v[76:79]
	v_mfma_f32_16x16x32_bf16 v[72:75], v[162:165], v[210:213], v[72:75]
	v_mfma_f32_16x16x32_bf16 v[124:127], v[158:161], v[190:193], v[124:127]
	v_mfma_f32_16x16x32_bf16 v[120:123], v[166:169], v[190:193], v[120:123]
	v_mfma_f32_16x16x32_bf16 v[108:111], v[158:161], v[198:201], v[108:111]
	v_mfma_f32_16x16x32_bf16 v[104:107], v[166:169], v[198:201], v[104:107]
	v_mfma_f32_16x16x32_bf16 v[92:95], v[158:161], v[206:209], v[92:95]
	v_mfma_f32_16x16x32_bf16 v[88:91], v[166:169], v[206:209], v[88:91]
	v_mfma_f32_16x16x32_bf16 v[76:79], v[158:161], v[214:217], v[76:79]
	v_mfma_f32_16x16x32_bf16 v[72:75], v[166:169], v[214:217], v[72:75]
	s_setprio 0
	s_setprio 1
	v_mfma_f32_16x16x32_bf16 v[116:119], v[170:173], v[186:189], v[116:119]
	v_mfma_f32_16x16x32_bf16 v[112:115], v[178:181], v[186:189], v[112:115]
	v_mfma_f32_16x16x32_bf16 v[100:103], v[170:173], v[194:197], v[100:103]
	v_mfma_f32_16x16x32_bf16 v[96:99], v[178:181], v[194:197], v[96:99]
	v_mfma_f32_16x16x32_bf16 v[84:87], v[170:173], v[202:205], v[84:87]
	v_mfma_f32_16x16x32_bf16 v[80:83], v[178:181], v[202:205], v[80:83]
	v_mfma_f32_16x16x32_bf16 v[68:71], v[170:173], v[210:213], v[68:71]
	v_mfma_f32_16x16x32_bf16 v[64:67], v[178:181], v[210:213], v[64:67]
	v_mfma_f32_16x16x32_bf16 v[116:119], v[174:177], v[190:193], v[116:119]
	v_mfma_f32_16x16x32_bf16 v[112:115], v[182:185], v[190:193], v[112:115]
	v_mfma_f32_16x16x32_bf16 v[100:103], v[174:177], v[198:201], v[100:103]
	v_mfma_f32_16x16x32_bf16 v[96:99], v[182:185], v[198:201], v[96:99]
	v_mfma_f32_16x16x32_bf16 v[84:87], v[174:177], v[206:209], v[84:87]
	v_mfma_f32_16x16x32_bf16 v[80:83], v[182:185], v[206:209], v[80:83]
	v_mfma_f32_16x16x32_bf16 v[68:71], v[174:177], v[214:217], v[68:71]
	v_mfma_f32_16x16x32_bf16 v[64:67], v[182:185], v[214:217], v[64:67]
	s_setprio 0
	s_barrier
; #define PG8_STAGE(bufoff, gbase, voff) do { _Pragma("unroll") for (int _i = 0; _i < 2; ++_i) \
;         __builtin_amdgcn_global_load_lds((const unsigned*)((const char*)(gbase) + (voff)[_i]), (LAS unsigned*)(lds + (bufoff) + ldsw + _i * 8192), 16, 0, 0); } while (0)
; #define PG8_LDA(dst, b, h) do { _Pragma("unroll") for (int m = 0; m < 4; ++m) _Pragma("unroll") for (int k = 0; k < 2; ++k) dst[m][k] = *(const LAS bf16x8*)(lds + PG8_SA(b, h) + aoff + m * 2048 + k * 1024); } while (0)
; #define PG8_LDB(dst, b, h) do { _Pragma("unroll") for (int n = 0; n < 2; ++n) _Pragma("unroll") for (int k = 0; k < 2; ++k) dst[n][k] = *(const LAS bf16x8*)(lds + PG8_SB(b, h) + boff + n * 2048 + k * 1024); } while (0)
; #define PG8_WAIT_V(n) asm volatile("s_waitcnt vmcnt(" #n ")" ::: "memory")
; template <class Epi>
; __device__ __forceinline__ void gemm_phase(LAS unsigned char* lds, const Gemm g, const StaticOrder& S, const Epi& E, int wave_s) {
;     ...
;         for (int t = 0; t < nt; t += 2) {
;             const bool last = (t == nt - 2);
;             const char* a1 = cA + (size_t)(t + 1) * kstep;
;             const char* a2 = last ? nA : cA + (size_t)(t + 2) * kstep; const char* b2 = last ? nB : cB + (size_t)(t + 2) * kstep;
;             const char* a3 = a2 + kstep; const char* b3 = b2 + kstep;
;             PG8_LDB(B0, 0, 0); PG8_LDB(B1, 0, 1); PG8_SCHED; PG8_LDA(At, 0, 0); PG8_STAGE(PG8_SA(1, 1), a1 + hstepA, voffA);
;             PG8_WAIT_V(8); PG8_WAIT_L(0); PG8_BAR; PG8_MMA(0, 0, At, B0); PG8_MMA(0, 1, At, B1); PG8_BAR; PG8_SCHED;
;             PG8_LDA(At, 0, 1); PG8_STAGE(PG8_SB(0, 0), b2, voffB); PG8_STAGE(PG8_SB(0, 1), b2 + hstepB, voffB); PG8_STAGE(PG8_SA(0, 0), a2, voffA);
;             PG8_WAIT_V(8); PG8_WAIT_L(0); PG8_BAR; PG8_MMA(1, 0, At, B0); PG8_MMA(1, 1, At, B1); PG8_BAR; PG8_SCHED;
;             PG8_LDB(B0, 1, 0); PG8_LDB(B1, 1, 1); PG8_SCHED; PG8_LDA(At, 1, 0); PG8_STAGE(PG8_SA(0, 1), a2 + hstepA, voffA);
;             PG8_WAIT_V(8); PG8_WAIT_L(0); PG8_BAR; PG8_MMA(0, 0, At, B0); PG8_MMA(0, 1, At, B1); PG8_BAR; PG8_SCHED;
;             PG8_LDA(At, 1, 1); PG8_STAGE(PG8_SB(1, 0), b3, voffB); PG8_STAGE(PG8_SB(1, 1), b3 + hstepB, voffB); PG8_STAGE(PG8_SA(1, 0), a3, voffA);
;             PG8_WAIT_V(8); PG8_WAIT_L(0); PG8_BAR; PG8_MMA(1, 0, At, B0); PG8_MMA(1, 1, At, B1); PG8_BAR; PG8_SCHED;
;         }
;         if (wr == 0) PG8_BAR;
	s_add_i32 s40, s61, s2
	v_lshl_add_u64 v[148:149], v[148:149], 0, s[22:23]
	s_mov_b32 m0, s40
	s_nop 0
	global_load_lds_dwordx4 v[148:149], off
	s_add_i32 m0, s40, 0x2000
	s_add_u32 s38, s38, 0x20080
	v_lshl_add_u64 v[148:149], v[218:219], 0, s[22:23]
	s_addc_u32 s39, s39, 0
	s_add_i32 s40, s62, s2
	global_load_lds_dwordx4 v[148:149], off
	v_lshl_add_u64 v[148:149], s[38:39], 0, v[132:133]
	s_mov_b32 m0, s40
	s_nop 0
	global_load_lds_dwordx4 v[148:149], off
	v_lshl_add_u64 v[148:149], s[38:39], 0, v[128:129]
	s_add_i32 m0, s40, 0x2000
	s_nop 0
	global_load_lds_dwordx4 v[148:149], off
	v_lshl_add_u64 v[148:149], v[220:221], 0, s[22:23]
	s_mov_b32 m0, s46
	s_nop 0
	global_load_lds_dwordx4 v[148:149], off
	v_lshl_add_u64 v[148:149], v[222:223], 0, s[22:23]
	s_mov_b32 m0, s47
	s_nop 0
	global_load_lds_dwordx4 v[148:149], off
	ds_read_b128 v[186:189], v155 offset:49152
	ds_read_b128 v[190:193], v155 offset:50176
	ds_read_b128 v[194:197], v155 offset:51200
	ds_read_b128 v[198:201], v155 offset:52224
	ds_read_b128 v[202:205], v155 offset:53248
	ds_read_b128 v[206:209], v155 offset:54272
	ds_read_b128 v[210:213], v155 offset:55296
	ds_read_b128 v[214:217], v155 offset:56320
	s_waitcnt vmcnt(8)
	s_waitcnt lgkmcnt(0)
	s_barrier
	s_setprio 1
	s_waitcnt lgkmcnt(0)
	v_mfma_f32_16x16x32_bf16 v[60:63], v[144:147], v[186:189], v[60:63]
	v_mfma_f32_16x16x32_bf16 v[56:59], v[162:165], v[186:189], v[56:59]
	v_mfma_f32_16x16x32_bf16 v[44:47], v[144:147], v[194:197], v[44:47]
	v_mfma_f32_16x16x32_bf16 v[40:43], v[162:165], v[194:197], v[40:43]
	v_mfma_f32_16x16x32_bf16 v[28:31], v[144:147], v[202:205], v[28:31]
	v_mfma_f32_16x16x32_bf16 v[24:27], v[162:165], v[202:205], v[24:27]
	v_mfma_f32_16x16x32_bf16 v[12:15], v[144:147], v[210:213], v[12:15]
	v_mfma_f32_16x16x32_bf16 v[8:11], v[162:165], v[210:213], v[8:11]
	v_mfma_f32_16x16x32_bf16 v[60:63], v[158:161], v[190:193], v[60:63]
	v_mfma_f32_16x16x32_bf16 v[56:59], v[166:169], v[190:193], v[56:59]
	v_mfma_f32_16x16x32_bf16 v[44:47], v[158:161], v[198:201], v[44:47]
	v_mfma_f32_16x16x32_bf16 v[40:43], v[166:169], v[198:201], v[40:43]
	v_mfma_f32_16x16x32_bf16 v[28:31], v[158:161], v[206:209], v[28:31]
	v_mfma_f32_16x16x32_bf16 v[24:27], v[166:169], v[206:209], v[24:27]
	v_mfma_f32_16x16x32_bf16 v[12:15], v[158:161], v[214:217], v[12:15]
	v_mfma_f32_16x16x32_bf16 v[8:11], v[166:169], v[214:217], v[8:11]
	s_setprio 0
	s_setprio 1
	v_mfma_f32_16x16x32_bf16 v[52:55], v[170:173], v[186:189], v[52:55]
	v_mfma_f32_16x16x32_bf16 v[48:51], v[178:181], v[186:189], v[48:51]
	v_mfma_f32_16x16x32_bf16 v[36:39], v[170:173], v[194:197], v[36:39]
	v_mfma_f32_16x16x32_bf16 v[32:35], v[178:181], v[194:197], v[32:35]
	v_mfma_f32_16x16x32_bf16 v[20:23], v[170:173], v[202:205], v[20:23]
	v_mfma_f32_16x16x32_bf16 v[16:19], v[178:181], v[202:205], v[16:19]
	v_mfma_f32_16x16x32_bf16 v[4:7], v[170:173], v[210:213], v[4:7]
	v_mfma_f32_16x16x32_bf16 v[0:3], v[178:181], v[210:213], v[0:3]
	v_mfma_f32_16x16x32_bf16 v[52:55], v[174:177], v[190:193], v[52:55]
	v_mfma_f32_16x16x32_bf16 v[48:51], v[182:185], v[190:193], v[48:51]
	v_mfma_f32_16x16x32_bf16 v[36:39], v[174:177], v[198:201], v[36:39]
	v_mfma_f32_16x16x32_bf16 v[32:35], v[182:185], v[198:201], v[32:35]
	v_mfma_f32_16x16x32_bf16 v[20:23], v[174:177], v[206:209], v[20:23]
	v_mfma_f32_16x16x32_bf16 v[16:19], v[182:185], v[206:209], v[16:19]
	v_mfma_f32_16x16x32_bf16 v[4:7], v[174:177], v[214:217], v[4:7]
	v_mfma_f32_16x16x32_bf16 v[0:3], v[182:185], v[214:217], v[0:3]
	s_setprio 0
	s_barrier
	s_add_i32 s60, s60, 2
	s_add_u32 s36, s36, 0x100
	s_addc_u32 s37, s37, 0
	s_add_u32 s58, s58, 0x100
	s_addc_u32 s59, s59, 0
	s_cmp_gt_u32 s60, 5
	s_cbranch_scc0 .LBB0_1524
	s_and_b64 vcc, exec, s[24:25]
	s_cbranch_vccz .LBB0_1527
	s_barrier

; #define PG8_STAGE(bufoff, gbase, voff) do { _Pragma("unroll") for (int _i = 0; _i < 2; ++_i) \
;         __builtin_amdgcn_global_load_lds((const unsigned*)((const char*)(gbase) + (voff)[_i]), (LAS unsigned*)(lds + (bufoff) + ldsw + _i * 8192), 16, 0, 0); } while (0)
; #define PG8_LDA(dst, b, h) do { _Pragma("unroll") for (int m = 0; m < 4; ++m) _Pragma("unroll") for (int k = 0; k < 2; ++k) dst[m][k] = *(const LAS bf16x8*)(lds + PG8_SA(b, h) + aoff + m * 2048 + k * 1024); } while (0)
; #define PG8_LDB(dst, b, h) do { _Pragma("unroll") for (int n = 0; n < 2; ++n) _Pragma("unroll") for (int k = 0; k < 2; ++k) dst[n][k] = *(const LAS bf16x8*)(lds + PG8_SB(b, h) + boff + n * 2048 + k * 1024); } while (0)
; #define PG8_MMA(ai, bj, At, Bt) do { __builtin_amdgcn_s_setprio(1); _Pragma("unroll") for (int m = 0; m < 4; ++m) _Pragma("unroll") for (int n = 0; n < 2; ++n) _Pragma("unroll") for (int k = 0; k < 2; ++k) \
;         acc[ai][bj][m][n] = __builtin_amdgcn_mfma_f32_16x16x32_bf16(Bt[n][k], At[m][k], acc[ai][bj][m][n], 0, 0, 0); __builtin_amdgcn_s_setprio(0); } while (0)
; #define PG8_BAR __builtin_amdgcn_s_barrier()
; template <class Epi>
; __device__ __forceinline__ void gemm_phase(LAS unsigned char* lds, const Gemm g, const StaticOrder& S, const Epi& E, int wave_s) {
;     ...
;     for (;;) {
;         const bool has_next = S.next(ui + 1, nxt);
;         const char* nA = has_next ? (const char*)g.A + (size_t)nxt.pm * tstepA : cA; const char* nB = has_next ? (const char*)g.Bt + (size_t)nxt.pn * tstepB : cB;
;         for (int t = 0; t < nt; t += 2) {
;             const bool last = (t == nt - 2);
;             const char* a1 = cA + (size_t)(t + 1) * kstep;
;             const char* a2 = last ? nA : cA + (size_t)(t + 2) * kstep; const char* b2 = last ? nB : cB + (size_t)(t + 2) * kstep;
;             const char* a3 = a2 + kstep; const char* b3 = b2 + kstep;
;             PG8_LDB(B0, 0, 0); PG8_LDB(B1, 0, 1); PG8_SCHED; PG8_LDA(At, 0, 0); PG8_STAGE(PG8_SA(1, 1), a1 + hstepA, voffA);
;             PG8_WAIT_V(8); PG8_WAIT_L(0); PG8_BAR; PG8_MMA(0, 0, At, B0); PG8_MMA(0, 1, At, B1); PG8_BAR; PG8_SCHED;
;             PG8_LDA(At, 0, 1); PG8_STAGE(PG8_SB(0, 0), b2, voffB); PG8_STAGE(PG8_SB(0, 1), b2 + hstepB, voffB); PG8_STAGE(PG8_SA(0, 0), a2, voffA);
;             PG8_WAIT_V(8); PG8_WAIT_L(0); PG8_BAR; PG8_MMA(1, 0, At, B0); PG8_MMA(1, 1, At, B1); PG8_BAR; PG8_SCHED;
.LBB0_1547:
	s_ashr_i32 s39, s38, 31
	s_lshl_b64 s[40:41], s[38:39], 19
	s_add_u32 s40, s3, s40
	s_addc_u32 s41, s4, s41
	s_and_b64 s[42:43], s[6:7], exec
	s_cselect_b32 s51, s41, s45
	s_cselect_b32 s50, s40, s44
	s_ashr_i32 s37, s36, 31
	s_lshl_b64 s[42:43], s[36:37], 17
	s_add_u32 s42, s0, s42
	s_addc_u32 s43, s1, s43
	s_and_b64 s[48:49], s[6:7], exec
	s_cselect_b32 s49, s43, s47
	s_cselect_b32 s48, s42, s46
	s_add_u32 s72, s44, 0x40080
	s_addc_u32 s73, s45, 0
	s_add_i32 s75, s54, 0xc000
	v_lshl_add_u64 v[64:65], s[72:73], 0, v[128:129]
	s_mov_b32 m0, s75
	s_add_i32 s9, s54, 0xe000
	global_load_lds_dwordx4 v[64:65], off
	v_lshl_add_u64 v[64:65], s[72:73], 0, v[132:133]
	s_mov_b32 m0, s9
	s_nop 0
	global_load_lds_dwordx4 v[64:65], off
	ds_read_b128 v[0:3], v154
	ds_read_b128 v[4:7], v154 offset:1024
	ds_read_b128 v[8:11], v154 offset:2048
	ds_read_b128 v[12:15], v154 offset:3072
	ds_read_b128 v[16:19], v155
	ds_read_b128 v[20:23], v155 offset:1024
	ds_read_b128 v[24:27], v155 offset:2048
	ds_read_b128 v[28:31], v155 offset:3072
	ds_read_b128 v[32:35], v156
	ds_read_b128 v[36:39], v156 offset:1024
	ds_read_b128 v[40:43], v156 offset:2048
	ds_read_b128 v[44:47], v156 offset:3072
	ds_read_b128 v[48:51], v156 offset:4096
	ds_read_b128 v[52:55], v156 offset:5120
	ds_read_b128 v[56:59], v156 offset:6144
	ds_read_b128 v[60:63], v156 offset:7168
	s_waitcnt vmcnt(8)
	s_waitcnt lgkmcnt(0)
	s_barrier
	s_setprio 1
	s_waitcnt lgkmcnt(0)
	v_mfma_f32_16x16x32_bf16 v[64:67], v[0:3], v[32:35], 0
	v_mfma_f32_16x16x32_bf16 v[68:71], v[8:11], v[32:35], 0
	v_mfma_f32_16x16x32_bf16 v[72:75], v[0:3], v[40:43], 0
	v_mfma_f32_16x16x32_bf16 v[76:79], v[8:11], v[40:43], 0
	v_mfma_f32_16x16x32_bf16 v[80:83], v[0:3], v[48:51], 0
	v_mfma_f32_16x16x32_bf16 v[84:87], v[8:11], v[48:51], 0
	v_mfma_f32_16x16x32_bf16 v[88:91], v[0:3], v[56:59], 0
	v_mfma_f32_16x16x32_bf16 v[92:95], v[8:11], v[56:59], 0
	v_mfma_f32_16x16x32_bf16 v[64:67], v[4:7], v[36:39], v[64:67]
	v_mfma_f32_16x16x32_bf16 v[68:71], v[12:15], v[36:39], v[68:71]
	v_mfma_f32_16x16x32_bf16 v[72:75], v[4:7], v[44:47], v[72:75]
	v_mfma_f32_16x16x32_bf16 v[76:79], v[12:15], v[44:47], v[76:79]
	v_mfma_f32_16x16x32_bf16 v[80:83], v[4:7], v[52:55], v[80:83]
	v_mfma_f32_16x16x32_bf16 v[84:87], v[12:15], v[52:55], v[84:87]
	v_mfma_f32_16x16x32_bf16 v[88:91], v[4:7], v[60:63], v[88:91]
	v_mfma_f32_16x16x32_bf16 v[92:95], v[12:15], v[60:63], v[92:95]
	s_setprio 0
	s_setprio 1
	v_mfma_f32_16x16x32_bf16 v[96:99], v[16:19], v[32:35], 0
	v_mfma_f32_16x16x32_bf16 v[32:35], v[24:27], v[32:35], 0
	v_mfma_f32_16x16x32_bf16 v[96:99], v[20:23], v[36:39], v[96:99]
	v_mfma_f32_16x16x32_bf16 v[32:35], v[28:31], v[36:39], v[32:35]
	v_mfma_f32_16x16x32_bf16 v[36:39], v[16:19], v[40:43], 0
	v_mfma_f32_16x16x32_bf16 v[40:43], v[24:27], v[40:43], 0
	v_mfma_f32_16x16x32_bf16 v[36:39], v[20:23], v[44:47], v[36:39]
	v_mfma_f32_16x16x32_bf16 v[40:43], v[28:31], v[44:47], v[40:43]
	v_mfma_f32_16x16x32_bf16 v[44:47], v[16:19], v[48:51], 0
	v_mfma_f32_16x16x32_bf16 v[48:51], v[24:27], v[48:51], 0
	v_mfma_f32_16x16x32_bf16 v[44:47], v[20:23], v[52:55], v[44:47]
	v_mfma_f32_16x16x32_bf16 v[48:51], v[28:31], v[52:55], v[48:51]
	v_mfma_f32_16x16x32_bf16 v[52:55], v[16:19], v[56:59], 0
	v_mfma_f32_16x16x32_bf16 v[56:59], v[24:27], v[56:59], 0
	v_mfma_f32_16x16x32_bf16 v[52:55], v[20:23], v[60:63], v[52:55]
	v_mfma_f32_16x16x32_bf16 v[56:59], v[28:31], v[60:63], v[56:59]
	s_setprio 0
	s_barrier
	s_add_i32 s73, s64, s33
	v_lshl_add_u64 v[212:213], s[46:47], 0, v[130:131]
	s_add_i32 s37, s73, 0x2000
	v_lshl_add_u64 v[140:141], v[212:213], 0, s[30:31]
	s_mov_b32 m0, s73
	v_lshl_add_u64 v[214:215], s[46:47], 0, v[134:135]
	s_add_u32 s76, s46, 0x10100
	global_load_lds_dwordx4 v[140:141], off
	v_lshl_add_u64 v[140:141], v[214:215], 0, s[30:31]
	s_mov_b32 m0, s37
	s_addc_u32 s77, s47, 0
	s_add_i32 s39, s65, s33
	global_load_lds_dwordx4 v[140:141], off
	v_lshl_add_u64 v[140:141], s[76:77], 0, v[130:131]
	s_mov_b32 m0, s39
	s_add_i32 s72, s39, 0x2000
	global_load_lds_dwordx4 v[140:141], off
	v_lshl_add_u64 v[140:141], s[76:77], 0, v[134:135]
	s_mov_b32 m0, s72
	v_lshl_add_u64 v[216:217], s[44:45], 0, v[128:129]
	global_load_lds_dwordx4 v[140:141], off
	v_lshl_add_u64 v[140:141], v[216:217], 0, s[30:31]
	s_mov_b32 m0, s54
	v_lshl_add_u64 v[218:219], s[44:45], 0, v[132:133]
	global_load_lds_dwordx4 v[140:141], off
	v_lshl_add_u64 v[140:141], v[218:219], 0, s[30:31]
	s_mov_b32 m0, s55
	s_nop 0
	global_load_lds_dwordx4 v[140:141], off
	ds_read_b128 v[60:63], v156 offset:16384
	ds_read_b128 v[100:103], v156 offset:17408
	ds_read_b128 v[104:107], v156 offset:18432
	ds_read_b128 v[108:111], v156 offset:19456
	ds_read_b128 v[112:115], v156 offset:20480
	ds_read_b128 v[116:119], v156 offset:21504
	ds_read_b128 v[120:123], v156 offset:22528
	ds_read_b128 v[124:127], v156 offset:23552
	s_waitcnt vmcnt(8)
	s_waitcnt lgkmcnt(0)
	s_barrier
; #define PG8_STAGE(bufoff, gbase, voff) do { _Pragma("unroll") for (int _i = 0; _i < 2; ++_i) \
;         __builtin_amdgcn_global_load_lds((const unsigned*)((const char*)(gbase) + (voff)[_i]), (LAS unsigned*)(lds + (bufoff) + ldsw + _i * 8192), 16, 0, 0); } while (0)
; #define PG8_LDA(dst, b, h) do { _Pragma("unroll") for (int m = 0; m < 4; ++m) _Pragma("unroll") for (int k = 0; k < 2; ++k) dst[m][k] = *(const LAS bf16x8*)(lds + PG8_SA(b, h) + aoff + m * 2048 + k * 1024); } while (0)
; #define PG8_LDB(dst, b, h) do { _Pragma("unroll") for (int n = 0; n < 2; ++n) _Pragma("unroll") for (int k = 0; k < 2; ++k) dst[n][k] = *(const LAS bf16x8*)(lds + PG8_SB(b, h) + boff + n * 2048 + k * 1024); } while (0)
; #define PG8_MMA(ai, bj, At, Bt) do { __builtin_amdgcn_s_setprio(1); _Pragma("unroll") for (int m = 0; m < 4; ++m) _Pragma("unroll") for (int n = 0; n < 2; ++n) _Pragma("unroll") for (int k = 0; k < 2; ++k) \
;         acc[ai][bj][m][n] = __builtin_amdgcn_mfma_f32_16x16x32_bf16(Bt[n][k], At[m][k], acc[ai][bj][m][n], 0, 0, 0); __builtin_amdgcn_s_setprio(0); } while (0)
; #define PG8_WAIT_V(n) asm volatile("s_waitcnt vmcnt(" #n ")" ::: "memory")
; #define PG8_WAIT_L(n) asm volatile("s_waitcnt lgkmcnt(" #n ")" ::: "memory")
; #define PG8_BAR __builtin_amdgcn_s_barrier()
; #define PG8_SCHED __builtin_amdgcn_sched_barrier(0)
; template <class Epi>
; __device__ __forceinline__ void gemm_phase(LAS unsigned char* lds, const Gemm g, const StaticOrder& S, const Epi& E, int wave_s) {
;     ...
;             PG8_WAIT_V(8); PG8_WAIT_L(0); PG8_BAR; PG8_MMA(0, 0, At, B0); PG8_MMA(0, 1, At, B1); PG8_BAR; PG8_SCHED;
;             PG8_LDA(At, 0, 1); PG8_STAGE(PG8_SB(0, 0), b2, voffB); PG8_STAGE(PG8_SB(0, 1), b2 + hstepB, voffB); PG8_STAGE(PG8_SA(0, 0), a2, voffA);
;             PG8_WAIT_V(8); PG8_WAIT_L(0); PG8_BAR; PG8_MMA(1, 0, At, B0); PG8_MMA(1, 1, At, B1); PG8_BAR; PG8_SCHED;
;             PG8_LDB(B0, 1, 0); PG8_LDB(B1, 1, 1); PG8_SCHED; PG8_LDA(At, 1, 0); PG8_STAGE(PG8_SA(0, 1), a2 + hstepA, voffA);
;             PG8_WAIT_V(8); PG8_WAIT_L(0); PG8_BAR; PG8_MMA(0, 0, At, B0); PG8_MMA(0, 1, At, B1); PG8_BAR; PG8_SCHED;
	s_setprio 1
	s_waitcnt lgkmcnt(0)
	v_mfma_f32_16x16x32_bf16 v[140:143], v[0:3], v[60:63], 0
	v_mfma_f32_16x16x32_bf16 v[150:153], v[0:3], v[104:107], 0
	v_mfma_f32_16x16x32_bf16 v[164:167], v[0:3], v[112:115], 0
	v_mfma_f32_16x16x32_bf16 v[0:3], v[0:3], v[120:123], 0
	v_mfma_f32_16x16x32_bf16 v[140:143], v[4:7], v[100:103], v[140:143]
	v_mfma_f32_16x16x32_bf16 v[150:153], v[4:7], v[108:111], v[150:153]
	v_mfma_f32_16x16x32_bf16 v[164:167], v[4:7], v[116:119], v[164:167]
	v_mfma_f32_16x16x32_bf16 v[0:3], v[4:7], v[124:127], v[0:3]
	v_mfma_f32_16x16x32_bf16 v[4:7], v[8:11], v[120:123], 0
	v_mfma_f32_16x16x32_bf16 v[144:147], v[8:11], v[60:63], 0
	v_mfma_f32_16x16x32_bf16 v[160:163], v[8:11], v[104:107], 0
	v_mfma_f32_16x16x32_bf16 v[168:171], v[8:11], v[112:115], 0
	v_mfma_f32_16x16x32_bf16 v[4:7], v[12:15], v[124:127], v[4:7]
	v_mfma_f32_16x16x32_bf16 v[144:147], v[12:15], v[100:103], v[144:147]
	v_mfma_f32_16x16x32_bf16 v[160:163], v[12:15], v[108:111], v[160:163]
	v_mfma_f32_16x16x32_bf16 v[168:171], v[12:15], v[116:119], v[168:171]
	s_setprio 0
	s_setprio 1
	v_mfma_f32_16x16x32_bf16 v[8:11], v[16:19], v[60:63], 0
	v_mfma_f32_16x16x32_bf16 v[12:15], v[24:27], v[60:63], 0
	v_mfma_f32_16x16x32_bf16 v[8:11], v[20:23], v[100:103], v[8:11]
	v_mfma_f32_16x16x32_bf16 v[12:15], v[28:31], v[100:103], v[12:15]
	v_mfma_f32_16x16x32_bf16 v[60:63], v[16:19], v[104:107], 0
	v_mfma_f32_16x16x32_bf16 v[100:103], v[24:27], v[104:107], 0
	v_mfma_f32_16x16x32_bf16 v[104:107], v[16:19], v[112:115], 0
	v_mfma_f32_16x16x32_bf16 v[16:19], v[16:19], v[120:123], 0
	v_mfma_f32_16x16x32_bf16 v[60:63], v[20:23], v[108:111], v[60:63]
	v_mfma_f32_16x16x32_bf16 v[100:103], v[28:31], v[108:111], v[100:103]
	v_mfma_f32_16x16x32_bf16 v[104:107], v[20:23], v[116:119], v[104:107]
	v_mfma_f32_16x16x32_bf16 v[108:111], v[24:27], v[112:115], 0
	v_mfma_f32_16x16x32_bf16 v[16:19], v[20:23], v[124:127], v[16:19]
	v_mfma_f32_16x16x32_bf16 v[20:23], v[24:27], v[120:123], 0
	v_mfma_f32_16x16x32_bf16 v[108:111], v[28:31], v[116:119], v[108:111]
	v_mfma_f32_16x16x32_bf16 v[20:23], v[28:31], v[124:127], v[20:23]
	s_setprio 0
	s_barrier
	s_add_i32 s74, 0, 0x18000
	s_add_i32 s82, 0, 0x1c000
	s_add_u32 s76, s44, 0x40100
	s_addc_u32 s77, s45, 0
	s_mov_b32 m0, s56
	v_lshl_add_u64 v[220:221], s[76:77], 0, v[128:129]
	global_load_lds_dwordx4 v[220:221], off
	v_lshl_add_u64 v[220:221], s[76:77], 0, v[132:133]
	s_mov_b32 m0, s57
	s_nop 0
	global_load_lds_dwordx4 v[220:221], off
	v_add_u32_e32 v148, s74, v149
	v_add_u32_e32 v224, s82, v149
	ds_read_b128 v[24:27], v148
	ds_read_b128 v[28:31], v148 offset:1024
	ds_read_b128 v[112:115], v148 offset:2048
	ds_read_b128 v[116:119], v148 offset:3072
	ds_read_b128 v[120:123], v224
	ds_read_b128 v[124:127], v224 offset:1024
	ds_read_b128 v[172:175], v224 offset:2048
	ds_read_b128 v[176:179], v224 offset:3072
	ds_read_b128 v[180:183], v156 offset:32768
	ds_read_b128 v[184:187], v156 offset:33792
	ds_read_b128 v[188:191], v156 offset:34816
	ds_read_b128 v[192:195], v156 offset:35840
	ds_read_b128 v[196:199], v156 offset:36864
	ds_read_b128 v[200:203], v156 offset:37888
	ds_read_b128 v[204:207], v156 offset:38912
	ds_read_b128 v[208:211], v156 offset:39936
	s_waitcnt vmcnt(8)
	s_waitcnt lgkmcnt(0)
	s_barrier
	s_setprio 1
	s_waitcnt lgkmcnt(0)
	v_mfma_f32_16x16x32_bf16 v[64:67], v[24:27], v[180:183], v[64:67]
	v_mfma_f32_16x16x32_bf16 v[68:71], v[112:115], v[180:183], v[68:71]
	v_mfma_f32_16x16x32_bf16 v[72:75], v[24:27], v[188:191], v[72:75]
	v_mfma_f32_16x16x32_bf16 v[76:79], v[112:115], v[188:191], v[76:79]
	v_mfma_f32_16x16x32_bf16 v[80:83], v[24:27], v[196:199], v[80:83]
	v_mfma_f32_16x16x32_bf16 v[84:87], v[112:115], v[196:199], v[84:87]
	v_mfma_f32_16x16x32_bf16 v[88:91], v[24:27], v[204:207], v[88:91]
	v_mfma_f32_16x16x32_bf16 v[92:95], v[112:115], v[204:207], v[92:95]
	v_mfma_f32_16x16x32_bf16 v[64:67], v[28:31], v[184:187], v[64:67]
	v_mfma_f32_16x16x32_bf16 v[68:71], v[116:119], v[184:187], v[68:71]
	v_mfma_f32_16x16x32_bf16 v[72:75], v[28:31], v[192:195], v[72:75]
	v_mfma_f32_16x16x32_bf16 v[76:79], v[116:119], v[192:195], v[76:79]
	v_mfma_f32_16x16x32_bf16 v[80:83], v[28:31], v[200:203], v[80:83]
	v_mfma_f32_16x16x32_bf16 v[84:87], v[116:119], v[200:203], v[84:87]
	v_mfma_f32_16x16x32_bf16 v[88:91], v[28:31], v[208:211], v[88:91]
	v_mfma_f32_16x16x32_bf16 v[92:95], v[116:119], v[208:211], v[92:95]
	s_setprio 0
	s_setprio 1
	v_mfma_f32_16x16x32_bf16 v[96:99], v[120:123], v[180:183], v[96:99]
	v_mfma_f32_16x16x32_bf16 v[32:35], v[172:175], v[180:183], v[32:35]
	v_mfma_f32_16x16x32_bf16 v[36:39], v[120:123], v[188:191], v[36:39]
	v_mfma_f32_16x16x32_bf16 v[40:43], v[172:175], v[188:191], v[40:43]
	v_mfma_f32_16x16x32_bf16 v[44:47], v[120:123], v[196:199], v[44:47]
	v_mfma_f32_16x16x32_bf16 v[48:51], v[172:175], v[196:199], v[48:51]
	v_mfma_f32_16x16x32_bf16 v[52:55], v[120:123], v[204:207], v[52:55]
	v_mfma_f32_16x16x32_bf16 v[56:59], v[172:175], v[204:207], v[56:59]
	v_mfma_f32_16x16x32_bf16 v[96:99], v[124:127], v[184:187], v[96:99]
	v_mfma_f32_16x16x32_bf16 v[32:35], v[176:179], v[184:187], v[32:35]
	v_mfma_f32_16x16x32_bf16 v[36:39], v[124:127], v[192:195], v[36:39]
	v_mfma_f32_16x16x32_bf16 v[40:43], v[176:179], v[192:195], v[40:43]
	v_mfma_f32_16x16x32_bf16 v[44:47], v[124:127], v[200:203], v[44:47]
	v_mfma_f32_16x16x32_bf16 v[48:51], v[176:179], v[200:203], v[48:51]
	v_mfma_f32_16x16x32_bf16 v[52:55], v[124:127], v[208:211], v[52:55]
	v_mfma_f32_16x16x32_bf16 v[56:59], v[176:179], v[208:211], v[56:59]
	s_setprio 0
	s_barrier
; #define PG8_STAGE(bufoff, gbase, voff) do { _Pragma("unroll") for (int _i = 0; _i < 2; ++_i) \
;         __builtin_amdgcn_global_load_lds((const unsigned*)((const char*)(gbase) + (voff)[_i]), (LAS unsigned*)(lds + (bufoff) + ldsw + _i * 8192), 16, 0, 0); } while (0)
; #define PG8_LDA(dst, b, h) do { _Pragma("unroll") for (int m = 0; m < 4; ++m) _Pragma("unroll") for (int k = 0; k < 2; ++k) dst[m][k] = *(const LAS bf16x8*)(lds + PG8_SA(b, h) + aoff + m * 2048 + k * 1024); } while (0)
; #define PG8_LDB(dst, b, h) do { _Pragma("unroll") for (int n = 0; n < 2; ++n) _Pragma("unroll") for (int k = 0; k < 2; ++k) dst[n][k] = *(const LAS bf16x8*)(lds + PG8_SB(b, h) + boff + n * 2048 + k * 1024); } while (0)
; #define PG8_MMA(ai, bj, At, Bt) do { __builtin_amdgcn_s_setprio(1); _Pragma("unroll") for (int m = 0; m < 4; ++m) _Pragma("unroll") for (int n = 0; n < 2; ++n) _Pragma("unroll") for (int k = 0; k < 2; ++k) \
;         acc[ai][bj][m][n] = __builtin_amdgcn_mfma_f32_16x16x32_bf16(Bt[n][k], At[m][k], acc[ai][bj][m][n], 0, 0, 0); __builtin_amdgcn_s_setprio(0); } while (0)
; #define PG8_WAIT_V(n) asm volatile("s_waitcnt vmcnt(" #n ")" ::: "memory")
; #define PG8_BAR __builtin_amdgcn_s_barrier()
; template <class Epi>
; __device__ __forceinline__ void gemm_phase(LAS unsigned char* lds, const Gemm g, const StaticOrder& S, const Epi& E, int wave_s) {
;     ...
;             PG8_LDB(B0, 0, 0); PG8_LDB(B1, 0, 1); PG8_SCHED; PG8_LDA(At, 0, 0); PG8_STAGE(PG8_SA(1, 1), a1 + hstepA, voffA);
;             PG8_WAIT_V(8); PG8_WAIT_L(0); PG8_BAR; PG8_MMA(0, 0, At, B0); PG8_MMA(0, 1, At, B1); PG8_BAR; PG8_SCHED;
;             PG8_LDA(At, 0, 1); PG8_STAGE(PG8_SB(0, 0), b2, voffB); PG8_STAGE(PG8_SB(0, 1), b2 + hstepB, voffB); PG8_STAGE(PG8_SA(0, 0), a2, voffA);
;             PG8_WAIT_V(8); PG8_WAIT_L(0); PG8_BAR; PG8_MMA(1, 0, At, B0); PG8_MMA(1, 1, At, B1); PG8_BAR; PG8_SCHED;
;             PG8_LDB(B0, 1, 0); PG8_LDB(B1, 1, 1); PG8_SCHED; PG8_LDA(At, 1, 0); PG8_STAGE(PG8_SA(0, 1), a2 + hstepA, voffA);
;             PG8_WAIT_V(8); PG8_WAIT_L(0); PG8_BAR; PG8_MMA(0, 0, At, B0); PG8_MMA(0, 1, At, B1); PG8_BAR; PG8_SCHED;
;             PG8_LDA(At, 1, 1); PG8_STAGE(PG8_SB(1, 0), b3, voffB); PG8_STAGE(PG8_SB(1, 1), b3 + hstepB, voffB); PG8_STAGE(PG8_SA(1, 0), a3, voffA);
;             PG8_WAIT_V(8); PG8_WAIT_L(0); PG8_BAR; PG8_MMA(1, 0, At, B0); PG8_MMA(1, 1, At, B1); PG8_BAR; PG8_SCHED;
	s_add_i32 s76, s74, s33
	s_add_i32 s74, s76, 0x2000
	v_lshl_add_u64 v[212:213], v[212:213], 0, s[34:35]
	s_mov_b32 m0, s76
	s_add_u32 s78, s46, 0x10180
	global_load_lds_dwordx4 v[212:213], off
	v_lshl_add_u64 v[212:213], v[214:215], 0, s[34:35]
	s_mov_b32 m0, s74
	s_addc_u32 s79, s47, 0
	s_add_i32 s46, s82, s33
	global_load_lds_dwordx4 v[212:213], off
	v_lshl_add_u64 v[212:213], s[78:79], 0, v[130:131]
	s_mov_b32 m0, s46
	s_add_i32 s47, s46, 0x2000
	global_load_lds_dwordx4 v[212:213], off
	v_lshl_add_u64 v[212:213], s[78:79], 0, v[134:135]
	s_mov_b32 m0, s47
	s_nop 0
	global_load_lds_dwordx4 v[212:213], off
	v_lshl_add_u64 v[212:213], v[216:217], 0, s[34:35]
	s_mov_b32 m0, s60
	s_nop 0
	global_load_lds_dwordx4 v[212:213], off
	v_lshl_add_u64 v[212:213], v[218:219], 0, s[34:35]
	s_mov_b32 m0, s61
	s_nop 0
	global_load_lds_dwordx4 v[212:213], off
	ds_read_b128 v[180:183], v156 offset:49152
	ds_read_b128 v[184:187], v156 offset:50176
	ds_read_b128 v[188:191], v156 offset:51200
	ds_read_b128 v[192:195], v156 offset:52224
	ds_read_b128 v[196:199], v156 offset:53248
	ds_read_b128 v[200:203], v156 offset:54272
	ds_read_b128 v[204:207], v156 offset:55296
	ds_read_b128 v[208:211], v156 offset:56320
	s_waitcnt vmcnt(8)
	s_waitcnt lgkmcnt(0)
	s_barrier
	s_setprio 1
	s_waitcnt lgkmcnt(0)
	v_mfma_f32_16x16x32_bf16 v[0:3], v[24:27], v[204:207], v[0:3]
	v_mfma_f32_16x16x32_bf16 v[4:7], v[112:115], v[204:207], v[4:7]
	v_mfma_f32_16x16x32_bf16 v[140:143], v[24:27], v[180:183], v[140:143]
	v_mfma_f32_16x16x32_bf16 v[144:147], v[112:115], v[180:183], v[144:147]
	v_mfma_f32_16x16x32_bf16 v[150:153], v[24:27], v[188:191], v[150:153]
	v_mfma_f32_16x16x32_bf16 v[160:163], v[112:115], v[188:191], v[160:163]
	v_mfma_f32_16x16x32_bf16 v[164:167], v[24:27], v[196:199], v[164:167]
	v_mfma_f32_16x16x32_bf16 v[168:171], v[112:115], v[196:199], v[168:171]
	v_mfma_f32_16x16x32_bf16 v[0:3], v[28:31], v[208:211], v[0:3]
	v_mfma_f32_16x16x32_bf16 v[4:7], v[116:119], v[208:211], v[4:7]
	v_mfma_f32_16x16x32_bf16 v[140:143], v[28:31], v[184:187], v[140:143]
	v_mfma_f32_16x16x32_bf16 v[144:147], v[116:119], v[184:187], v[144:147]
	v_mfma_f32_16x16x32_bf16 v[150:153], v[28:31], v[192:195], v[150:153]
	v_mfma_f32_16x16x32_bf16 v[160:163], v[116:119], v[192:195], v[160:163]
	v_mfma_f32_16x16x32_bf16 v[164:167], v[28:31], v[200:203], v[164:167]
	v_mfma_f32_16x16x32_bf16 v[168:171], v[116:119], v[200:203], v[168:171]
	s_setprio 0
	s_setprio 1
	v_mfma_f32_16x16x32_bf16 v[8:11], v[120:123], v[180:183], v[8:11]
	v_mfma_f32_16x16x32_bf16 v[12:15], v[172:175], v[180:183], v[12:15]
	v_mfma_f32_16x16x32_bf16 v[24:27], v[120:123], v[188:191], v[60:63]
	v_mfma_f32_16x16x32_bf16 v[28:31], v[172:175], v[188:191], v[100:103]
	v_mfma_f32_16x16x32_bf16 v[60:63], v[120:123], v[196:199], v[104:107]
	v_mfma_f32_16x16x32_bf16 v[100:103], v[172:175], v[196:199], v[108:111]
	v_mfma_f32_16x16x32_bf16 v[16:19], v[120:123], v[204:207], v[16:19]
	v_mfma_f32_16x16x32_bf16 v[20:23], v[172:175], v[204:207], v[20:23]
	v_mfma_f32_16x16x32_bf16 v[8:11], v[124:127], v[184:187], v[8:11]
	v_mfma_f32_16x16x32_bf16 v[12:15], v[176:179], v[184:187], v[12:15]
	v_mfma_f32_16x16x32_bf16 v[24:27], v[124:127], v[192:195], v[24:27]
	v_mfma_f32_16x16x32_bf16 v[28:31], v[176:179], v[192:195], v[28:31]
	v_mfma_f32_16x16x32_bf16 v[60:63], v[124:127], v[200:203], v[60:63]
	v_mfma_f32_16x16x32_bf16 v[100:103], v[176:179], v[200:203], v[100:103]
	v_mfma_f32_16x16x32_bf16 v[16:19], v[124:127], v[208:211], v[16:19]
	v_mfma_f32_16x16x32_bf16 v[20:23], v[176:179], v[208:211], v[20:23]
	s_setprio 0
	s_barrier
	s_add_u32 s44, s44, 0x40180
	s_addc_u32 s45, s45, 0
	s_mov_b32 m0, s75
	v_lshl_add_u64 v[212:213], s[44:45], 0, v[128:129]
	global_load_lds_dwordx4 v[212:213], off
	v_lshl_add_u64 v[212:213], s[44:45], 0, v[132:133]
	s_mov_b32 m0, s9
	s_nop 0
	global_load_lds_dwordx4 v[212:213], off
	ds_read_b128 v[104:107], v154
	ds_read_b128 v[108:111], v154 offset:1024
	ds_read_b128 v[112:115], v154 offset:2048
	ds_read_b128 v[116:119], v154 offset:3072
	ds_read_b128 v[120:123], v155
	ds_read_b128 v[124:127], v155 offset:1024
	ds_read_b128 v[172:175], v155 offset:2048
	ds_read_b128 v[176:179], v155 offset:3072
	ds_read_b128 v[180:183], v156
	ds_read_b128 v[184:187], v156 offset:1024
	ds_read_b128 v[188:191], v156 offset:2048
	ds_read_b128 v[192:195], v156 offset:3072
	ds_read_b128 v[196:199], v156 offset:4096
	ds_read_b128 v[200:203], v156 offset:5120
	ds_read_b128 v[204:207], v156 offset:6144
	ds_read_b128 v[208:211], v156 offset:7168
	s_waitcnt vmcnt(8)
	s_waitcnt lgkmcnt(0)
	s_barrier
; #define PG8_STAGE(bufoff, gbase, voff) do { _Pragma("unroll") for (int _i = 0; _i < 2; ++_i) \
;         __builtin_amdgcn_global_load_lds((const unsigned*)((const char*)(gbase) + (voff)[_i]), (LAS unsigned*)(lds + (bufoff) + ldsw + _i * 8192), 16, 0, 0); } while (0)
; #define PG8_LDA(dst, b, h) do { _Pragma("unroll") for (int m = 0; m < 4; ++m) _Pragma("unroll") for (int k = 0; k < 2; ++k) dst[m][k] = *(const LAS bf16x8*)(lds + PG8_SA(b, h) + aoff + m * 2048 + k * 1024); } while (0)
; #define PG8_LDB(dst, b, h) do { _Pragma("unroll") for (int n = 0; n < 2; ++n) _Pragma("unroll") for (int k = 0; k < 2; ++k) dst[n][k] = *(const LAS bf16x8*)(lds + PG8_SB(b, h) + boff + n * 2048 + k * 1024); } while (0)
; #define PG8_MMA(ai, bj, At, Bt) do { __builtin_amdgcn_s_setprio(1); _Pragma("unroll") for (int m = 0; m < 4; ++m) _Pragma("unroll") for (int n = 0; n < 2; ++n) _Pragma("unroll") for (int k = 0; k < 2; ++k) \
;         acc[ai][bj][m][n] = __builtin_amdgcn_mfma_f32_16x16x32_bf16(Bt[n][k], At[m][k], acc[ai][bj][m][n], 0, 0, 0); __builtin_amdgcn_s_setprio(0); } while (0)
; #define PG8_WAIT_V(n) asm volatile("s_waitcnt vmcnt(" #n ")" ::: "memory")
; #define PG8_WAIT_L(n) asm volatile("s_waitcnt lgkmcnt(" #n ")" ::: "memory")
; #define PG8_BAR __builtin_amdgcn_s_barrier()
; #define PG8_SCHED __builtin_amdgcn_sched_barrier(0)
; template <class Epi>
; __device__ __forceinline__ void gemm_phase(LAS unsigned char* lds, const Gemm g, const StaticOrder& S, const Epi& E, int wave_s) {
;     ...
;             PG8_LDB(B0, 0, 0); PG8_LDB(B1, 0, 1); PG8_SCHED; PG8_LDA(At, 0, 0); PG8_STAGE(PG8_SA(1, 1), a1 + hstepA, voffA);
;             PG8_WAIT_V(8); PG8_WAIT_L(0); PG8_BAR; PG8_MMA(0, 0, At, B0); PG8_MMA(0, 1, At, B1); PG8_BAR; PG8_SCHED;
;             PG8_LDA(At, 0, 1); PG8_STAGE(PG8_SB(0, 0), b2, voffB); PG8_STAGE(PG8_SB(0, 1), b2 + hstepB, voffB); PG8_STAGE(PG8_SA(0, 0), a2, voffA);
;             PG8_WAIT_V(8); PG8_WAIT_L(0); PG8_BAR; PG8_MMA(1, 0, At, B0); PG8_MMA(1, 1, At, B1); PG8_BAR; PG8_SCHED;
;             PG8_LDB(B0, 1, 0); PG8_LDB(B1, 1, 1); PG8_SCHED; PG8_LDA(At, 1, 0); PG8_STAGE(PG8_SA(0, 1), a2 + hstepA, voffA);
	s_setprio 1
	s_waitcnt lgkmcnt(0)
	v_mfma_f32_16x16x32_bf16 v[64:67], v[104:107], v[180:183], v[64:67]
	v_mfma_f32_16x16x32_bf16 v[68:71], v[112:115], v[180:183], v[68:71]
	v_mfma_f32_16x16x32_bf16 v[72:75], v[104:107], v[188:191], v[72:75]
	v_mfma_f32_16x16x32_bf16 v[76:79], v[112:115], v[188:191], v[76:79]
	v_mfma_f32_16x16x32_bf16 v[80:83], v[104:107], v[196:199], v[80:83]
	v_mfma_f32_16x16x32_bf16 v[84:87], v[112:115], v[196:199], v[84:87]
	v_mfma_f32_16x16x32_bf16 v[88:91], v[104:107], v[204:207], v[88:91]
	v_mfma_f32_16x16x32_bf16 v[64:67], v[108:111], v[184:187], v[64:67]
	v_mfma_f32_16x16x32_bf16 v[68:71], v[116:119], v[184:187], v[68:71]
	v_mfma_f32_16x16x32_bf16 v[72:75], v[108:111], v[192:195], v[72:75]
	v_mfma_f32_16x16x32_bf16 v[76:79], v[116:119], v[192:195], v[76:79]
	v_mfma_f32_16x16x32_bf16 v[80:83], v[108:111], v[200:203], v[80:83]
	v_mfma_f32_16x16x32_bf16 v[84:87], v[116:119], v[200:203], v[84:87]
	v_mfma_f32_16x16x32_bf16 v[212:215], v[108:111], v[208:211], v[88:91]
	v_mfma_f32_16x16x32_bf16 v[88:91], v[112:115], v[204:207], v[92:95]
	v_mfma_f32_16x16x32_bf16 v[216:219], v[116:119], v[208:211], v[88:91]
	s_setprio 0
	s_setprio 1
	v_mfma_f32_16x16x32_bf16 v[88:91], v[120:123], v[180:183], v[96:99]
	v_mfma_f32_16x16x32_bf16 v[32:35], v[172:175], v[180:183], v[32:35]
	v_mfma_f32_16x16x32_bf16 v[36:39], v[120:123], v[188:191], v[36:39]
	v_mfma_f32_16x16x32_bf16 v[40:43], v[172:175], v[188:191], v[40:43]
	v_mfma_f32_16x16x32_bf16 v[44:47], v[120:123], v[196:199], v[44:47]
	v_mfma_f32_16x16x32_bf16 v[48:51], v[172:175], v[196:199], v[48:51]
	v_mfma_f32_16x16x32_bf16 v[52:55], v[120:123], v[204:207], v[52:55]
	v_mfma_f32_16x16x32_bf16 v[56:59], v[172:175], v[204:207], v[56:59]
	v_mfma_f32_16x16x32_bf16 v[96:99], v[124:127], v[184:187], v[88:91]
	v_mfma_f32_16x16x32_bf16 v[32:35], v[176:179], v[184:187], v[32:35]
	v_mfma_f32_16x16x32_bf16 v[36:39], v[124:127], v[192:195], v[36:39]
	v_mfma_f32_16x16x32_bf16 v[40:43], v[176:179], v[192:195], v[40:43]
	v_mfma_f32_16x16x32_bf16 v[44:47], v[124:127], v[200:203], v[44:47]
	v_mfma_f32_16x16x32_bf16 v[48:51], v[176:179], v[200:203], v[48:51]
	v_mfma_f32_16x16x32_bf16 v[52:55], v[124:127], v[208:211], v[52:55]
	v_mfma_f32_16x16x32_bf16 v[56:59], v[176:179], v[208:211], v[56:59]
	s_setprio 0
	s_barrier
	s_mov_b32 m0, s73
	v_lshl_add_u64 v[244:245], s[48:49], 0, v[130:131]
	s_add_u32 s44, s48, 0x10000
	global_load_lds_dwordx4 v[244:245], off
	v_lshl_add_u64 v[246:247], s[48:49], 0, v[134:135]
	s_mov_b32 m0, s37
	s_addc_u32 s45, s49, 0
	global_load_lds_dwordx4 v[246:247], off
	v_lshl_add_u64 v[204:205], s[44:45], 0, v[130:131]
	s_mov_b32 m0, s39
	v_lshl_add_u64 v[248:249], s[50:51], 0, v[128:129]
	global_load_lds_dwordx4 v[204:205], off
	v_lshl_add_u64 v[204:205], s[44:45], 0, v[134:135]
	s_mov_b32 m0, s72
	v_lshl_add_u64 v[250:251], s[50:51], 0, v[132:133]
	global_load_lds_dwordx4 v[204:205], off
	s_mov_b32 m0, s54
	s_nop 0
	global_load_lds_dwordx4 v[248:249], off
	s_mov_b32 m0, s55
	s_nop 0
	global_load_lds_dwordx4 v[250:251], off
	ds_read_b128 v[88:91], v156 offset:16384
	ds_read_b128 v[92:95], v156 offset:17408
	ds_read_b128 v[180:183], v156 offset:18432
	ds_read_b128 v[184:187], v156 offset:19456
	ds_read_b128 v[188:191], v156 offset:20480
	ds_read_b128 v[192:195], v156 offset:21504
	ds_read_b128 v[196:199], v156 offset:22528
	ds_read_b128 v[200:203], v156 offset:23552
	s_waitcnt vmcnt(8)
	s_waitcnt lgkmcnt(0)
	s_barrier
	s_setprio 1
	s_waitcnt lgkmcnt(0)
	v_mfma_f32_16x16x32_bf16 v[0:3], v[104:107], v[196:199], v[0:3]
	v_mfma_f32_16x16x32_bf16 v[4:7], v[112:115], v[196:199], v[4:7]
	v_mfma_f32_16x16x32_bf16 v[140:143], v[104:107], v[88:91], v[140:143]
	v_mfma_f32_16x16x32_bf16 v[144:147], v[112:115], v[88:91], v[144:147]
	v_mfma_f32_16x16x32_bf16 v[150:153], v[104:107], v[180:183], v[150:153]
	v_mfma_f32_16x16x32_bf16 v[160:163], v[112:115], v[180:183], v[160:163]
	v_mfma_f32_16x16x32_bf16 v[164:167], v[104:107], v[188:191], v[164:167]
	v_mfma_f32_16x16x32_bf16 v[168:171], v[112:115], v[188:191], v[168:171]
	v_mfma_f32_16x16x32_bf16 v[0:3], v[108:111], v[200:203], v[0:3]
	v_mfma_f32_16x16x32_bf16 v[4:7], v[116:119], v[200:203], v[4:7]
	v_mfma_f32_16x16x32_bf16 v[140:143], v[108:111], v[92:95], v[140:143]
	v_mfma_f32_16x16x32_bf16 v[144:147], v[116:119], v[92:95], v[144:147]
	v_mfma_f32_16x16x32_bf16 v[150:153], v[108:111], v[184:187], v[150:153]
	v_mfma_f32_16x16x32_bf16 v[160:163], v[116:119], v[184:187], v[160:163]
	v_mfma_f32_16x16x32_bf16 v[164:167], v[108:111], v[192:195], v[164:167]
	v_mfma_f32_16x16x32_bf16 v[168:171], v[116:119], v[192:195], v[168:171]
	s_setprio 0
	s_setprio 1
	v_mfma_f32_16x16x32_bf16 v[8:11], v[120:123], v[88:91], v[8:11]
	v_mfma_f32_16x16x32_bf16 v[204:207], v[124:127], v[92:95], v[8:11]
	v_mfma_f32_16x16x32_bf16 v[8:11], v[172:175], v[88:91], v[12:15]
	v_mfma_f32_16x16x32_bf16 v[208:211], v[176:179], v[92:95], v[8:11]
	v_mfma_f32_16x16x32_bf16 v[8:11], v[120:123], v[180:183], v[24:27]
	v_mfma_f32_16x16x32_bf16 v[220:223], v[124:127], v[184:187], v[8:11]
	v_mfma_f32_16x16x32_bf16 v[8:11], v[172:175], v[180:183], v[28:31]
	v_mfma_f32_16x16x32_bf16 v[180:183], v[176:179], v[184:187], v[8:11]
	v_mfma_f32_16x16x32_bf16 v[8:11], v[120:123], v[188:191], v[60:63]
	v_mfma_f32_16x16x32_bf16 v[184:187], v[124:127], v[192:195], v[8:11]
	v_mfma_f32_16x16x32_bf16 v[8:11], v[172:175], v[188:191], v[100:103]
	v_mfma_f32_16x16x32_bf16 v[188:191], v[176:179], v[192:195], v[8:11]
	v_mfma_f32_16x16x32_bf16 v[8:11], v[120:123], v[196:199], v[16:19]
	v_mfma_f32_16x16x32_bf16 v[192:195], v[124:127], v[200:203], v[8:11]
	v_mfma_f32_16x16x32_bf16 v[8:11], v[172:175], v[196:199], v[20:23]
	v_mfma_f32_16x16x32_bf16 v[172:175], v[176:179], v[200:203], v[8:11]
	s_setprio 0
	s_barrier
; #define PG8_STAGE(bufoff, gbase, voff) do { _Pragma("unroll") for (int _i = 0; _i < 2; ++_i) \
;         __builtin_amdgcn_global_load_lds((const unsigned*)((const char*)(gbase) + (voff)[_i]), (LAS unsigned*)(lds + (bufoff) + ldsw + _i * 8192), 16, 0, 0); } while (0)
; #define PG8_LDA(dst, b, h) do { _Pragma("unroll") for (int m = 0; m < 4; ++m) _Pragma("unroll") for (int k = 0; k < 2; ++k) dst[m][k] = *(const LAS bf16x8*)(lds + PG8_SA(b, h) + aoff + m * 2048 + k * 1024); } while (0)
; #define PG8_LDB(dst, b, h) do { _Pragma("unroll") for (int n = 0; n < 2; ++n) _Pragma("unroll") for (int k = 0; k < 2; ++k) dst[n][k] = *(const LAS bf16x8*)(lds + PG8_SB(b, h) + boff + n * 2048 + k * 1024); } while (0)
; #define PG8_WAIT_V(n) asm volatile("s_waitcnt vmcnt(" #n ")" ::: "memory")
; template <class Epi>
; __device__ __forceinline__ void gemm_phase(LAS unsigned char* lds, const Gemm g, const StaticOrder& S, const Epi& E, int wave_s) {
;     ...
;         for (int t = 0; t < nt; t += 2) {
;             const bool last = (t == nt - 2);
;             const char* a1 = cA + (size_t)(t + 1) * kstep;
;             const char* a2 = last ? nA : cA + (size_t)(t + 2) * kstep; const char* b2 = last ? nB : cB + (size_t)(t + 2) * kstep;
;             const char* a3 = a2 + kstep; const char* b3 = b2 + kstep;
;             PG8_LDB(B0, 0, 0); PG8_LDB(B1, 0, 1); PG8_SCHED; PG8_LDA(At, 0, 0); PG8_STAGE(PG8_SA(1, 1), a1 + hstepA, voffA);
;             PG8_WAIT_V(8); PG8_WAIT_L(0); PG8_BAR; PG8_MMA(0, 0, At, B0); PG8_MMA(0, 1, At, B1); PG8_BAR; PG8_SCHED;
;             PG8_LDA(At, 0, 1); PG8_STAGE(PG8_SB(0, 0), b2, voffB); PG8_STAGE(PG8_SB(0, 1), b2 + hstepB, voffB); PG8_STAGE(PG8_SA(0, 0), a2, voffA);
;             PG8_WAIT_V(8); PG8_WAIT_L(0); PG8_BAR; PG8_MMA(1, 0, At, B0); PG8_MMA(1, 1, At, B1); PG8_BAR; PG8_SCHED;
;             PG8_LDB(B0, 1, 0); PG8_LDB(B1, 1, 1); PG8_SCHED; PG8_LDA(At, 1, 0); PG8_STAGE(PG8_SA(0, 1), a2 + hstepA, voffA);
;             PG8_WAIT_V(8); PG8_WAIT_L(0); PG8_BAR; PG8_MMA(0, 0, At, B0); PG8_MMA(0, 1, At, B1); PG8_BAR; PG8_SCHED;
;             PG8_LDA(At, 1, 1); PG8_STAGE(PG8_SB(1, 0), b3, voffB); PG8_STAGE(PG8_SB(1, 1), b3 + hstepB, voffB); PG8_STAGE(PG8_SA(1, 0), a3, voffA);
;             PG8_WAIT_V(8); PG8_WAIT_L(0); PG8_BAR; PG8_MMA(1, 0, At, B0); PG8_MMA(1, 1, At, B1); PG8_BAR; PG8_SCHED;
;         }
;         if (wr == 0) PG8_BAR;
	s_nop 4
	s_add_u32 s44, s50, 0x40000
	s_addc_u32 s45, s51, 0
	s_mov_b32 m0, s56
	v_lshl_add_u64 v[88:89], s[44:45], 0, v[128:129]
	global_load_lds_dwordx4 v[88:89], off
	v_lshl_add_u64 v[88:89], s[44:45], 0, v[132:133]
	s_mov_b32 m0, s57
	s_nop 0
	global_load_lds_dwordx4 v[88:89], off
	ds_read_b128 v[8:11], v148
	ds_read_b128 v[12:15], v148 offset:1024
	ds_read_b128 v[16:19], v148 offset:2048
	ds_read_b128 v[20:23], v148 offset:3072
	ds_read_b128 v[176:179], v224
	ds_read_b128 v[196:199], v224 offset:1024
	ds_read_b128 v[200:203], v224 offset:2048
	ds_read_b128 v[224:227], v224 offset:3072
	ds_read_b128 v[24:27], v156 offset:32768
	ds_read_b128 v[28:31], v156 offset:33792
	ds_read_b128 v[60:63], v156 offset:34816
	ds_read_b128 v[100:103], v156 offset:35840
	ds_read_b128 v[228:231], v156 offset:36864
	ds_read_b128 v[232:235], v156 offset:37888
	ds_read_b128 v[236:239], v156 offset:38912
	ds_read_b128 v[240:243], v156 offset:39936
	s_waitcnt vmcnt(8)
	s_waitcnt lgkmcnt(0)
	s_barrier
	s_setprio 1
	s_waitcnt lgkmcnt(0)
	v_mfma_f32_16x16x32_bf16 v[64:67], v[8:11], v[24:27], v[64:67]
	v_mfma_f32_16x16x32_bf16 v[124:127], v[12:15], v[28:31], v[64:67]
	v_mfma_f32_16x16x32_bf16 v[64:67], v[16:19], v[24:27], v[68:71]
	v_mfma_f32_16x16x32_bf16 v[120:123], v[20:23], v[28:31], v[64:67]
	v_mfma_f32_16x16x32_bf16 v[64:67], v[8:11], v[60:63], v[72:75]
	v_mfma_f32_16x16x32_bf16 v[108:111], v[12:15], v[100:103], v[64:67]
	v_mfma_f32_16x16x32_bf16 v[64:67], v[16:19], v[60:63], v[76:79]
	v_mfma_f32_16x16x32_bf16 v[104:107], v[20:23], v[100:103], v[64:67]
	v_mfma_f32_16x16x32_bf16 v[64:67], v[8:11], v[228:231], v[80:83]
	v_mfma_f32_16x16x32_bf16 v[92:95], v[12:15], v[232:235], v[64:67]
	v_mfma_f32_16x16x32_bf16 v[64:67], v[16:19], v[228:231], v[84:87]
	v_mfma_f32_16x16x32_bf16 v[88:91], v[20:23], v[232:235], v[64:67]
	v_mfma_f32_16x16x32_bf16 v[64:67], v[8:11], v[236:239], v[212:215]
	v_mfma_f32_16x16x32_bf16 v[76:79], v[12:15], v[240:243], v[64:67]
	v_mfma_f32_16x16x32_bf16 v[64:67], v[16:19], v[236:239], v[216:219]
	v_mfma_f32_16x16x32_bf16 v[72:75], v[20:23], v[240:243], v[64:67]
	s_setprio 0
	s_setprio 1
	v_mfma_f32_16x16x32_bf16 v[64:67], v[176:179], v[24:27], v[96:99]
	v_mfma_f32_16x16x32_bf16 v[24:27], v[200:203], v[24:27], v[32:35]
	v_mfma_f32_16x16x32_bf16 v[116:119], v[224:227], v[28:31], v[24:27]
	v_mfma_f32_16x16x32_bf16 v[24:27], v[176:179], v[60:63], v[36:39]
	v_mfma_f32_16x16x32_bf16 v[96:99], v[196:199], v[100:103], v[24:27]
	v_mfma_f32_16x16x32_bf16 v[24:27], v[200:203], v[60:63], v[40:43]
	v_mfma_f32_16x16x32_bf16 v[100:103], v[224:227], v[100:103], v[24:27]
	v_mfma_f32_16x16x32_bf16 v[24:27], v[176:179], v[228:231], v[44:47]
	v_mfma_f32_16x16x32_bf16 v[80:83], v[196:199], v[232:235], v[24:27]
	v_mfma_f32_16x16x32_bf16 v[24:27], v[200:203], v[228:231], v[48:51]
	v_mfma_f32_16x16x32_bf16 v[84:87], v[224:227], v[232:235], v[24:27]
	v_mfma_f32_16x16x32_bf16 v[24:27], v[176:179], v[236:239], v[52:55]
	v_mfma_f32_16x16x32_bf16 v[112:115], v[196:199], v[28:31], v[64:67]
	v_mfma_f32_16x16x32_bf16 v[64:67], v[196:199], v[240:243], v[24:27]
	v_mfma_f32_16x16x32_bf16 v[24:27], v[200:203], v[236:239], v[56:59]
	v_mfma_f32_16x16x32_bf16 v[68:71], v[224:227], v[240:243], v[24:27]
	s_setprio 0
	s_barrier
	s_mov_b32 m0, s76
	s_nop 3
	v_lshl_add_u64 v[24:25], v[244:245], 0, s[24:25]
	s_add_u32 s44, s48, 0x10080
	global_load_lds_dwordx4 v[24:25], off
	v_lshl_add_u64 v[24:25], v[246:247], 0, s[24:25]
	s_mov_b32 m0, s74
	s_addc_u32 s45, s49, 0
	global_load_lds_dwordx4 v[24:25], off
	v_lshl_add_u64 v[24:25], s[44:45], 0, v[130:131]
	s_mov_b32 m0, s46
	s_nop 0
	global_load_lds_dwordx4 v[24:25], off
	v_lshl_add_u64 v[24:25], s[44:45], 0, v[134:135]
	s_mov_b32 m0, s47
	s_nop 0
	global_load_lds_dwordx4 v[24:25], off
	v_lshl_add_u64 v[24:25], v[248:249], 0, s[24:25]
	s_mov_b32 m0, s60
	s_nop 0
	global_load_lds_dwordx4 v[24:25], off
	v_lshl_add_u64 v[24:25], v[250:251], 0, s[24:25]
	s_mov_b32 m0, s61
	s_nop 0
	global_load_lds_dwordx4 v[24:25], off
	ds_read_b128 v[32:35], v156 offset:49152
	ds_read_b128 v[36:39], v156 offset:50176
	ds_read_b128 v[212:215], v156 offset:51200
	ds_read_b128 v[216:219], v156 offset:52224
	ds_read_b128 v[228:231], v156 offset:53248
	ds_read_b128 v[232:235], v156 offset:54272
	ds_read_b128 v[236:239], v156 offset:55296
	ds_read_b128 v[240:243], v156 offset:56320
	s_waitcnt vmcnt(8)
	s_waitcnt lgkmcnt(0)
	s_barrier
	s_setprio 1
	s_waitcnt lgkmcnt(0)
	v_mfma_f32_16x16x32_bf16 v[24:27], v[8:11], v[32:35], v[140:143]
	v_mfma_f32_16x16x32_bf16 v[60:63], v[12:15], v[36:39], v[24:27]
	v_mfma_f32_16x16x32_bf16 v[24:27], v[16:19], v[32:35], v[144:147]
	v_mfma_f32_16x16x32_bf16 v[56:59], v[20:23], v[36:39], v[24:27]
	v_mfma_f32_16x16x32_bf16 v[24:27], v[8:11], v[212:215], v[150:153]
	v_mfma_f32_16x16x32_bf16 v[44:47], v[12:15], v[216:219], v[24:27]
	v_mfma_f32_16x16x32_bf16 v[24:27], v[16:19], v[212:215], v[160:163]
	v_mfma_f32_16x16x32_bf16 v[40:43], v[20:23], v[216:219], v[24:27]
	v_mfma_f32_16x16x32_bf16 v[24:27], v[8:11], v[228:231], v[164:167]
	v_mfma_f32_16x16x32_bf16 v[0:3], v[8:11], v[236:239], v[0:3]
	v_mfma_f32_16x16x32_bf16 v[28:31], v[12:15], v[232:235], v[24:27]
	v_mfma_f32_16x16x32_bf16 v[24:27], v[16:19], v[228:231], v[168:171]
	v_mfma_f32_16x16x32_bf16 v[12:15], v[12:15], v[240:243], v[0:3]
	v_mfma_f32_16x16x32_bf16 v[0:3], v[16:19], v[236:239], v[4:7]
	v_mfma_f32_16x16x32_bf16 v[24:27], v[20:23], v[232:235], v[24:27]
	v_mfma_f32_16x16x32_bf16 v[8:11], v[20:23], v[240:243], v[0:3]
	s_setprio 0
	s_setprio 1
	v_mfma_f32_16x16x32_bf16 v[0:3], v[176:179], v[32:35], v[204:207]
	v_mfma_f32_16x16x32_bf16 v[48:51], v[196:199], v[36:39], v[0:3]
	v_mfma_f32_16x16x32_bf16 v[0:3], v[200:203], v[32:35], v[208:211]
	v_mfma_f32_16x16x32_bf16 v[52:55], v[224:227], v[36:39], v[0:3]
	v_mfma_f32_16x16x32_bf16 v[0:3], v[176:179], v[212:215], v[220:223]
	v_mfma_f32_16x16x32_bf16 v[32:35], v[196:199], v[216:219], v[0:3]
	v_mfma_f32_16x16x32_bf16 v[0:3], v[200:203], v[212:215], v[180:183]
	v_mfma_f32_16x16x32_bf16 v[36:39], v[224:227], v[216:219], v[0:3]
	v_mfma_f32_16x16x32_bf16 v[0:3], v[176:179], v[228:231], v[184:187]
	v_mfma_f32_16x16x32_bf16 v[16:19], v[196:199], v[232:235], v[0:3]
	v_mfma_f32_16x16x32_bf16 v[0:3], v[200:203], v[228:231], v[188:191]
	v_mfma_f32_16x16x32_bf16 v[20:23], v[224:227], v[232:235], v[0:3]
	v_mfma_f32_16x16x32_bf16 v[0:3], v[176:179], v[236:239], v[192:195]
	v_mfma_f32_16x16x32_bf16 v[4:7], v[200:203], v[236:239], v[172:175]
	v_mfma_f32_16x16x32_bf16 v[0:3], v[196:199], v[240:243], v[0:3]
	v_mfma_f32_16x16x32_bf16 v[4:7], v[224:227], v[240:243], v[4:7]
	s_setprio 0
	s_barrier
	s_andn2_b64 vcc, exec, s[26:27]
	s_cbranch_vccnz .LBB0_1549
	s_barrier

; #define PG8_STAGE(bufoff, gbase, voff) do { _Pragma("unroll") for (int _i = 0; _i < 2; ++_i) \
;         __builtin_amdgcn_global_load_lds((const unsigned*)((const char*)(gbase) + (voff)[_i]), (LAS unsigned*)(lds + (bufoff) + ldsw + _i * 8192), 16, 0, 0); } while (0)
; #define PG8_LDA(dst, b, h) do { _Pragma("unroll") for (int m = 0; m < 4; ++m) _Pragma("unroll") for (int k = 0; k < 2; ++k) dst[m][k] = *(const LAS bf16x8*)(lds + PG8_SA(b, h) + aoff + m * 2048 + k * 1024); } while (0)
; #define PG8_LDB(dst, b, h) do { _Pragma("unroll") for (int n = 0; n < 2; ++n) _Pragma("unroll") for (int k = 0; k < 2; ++k) dst[n][k] = *(const LAS bf16x8*)(lds + PG8_SB(b, h) + boff + n * 2048 + k * 1024); } while (0)
; #define PG8_MMA(ai, bj, At, Bt) do { __builtin_amdgcn_s_setprio(1); _Pragma("unroll") for (int m = 0; m < 4; ++m) _Pragma("unroll") for (int n = 0; n < 2; ++n) _Pragma("unroll") for (int k = 0; k < 2; ++k) \
;         acc[ai][bj][m][n] = __builtin_amdgcn_mfma_f32_16x16x32_bf16(Bt[n][k], At[m][k], acc[ai][bj][m][n], 0, 0, 0); __builtin_amdgcn_s_setprio(0); } while (0)
; #define PG8_BAR __builtin_amdgcn_s_barrier()
; template <class Epi>
; __device__ __forceinline__ void gemm_phase(LAS unsigned char* lds, const Gemm g, const StaticOrder& S, const Epi& E, int wave_s) {
;     ...
;         const bool has_next = S.next(ui + 1, nxt);
;         const char* nA = has_next ? (const char*)g.A + (size_t)nxt.pm * tstepA : cA; const char* nB = has_next ? (const char*)g.Bt + (size_t)nxt.pn * tstepB : cB;
;         for (int t = 0; t < nt; t += 2) {
;             const bool last = (t == nt - 2);
;             const char* a1 = cA + (size_t)(t + 1) * kstep;
;             const char* a2 = last ? nA : cA + (size_t)(t + 2) * kstep; const char* b2 = last ? nB : cB + (size_t)(t + 2) * kstep;
;             const char* a3 = a2 + kstep; const char* b3 = b2 + kstep;
;             PG8_LDB(B0, 0, 0); PG8_LDB(B1, 0, 1); PG8_SCHED; PG8_LDA(At, 0, 0); PG8_STAGE(PG8_SA(1, 1), a1 + hstepA, voffA);
;             PG8_WAIT_V(8); PG8_WAIT_L(0); PG8_BAR; PG8_MMA(0, 0, At, B0); PG8_MMA(0, 1, At, B1); PG8_BAR; PG8_SCHED;
;             PG8_LDA(At, 0, 1); PG8_STAGE(PG8_SB(0, 0), b2, voffB); PG8_STAGE(PG8_SB(0, 1), b2 + hstepB, voffB); PG8_STAGE(PG8_SA(0, 0), a2, voffA);
;             PG8_WAIT_V(8); PG8_WAIT_L(0); PG8_BAR; PG8_MMA(1, 0, At, B0); PG8_MMA(1, 1, At, B1); PG8_BAR; PG8_SCHED;
.LBB0_1570:
	s_add_u32 s49, s10, s48
	s_addc_u32 s54, s11, 0
	s_add_u32 s52, s49, 0x100
	s_addc_u32 s53, s54, 0
	s_and_b64 s[50:51], s[46:47], exec
	s_cselect_b32 s51, s37, s53
	s_cselect_b32 s50, s73, s52
	s_add_u32 s48, s8, s48
	s_addc_u32 s52, s9, 0
	s_add_u32 s48, s48, 0x100
	s_addc_u32 s52, s52, 0
	s_and_b64 s[46:47], s[46:47], exec
	s_cselect_b32 s53, s35, s52
	s_cselect_b32 s52, s74, s48
	s_add_u32 s56, s49, 0x10080
	s_addc_u32 s57, s54, 0
	s_add_i32 s84, s66, s58
	s_add_i32 m0, s43, 0xc000
	s_add_i32 s87, s43, 0xe000
	s_add_i32 s79, s84, 0x2000
	s_add_u32 s54, s52, 0x40000
	s_addc_u32 s55, s53, 0
	s_add_i32 s83, s67, s58
	s_add_i32 s82, s83, 0x2000
	s_add_i32 s78, 0, 0x18000
	s_add_i32 s77, 0, 0x1c000
	s_add_u32 s48, s50, 0x10000
	s_addc_u32 s49, s51, 0
	s_add_i32 s76, s78, s58
	s_add_i32 s75, s76, 0x2000
	s_add_u32 s46, s52, 0x40080
	s_addc_u32 s47, s53, 0
	s_add_i32 s86, s77, s58
	s_add_i32 s85, s86, 0x2000
	v_lshl_add_u64 v[156:157], s[56:57], 0, v[128:129]
	global_load_lds_dwordx4 v[156:157], off
	v_lshl_add_u64 v[156:157], s[56:57], 0, v[132:133]
	s_mov_b32 m0, s87
	s_nop 0
	global_load_lds_dwordx4 v[156:157], off
	ds_read_b128 v[140:143], v161
	ds_read_b128 v[144:147], v161 offset:1024
	ds_read_b128 v[148:151], v161 offset:2048
	ds_read_b128 v[152:155], v161 offset:3072
	ds_read_b128 v[166:169], v162
	ds_read_b128 v[170:173], v162 offset:1024
	ds_read_b128 v[174:177], v162 offset:2048
	ds_read_b128 v[178:181], v162 offset:3072
	ds_read_b128 v[182:185], v163
	ds_read_b128 v[186:189], v163 offset:1024
	ds_read_b128 v[190:193], v163 offset:2048
	ds_read_b128 v[194:197], v163 offset:3072
	ds_read_b128 v[198:201], v163 offset:4096
	ds_read_b128 v[202:205], v163 offset:5120
	ds_read_b128 v[206:209], v163 offset:6144
	ds_read_b128 v[210:213], v163 offset:7168
	s_waitcnt vmcnt(8)
	s_waitcnt lgkmcnt(0)
	s_barrier
	s_setprio 1
	s_waitcnt lgkmcnt(0)
	v_mfma_f32_16x16x32_bf16 v[124:127], v[140:143], v[182:185], v[124:127]
	v_mfma_f32_16x16x32_bf16 v[120:123], v[148:151], v[182:185], v[120:123]
	v_mfma_f32_16x16x32_bf16 v[112:115], v[140:143], v[190:193], v[112:115]
	v_mfma_f32_16x16x32_bf16 v[108:111], v[148:151], v[190:193], v[108:111]
	v_mfma_f32_16x16x32_bf16 v[100:103], v[140:143], v[198:201], v[100:103]
	v_mfma_f32_16x16x32_bf16 v[92:95], v[148:151], v[198:201], v[92:95]
	v_mfma_f32_16x16x32_bf16 v[84:87], v[140:143], v[206:209], v[84:87]
	v_mfma_f32_16x16x32_bf16 v[76:79], v[148:151], v[206:209], v[76:79]
	v_mfma_f32_16x16x32_bf16 v[124:127], v[144:147], v[186:189], v[124:127]
	v_mfma_f32_16x16x32_bf16 v[120:123], v[152:155], v[186:189], v[120:123]
	v_mfma_f32_16x16x32_bf16 v[112:115], v[144:147], v[194:197], v[112:115]
	v_mfma_f32_16x16x32_bf16 v[108:111], v[152:155], v[194:197], v[108:111]
	v_mfma_f32_16x16x32_bf16 v[100:103], v[144:147], v[202:205], v[100:103]
	v_mfma_f32_16x16x32_bf16 v[92:95], v[152:155], v[202:205], v[92:95]
	v_mfma_f32_16x16x32_bf16 v[84:87], v[144:147], v[210:213], v[84:87]
	v_mfma_f32_16x16x32_bf16 v[76:79], v[152:155], v[210:213], v[76:79]
	s_setprio 0
	s_setprio 1
	v_mfma_f32_16x16x32_bf16 v[116:119], v[166:169], v[182:185], v[116:119]
	v_mfma_f32_16x16x32_bf16 v[104:107], v[174:177], v[182:185], v[104:107]
	v_mfma_f32_16x16x32_bf16 v[96:99], v[166:169], v[190:193], v[96:99]
	v_mfma_f32_16x16x32_bf16 v[88:91], v[174:177], v[190:193], v[88:91]
	v_mfma_f32_16x16x32_bf16 v[80:83], v[166:169], v[198:201], v[80:83]
	v_mfma_f32_16x16x32_bf16 v[72:75], v[174:177], v[198:201], v[72:75]
	v_mfma_f32_16x16x32_bf16 v[68:71], v[166:169], v[206:209], v[68:71]
	v_mfma_f32_16x16x32_bf16 v[64:67], v[174:177], v[206:209], v[64:67]
	v_mfma_f32_16x16x32_bf16 v[116:119], v[170:173], v[186:189], v[116:119]
	v_mfma_f32_16x16x32_bf16 v[104:107], v[178:181], v[186:189], v[104:107]
	v_mfma_f32_16x16x32_bf16 v[96:99], v[170:173], v[194:197], v[96:99]
	v_mfma_f32_16x16x32_bf16 v[88:91], v[178:181], v[194:197], v[88:91]
	v_mfma_f32_16x16x32_bf16 v[80:83], v[170:173], v[202:205], v[80:83]
	v_mfma_f32_16x16x32_bf16 v[72:75], v[178:181], v[202:205], v[72:75]
	v_mfma_f32_16x16x32_bf16 v[68:71], v[170:173], v[210:213], v[68:71]
	v_mfma_f32_16x16x32_bf16 v[64:67], v[178:181], v[210:213], v[64:67]
	s_setprio 0
	s_barrier
	s_mov_b32 m0, s84
	v_lshl_add_u64 v[156:157], s[52:53], 0, v[130:131]
	global_load_lds_dwordx4 v[156:157], off
	v_lshl_add_u64 v[214:215], s[52:53], 0, v[134:135]
	s_mov_b32 m0, s79
	v_lshl_add_u64 v[216:217], s[54:55], 0, v[130:131]
	global_load_lds_dwordx4 v[214:215], off
	s_mov_b32 m0, s83
	v_lshl_add_u64 v[218:219], s[50:51], 0, v[132:133]
	global_load_lds_dwordx4 v[216:217], off
	v_lshl_add_u64 v[216:217], s[54:55], 0, v[134:135]
	s_mov_b32 m0, s82
	s_nop 0
	global_load_lds_dwordx4 v[216:217], off
	v_lshl_add_u64 v[216:217], s[50:51], 0, v[128:129]
	s_mov_b32 m0, s43
	s_nop 0
	global_load_lds_dwordx4 v[216:217], off
	s_mov_b32 m0, s59
	s_nop 0
	global_load_lds_dwordx4 v[218:219], off
	ds_read_b128 v[182:185], v163 offset:16384
	ds_read_b128 v[186:189], v163 offset:17408
	ds_read_b128 v[190:193], v163 offset:18432
	ds_read_b128 v[194:197], v163 offset:19456
	ds_read_b128 v[198:201], v163 offset:20480
	ds_read_b128 v[202:205], v163 offset:21504
	ds_read_b128 v[206:209], v163 offset:22528
	ds_read_b128 v[210:213], v163 offset:23552
	s_waitcnt vmcnt(8)
	s_waitcnt lgkmcnt(0)
	s_barrier
; #define PG8_STAGE(bufoff, gbase, voff) do { _Pragma("unroll") for (int _i = 0; _i < 2; ++_i) \
;         __builtin_amdgcn_global_load_lds((const unsigned*)((const char*)(gbase) + (voff)[_i]), (LAS unsigned*)(lds + (bufoff) + ldsw + _i * 8192), 16, 0, 0); } while (0)
; #define PG8_LDA(dst, b, h) do { _Pragma("unroll") for (int m = 0; m < 4; ++m) _Pragma("unroll") for (int k = 0; k < 2; ++k) dst[m][k] = *(const LAS bf16x8*)(lds + PG8_SA(b, h) + aoff + m * 2048 + k * 1024); } while (0)
; #define PG8_LDB(dst, b, h) do { _Pragma("unroll") for (int n = 0; n < 2; ++n) _Pragma("unroll") for (int k = 0; k < 2; ++k) dst[n][k] = *(const LAS bf16x8*)(lds + PG8_SB(b, h) + boff + n * 2048 + k * 1024); } while (0)
; #define PG8_MMA(ai, bj, At, Bt) do { __builtin_amdgcn_s_setprio(1); _Pragma("unroll") for (int m = 0; m < 4; ++m) _Pragma("unroll") for (int n = 0; n < 2; ++n) _Pragma("unroll") for (int k = 0; k < 2; ++k) \
;         acc[ai][bj][m][n] = __builtin_amdgcn_mfma_f32_16x16x32_bf16(Bt[n][k], At[m][k], acc[ai][bj][m][n], 0, 0, 0); __builtin_amdgcn_s_setprio(0); } while (0)
; #define PG8_WAIT_V(n) asm volatile("s_waitcnt vmcnt(" #n ")" ::: "memory")
; #define PG8_WAIT_L(n) asm volatile("s_waitcnt lgkmcnt(" #n ")" ::: "memory")
; #define PG8_BAR __builtin_amdgcn_s_barrier()
; #define PG8_SCHED __builtin_amdgcn_sched_barrier(0)
; template <class Epi>
; __device__ __forceinline__ void gemm_phase(LAS unsigned char* lds, const Gemm g, const StaticOrder& S, const Epi& E, int wave_s) {
;     ...
;             PG8_WAIT_V(8); PG8_WAIT_L(0); PG8_BAR; PG8_MMA(0, 0, At, B0); PG8_MMA(0, 1, At, B1); PG8_BAR; PG8_SCHED;
;             PG8_LDA(At, 0, 1); PG8_STAGE(PG8_SB(0, 0), b2, voffB); PG8_STAGE(PG8_SB(0, 1), b2 + hstepB, voffB); PG8_STAGE(PG8_SA(0, 0), a2, voffA);
;             PG8_WAIT_V(8); PG8_WAIT_L(0); PG8_BAR; PG8_MMA(1, 0, At, B0); PG8_MMA(1, 1, At, B1); PG8_BAR; PG8_SCHED;
;             PG8_LDB(B0, 1, 0); PG8_LDB(B1, 1, 1); PG8_SCHED; PG8_LDA(At, 1, 0); PG8_STAGE(PG8_SA(0, 1), a2 + hstepA, voffA);
;             PG8_WAIT_V(8); PG8_WAIT_L(0); PG8_BAR; PG8_MMA(0, 0, At, B0); PG8_MMA(0, 1, At, B1); PG8_BAR; PG8_SCHED;
	s_setprio 1
	s_waitcnt lgkmcnt(0)
	v_mfma_f32_16x16x32_bf16 v[60:63], v[140:143], v[182:185], v[60:63]
	v_mfma_f32_16x16x32_bf16 v[56:59], v[148:151], v[182:185], v[56:59]
	v_mfma_f32_16x16x32_bf16 v[52:55], v[140:143], v[190:193], v[52:55]
	v_mfma_f32_16x16x32_bf16 v[44:47], v[148:151], v[190:193], v[44:47]
	v_mfma_f32_16x16x32_bf16 v[36:39], v[140:143], v[198:201], v[36:39]
	v_mfma_f32_16x16x32_bf16 v[28:31], v[148:151], v[198:201], v[28:31]
	v_mfma_f32_16x16x32_bf16 v[20:23], v[140:143], v[206:209], v[20:23]
	v_mfma_f32_16x16x32_bf16 v[12:15], v[148:151], v[206:209], v[12:15]
	v_mfma_f32_16x16x32_bf16 v[60:63], v[144:147], v[186:189], v[60:63]
	v_mfma_f32_16x16x32_bf16 v[56:59], v[152:155], v[186:189], v[56:59]
	v_mfma_f32_16x16x32_bf16 v[52:55], v[144:147], v[194:197], v[52:55]
	v_mfma_f32_16x16x32_bf16 v[44:47], v[152:155], v[194:197], v[44:47]
	v_mfma_f32_16x16x32_bf16 v[36:39], v[144:147], v[202:205], v[36:39]
	v_mfma_f32_16x16x32_bf16 v[28:31], v[152:155], v[202:205], v[28:31]
	v_mfma_f32_16x16x32_bf16 v[20:23], v[144:147], v[210:213], v[20:23]
	v_mfma_f32_16x16x32_bf16 v[12:15], v[152:155], v[210:213], v[12:15]
	s_setprio 0
	s_setprio 1
	v_mfma_f32_16x16x32_bf16 v[48:51], v[166:169], v[182:185], v[48:51]
	v_mfma_f32_16x16x32_bf16 v[40:43], v[174:177], v[182:185], v[40:43]
	v_mfma_f32_16x16x32_bf16 v[32:35], v[166:169], v[190:193], v[32:35]
	v_mfma_f32_16x16x32_bf16 v[24:27], v[174:177], v[190:193], v[24:27]
	v_mfma_f32_16x16x32_bf16 v[16:19], v[166:169], v[198:201], v[16:19]
	v_mfma_f32_16x16x32_bf16 v[8:11], v[174:177], v[198:201], v[8:11]
	v_mfma_f32_16x16x32_bf16 v[4:7], v[166:169], v[206:209], v[4:7]
	v_mfma_f32_16x16x32_bf16 v[0:3], v[174:177], v[206:209], v[0:3]
	v_mfma_f32_16x16x32_bf16 v[48:51], v[170:173], v[186:189], v[48:51]
	v_mfma_f32_16x16x32_bf16 v[40:43], v[178:181], v[186:189], v[40:43]
	v_mfma_f32_16x16x32_bf16 v[32:35], v[170:173], v[194:197], v[32:35]
	v_mfma_f32_16x16x32_bf16 v[24:27], v[178:181], v[194:197], v[24:27]
	v_mfma_f32_16x16x32_bf16 v[16:19], v[170:173], v[202:205], v[16:19]
	v_mfma_f32_16x16x32_bf16 v[8:11], v[178:181], v[202:205], v[8:11]
	v_mfma_f32_16x16x32_bf16 v[4:7], v[170:173], v[210:213], v[4:7]
	v_mfma_f32_16x16x32_bf16 v[0:3], v[178:181], v[210:213], v[0:3]
	s_setprio 0
	s_barrier
	s_mov_b32 m0, s60
	v_lshl_add_u64 v[220:221], s[48:49], 0, v[128:129]
	global_load_lds_dwordx4 v[220:221], off
	v_lshl_add_u64 v[220:221], s[48:49], 0, v[132:133]
	s_mov_b32 m0, s61
	s_nop 0
	global_load_lds_dwordx4 v[220:221], off
	v_add_u32_e32 v152, s78, v159
	v_add_u32_e32 v178, s77, v159
	ds_read_b128 v[140:143], v152
	ds_read_b128 v[144:147], v152 offset:1024
	ds_read_b128 v[148:151], v152 offset:2048
	ds_read_b128 v[152:155], v152 offset:3072
	ds_read_b128 v[166:169], v178
	ds_read_b128 v[170:173], v178 offset:1024
	ds_read_b128 v[174:177], v178 offset:2048
	ds_read_b128 v[178:181], v178 offset:3072
	ds_read_b128 v[182:185], v163 offset:32768
	ds_read_b128 v[186:189], v163 offset:33792
	ds_read_b128 v[190:193], v163 offset:34816
	ds_read_b128 v[194:197], v163 offset:35840
	ds_read_b128 v[198:201], v163 offset:36864
	ds_read_b128 v[202:205], v163 offset:37888
	ds_read_b128 v[206:209], v163 offset:38912
	ds_read_b128 v[210:213], v163 offset:39936
	s_waitcnt vmcnt(8)
	s_waitcnt lgkmcnt(0)
	s_barrier
	s_setprio 1
	s_waitcnt lgkmcnt(0)
	v_mfma_f32_16x16x32_bf16 v[124:127], v[140:143], v[182:185], v[124:127]
	v_mfma_f32_16x16x32_bf16 v[120:123], v[148:151], v[182:185], v[120:123]
	v_mfma_f32_16x16x32_bf16 v[112:115], v[140:143], v[190:193], v[112:115]
	v_mfma_f32_16x16x32_bf16 v[108:111], v[148:151], v[190:193], v[108:111]
	v_mfma_f32_16x16x32_bf16 v[100:103], v[140:143], v[198:201], v[100:103]
	v_mfma_f32_16x16x32_bf16 v[92:95], v[148:151], v[198:201], v[92:95]
	v_mfma_f32_16x16x32_bf16 v[84:87], v[140:143], v[206:209], v[84:87]
	v_mfma_f32_16x16x32_bf16 v[76:79], v[148:151], v[206:209], v[76:79]
	v_mfma_f32_16x16x32_bf16 v[124:127], v[144:147], v[186:189], v[124:127]
	v_mfma_f32_16x16x32_bf16 v[120:123], v[152:155], v[186:189], v[120:123]
	v_mfma_f32_16x16x32_bf16 v[112:115], v[144:147], v[194:197], v[112:115]
	v_mfma_f32_16x16x32_bf16 v[108:111], v[152:155], v[194:197], v[108:111]
	v_mfma_f32_16x16x32_bf16 v[100:103], v[144:147], v[202:205], v[100:103]
	v_mfma_f32_16x16x32_bf16 v[92:95], v[152:155], v[202:205], v[92:95]
	v_mfma_f32_16x16x32_bf16 v[84:87], v[144:147], v[210:213], v[84:87]
	v_mfma_f32_16x16x32_bf16 v[76:79], v[152:155], v[210:213], v[76:79]
	s_setprio 0
	s_setprio 1
	v_mfma_f32_16x16x32_bf16 v[116:119], v[166:169], v[182:185], v[116:119]
	v_mfma_f32_16x16x32_bf16 v[104:107], v[174:177], v[182:185], v[104:107]
	v_mfma_f32_16x16x32_bf16 v[96:99], v[166:169], v[190:193], v[96:99]
	v_mfma_f32_16x16x32_bf16 v[88:91], v[174:177], v[190:193], v[88:91]
	v_mfma_f32_16x16x32_bf16 v[80:83], v[166:169], v[198:201], v[80:83]
	v_mfma_f32_16x16x32_bf16 v[72:75], v[174:177], v[198:201], v[72:75]
	v_mfma_f32_16x16x32_bf16 v[68:71], v[166:169], v[206:209], v[68:71]
	v_mfma_f32_16x16x32_bf16 v[64:67], v[174:177], v[206:209], v[64:67]
	v_mfma_f32_16x16x32_bf16 v[116:119], v[170:173], v[186:189], v[116:119]
	v_mfma_f32_16x16x32_bf16 v[104:107], v[178:181], v[186:189], v[104:107]
	v_mfma_f32_16x16x32_bf16 v[96:99], v[170:173], v[194:197], v[96:99]
	v_mfma_f32_16x16x32_bf16 v[88:91], v[178:181], v[194:197], v[88:91]
	v_mfma_f32_16x16x32_bf16 v[80:83], v[170:173], v[202:205], v[80:83]
	v_mfma_f32_16x16x32_bf16 v[72:75], v[178:181], v[202:205], v[72:75]
	v_mfma_f32_16x16x32_bf16 v[68:71], v[170:173], v[210:213], v[68:71]
	v_mfma_f32_16x16x32_bf16 v[64:67], v[178:181], v[210:213], v[64:67]
	s_setprio 0
	s_barrier
; #define PG8_STAGE(bufoff, gbase, voff) do { _Pragma("unroll") for (int _i = 0; _i < 2; ++_i) \
;         __builtin_amdgcn_global_load_lds((const unsigned*)((const char*)(gbase) + (voff)[_i]), (LAS unsigned*)(lds + (bufoff) + ldsw + _i * 8192), 16, 0, 0); } while (0)
; #define PG8_LDA(dst, b, h) do { _Pragma("unroll") for (int m = 0; m < 4; ++m) _Pragma("unroll") for (int k = 0; k < 2; ++k) dst[m][k] = *(const LAS bf16x8*)(lds + PG8_SA(b, h) + aoff + m * 2048 + k * 1024); } while (0)
; #define PG8_MMA(ai, bj, At, Bt) do { __builtin_amdgcn_s_setprio(1); _Pragma("unroll") for (int m = 0; m < 4; ++m) _Pragma("unroll") for (int n = 0; n < 2; ++n) _Pragma("unroll") for (int k = 0; k < 2; ++k) \
;         acc[ai][bj][m][n] = __builtin_amdgcn_mfma_f32_16x16x32_bf16(Bt[n][k], At[m][k], acc[ai][bj][m][n], 0, 0, 0); __builtin_amdgcn_s_setprio(0); } while (0)
; #define PG8_WAIT_V(n) asm volatile("s_waitcnt vmcnt(" #n ")" ::: "memory")
; #define PG8_WAIT_L(n) asm volatile("s_waitcnt lgkmcnt(" #n ")" ::: "memory")
; #define PG8_BAR __builtin_amdgcn_s_barrier()
; #define PG8_SCHED __builtin_amdgcn_sched_barrier(0)
; template <class Epi>
; __device__ __forceinline__ void gemm_phase(LAS unsigned char* lds, const Gemm g, const StaticOrder& S, const Epi& E, int wave_s) {
;     ...
;             PG8_WAIT_V(8); PG8_WAIT_L(0); PG8_BAR; PG8_MMA(0, 0, At, B0); PG8_MMA(0, 1, At, B1); PG8_BAR; PG8_SCHED;
;             PG8_LDA(At, 1, 1); PG8_STAGE(PG8_SB(1, 0), b3, voffB); PG8_STAGE(PG8_SB(1, 1), b3 + hstepB, voffB); PG8_STAGE(PG8_SA(1, 0), a3, voffA);
;             PG8_WAIT_V(8); PG8_WAIT_L(0); PG8_BAR; PG8_MMA(1, 0, At, B0); PG8_MMA(1, 1, At, B1); PG8_BAR; PG8_SCHED;
;         }
;         if (wr == 0) PG8_BAR;
	s_mov_b32 m0, s76
	v_lshl_add_u64 v[156:157], v[156:157], 0, s[20:21]
	global_load_lds_dwordx4 v[156:157], off
	v_lshl_add_u64 v[156:157], v[214:215], 0, s[20:21]
	s_mov_b32 m0, s75
	s_nop 0
	global_load_lds_dwordx4 v[156:157], off
	v_lshl_add_u64 v[156:157], s[46:47], 0, v[130:131]
	s_mov_b32 m0, s86
	s_nop 0
	global_load_lds_dwordx4 v[156:157], off
	v_lshl_add_u64 v[156:157], s[46:47], 0, v[134:135]
	s_mov_b32 m0, s85
	s_nop 0
	global_load_lds_dwordx4 v[156:157], off
	v_lshl_add_u64 v[156:157], v[216:217], 0, s[20:21]
	s_mov_b32 m0, s5
	s_nop 0
	global_load_lds_dwordx4 v[156:157], off
	v_lshl_add_u64 v[156:157], v[218:219], 0, s[20:21]
	s_mov_b32 m0, s63
	s_nop 0
	global_load_lds_dwordx4 v[156:157], off
	ds_read_b128 v[182:185], v163 offset:49152
	ds_read_b128 v[186:189], v163 offset:50176
	ds_read_b128 v[190:193], v163 offset:51200
	ds_read_b128 v[194:197], v163 offset:52224
	ds_read_b128 v[198:201], v163 offset:53248
	ds_read_b128 v[202:205], v163 offset:54272
	ds_read_b128 v[206:209], v163 offset:55296
	ds_read_b128 v[210:213], v163 offset:56320
	s_waitcnt vmcnt(8)
	s_waitcnt lgkmcnt(0)
	s_barrier
	s_setprio 1
	s_waitcnt lgkmcnt(0)
	v_mfma_f32_16x16x32_bf16 v[60:63], v[140:143], v[182:185], v[60:63]
	v_mfma_f32_16x16x32_bf16 v[56:59], v[148:151], v[182:185], v[56:59]
	v_mfma_f32_16x16x32_bf16 v[52:55], v[140:143], v[190:193], v[52:55]
	v_mfma_f32_16x16x32_bf16 v[44:47], v[148:151], v[190:193], v[44:47]
	v_mfma_f32_16x16x32_bf16 v[36:39], v[140:143], v[198:201], v[36:39]
	v_mfma_f32_16x16x32_bf16 v[28:31], v[148:151], v[198:201], v[28:31]
	v_mfma_f32_16x16x32_bf16 v[20:23], v[140:143], v[206:209], v[20:23]
	v_mfma_f32_16x16x32_bf16 v[12:15], v[148:151], v[206:209], v[12:15]
	v_mfma_f32_16x16x32_bf16 v[60:63], v[144:147], v[186:189], v[60:63]
	v_mfma_f32_16x16x32_bf16 v[56:59], v[152:155], v[186:189], v[56:59]
	v_mfma_f32_16x16x32_bf16 v[52:55], v[144:147], v[194:197], v[52:55]
	v_mfma_f32_16x16x32_bf16 v[44:47], v[152:155], v[194:197], v[44:47]
	v_mfma_f32_16x16x32_bf16 v[36:39], v[144:147], v[202:205], v[36:39]
	v_mfma_f32_16x16x32_bf16 v[28:31], v[152:155], v[202:205], v[28:31]
	v_mfma_f32_16x16x32_bf16 v[20:23], v[144:147], v[210:213], v[20:23]
	v_mfma_f32_16x16x32_bf16 v[12:15], v[152:155], v[210:213], v[12:15]
	s_setprio 0
	s_setprio 1
	v_mfma_f32_16x16x32_bf16 v[48:51], v[166:169], v[182:185], v[48:51]
	v_mfma_f32_16x16x32_bf16 v[40:43], v[174:177], v[182:185], v[40:43]
	v_mfma_f32_16x16x32_bf16 v[32:35], v[166:169], v[190:193], v[32:35]
	v_mfma_f32_16x16x32_bf16 v[24:27], v[174:177], v[190:193], v[24:27]
	v_mfma_f32_16x16x32_bf16 v[16:19], v[166:169], v[198:201], v[16:19]
	v_mfma_f32_16x16x32_bf16 v[8:11], v[174:177], v[198:201], v[8:11]
	v_mfma_f32_16x16x32_bf16 v[4:7], v[166:169], v[206:209], v[4:7]
	v_mfma_f32_16x16x32_bf16 v[0:3], v[174:177], v[206:209], v[0:3]
	v_mfma_f32_16x16x32_bf16 v[48:51], v[170:173], v[186:189], v[48:51]
	v_mfma_f32_16x16x32_bf16 v[40:43], v[178:181], v[186:189], v[40:43]
	v_mfma_f32_16x16x32_bf16 v[32:35], v[170:173], v[194:197], v[32:35]
	v_mfma_f32_16x16x32_bf16 v[24:27], v[178:181], v[194:197], v[24:27]
	v_mfma_f32_16x16x32_bf16 v[16:19], v[170:173], v[202:205], v[16:19]
	v_mfma_f32_16x16x32_bf16 v[8:11], v[178:181], v[202:205], v[8:11]
	v_mfma_f32_16x16x32_bf16 v[4:7], v[170:173], v[210:213], v[4:7]
	v_mfma_f32_16x16x32_bf16 v[0:3], v[178:181], v[210:213], v[0:3]
	s_setprio 0
	s_barrier
	s_movk_i32 s48, 0x100
	s_andn2_b64 vcc, exec, s[44:45]
	s_mov_b64 s[46:47], -1
	s_mov_b64 s[44:45], 0
	s_cbranch_vccz .LBB0_1570
	s_and_b64 vcc, exec, s[22:23]
	s_cbranch_vccz .LBB0_1573
	s_barrier

; #define PG8_STAGE(bufoff, gbase, voff) do { _Pragma("unroll") for (int _i = 0; _i < 2; ++_i) \
;         __builtin_amdgcn_global_load_lds((const unsigned*)((const char*)(gbase) + (voff)[_i]), (LAS unsigned*)(lds + (bufoff) + ldsw + _i * 8192), 16, 0, 0); } while (0)
; #define PG8_LDA(dst, b, h) do { _Pragma("unroll") for (int m = 0; m < 4; ++m) _Pragma("unroll") for (int k = 0; k < 2; ++k) dst[m][k] = *(const LAS bf16x8*)(lds + PG8_SA(b, h) + aoff + m * 2048 + k * 1024); } while (0)
; #define PG8_LDB(dst, b, h) do { _Pragma("unroll") for (int n = 0; n < 2; ++n) _Pragma("unroll") for (int k = 0; k < 2; ++k) dst[n][k] = *(const LAS bf16x8*)(lds + PG8_SB(b, h) + boff + n * 2048 + k * 1024); } while (0)
; #define PG8_MMA(ai, bj, At, Bt) do { __builtin_amdgcn_s_setprio(1); _Pragma("unroll") for (int m = 0; m < 4; ++m) _Pragma("unroll") for (int n = 0; n < 2; ++n) _Pragma("unroll") for (int k = 0; k < 2; ++k) \
;         acc[ai][bj][m][n] = __builtin_amdgcn_mfma_f32_16x16x32_bf16(Bt[n][k], At[m][k], acc[ai][bj][m][n], 0, 0, 0); __builtin_amdgcn_s_setprio(0); } while (0)
; #define PG8_WAIT_V(n) asm volatile("s_waitcnt vmcnt(" #n ")" ::: "memory")
; #define PG8_WAIT_L(n) asm volatile("s_waitcnt lgkmcnt(" #n ")" ::: "memory")
; #define PG8_BAR __builtin_amdgcn_s_barrier()
; #define PG8_SCHED __builtin_amdgcn_sched_barrier(0)
; template <class Epi>
; __device__ __forceinline__ void gemm_phase(LAS unsigned char* lds, const Gemm g, const StaticOrder& S, const Epi& E, int wave_s) {
;     ...
;         for (int t = 0; t < nt; t += 2) {
;             const bool last = (t == nt - 2);
;             const char* a1 = cA + (size_t)(t + 1) * kstep;
;             const char* a2 = last ? nA : cA + (size_t)(t + 2) * kstep; const char* b2 = last ? nB : cB + (size_t)(t + 2) * kstep;
;             const char* a3 = a2 + kstep; const char* b3 = b2 + kstep;
;             PG8_LDB(B0, 0, 0); PG8_LDB(B1, 0, 1); PG8_SCHED; PG8_LDA(At, 0, 0); PG8_STAGE(PG8_SA(1, 1), a1 + hstepA, voffA);
;             PG8_WAIT_V(8); PG8_WAIT_L(0); PG8_BAR; PG8_MMA(0, 0, At, B0); PG8_MMA(0, 1, At, B1); PG8_BAR; PG8_SCHED;
;             PG8_LDA(At, 0, 1); PG8_STAGE(PG8_SB(0, 0), b2, voffB); PG8_STAGE(PG8_SB(0, 1), b2 + hstepB, voffB); PG8_STAGE(PG8_SA(0, 0), a2, voffA);
;             PG8_WAIT_V(8); PG8_WAIT_L(0); PG8_BAR; PG8_MMA(1, 0, At, B0); PG8_MMA(1, 1, At, B1); PG8_BAR; PG8_SCHED;
.LBB0_2225:
	s_add_u32 s24, s22, 0x100
	s_addc_u32 s25, s23, 0
	s_cmp_eq_u32 s50, 40
	s_cselect_b32 s29, s7, s25
	s_cselect_b32 s28, s6, s24
	s_cselect_b32 s27, s21, s49
	s_cselect_b32 s26, s20, s48
	v_lshl_add_u64 v[192:193], s[22:23], 0, v[172:173]
	s_add_i32 m0, s33, 0xc000
	s_nop 0
	global_load_lds_dwordx4 v[192:193], off
	v_lshl_add_u64 v[192:193], s[22:23], 0, v[174:175]
	s_add_i32 m0, s33, 0xe000
	s_nop 0
	global_load_lds_dwordx4 v[192:193], off
	ds_read_b128 v[128:131], v197
	ds_read_b128 v[132:135], v197 offset:1024
	ds_read_b128 v[136:139], v197 offset:2048
	ds_read_b128 v[140:143], v197 offset:3072
	ds_read_b128 v[144:147], v198
	ds_read_b128 v[148:151], v198 offset:1024
	ds_read_b128 v[152:155], v198 offset:2048
	ds_read_b128 v[156:159], v198 offset:3072
	ds_read_b128 v[160:163], v199
	ds_read_b128 v[180:183], v199 offset:1024
	ds_read_b128 v[184:187], v199 offset:2048
	ds_read_b128 v[188:191], v199 offset:3072
	ds_read_b128 v[200:203], v199 offset:4096
	ds_read_b128 v[204:207], v199 offset:5120
	ds_read_b128 v[208:211], v199 offset:6144
	ds_read_b128 v[212:215], v199 offset:7168
	s_waitcnt vmcnt(8)
	s_waitcnt lgkmcnt(0)
	s_barrier
	s_setprio 1
	s_waitcnt lgkmcnt(0)
	v_mfma_f32_16x16x32_bf16 v[124:127], v[128:131], v[160:163], v[124:127]
	v_mfma_f32_16x16x32_bf16 v[120:123], v[136:139], v[160:163], v[120:123]
	v_mfma_f32_16x16x32_bf16 v[108:111], v[128:131], v[184:187], v[108:111]
	v_mfma_f32_16x16x32_bf16 v[104:107], v[136:139], v[184:187], v[104:107]
	v_mfma_f32_16x16x32_bf16 v[96:99], v[128:131], v[200:203], v[96:99]
	v_mfma_f32_16x16x32_bf16 v[88:91], v[136:139], v[200:203], v[88:91]
	v_mfma_f32_16x16x32_bf16 v[80:83], v[128:131], v[208:211], v[80:83]
	v_mfma_f32_16x16x32_bf16 v[72:75], v[136:139], v[208:211], v[72:75]
	v_mfma_f32_16x16x32_bf16 v[124:127], v[132:135], v[180:183], v[124:127]
	v_mfma_f32_16x16x32_bf16 v[120:123], v[140:143], v[180:183], v[120:123]
	v_mfma_f32_16x16x32_bf16 v[108:111], v[132:135], v[188:191], v[108:111]
	v_mfma_f32_16x16x32_bf16 v[104:107], v[140:143], v[188:191], v[104:107]
	v_mfma_f32_16x16x32_bf16 v[96:99], v[132:135], v[204:207], v[96:99]
	v_mfma_f32_16x16x32_bf16 v[88:91], v[140:143], v[204:207], v[88:91]
	v_mfma_f32_16x16x32_bf16 v[80:83], v[132:135], v[212:215], v[80:83]
	v_mfma_f32_16x16x32_bf16 v[72:75], v[140:143], v[212:215], v[72:75]
	s_setprio 0
	s_setprio 1
	v_mfma_f32_16x16x32_bf16 v[116:119], v[144:147], v[160:163], v[116:119]
	v_mfma_f32_16x16x32_bf16 v[112:115], v[152:155], v[160:163], v[112:115]
	v_mfma_f32_16x16x32_bf16 v[100:103], v[144:147], v[184:187], v[100:103]
	v_mfma_f32_16x16x32_bf16 v[92:95], v[152:155], v[184:187], v[92:95]
	v_mfma_f32_16x16x32_bf16 v[84:87], v[144:147], v[200:203], v[84:87]
	v_mfma_f32_16x16x32_bf16 v[76:79], v[152:155], v[200:203], v[76:79]
	v_mfma_f32_16x16x32_bf16 v[68:71], v[144:147], v[208:211], v[68:71]
	v_mfma_f32_16x16x32_bf16 v[64:67], v[152:155], v[208:211], v[64:67]
	v_mfma_f32_16x16x32_bf16 v[116:119], v[148:151], v[180:183], v[116:119]
	v_mfma_f32_16x16x32_bf16 v[112:115], v[156:159], v[180:183], v[112:115]
	v_mfma_f32_16x16x32_bf16 v[100:103], v[148:151], v[188:191], v[100:103]
	v_mfma_f32_16x16x32_bf16 v[92:95], v[156:159], v[188:191], v[92:95]
	v_mfma_f32_16x16x32_bf16 v[84:87], v[148:151], v[204:207], v[84:87]
	v_mfma_f32_16x16x32_bf16 v[76:79], v[156:159], v[204:207], v[76:79]
	v_mfma_f32_16x16x32_bf16 v[68:71], v[148:151], v[212:215], v[68:71]
	v_mfma_f32_16x16x32_bf16 v[64:67], v[156:159], v[212:215], v[64:67]
	s_setprio 0
	s_barrier
	s_add_i32 s22, s42, s31
	v_lshl_add_u64 v[192:193], s[26:27], 0, v[166:167]
	s_mov_b32 m0, s22
	s_nop 0
	global_load_lds_dwordx4 v[192:193], off
	s_add_i32 m0, s22, 0x2000
	s_add_u32 s22, s26, 0xb0000
	v_lshl_add_u64 v[216:217], s[26:27], 0, v[170:171]
	s_addc_u32 s23, s27, 0
	s_add_i32 s51, s43, s31
	global_load_lds_dwordx4 v[216:217], off
	v_lshl_add_u64 v[218:219], s[22:23], 0, v[166:167]
	s_mov_b32 m0, s51
	v_lshl_add_u64 v[220:221], s[28:29], 0, v[168:169]
	global_load_lds_dwordx4 v[218:219], off
	v_lshl_add_u64 v[218:219], s[22:23], 0, v[170:171]
	s_add_i32 m0, s51, 0x2000
	s_nop 0
	global_load_lds_dwordx4 v[218:219], off
	v_lshl_add_u64 v[218:219], s[28:29], 0, v[164:165]
	s_mov_b32 m0, s33
	s_nop 0
	global_load_lds_dwordx4 v[218:219], off
	s_mov_b32 m0, s34
	s_nop 0
	global_load_lds_dwordx4 v[220:221], off
	ds_read_b128 v[160:163], v199 offset:16384
	ds_read_b128 v[180:183], v199 offset:17408
	ds_read_b128 v[184:187], v199 offset:18432
	ds_read_b128 v[188:191], v199 offset:19456
	ds_read_b128 v[200:203], v199 offset:20480
	ds_read_b128 v[204:207], v199 offset:21504
	ds_read_b128 v[208:211], v199 offset:22528
	ds_read_b128 v[212:215], v199 offset:23552
	s_waitcnt vmcnt(8)
	s_waitcnt lgkmcnt(0)
	s_barrier
; #define PG8_STAGE(bufoff, gbase, voff) do { _Pragma("unroll") for (int _i = 0; _i < 2; ++_i) \
;         __builtin_amdgcn_global_load_lds((const unsigned*)((const char*)(gbase) + (voff)[_i]), (LAS unsigned*)(lds + (bufoff) + ldsw + _i * 8192), 16, 0, 0); } while (0)
; #define PG8_LDA(dst, b, h) do { _Pragma("unroll") for (int m = 0; m < 4; ++m) _Pragma("unroll") for (int k = 0; k < 2; ++k) dst[m][k] = *(const LAS bf16x8*)(lds + PG8_SA(b, h) + aoff + m * 2048 + k * 1024); } while (0)
; #define PG8_LDB(dst, b, h) do { _Pragma("unroll") for (int n = 0; n < 2; ++n) _Pragma("unroll") for (int k = 0; k < 2; ++k) dst[n][k] = *(const LAS bf16x8*)(lds + PG8_SB(b, h) + boff + n * 2048 + k * 1024); } while (0)
; #define PG8_MMA(ai, bj, At, Bt) do { __builtin_amdgcn_s_setprio(1); _Pragma("unroll") for (int m = 0; m < 4; ++m) _Pragma("unroll") for (int n = 0; n < 2; ++n) _Pragma("unroll") for (int k = 0; k < 2; ++k) \
;         acc[ai][bj][m][n] = __builtin_amdgcn_mfma_f32_16x16x32_bf16(Bt[n][k], At[m][k], acc[ai][bj][m][n], 0, 0, 0); __builtin_amdgcn_s_setprio(0); } while (0)
; #define PG8_WAIT_V(n) asm volatile("s_waitcnt vmcnt(" #n ")" ::: "memory")
; #define PG8_WAIT_L(n) asm volatile("s_waitcnt lgkmcnt(" #n ")" ::: "memory")
; #define PG8_BAR __builtin_amdgcn_s_barrier()
; #define PG8_SCHED __builtin_amdgcn_sched_barrier(0)
; template <class Epi>
; __device__ __forceinline__ void gemm_phase(LAS unsigned char* lds, const Gemm g, const StaticOrder& S, const Epi& E, int wave_s) {
;     ...
;             PG8_WAIT_V(8); PG8_WAIT_L(0); PG8_BAR; PG8_MMA(0, 0, At, B0); PG8_MMA(0, 1, At, B1); PG8_BAR; PG8_SCHED;
;             PG8_LDA(At, 0, 1); PG8_STAGE(PG8_SB(0, 0), b2, voffB); PG8_STAGE(PG8_SB(0, 1), b2 + hstepB, voffB); PG8_STAGE(PG8_SA(0, 0), a2, voffA);
;             PG8_WAIT_V(8); PG8_WAIT_L(0); PG8_BAR; PG8_MMA(1, 0, At, B0); PG8_MMA(1, 1, At, B1); PG8_BAR; PG8_SCHED;
;             PG8_LDB(B0, 1, 0); PG8_LDB(B1, 1, 1); PG8_SCHED; PG8_LDA(At, 1, 0); PG8_STAGE(PG8_SA(0, 1), a2 + hstepA, voffA);
;             PG8_WAIT_V(8); PG8_WAIT_L(0); PG8_BAR; PG8_MMA(0, 0, At, B0); PG8_MMA(0, 1, At, B1); PG8_BAR; PG8_SCHED;
	s_setprio 1
	s_waitcnt lgkmcnt(0)
	v_mfma_f32_16x16x32_bf16 v[60:63], v[128:131], v[160:163], v[60:63]
	v_mfma_f32_16x16x32_bf16 v[56:59], v[136:139], v[160:163], v[56:59]
	v_mfma_f32_16x16x32_bf16 v[48:51], v[128:131], v[184:187], v[48:51]
	v_mfma_f32_16x16x32_bf16 v[40:43], v[136:139], v[184:187], v[40:43]
	v_mfma_f32_16x16x32_bf16 v[32:35], v[128:131], v[200:203], v[32:35]
	v_mfma_f32_16x16x32_bf16 v[24:27], v[136:139], v[200:203], v[24:27]
	v_mfma_f32_16x16x32_bf16 v[16:19], v[128:131], v[208:211], v[16:19]
	v_mfma_f32_16x16x32_bf16 v[8:11], v[136:139], v[208:211], v[8:11]
	v_mfma_f32_16x16x32_bf16 v[60:63], v[132:135], v[180:183], v[60:63]
	v_mfma_f32_16x16x32_bf16 v[56:59], v[140:143], v[180:183], v[56:59]
	v_mfma_f32_16x16x32_bf16 v[48:51], v[132:135], v[188:191], v[48:51]
	v_mfma_f32_16x16x32_bf16 v[40:43], v[140:143], v[188:191], v[40:43]
	v_mfma_f32_16x16x32_bf16 v[32:35], v[132:135], v[204:207], v[32:35]
	v_mfma_f32_16x16x32_bf16 v[24:27], v[140:143], v[204:207], v[24:27]
	v_mfma_f32_16x16x32_bf16 v[16:19], v[132:135], v[212:215], v[16:19]
	v_mfma_f32_16x16x32_bf16 v[8:11], v[140:143], v[212:215], v[8:11]
	s_setprio 0
	s_setprio 1
	v_mfma_f32_16x16x32_bf16 v[52:55], v[144:147], v[160:163], v[52:55]
	v_mfma_f32_16x16x32_bf16 v[44:47], v[152:155], v[160:163], v[44:47]
	v_mfma_f32_16x16x32_bf16 v[36:39], v[144:147], v[184:187], v[36:39]
	v_mfma_f32_16x16x32_bf16 v[28:31], v[152:155], v[184:187], v[28:31]
	v_mfma_f32_16x16x32_bf16 v[20:23], v[144:147], v[200:203], v[20:23]
	v_mfma_f32_16x16x32_bf16 v[12:15], v[152:155], v[200:203], v[12:15]
	v_mfma_f32_16x16x32_bf16 v[4:7], v[144:147], v[208:211], v[4:7]
	v_mfma_f32_16x16x32_bf16 v[0:3], v[152:155], v[208:211], v[0:3]
	v_mfma_f32_16x16x32_bf16 v[52:55], v[148:151], v[180:183], v[52:55]
	v_mfma_f32_16x16x32_bf16 v[44:47], v[156:159], v[180:183], v[44:47]
	v_mfma_f32_16x16x32_bf16 v[36:39], v[148:151], v[188:191], v[36:39]
	v_mfma_f32_16x16x32_bf16 v[28:31], v[156:159], v[188:191], v[28:31]
	v_mfma_f32_16x16x32_bf16 v[20:23], v[148:151], v[204:207], v[20:23]
	v_mfma_f32_16x16x32_bf16 v[12:15], v[156:159], v[204:207], v[12:15]
	v_mfma_f32_16x16x32_bf16 v[4:7], v[148:151], v[212:215], v[4:7]
	v_mfma_f32_16x16x32_bf16 v[0:3], v[156:159], v[212:215], v[0:3]
	s_setprio 0
	s_barrier
	s_add_i32 s51, 0, 0x18000
	s_add_i32 s52, 0, 0x1c000
	s_add_u32 s22, s28, 0xb0000
	s_addc_u32 s23, s29, 0
	s_mov_b32 m0, s35
	v_lshl_add_u64 v[222:223], s[22:23], 0, v[164:165]
	global_load_lds_dwordx4 v[222:223], off
	v_lshl_add_u64 v[222:223], s[22:23], 0, v[168:169]
	s_mov_b32 m0, s36
	s_nop 0
	global_load_lds_dwordx4 v[222:223], off
	v_add_u32_e32 v140, s51, v195
	v_add_u32_e32 v156, s52, v195
	ds_read_b128 v[128:131], v140
	ds_read_b128 v[132:135], v140 offset:1024
	ds_read_b128 v[136:139], v140 offset:2048
	ds_read_b128 v[140:143], v140 offset:3072
	ds_read_b128 v[144:147], v156
	ds_read_b128 v[148:151], v156 offset:1024
	ds_read_b128 v[152:155], v156 offset:2048
	ds_read_b128 v[156:159], v156 offset:3072
	ds_read_b128 v[160:163], v199 offset:32768
	ds_read_b128 v[180:183], v199 offset:33792
	ds_read_b128 v[184:187], v199 offset:34816
	ds_read_b128 v[188:191], v199 offset:35840
	ds_read_b128 v[200:203], v199 offset:36864
	ds_read_b128 v[204:207], v199 offset:37888
	ds_read_b128 v[208:211], v199 offset:38912
	ds_read_b128 v[212:215], v199 offset:39936
	s_waitcnt vmcnt(8)
	s_waitcnt lgkmcnt(0)
	s_barrier
	s_setprio 1
	s_waitcnt lgkmcnt(0)
	v_mfma_f32_16x16x32_bf16 v[124:127], v[128:131], v[160:163], v[124:127]
	v_mfma_f32_16x16x32_bf16 v[120:123], v[136:139], v[160:163], v[120:123]
	v_mfma_f32_16x16x32_bf16 v[108:111], v[128:131], v[184:187], v[108:111]
	v_mfma_f32_16x16x32_bf16 v[104:107], v[136:139], v[184:187], v[104:107]
	v_mfma_f32_16x16x32_bf16 v[96:99], v[128:131], v[200:203], v[96:99]
	v_mfma_f32_16x16x32_bf16 v[88:91], v[136:139], v[200:203], v[88:91]
	v_mfma_f32_16x16x32_bf16 v[80:83], v[128:131], v[208:211], v[80:83]
	v_mfma_f32_16x16x32_bf16 v[72:75], v[136:139], v[208:211], v[72:75]
	v_mfma_f32_16x16x32_bf16 v[124:127], v[132:135], v[180:183], v[124:127]
	v_mfma_f32_16x16x32_bf16 v[120:123], v[140:143], v[180:183], v[120:123]
	v_mfma_f32_16x16x32_bf16 v[108:111], v[132:135], v[188:191], v[108:111]
	v_mfma_f32_16x16x32_bf16 v[104:107], v[140:143], v[188:191], v[104:107]
	v_mfma_f32_16x16x32_bf16 v[96:99], v[132:135], v[204:207], v[96:99]
	v_mfma_f32_16x16x32_bf16 v[88:91], v[140:143], v[204:207], v[88:91]
	v_mfma_f32_16x16x32_bf16 v[80:83], v[132:135], v[212:215], v[80:83]
	v_mfma_f32_16x16x32_bf16 v[72:75], v[140:143], v[212:215], v[72:75]
	s_setprio 0
	s_setprio 1
	v_mfma_f32_16x16x32_bf16 v[116:119], v[144:147], v[160:163], v[116:119]
	v_mfma_f32_16x16x32_bf16 v[112:115], v[152:155], v[160:163], v[112:115]
	v_mfma_f32_16x16x32_bf16 v[100:103], v[144:147], v[184:187], v[100:103]
	v_mfma_f32_16x16x32_bf16 v[92:95], v[152:155], v[184:187], v[92:95]
	v_mfma_f32_16x16x32_bf16 v[84:87], v[144:147], v[200:203], v[84:87]
	v_mfma_f32_16x16x32_bf16 v[76:79], v[152:155], v[200:203], v[76:79]
	v_mfma_f32_16x16x32_bf16 v[68:71], v[144:147], v[208:211], v[68:71]
	v_mfma_f32_16x16x32_bf16 v[64:67], v[152:155], v[208:211], v[64:67]
	v_mfma_f32_16x16x32_bf16 v[116:119], v[148:151], v[180:183], v[116:119]
	v_mfma_f32_16x16x32_bf16 v[112:115], v[156:159], v[180:183], v[112:115]
	v_mfma_f32_16x16x32_bf16 v[100:103], v[148:151], v[188:191], v[100:103]
	v_mfma_f32_16x16x32_bf16 v[92:95], v[156:159], v[188:191], v[92:95]
	v_mfma_f32_16x16x32_bf16 v[84:87], v[148:151], v[204:207], v[84:87]
	v_mfma_f32_16x16x32_bf16 v[76:79], v[156:159], v[204:207], v[76:79]
	v_mfma_f32_16x16x32_bf16 v[68:71], v[148:151], v[212:215], v[68:71]
	v_mfma_f32_16x16x32_bf16 v[64:67], v[156:159], v[212:215], v[64:67]
	s_setprio 0
	s_barrier
; #define PG8_STAGE(bufoff, gbase, voff) do { _Pragma("unroll") for (int _i = 0; _i < 2; ++_i) \
;         __builtin_amdgcn_global_load_lds((const unsigned*)((const char*)(gbase) + (voff)[_i]), (LAS unsigned*)(lds + (bufoff) + ldsw + _i * 8192), 16, 0, 0); } while (0)
; #define PG8_LDA(dst, b, h) do { _Pragma("unroll") for (int m = 0; m < 4; ++m) _Pragma("unroll") for (int k = 0; k < 2; ++k) dst[m][k] = *(const LAS bf16x8*)(lds + PG8_SA(b, h) + aoff + m * 2048 + k * 1024); } while (0)
; #define PG8_MMA(ai, bj, At, Bt) do { __builtin_amdgcn_s_setprio(1); _Pragma("unroll") for (int m = 0; m < 4; ++m) _Pragma("unroll") for (int n = 0; n < 2; ++n) _Pragma("unroll") for (int k = 0; k < 2; ++k) \
;         acc[ai][bj][m][n] = __builtin_amdgcn_mfma_f32_16x16x32_bf16(Bt[n][k], At[m][k], acc[ai][bj][m][n], 0, 0, 0); __builtin_amdgcn_s_setprio(0); } while (0)
; #define PG8_WAIT_V(n) asm volatile("s_waitcnt vmcnt(" #n ")" ::: "memory")
; #define PG8_WAIT_L(n) asm volatile("s_waitcnt lgkmcnt(" #n ")" ::: "memory")
; #define PG8_BAR __builtin_amdgcn_s_barrier()
; #define PG8_SCHED __builtin_amdgcn_sched_barrier(0)
; template <class Epi>
; __device__ __forceinline__ void gemm_phase(LAS unsigned char* lds, const Gemm g, const StaticOrder& S, const Epi& E, int wave_s) {
;     ...
;             PG8_WAIT_V(8); PG8_WAIT_L(0); PG8_BAR; PG8_MMA(0, 0, At, B0); PG8_MMA(0, 1, At, B1); PG8_BAR; PG8_SCHED;
;             PG8_LDA(At, 1, 1); PG8_STAGE(PG8_SB(1, 0), b3, voffB); PG8_STAGE(PG8_SB(1, 1), b3 + hstepB, voffB); PG8_STAGE(PG8_SA(1, 0), a3, voffA);
;             PG8_WAIT_V(8); PG8_WAIT_L(0); PG8_BAR; PG8_MMA(1, 0, At, B0); PG8_MMA(1, 1, At, B1); PG8_BAR; PG8_SCHED;
;         }
;         if (wr == 0) PG8_BAR;
	s_add_i32 s22, s51, s31
	v_lshl_add_u64 v[192:193], v[192:193], 0, s[14:15]
	s_mov_b32 m0, s22
	s_nop 0
	global_load_lds_dwordx4 v[192:193], off
	s_add_i32 m0, s22, 0x2000
	s_add_u32 s22, s26, 0xb0080
	v_lshl_add_u64 v[192:193], v[216:217], 0, s[14:15]
	s_addc_u32 s23, s27, 0
	s_add_i32 s26, s52, s31
	global_load_lds_dwordx4 v[192:193], off
	v_lshl_add_u64 v[192:193], s[22:23], 0, v[166:167]
	s_mov_b32 m0, s26
	s_nop 0
	global_load_lds_dwordx4 v[192:193], off
	v_lshl_add_u64 v[192:193], s[22:23], 0, v[170:171]
	s_add_i32 m0, s26, 0x2000
	s_nop 0
	global_load_lds_dwordx4 v[192:193], off
	v_lshl_add_u64 v[192:193], v[218:219], 0, s[14:15]
	s_mov_b32 m0, s38
	s_nop 0
	global_load_lds_dwordx4 v[192:193], off
	v_lshl_add_u64 v[192:193], v[220:221], 0, s[14:15]
	s_mov_b32 m0, s39
	s_nop 0
	global_load_lds_dwordx4 v[192:193], off
	ds_read_b128 v[160:163], v199 offset:49152
	ds_read_b128 v[180:183], v199 offset:50176
	ds_read_b128 v[184:187], v199 offset:51200
	ds_read_b128 v[188:191], v199 offset:52224
	ds_read_b128 v[200:203], v199 offset:53248
	ds_read_b128 v[204:207], v199 offset:54272
	ds_read_b128 v[208:211], v199 offset:55296
	ds_read_b128 v[212:215], v199 offset:56320
	s_waitcnt vmcnt(8)
	s_waitcnt lgkmcnt(0)
	s_barrier
	s_setprio 1
	s_waitcnt lgkmcnt(0)
	v_mfma_f32_16x16x32_bf16 v[60:63], v[128:131], v[160:163], v[60:63]
	v_mfma_f32_16x16x32_bf16 v[56:59], v[136:139], v[160:163], v[56:59]
	v_mfma_f32_16x16x32_bf16 v[48:51], v[128:131], v[184:187], v[48:51]
	v_mfma_f32_16x16x32_bf16 v[40:43], v[136:139], v[184:187], v[40:43]
	v_mfma_f32_16x16x32_bf16 v[32:35], v[128:131], v[200:203], v[32:35]
	v_mfma_f32_16x16x32_bf16 v[24:27], v[136:139], v[200:203], v[24:27]
	v_mfma_f32_16x16x32_bf16 v[16:19], v[128:131], v[208:211], v[16:19]
	v_mfma_f32_16x16x32_bf16 v[8:11], v[136:139], v[208:211], v[8:11]
	v_mfma_f32_16x16x32_bf16 v[60:63], v[132:135], v[180:183], v[60:63]
	v_mfma_f32_16x16x32_bf16 v[56:59], v[140:143], v[180:183], v[56:59]
	v_mfma_f32_16x16x32_bf16 v[48:51], v[132:135], v[188:191], v[48:51]
	v_mfma_f32_16x16x32_bf16 v[40:43], v[140:143], v[188:191], v[40:43]
	v_mfma_f32_16x16x32_bf16 v[32:35], v[132:135], v[204:207], v[32:35]
	v_mfma_f32_16x16x32_bf16 v[24:27], v[140:143], v[204:207], v[24:27]
	v_mfma_f32_16x16x32_bf16 v[16:19], v[132:135], v[212:215], v[16:19]
	v_mfma_f32_16x16x32_bf16 v[8:11], v[140:143], v[212:215], v[8:11]
	s_setprio 0
	s_setprio 1
	v_mfma_f32_16x16x32_bf16 v[52:55], v[144:147], v[160:163], v[52:55]
	v_mfma_f32_16x16x32_bf16 v[44:47], v[152:155], v[160:163], v[44:47]
	v_mfma_f32_16x16x32_bf16 v[36:39], v[144:147], v[184:187], v[36:39]
	v_mfma_f32_16x16x32_bf16 v[28:31], v[152:155], v[184:187], v[28:31]
	v_mfma_f32_16x16x32_bf16 v[20:23], v[144:147], v[200:203], v[20:23]
	v_mfma_f32_16x16x32_bf16 v[12:15], v[152:155], v[200:203], v[12:15]
	v_mfma_f32_16x16x32_bf16 v[4:7], v[144:147], v[208:211], v[4:7]
	v_mfma_f32_16x16x32_bf16 v[0:3], v[152:155], v[208:211], v[0:3]
	v_mfma_f32_16x16x32_bf16 v[52:55], v[148:151], v[180:183], v[52:55]
	v_mfma_f32_16x16x32_bf16 v[44:47], v[156:159], v[180:183], v[44:47]
	v_mfma_f32_16x16x32_bf16 v[36:39], v[148:151], v[188:191], v[36:39]
	v_mfma_f32_16x16x32_bf16 v[28:31], v[156:159], v[188:191], v[28:31]
	v_mfma_f32_16x16x32_bf16 v[20:23], v[148:151], v[204:207], v[20:23]
	v_mfma_f32_16x16x32_bf16 v[12:15], v[156:159], v[204:207], v[12:15]
	v_mfma_f32_16x16x32_bf16 v[4:7], v[148:151], v[212:215], v[4:7]
	v_mfma_f32_16x16x32_bf16 v[0:3], v[156:159], v[212:215], v[0:3]
	s_setprio 0
	s_barrier
	s_add_i32 s50, s50, 2
	s_add_u32 s48, s48, 0x100
	s_addc_u32 s49, s49, 0
	s_cmp_gt_u32 s50, 41
	s_mov_b64 s[22:23], s[24:25]
	s_cbranch_scc0 .LBB0_2225
	s_and_b64 vcc, exec, s[18:19]
	s_cbranch_vccz .LBB0_2228
	s_barrier
